# v25 plus arrival-counter polling, rsqrt scaling removal, P3 epilogue gate-load hoist, b_unit table prefetch (stack check)
# baseline (speedup 1.0000x reference)
; __device__ __forceinline__ unsigned xb_ld(unsigned* p)              { return __hip_atomic_load(p, __ATOMIC_RELAXED, __HIP_MEMORY_SCOPE_AGENT); }
; __device__ __forceinline__ unsigned xb_add(unsigned* p, unsigned v) { return __hip_atomic_fetch_add(p, v, __ATOMIC_RELAXED, __HIP_MEMORY_SCOPE_AGENT); }
; #define XB_SPIN(cond, bar) do { unsigned _sp = 0; while (cond) { __builtin_amdgcn_s_sleep(1); \
;     if ((++_sp & 255u) == 0u) { if (xb_ld(&(bar)[XB_TMO])) break; if (_sp > XB_SPIN_CAP) { atomicAdd(&(bar)[XB_TMO], 1u); break; } } } } while (0)
; __device__ __forceinline__ bool is_t0(int wave) { return wave == 0 && olane() == 0; }
; __device__ __forceinline__ void xcdl_barrier(const XcdBarrier& b) {
;     asm volatile("s_waitcnt vmcnt(0)" ::: "memory");
;     __syncthreads();
;     if (is_t0(b.wave)) {
;         unsigned* bar = b.bar; asm volatile("" : "+s"(bar));
;         __builtin_amdgcn_s_waitcnt(0);
;         const unsigned old = xb_add(&bar[XB_LSUB(b.x)], 1u);
;         const unsigned gen = old >> 5;
;         if ((old & 31u) == 31u) xb_add(&bar[XB_LGEN(b.x)], 1u);
;         else XB_SPIN(xb_ld(&bar[XB_LGEN(b.x)]) == gen, bar);
;         __builtin_amdgcn_fence(__ATOMIC_ACQUIRE, "agent");
;         asm volatile("s_waitcnt vmcnt(0)" ::: "memory");
;     }
;     __syncthreads();
; }
.LBB0_447:
	s_and_b64 vcc, exec, s[0:1]
	s_cbranch_vccz .LBB0_467
	s_waitcnt vmcnt(0)
	s_and_b64 vcc, exec, s[46:47]
	s_waitcnt vmcnt(0)
	s_barrier
	s_cbranch_vccnz .LBB0_466
	v_mbcnt_lo_u32_b32 v0, -1, 0
	v_mbcnt_hi_u32_b32 v0, -1, v0
	s_nop 0
	v_cmp_eq_u32_e32 vcc, 0, v0
	s_and_saveexec_b64 s[2:3], vcc
	s_cbranch_execz .LBB0_465
	s_mov_b64 s[0:1], s[26:27]
	s_lshl_b32 s6, s23, 2
	s_add_u32 s6, s0, s6
	s_addc_u32 s7, s1, 0
	v_mov_b32_e32 v0, s6
	v_add_co_u32_e32 v0, vcc, 0x3000, v0
	v_mov_b32_e32 v1, s7
	s_nop 0
	v_addc_co_u32_e32 v1, vcc, 0, v1, vcc
	v_mov_b32_e32 v2, 1
	s_waitcnt vmcnt(0) expcnt(0) lgkmcnt(0)
	flat_atomic_add v2, v[0:1], v2 offset:1536 sc0
	s_add_u32 s28, s6, 0x4600
	s_addc_u32 s29, s7, 0
	s_add_u32 s98, s6, 0x3600
	s_addc_u32 s99, s7, 0
	s_nop 0
	s_nop 0
	s_nop 0
	s_nop 0
	s_nop 0
	s_nop 0
	s_nop 0
	s_nop 0
	s_nop 0
	s_nop 0
	s_nop 0
	s_mov_b64 s[8:9], -1
	s_waitcnt vmcnt(0) lgkmcnt(0)
	v_and_b32_e32 v0, 31, v2
	v_cmp_ne_u32_e32 vcc, 31, v0
	v_mov_b64_e32 v[0:1], s[28:29]
	s_and_saveexec_b64 s[6:7], vcc
	s_cbranch_execz .LBB0_462
	v_mov_b64_e32 v[0:1], s[98:99]
	flat_load_dword v1, v[0:1] sc1
	v_lshrrev_b32_e32 v0, 5, v2
	s_mov_b64 s[8:9], 0
	s_waitcnt vmcnt(0) lgkmcnt(0)
	v_lshrrev_b32_e32 v1, 5, v1
	v_cmp_eq_u32_e32 vcc, v1, v0
	s_and_saveexec_b64 s[38:39], vcc
	s_cbranch_execz .LBB0_461
	s_add_u32 s30, s0, 0x200
	s_addc_u32 s31, s1, 0
	s_mov_b32 s17, 1
	s_mov_b64 s[0:1], 0
	s_branch .LBB0_454

; __device__ __forceinline__ unsigned xb_ld(unsigned* p)              { return __hip_atomic_load(p, __ATOMIC_RELAXED, __HIP_MEMORY_SCOPE_AGENT); }
; #define XB_SPIN(cond, bar) do { unsigned _sp = 0; while (cond) { __builtin_amdgcn_s_sleep(1); \
;     if ((++_sp & 255u) == 0u) { if (xb_ld(&(bar)[XB_TMO])) break; if (_sp > XB_SPIN_CAP) { atomicAdd(&(bar)[XB_TMO], 1u); break; } } } } while (0)
; __device__ __forceinline__ void xcdl_barrier(const XcdBarrier& b) {
;     ...
;         else XB_SPIN(xb_ld(&bar[XB_LGEN(b.x)]) == gen, bar);
.LBB0_459:
	v_mov_b64_e32 v[2:3], s[98:99]
	flat_load_dword v1, v[2:3] sc1
	s_add_i32 s17, s17, 1
	s_or_b64 s[36:37], s[36:37], exec
	s_waitcnt vmcnt(0) lgkmcnt(0)
	v_lshrrev_b32_e32 v1, 5, v1
	v_cmp_ne_u32_e32 vcc, v1, v0
	s_orn2_b64 s[10:11], vcc, exec
	s_branch .LBB0_453

; #define LAS __attribute__((address_space(3)))
; #define BU_LOAD(buf, ib) do { _Pragma("unroll") for (int h = 0; h < 2; ++h) { const int it = (2 * (ib) + h + k2) & 7, l = 16 * w + 2 * it + rp; \
;             _Pragma("unroll") for (int s2 = 0; s2 < 8; ++s2) c4[buf][h][s2] = *(const GAS u32x4*)(z0 + (size_t)l * 2048 + 256 * s2); } } while (0)
; __device__ __forceinline__ void b_unit(Frame& F, int u, bool dry) {
;     ...
;     LAS unsigned char* Bt = F.lds;
;     {
;         const f32x2* TW = (const f32x2*)(ws_ + WS_TW) + k2 * 256 + 8 * sg; const f32x2* W8 = (const f32x2*)(ws_ + WS_W8);
;         f32x2 tw[8], w8[8];
; #pragma unroll
;         for (int j = 0; j < 8; ++j) { tw[j] = TW[j]; w8[j] = W8[(j * k2) & 7]; }
;         const bf16_t* z0 = (const bf16_t*)(ws_ + WS_ZT) + (size_t)(b * 512 + g * 128) * 2048 + 8 * sg;
;         u32x4 c4[2][2][8];
;     ...
;         BU_LOAD(0, 0);
;         BU_LOAD(1, 1); BU_RED(0, 0);
.LBB0_468:
	s_cmp_le_i32 s66, s16
	s_cselect_b64 s[0:1], -1, 0
	s_and_b64 s[4:5], s[0:1], s[4:5]
	s_andn2_b64 vcc, exec, s[4:5]
	s_cbranch_vccnz .LBB0_562
	s_mov_b64 s[2:3], s[82:83]
	v_readlane_b32 s0, v254, 23
	v_mbcnt_lo_u32_b32 v170, -1, 0
	v_mbcnt_hi_u32_b32 v170, -1, v170
	s_add_u32 s0, s2, s0
	v_and_b32_e32 v18, 31, v170
	s_addc_u32 s1, s3, 0
	v_lshlrev_b32_e32 v192, 6, v18
	v_lshl_add_u64 v[0:1], s[0:1], 0, v[192:193]
	s_mov_b64 s[0:1], 0x1dd0000
	v_lshl_add_u64 v[2:3], v[0:1], 0, s[0:1]
	s_mov_b32 s0, 0x1dd0000
	v_add_co_u32_e32 v0, vcc, s0, v0
	s_add_u32 s6, s2, 0x1dd4000
	s_nop 0
	v_addc_co_u32_e32 v1, vcc, 0, v1, vcc
	s_addc_u32 s7, s3, 0
	flat_load_dwordx4 v[8:11], v[0:1]
	v_mov_b32_e32 v0, s2
	s_mov_b32 s8, 0x1dd4000
	v_readlane_b32 s0, v254, 24
	v_add_co_u32_e32 v0, vcc, s8, v0
	v_mov_b32_e32 v1, s3
	s_add_u32 s0, s6, s0
	v_addc_co_u32_e32 v1, vcc, 0, v1, vcc
	s_addc_u32 s1, s7, 0
	flat_load_dwordx2 v[144:145], v[0:1]
	v_mov_b64_e32 v[0:1], s[0:1]
	v_readlane_b32 s0, v254, 25
	s_add_u32 s0, s6, s0
	s_addc_u32 s1, s7, 0
	flat_load_dwordx2 v[146:147], v[0:1]
	flat_load_dwordx4 v[12:15], v[2:3] offset:16
	v_mov_b64_e32 v[0:1], s[0:1]
	v_readlane_b32 s0, v254, 26
	s_add_u32 s0, s6, s0
	s_addc_u32 s1, s7, 0
	flat_load_dwordx2 v[148:149], v[0:1]
	v_mov_b64_e32 v[0:1], s[0:1]
	v_readlane_b32 s0, v254, 27
	s_add_u32 s0, s6, s0
	s_addc_u32 s1, s7, 0
	flat_load_dwordx2 v[150:151], v[0:1]
	flat_load_dwordx4 v[4:7], v[2:3] offset:32
	v_mov_b64_e32 v[0:1], s[0:1]
	v_readlane_b32 s0, v254, 28
	s_add_u32 s0, s6, s0
	s_addc_u32 s1, s7, 0
	flat_load_dwordx2 v[152:153], v[0:1]
	v_mov_b64_e32 v[0:1], s[0:1]
	v_readlane_b32 s0, v254, 29
	s_add_u32 s0, s6, s0
	s_addc_u32 s1, s7, 0
	v_mov_b64_e32 v[16:17], s[0:1]
	v_readlane_b32 s0, v254, 30
	s_add_u32 s0, s6, s0
	s_addc_u32 s1, s7, 0
	flat_load_dwordx2 v[154:155], v[0:1]
	s_nop 0
	flat_load_dwordx4 v[0:3], v[2:3] offset:48
	v_lshlrev_b32_e32 v192, 4, v18
	flat_load_dwordx2 v[156:157], v[16:17]
	v_mov_b64_e32 v[16:17], s[0:1]
	v_readlane_b32 s0, v253, 43
	v_readlane_b32 s1, v253, 44
	s_add_u32 s0, s2, s0
	s_addc_u32 s1, s3, s1
	flat_load_dwordx2 v[158:159], v[16:17]
	v_lshl_add_u64 v[16:17], s[0:1], 0, v[192:193]
	s_mov_b64 s[0:1], 0x8000000
	v_bfe_u32 v172, v170, 5, 1
	v_lshl_add_u64 v[162:163], v[16:17], 0, s[0:1]
	v_readlane_b32 s0, v253, 45
	v_mov_b32_e32 v139, v193
	v_readlane_b32 s1, v253, 46
	v_or_b32_e32 v138, s0, v172
	v_lshlrev_b64 v[16:17], 12, v[138:139]
	v_lshl_add_u64 v[16:17], v[162:163], 0, v[16:17]
	global_load_dwordx4 v[140:143], v[16:17], off sc1
	global_load_dwordx4 v[174:177], v[16:17], off offset:512 sc1
	global_load_dwordx4 v[72:75], v[16:17], off offset:1024 sc1
	global_load_dwordx4 v[104:107], v[16:17], off offset:1536 sc1
	global_load_dwordx4 v[112:115], v[16:17], off offset:2048 sc1
	global_load_dwordx4 v[116:119], v[16:17], off offset:2560 sc1
	global_load_dwordx4 v[120:123], v[16:17], off offset:3072 sc1
	global_load_dwordx4 v[124:127], v[16:17], off offset:3584 sc1
	v_or_b32_e32 v136, s1, v172
	v_mov_b32_e32 v137, v193
	v_lshlrev_b64 v[16:17], 12, v[136:137]
	v_lshl_add_u64 v[16:17], v[162:163], 0, v[16:17]
	global_load_dwordx4 v[108:111], v[16:17], off sc1
	global_load_dwordx4 v[76:79], v[16:17], off offset:512 sc1
	global_load_dwordx4 v[60:63], v[16:17], off offset:1024 sc1
	global_load_dwordx4 v[56:59], v[16:17], off offset:1536 sc1
	global_load_dwordx4 v[52:55], v[16:17], off offset:2048 sc1
	global_load_dwordx4 v[48:51], v[16:17], off offset:2560 sc1
	global_load_dwordx4 v[44:47], v[16:17], off offset:3072 sc1
	global_load_dwordx4 v[40:43], v[16:17], off offset:3584 sc1
	v_readlane_b32 s1, v253, 47
	v_mov_b32_e32 v167, v193
	v_mov_b32_e32 v165, v193
	v_or_b32_e32 v166, s1, v172
	v_lshlrev_b64 v[16:17], 12, v[166:167]
	v_lshl_add_u64 v[16:17], v[162:163], 0, v[16:17]
	global_load_dwordx4 v[132:135], v[16:17], off sc1
	global_load_dwordx4 v[128:131], v[16:17], off offset:512 sc1
	global_load_dwordx4 v[100:103], v[16:17], off offset:1024 sc1
	global_load_dwordx4 v[96:99], v[16:17], off offset:1536 sc1
	global_load_dwordx4 v[92:95], v[16:17], off offset:2048 sc1
	global_load_dwordx4 v[88:91], v[16:17], off offset:2560 sc1
	global_load_dwordx4 v[84:87], v[16:17], off offset:3072 sc1
	global_load_dwordx4 v[80:83], v[16:17], off offset:3584 sc1
	v_readlane_b32 s1, v253, 48
	s_movk_i32 s6, 0x410
	v_and_b32_e32 v171, 63, v170
	v_or_b32_e32 v164, s1, v172
	v_lshlrev_b64 v[16:17], 12, v[164:165]
	v_lshl_add_u64 v[16:17], v[162:163], 0, v[16:17]
	global_load_dwordx4 v[68:71], v[16:17], off sc1
	global_load_dwordx4 v[64:67], v[16:17], off offset:512 sc1
	global_load_dwordx4 v[36:39], v[16:17], off offset:1024 sc1
	global_load_dwordx4 v[32:35], v[16:17], off offset:1536 sc1
	global_load_dwordx4 v[28:31], v[16:17], off offset:2048 sc1
	global_load_dwordx4 v[24:27], v[16:17], off offset:2560 sc1
	global_load_dwordx4 v[20:23], v[16:17], off offset:3072 sc1
	s_nop 0
	global_load_dwordx4 v[16:19], v[16:17], off offset:3584 sc1
	s_mov_b32 s7, 0x1d90000
	s_mov_b64 s[28:29], s[82:83]
	s_waitcnt vmcnt(0)
	v_lshlrev_b32_e32 v160, 16, v140
	v_and_b32_e32 v161, 0xffff0000, v140
	v_lshlrev_b32_e32 v178, 16, v174
	v_and_b32_e32 v179, 0xffff0000, v174
	s_waitcnt lgkmcnt(0)
	v_pk_fma_f32 v[182:183], v[144:145], v[160:161], 0 op_sel_hi:[0,1,0]
	v_pk_fma_f32 v[160:161], v[144:145], v[160:161], 0 op_sel:[1,0,0] op_sel_hi:[1,1,0]
	v_pk_fma_f32 v[182:183], v[146:147], v[178:179], v[182:183] op_sel_hi:[0,1,1]
	v_pk_fma_f32 v[160:161], v[146:147], v[178:179], v[160:161] op_sel:[1,0,0]
	v_lshlrev_b32_e32 v178, 16, v72
	v_and_b32_e32 v179, 0xffff0000, v72
	v_pk_fma_f32 v[182:183], v[148:149], v[178:179], v[182:183] op_sel_hi:[0,1,1]
	v_pk_fma_f32 v[160:161], v[148:149], v[178:179], v[160:161] op_sel:[1,0,0]
	v_lshlrev_b32_e32 v178, 16, v104
	v_and_b32_e32 v179, 0xffff0000, v104
	v_pk_fma_f32 v[182:183], v[150:151], v[178:179], v[182:183] op_sel_hi:[0,1,1]
	v_pk_fma_f32 v[160:161], v[150:151], v[178:179], v[160:161] op_sel:[1,0,0]
	v_lshlrev_b32_e32 v178, 16, v112
	v_and_b32_e32 v179, 0xffff0000, v112
	v_pk_fma_f32 v[182:183], v[152:153], v[178:179], v[182:183] op_sel_hi:[0,1,1]
	v_pk_fma_f32 v[160:161], v[152:153], v[178:179], v[160:161] op_sel:[1,0,0]
	v_lshlrev_b32_e32 v178, 16, v116
	v_and_b32_e32 v179, 0xffff0000, v116
	v_pk_fma_f32 v[182:183], v[154:155], v[178:179], v[182:183] op_sel_hi:[0,1,1]
	v_pk_fma_f32 v[160:161], v[154:155], v[178:179], v[160:161] op_sel:[1,0,0]
	v_lshlrev_b32_e32 v178, 16, v120
	v_and_b32_e32 v179, 0xffff0000, v120
	v_pk_fma_f32 v[182:183], v[156:157], v[178:179], v[182:183] op_sel_hi:[0,1,1]
	v_pk_fma_f32 v[160:161], v[156:157], v[178:179], v[160:161] op_sel:[1,0,0]
	v_lshlrev_b32_e32 v178, 16, v124
	v_and_b32_e32 v179, 0xffff0000, v124
	v_pk_fma_f32 v[182:183], v[158:159], v[178:179], v[182:183] op_sel_hi:[0,1,1]
	v_pk_fma_f32 v[178:179], v[158:159], v[178:179], v[160:161] op_sel:[1,0,0]
	v_mov_b32_e32 v161, v10
	v_mov_b32_e32 v10, v9
	v_mov_b32_e32 v160, v8
	v_pk_mul_f32 v[8:9], v[10:11], v[178:179]
	v_lshlrev_b32_e32 v140, 16, v141
	v_and_b32_e32 v141, 0xffff0000, v141
	v_pk_fma_f32 v[184:185], v[160:161], v[182:183], v[8:9] neg_lo:[0,0,1] neg_hi:[0,0,1]
	v_pk_mul_f32 v[8:9], v[160:161], v[178:179]
	v_lshlrev_b32_e32 v174, 16, v175
	v_and_b32_e32 v175, 0xffff0000, v175
	v_pk_fma_f32 v[178:179], v[10:11], v[182:183], v[8:9]
	v_pk_fma_f32 v[8:9], v[144:145], v[140:141], 0 op_sel_hi:[0,1,0]
	v_pk_fma_f32 v[140:141], v[144:145], v[140:141], 0 op_sel:[1,0,0] op_sel_hi:[1,1,0]
	v_pk_fma_f32 v[8:9], v[146:147], v[174:175], v[8:9] op_sel_hi:[0,1,1]
	v_pk_fma_f32 v[140:141], v[146:147], v[174:175], v[140:141] op_sel:[1,0,0]
	v_lshlrev_b32_e32 v72, 16, v73
	v_and_b32_e32 v73, 0xffff0000, v73
	v_pk_fma_f32 v[8:9], v[148:149], v[72:73], v[8:9] op_sel_hi:[0,1,1]
	v_pk_fma_f32 v[72:73], v[148:149], v[72:73], v[140:141] op_sel:[1,0,0]
	v_lshlrev_b32_e32 v104, 16, v105
	v_and_b32_e32 v105, 0xffff0000, v105
	v_pk_fma_f32 v[8:9], v[150:151], v[104:105], v[8:9] op_sel_hi:[0,1,1]
	v_pk_fma_f32 v[72:73], v[150:151], v[104:105], v[72:73] op_sel:[1,0,0]
	v_lshlrev_b32_e32 v104, 16, v113
	v_and_b32_e32 v105, 0xffff0000, v113
	v_pk_fma_f32 v[8:9], v[152:153], v[104:105], v[8:9] op_sel_hi:[0,1,1]
	v_pk_fma_f32 v[72:73], v[152:153], v[104:105], v[72:73] op_sel:[1,0,0]
	v_lshlrev_b32_e32 v104, 16, v117
	v_and_b32_e32 v105, 0xffff0000, v117
	v_pk_fma_f32 v[8:9], v[154:155], v[104:105], v[8:9] op_sel_hi:[0,1,1]
	v_pk_fma_f32 v[72:73], v[154:155], v[104:105], v[72:73] op_sel:[1,0,0]
	v_lshlrev_b32_e32 v104, 16, v121
	v_and_b32_e32 v105, 0xffff0000, v121
	v_pk_fma_f32 v[8:9], v[156:157], v[104:105], v[8:9] op_sel_hi:[0,1,1]
	v_pk_fma_f32 v[72:73], v[156:157], v[104:105], v[72:73] op_sel:[1,0,0]
	v_lshlrev_b32_e32 v104, 16, v125
	v_and_b32_e32 v105, 0xffff0000, v125
	v_pk_fma_f32 v[112:113], v[158:159], v[104:105], v[8:9] op_sel_hi:[0,1,1]
	v_pk_fma_f32 v[72:73], v[158:159], v[104:105], v[72:73] op_sel:[1,0,0]
	v_mov_b32_e32 v9, v14
	v_mov_b32_e32 v14, v13
	v_mov_b32_e32 v8, v12
	v_pk_mul_f32 v[12:13], v[14:15], v[72:73]
	v_lshlrev_b32_e32 v168, 16, v142
	v_and_b32_e32 v169, 0xffff0000, v142
	v_pk_fma_f32 v[104:105], v[8:9], v[112:113], v[12:13] neg_lo:[0,0,1] neg_hi:[0,0,1]
	v_pk_mul_f32 v[12:13], v[8:9], v[72:73]
	v_lshlrev_b32_e32 v180, 16, v176
	v_and_b32_e32 v181, 0xffff0000, v176
	v_pk_fma_f32 v[112:113], v[14:15], v[112:113], v[12:13]
	v_pk_fma_f32 v[12:13], v[144:145], v[168:169], 0 op_sel_hi:[0,1,0]
	v_pk_fma_f32 v[72:73], v[144:145], v[168:169], 0 op_sel:[1,0,0] op_sel_hi:[1,1,0]
	v_pk_fma_f32 v[12:13], v[146:147], v[180:181], v[12:13] op_sel_hi:[0,1,1]
	v_pk_fma_f32 v[72:73], v[146:147], v[180:181], v[72:73] op_sel:[1,0,0]
	v_lshlrev_b32_e32 v116, 16, v74
	v_and_b32_e32 v117, 0xffff0000, v74
	v_pk_fma_f32 v[12:13], v[148:149], v[116:117], v[12:13] op_sel_hi:[0,1,1]
	v_pk_fma_f32 v[72:73], v[148:149], v[116:117], v[72:73] op_sel:[1,0,0]
	v_lshlrev_b32_e32 v116, 16, v106
	v_and_b32_e32 v117, 0xffff0000, v106
	v_pk_fma_f32 v[12:13], v[150:151], v[116:117], v[12:13] op_sel_hi:[0,1,1]
	v_pk_fma_f32 v[72:73], v[150:151], v[116:117], v[72:73] op_sel:[1,0,0]
	v_lshlrev_b32_e32 v116, 16, v114
	v_and_b32_e32 v117, 0xffff0000, v114
	v_pk_fma_f32 v[12:13], v[152:153], v[116:117], v[12:13] op_sel_hi:[0,1,1]
	v_pk_fma_f32 v[72:73], v[152:153], v[116:117], v[72:73] op_sel:[1,0,0]
	v_lshlrev_b32_e32 v116, 16, v118
	v_and_b32_e32 v117, 0xffff0000, v118
	v_pk_fma_f32 v[12:13], v[154:155], v[116:117], v[12:13] op_sel_hi:[0,1,1]
	v_pk_fma_f32 v[72:73], v[154:155], v[116:117], v[72:73] op_sel:[1,0,0]
	v_lshlrev_b32_e32 v116, 16, v122
	v_and_b32_e32 v117, 0xffff0000, v122
	v_pk_fma_f32 v[12:13], v[156:157], v[116:117], v[12:13] op_sel_hi:[0,1,1]
	v_pk_fma_f32 v[72:73], v[156:157], v[116:117], v[72:73] op_sel:[1,0,0]
	v_lshlrev_b32_e32 v116, 16, v126
	v_and_b32_e32 v117, 0xffff0000, v126
	v_pk_fma_f32 v[120:121], v[158:159], v[116:117], v[12:13] op_sel_hi:[0,1,1]
	v_pk_fma_f32 v[72:73], v[158:159], v[116:117], v[72:73] op_sel:[1,0,0]
	v_mov_b32_e32 v13, v6
	v_mov_b32_e32 v6, v5
	v_mov_b32_e32 v12, v4
	v_pk_mul_f32 v[4:5], v[6:7], v[72:73]
	v_lshlrev_b32_e32 v142, 16, v143
	v_and_b32_e32 v143, 0xffff0000, v143
	v_pk_fma_f32 v[116:117], v[12:13], v[120:121], v[4:5] neg_lo:[0,0,1] neg_hi:[0,0,1]
	v_pk_mul_f32 v[4:5], v[12:13], v[72:73]
	v_lshlrev_b32_e32 v176, 16, v177
	v_and_b32_e32 v177, 0xffff0000, v177
	v_pk_fma_f32 v[120:121], v[6:7], v[120:121], v[4:5]
	v_pk_fma_f32 v[4:5], v[144:145], v[142:143], 0 op_sel_hi:[0,1,0]
	v_pk_fma_f32 v[72:73], v[144:145], v[142:143], 0 op_sel:[1,0,0] op_sel_hi:[1,1,0]
	v_pk_fma_f32 v[4:5], v[146:147], v[176:177], v[4:5] op_sel_hi:[0,1,1]
	v_pk_fma_f32 v[72:73], v[146:147], v[176:177], v[72:73] op_sel:[1,0,0]
	v_lshlrev_b32_e32 v74, 16, v75
	v_and_b32_e32 v75, 0xffff0000, v75
	v_pk_fma_f32 v[4:5], v[148:149], v[74:75], v[4:5] op_sel_hi:[0,1,1]
	v_pk_fma_f32 v[72:73], v[148:149], v[74:75], v[72:73] op_sel:[1,0,0]
	v_lshlrev_b32_e32 v74, 16, v107
	v_and_b32_e32 v75, 0xffff0000, v107
	v_pk_fma_f32 v[4:5], v[150:151], v[74:75], v[4:5] op_sel_hi:[0,1,1]
	v_pk_fma_f32 v[72:73], v[150:151], v[74:75], v[72:73] op_sel:[1,0,0]
	v_lshlrev_b32_e32 v74, 16, v115
	v_and_b32_e32 v75, 0xffff0000, v115
	v_pk_fma_f32 v[4:5], v[152:153], v[74:75], v[4:5] op_sel_hi:[0,1,1]
	v_pk_fma_f32 v[72:73], v[152:153], v[74:75], v[72:73] op_sel:[1,0,0]
	v_lshlrev_b32_e32 v74, 16, v119
	v_and_b32_e32 v75, 0xffff0000, v119
	v_pk_fma_f32 v[4:5], v[154:155], v[74:75], v[4:5] op_sel_hi:[0,1,1]
	v_pk_fma_f32 v[72:73], v[154:155], v[74:75], v[72:73] op_sel:[1,0,0]
	v_lshlrev_b32_e32 v74, 16, v123
	v_and_b32_e32 v75, 0xffff0000, v123
	v_pk_fma_f32 v[4:5], v[156:157], v[74:75], v[4:5] op_sel_hi:[0,1,1]
	v_pk_fma_f32 v[72:73], v[156:157], v[74:75], v[72:73] op_sel:[1,0,0]
	v_lshlrev_b32_e32 v74, 16, v127
	v_and_b32_e32 v75, 0xffff0000, v127
	v_pk_fma_f32 v[106:107], v[158:159], v[74:75], v[4:5] op_sel_hi:[0,1,1]
	v_pk_fma_f32 v[72:73], v[158:159], v[74:75], v[72:73] op_sel:[1,0,0]
	v_mov_b32_e32 v5, v2
	v_mov_b32_e32 v2, v1
	v_mov_b32_e32 v4, v0
	v_pk_mul_f32 v[0:1], v[2:3], v[72:73]
	v_pk_mul_f32 v[72:73], v[4:5], v[72:73]
	v_pk_fma_f32 v[0:1], v[4:5], v[106:107], v[0:1] neg_lo:[0,0,1] neg_hi:[0,0,1]
	v_pk_fma_f32 v[106:107], v[2:3], v[106:107], v[72:73]
	v_cvt_pk_bf16_f32 v75, v0, v1
	v_mul_lo_u32 v0, v138, s6
	v_cvt_pk_bf16_f32 v72, v184, v185
	v_cvt_pk_bf16_f32 v73, v104, v105
	v_cvt_pk_bf16_f32 v74, v116, v117
	v_add3_u32 v0, 0, v0, v192
	ds_write_b128 v0, v[72:75]
	v_cvt_pk_bf16_f32 v72, v178, v179
	v_cvt_pk_bf16_f32 v73, v112, v113
	v_cvt_pk_bf16_f32 v74, v120, v121
	v_cvt_pk_bf16_f32 v75, v106, v107
	ds_write_b128 v0, v[72:75] offset:512
	v_lshlrev_b32_e32 v0, 16, v108
	v_and_b32_e32 v1, 0xffff0000, v108
	v_lshlrev_b32_e32 v74, 16, v110
	v_and_b32_e32 v75, 0xffff0000, v110
	v_lshlrev_b32_e32 v104, 16, v111
	v_and_b32_e32 v105, 0xffff0000, v111
	v_lshlrev_b32_e32 v106, 16, v76
	v_and_b32_e32 v107, 0xffff0000, v76
	v_pk_fma_f32 v[110:111], v[144:145], v[0:1], 0 op_sel_hi:[0,1,0]
	v_pk_fma_f32 v[0:1], v[144:145], v[0:1], 0 op_sel:[1,0,0] op_sel_hi:[1,1,0]
	v_pk_fma_f32 v[110:111], v[146:147], v[106:107], v[110:111] op_sel_hi:[0,1,1]
	v_pk_fma_f32 v[0:1], v[146:147], v[106:107], v[0:1] op_sel:[1,0,0]
	v_lshlrev_b32_e32 v106, 16, v60
	v_and_b32_e32 v107, 0xffff0000, v60
	v_pk_fma_f32 v[110:111], v[148:149], v[106:107], v[110:111] op_sel_hi:[0,1,1]
	v_pk_fma_f32 v[0:1], v[148:149], v[106:107], v[0:1] op_sel:[1,0,0]
	v_lshlrev_b32_e32 v106, 16, v56
	v_and_b32_e32 v107, 0xffff0000, v56
	v_pk_fma_f32 v[110:111], v[150:151], v[106:107], v[110:111] op_sel_hi:[0,1,1]
	v_pk_fma_f32 v[0:1], v[150:151], v[106:107], v[0:1] op_sel:[1,0,0]
	v_lshlrev_b32_e32 v106, 16, v52
	v_and_b32_e32 v107, 0xffff0000, v52
	v_pk_fma_f32 v[110:111], v[152:153], v[106:107], v[110:111] op_sel_hi:[0,1,1]
	v_pk_fma_f32 v[0:1], v[152:153], v[106:107], v[0:1] op_sel:[1,0,0]
	v_lshlrev_b32_e32 v106, 16, v48
	v_and_b32_e32 v107, 0xffff0000, v48
	v_pk_fma_f32 v[110:111], v[154:155], v[106:107], v[110:111] op_sel_hi:[0,1,1]
	v_pk_fma_f32 v[0:1], v[154:155], v[106:107], v[0:1] op_sel:[1,0,0]
	v_lshlrev_b32_e32 v106, 16, v44
	v_and_b32_e32 v107, 0xffff0000, v44
	v_pk_fma_f32 v[110:111], v[156:157], v[106:107], v[110:111] op_sel_hi:[0,1,1]
	v_pk_fma_f32 v[0:1], v[156:157], v[106:107], v[0:1] op_sel:[1,0,0]
	v_lshlrev_b32_e32 v106, 16, v40
	v_and_b32_e32 v107, 0xffff0000, v40
	v_pk_fma_f32 v[0:1], v[158:159], v[106:107], v[0:1] op_sel:[1,0,0]
	v_lshlrev_b32_e32 v72, 16, v109
	v_and_b32_e32 v73, 0xffff0000, v109
	v_pk_fma_f32 v[110:111], v[158:159], v[106:107], v[110:111] op_sel_hi:[0,1,1]
	v_pk_mul_f32 v[106:107], v[10:11], v[0:1]
	v_pk_mul_f32 v[0:1], v[160:161], v[0:1]
	v_lshlrev_b32_e32 v76, 16, v77
	v_and_b32_e32 v77, 0xffff0000, v77
	v_pk_fma_f32 v[106:107], v[160:161], v[110:111], v[106:107] neg_lo:[0,0,1] neg_hi:[0,0,1]
	v_pk_fma_f32 v[0:1], v[10:11], v[110:111], v[0:1]
	v_pk_fma_f32 v[110:111], v[144:145], v[72:73], 0 op_sel_hi:[0,1,0]
	v_pk_fma_f32 v[72:73], v[144:145], v[72:73], 0 op_sel:[1,0,0] op_sel_hi:[1,1,0]
	v_pk_fma_f32 v[110:111], v[146:147], v[76:77], v[110:111] op_sel_hi:[0,1,1]
	v_pk_fma_f32 v[72:73], v[146:147], v[76:77], v[72:73] op_sel:[1,0,0]
	v_lshlrev_b32_e32 v60, 16, v61
	v_and_b32_e32 v61, 0xffff0000, v61
	v_pk_fma_f32 v[76:77], v[148:149], v[60:61], v[110:111] op_sel_hi:[0,1,1]
	v_pk_fma_f32 v[60:61], v[148:149], v[60:61], v[72:73] op_sel:[1,0,0]
	v_lshlrev_b32_e32 v56, 16, v57
	v_and_b32_e32 v57, 0xffff0000, v57
	v_pk_fma_f32 v[72:73], v[150:151], v[56:57], v[76:77] op_sel_hi:[0,1,1]
	v_pk_fma_f32 v[56:57], v[150:151], v[56:57], v[60:61] op_sel:[1,0,0]
	v_lshlrev_b32_e32 v52, 16, v53
	v_and_b32_e32 v53, 0xffff0000, v53
	v_pk_fma_f32 v[60:61], v[152:153], v[52:53], v[72:73] op_sel_hi:[0,1,1]
	v_pk_fma_f32 v[52:53], v[152:153], v[52:53], v[56:57] op_sel:[1,0,0]
	v_lshlrev_b32_e32 v48, 16, v49
	v_and_b32_e32 v49, 0xffff0000, v49
	v_pk_fma_f32 v[56:57], v[154:155], v[48:49], v[60:61] op_sel_hi:[0,1,1]
	v_pk_fma_f32 v[48:49], v[154:155], v[48:49], v[52:53] op_sel:[1,0,0]
	v_lshlrev_b32_e32 v44, 16, v45
	v_and_b32_e32 v45, 0xffff0000, v45
	v_pk_fma_f32 v[52:53], v[156:157], v[44:45], v[56:57] op_sel_hi:[0,1,1]
	v_pk_fma_f32 v[44:45], v[156:157], v[44:45], v[48:49] op_sel:[1,0,0]
	v_lshlrev_b32_e32 v40, 16, v41
	v_and_b32_e32 v41, 0xffff0000, v41
	v_pk_fma_f32 v[48:49], v[158:159], v[40:41], v[52:53] op_sel_hi:[0,1,1]
	v_pk_fma_f32 v[40:41], v[158:159], v[40:41], v[44:45] op_sel:[1,0,0]
	v_lshlrev_b32_e32 v108, 16, v78
	v_pk_mul_f32 v[44:45], v[14:15], v[40:41]
	v_pk_mul_f32 v[40:41], v[8:9], v[40:41]
	v_and_b32_e32 v109, 0xffff0000, v78
	v_pk_fma_f32 v[44:45], v[8:9], v[48:49], v[44:45] neg_lo:[0,0,1] neg_hi:[0,0,1]
	v_pk_fma_f32 v[48:49], v[14:15], v[48:49], v[40:41]
	v_pk_fma_f32 v[40:41], v[144:145], v[74:75], 0 op_sel_hi:[0,1,0]
	v_pk_fma_f32 v[52:53], v[144:145], v[74:75], 0 op_sel:[1,0,0] op_sel_hi:[1,1,0]
	v_pk_fma_f32 v[40:41], v[146:147], v[108:109], v[40:41] op_sel_hi:[0,1,1]
	v_pk_fma_f32 v[52:53], v[146:147], v[108:109], v[52:53] op_sel:[1,0,0]
	v_lshlrev_b32_e32 v56, 16, v62
	v_and_b32_e32 v57, 0xffff0000, v62
	v_pk_fma_f32 v[40:41], v[148:149], v[56:57], v[40:41] op_sel_hi:[0,1,1]
	v_pk_fma_f32 v[52:53], v[148:149], v[56:57], v[52:53] op_sel:[1,0,0]
	v_lshlrev_b32_e32 v56, 16, v58
	v_and_b32_e32 v57, 0xffff0000, v58
	v_pk_fma_f32 v[40:41], v[150:151], v[56:57], v[40:41] op_sel_hi:[0,1,1]
	v_pk_fma_f32 v[52:53], v[150:151], v[56:57], v[52:53] op_sel:[1,0,0]
	v_lshlrev_b32_e32 v56, 16, v54
	v_and_b32_e32 v57, 0xffff0000, v54
	v_pk_fma_f32 v[40:41], v[152:153], v[56:57], v[40:41] op_sel_hi:[0,1,1]
	v_pk_fma_f32 v[52:53], v[152:153], v[56:57], v[52:53] op_sel:[1,0,0]
	v_lshlrev_b32_e32 v56, 16, v50
	v_and_b32_e32 v57, 0xffff0000, v50
	v_pk_fma_f32 v[40:41], v[154:155], v[56:57], v[40:41] op_sel_hi:[0,1,1]
	v_pk_fma_f32 v[52:53], v[154:155], v[56:57], v[52:53] op_sel:[1,0,0]
	v_lshlrev_b32_e32 v56, 16, v46
	v_and_b32_e32 v57, 0xffff0000, v46
	v_pk_fma_f32 v[40:41], v[156:157], v[56:57], v[40:41] op_sel_hi:[0,1,1]
	v_pk_fma_f32 v[52:53], v[156:157], v[56:57], v[52:53] op_sel:[1,0,0]
	v_lshlrev_b32_e32 v56, 16, v42
	v_and_b32_e32 v57, 0xffff0000, v42
	v_pk_fma_f32 v[52:53], v[158:159], v[56:57], v[52:53] op_sel:[1,0,0]
	v_pk_fma_f32 v[40:41], v[158:159], v[56:57], v[40:41] op_sel_hi:[0,1,1]
	v_pk_mul_f32 v[56:57], v[6:7], v[52:53]
	v_pk_mul_f32 v[52:53], v[12:13], v[52:53]
	v_lshlrev_b32_e32 v78, 16, v79
	v_and_b32_e32 v79, 0xffff0000, v79
	v_pk_fma_f32 v[56:57], v[12:13], v[40:41], v[56:57] neg_lo:[0,0,1] neg_hi:[0,0,1]
	v_pk_fma_f32 v[52:53], v[6:7], v[40:41], v[52:53]
	v_pk_fma_f32 v[40:41], v[144:145], v[104:105], 0 op_sel_hi:[0,1,0]
	v_pk_fma_f32 v[60:61], v[144:145], v[104:105], 0 op_sel:[1,0,0] op_sel_hi:[1,1,0]
	v_pk_fma_f32 v[40:41], v[146:147], v[78:79], v[40:41] op_sel_hi:[0,1,1]
	v_pk_fma_f32 v[60:61], v[146:147], v[78:79], v[60:61] op_sel:[1,0,0]
	v_lshlrev_b32_e32 v62, 16, v63
	v_and_b32_e32 v63, 0xffff0000, v63
	v_pk_fma_f32 v[40:41], v[148:149], v[62:63], v[40:41] op_sel_hi:[0,1,1]
	v_pk_fma_f32 v[60:61], v[148:149], v[62:63], v[60:61] op_sel:[1,0,0]
	v_lshlrev_b32_e32 v58, 16, v59
	v_and_b32_e32 v59, 0xffff0000, v59
	v_pk_fma_f32 v[40:41], v[150:151], v[58:59], v[40:41] op_sel_hi:[0,1,1]
	v_pk_fma_f32 v[58:59], v[150:151], v[58:59], v[60:61] op_sel:[1,0,0]
	v_lshlrev_b32_e32 v54, 16, v55
	v_and_b32_e32 v55, 0xffff0000, v55
	v_lshlrev_b32_e32 v174, 16, v132
	v_and_b32_e32 v175, 0xffff0000, v132
	v_pk_fma_f32 v[40:41], v[152:153], v[54:55], v[40:41] op_sel_hi:[0,1,1]
	v_pk_fma_f32 v[54:55], v[152:153], v[54:55], v[58:59] op_sel:[1,0,0]
	v_lshlrev_b32_e32 v50, 16, v51
	v_and_b32_e32 v51, 0xffff0000, v51
	v_lshlrev_b32_e32 v178, 16, v128
	v_and_b32_e32 v179, 0xffff0000, v128
	v_pk_fma_f32 v[182:183], v[144:145], v[174:175], 0 op_sel_hi:[0,1,0]
	v_pk_fma_f32 v[174:175], v[144:145], v[174:175], 0 op_sel:[1,0,0] op_sel_hi:[1,1,0]
	v_pk_fma_f32 v[40:41], v[154:155], v[50:51], v[40:41] op_sel_hi:[0,1,1]
	v_pk_fma_f32 v[50:51], v[154:155], v[50:51], v[54:55] op_sel:[1,0,0]
	v_lshlrev_b32_e32 v46, 16, v47
	v_and_b32_e32 v47, 0xffff0000, v47
	v_pk_fma_f32 v[182:183], v[146:147], v[178:179], v[182:183] op_sel_hi:[0,1,1]
	v_pk_fma_f32 v[174:175], v[146:147], v[178:179], v[174:175] op_sel:[1,0,0]
	v_lshlrev_b32_e32 v178, 16, v100
	v_and_b32_e32 v179, 0xffff0000, v100
	v_pk_fma_f32 v[40:41], v[156:157], v[46:47], v[40:41] op_sel_hi:[0,1,1]
	v_pk_fma_f32 v[46:47], v[156:157], v[46:47], v[50:51] op_sel:[1,0,0]
	v_lshlrev_b32_e32 v42, 16, v43
	v_and_b32_e32 v43, 0xffff0000, v43
	v_pk_fma_f32 v[182:183], v[148:149], v[178:179], v[182:183] op_sel_hi:[0,1,1]
	v_pk_fma_f32 v[174:175], v[148:149], v[178:179], v[174:175] op_sel:[1,0,0]
	v_lshlrev_b32_e32 v178, 16, v96
	v_and_b32_e32 v179, 0xffff0000, v96
	v_pk_fma_f32 v[40:41], v[158:159], v[42:43], v[40:41] op_sel_hi:[0,1,1]
	v_pk_fma_f32 v[42:43], v[158:159], v[42:43], v[46:47] op_sel:[1,0,0]
	v_pk_fma_f32 v[182:183], v[150:151], v[178:179], v[182:183] op_sel_hi:[0,1,1]
	v_pk_fma_f32 v[174:175], v[150:151], v[178:179], v[174:175] op_sel:[1,0,0]
	v_lshlrev_b32_e32 v178, 16, v92
	v_and_b32_e32 v179, 0xffff0000, v92
	v_pk_mul_f32 v[46:47], v[2:3], v[42:43]
	v_pk_mul_f32 v[42:43], v[4:5], v[42:43]
	v_pk_fma_f32 v[182:183], v[152:153], v[178:179], v[182:183] op_sel_hi:[0,1,1]
	v_pk_fma_f32 v[174:175], v[152:153], v[178:179], v[174:175] op_sel:[1,0,0]
	v_lshlrev_b32_e32 v178, 16, v88
	v_and_b32_e32 v179, 0xffff0000, v88
	v_pk_fma_f32 v[46:47], v[4:5], v[40:41], v[46:47] neg_lo:[0,0,1] neg_hi:[0,0,1]
	v_pk_fma_f32 v[50:51], v[2:3], v[40:41], v[42:43]
	v_cvt_pk_bf16_f32 v41, v44, v45
	v_mul_lo_u32 v44, v136, s6
	v_pk_fma_f32 v[182:183], v[154:155], v[178:179], v[182:183] op_sel_hi:[0,1,1]
	v_pk_fma_f32 v[174:175], v[154:155], v[178:179], v[174:175] op_sel:[1,0,0]
	v_lshlrev_b32_e32 v178, 16, v84
	v_and_b32_e32 v179, 0xffff0000, v84
	v_cvt_pk_bf16_f32 v40, v106, v107
	v_cvt_pk_bf16_f32 v42, v56, v57
	v_cvt_pk_bf16_f32 v43, v46, v47
	v_add3_u32 v44, 0, v44, v192
	v_bitop3_b32 v168, v172, 8, s0 bitop3:0x36
	v_mov_b32_e32 v169, v193
	v_pk_fma_f32 v[182:183], v[156:157], v[178:179], v[182:183] op_sel_hi:[0,1,1]
	v_pk_fma_f32 v[174:175], v[156:157], v[178:179], v[174:175] op_sel:[1,0,0]
	v_lshlrev_b32_e32 v178, 16, v80
	v_and_b32_e32 v179, 0xffff0000, v80
	ds_write_b128 v44, v[40:43]
	v_cvt_pk_bf16_f32 v40, v0, v1
	v_cvt_pk_bf16_f32 v41, v48, v49
	v_cvt_pk_bf16_f32 v42, v52, v53
	v_cvt_pk_bf16_f32 v43, v50, v51
	v_lshlrev_b64 v[0:1], 12, v[168:169]
	v_pk_fma_f32 v[174:175], v[158:159], v[178:179], v[174:175] op_sel:[1,0,0]
	ds_write_b128 v44, v[40:43] offset:512
	v_lshl_add_u64 v[0:1], v[162:163], 0, v[0:1]
	v_lshlrev_b32_e32 v132, 16, v133
	v_and_b32_e32 v133, 0xffff0000, v133
	v_pk_fma_f32 v[182:183], v[158:159], v[178:179], v[182:183] op_sel_hi:[0,1,1]
	v_pk_mul_f32 v[178:179], v[10:11], v[174:175]
	v_pk_mul_f32 v[174:175], v[160:161], v[174:175]
	global_load_dwordx4 v[140:143], v[0:1], off sc1
	global_load_dwordx4 v[136:139], v[0:1], off offset:512 sc1
	global_load_dwordx4 v[124:127], v[0:1], off offset:1024 sc1
	global_load_dwordx4 v[120:123], v[0:1], off offset:1536 sc1
	global_load_dwordx4 v[116:119], v[0:1], off offset:2048 sc1
	global_load_dwordx4 v[112:115], v[0:1], off offset:2560 sc1
	global_load_dwordx4 v[108:111], v[0:1], off offset:3072 sc1
	global_load_dwordx4 v[104:107], v[0:1], off offset:3584 sc1
	v_lshlrev_b32_e32 v128, 16, v129
	v_and_b32_e32 v129, 0xffff0000, v129
	v_pk_fma_f32 v[178:179], v[160:161], v[182:183], v[178:179] neg_lo:[0,0,1] neg_hi:[0,0,1]
	v_pk_fma_f32 v[174:175], v[10:11], v[182:183], v[174:175]
	v_pk_fma_f32 v[182:183], v[144:145], v[132:133], 0 op_sel_hi:[0,1,0]
	v_pk_fma_f32 v[132:133], v[144:145], v[132:133], 0 op_sel:[1,0,0] op_sel_hi:[1,1,0]
	v_pk_fma_f32 v[182:183], v[146:147], v[128:129], v[182:183] op_sel_hi:[0,1,1]
	v_pk_fma_f32 v[128:129], v[146:147], v[128:129], v[132:133] op_sel:[1,0,0]
	v_lshlrev_b32_e32 v100, 16, v101
	v_and_b32_e32 v101, 0xffff0000, v101
	v_pk_fma_f32 v[132:133], v[148:149], v[100:101], v[182:183] op_sel_hi:[0,1,1]
	v_pk_fma_f32 v[100:101], v[148:149], v[100:101], v[128:129] op_sel:[1,0,0]
	v_lshlrev_b32_e32 v96, 16, v97
	v_and_b32_e32 v97, 0xffff0000, v97
	v_pk_fma_f32 v[128:129], v[150:151], v[96:97], v[132:133] op_sel_hi:[0,1,1]
	v_pk_fma_f32 v[96:97], v[150:151], v[96:97], v[100:101] op_sel:[1,0,0]
	v_lshlrev_b32_e32 v92, 16, v93
	v_and_b32_e32 v93, 0xffff0000, v93
	v_pk_fma_f32 v[100:101], v[152:153], v[92:93], v[128:129] op_sel_hi:[0,1,1]
	v_pk_fma_f32 v[92:93], v[152:153], v[92:93], v[96:97] op_sel:[1,0,0]
	v_lshlrev_b32_e32 v88, 16, v89
	v_and_b32_e32 v89, 0xffff0000, v89
	v_pk_fma_f32 v[96:97], v[154:155], v[88:89], v[100:101] op_sel_hi:[0,1,1]
	v_pk_fma_f32 v[88:89], v[154:155], v[88:89], v[92:93] op_sel:[1,0,0]
	v_lshlrev_b32_e32 v84, 16, v85
	v_and_b32_e32 v85, 0xffff0000, v85
	v_pk_fma_f32 v[92:93], v[156:157], v[84:85], v[96:97] op_sel_hi:[0,1,1]
	v_pk_fma_f32 v[84:85], v[156:157], v[84:85], v[88:89] op_sel:[1,0,0]
	v_lshlrev_b32_e32 v80, 16, v81
	v_and_b32_e32 v81, 0xffff0000, v81
	v_pk_fma_f32 v[88:89], v[158:159], v[80:81], v[92:93] op_sel_hi:[0,1,1]
	v_pk_fma_f32 v[80:81], v[158:159], v[80:81], v[84:85] op_sel:[1,0,0]
	v_lshlrev_b32_e32 v176, 16, v134
	v_and_b32_e32 v177, 0xffff0000, v134
	v_pk_mul_f32 v[84:85], v[14:15], v[80:81]
	v_pk_mul_f32 v[80:81], v[8:9], v[80:81]
	v_lshlrev_b32_e32 v180, 16, v130
	v_and_b32_e32 v181, 0xffff0000, v130
	v_pk_fma_f32 v[84:85], v[8:9], v[88:89], v[84:85] neg_lo:[0,0,1] neg_hi:[0,0,1]
	v_pk_fma_f32 v[88:89], v[14:15], v[88:89], v[80:81]
	v_pk_fma_f32 v[80:81], v[144:145], v[176:177], 0 op_sel_hi:[0,1,0]
	v_pk_fma_f32 v[92:93], v[144:145], v[176:177], 0 op_sel:[1,0,0] op_sel_hi:[1,1,0]
	v_pk_fma_f32 v[80:81], v[146:147], v[180:181], v[80:81] op_sel_hi:[0,1,1]
	v_pk_fma_f32 v[92:93], v[146:147], v[180:181], v[92:93] op_sel:[1,0,0]
	v_lshlrev_b32_e32 v96, 16, v102
	v_and_b32_e32 v97, 0xffff0000, v102
	v_pk_fma_f32 v[80:81], v[148:149], v[96:97], v[80:81] op_sel_hi:[0,1,1]
	v_pk_fma_f32 v[92:93], v[148:149], v[96:97], v[92:93] op_sel:[1,0,0]
	v_lshlrev_b32_e32 v96, 16, v98
	v_and_b32_e32 v97, 0xffff0000, v98
	v_pk_fma_f32 v[80:81], v[150:151], v[96:97], v[80:81] op_sel_hi:[0,1,1]
	v_pk_fma_f32 v[92:93], v[150:151], v[96:97], v[92:93] op_sel:[1,0,0]
	v_lshlrev_b32_e32 v96, 16, v94
	v_and_b32_e32 v97, 0xffff0000, v94
	v_pk_fma_f32 v[80:81], v[152:153], v[96:97], v[80:81] op_sel_hi:[0,1,1]
	v_pk_fma_f32 v[92:93], v[152:153], v[96:97], v[92:93] op_sel:[1,0,0]
	v_lshlrev_b32_e32 v96, 16, v90
	v_and_b32_e32 v97, 0xffff0000, v90
	v_pk_fma_f32 v[80:81], v[154:155], v[96:97], v[80:81] op_sel_hi:[0,1,1]
	v_pk_fma_f32 v[92:93], v[154:155], v[96:97], v[92:93] op_sel:[1,0,0]
	v_lshlrev_b32_e32 v96, 16, v86
	v_and_b32_e32 v97, 0xffff0000, v86
	v_pk_fma_f32 v[80:81], v[156:157], v[96:97], v[80:81] op_sel_hi:[0,1,1]
	v_pk_fma_f32 v[92:93], v[156:157], v[96:97], v[92:93] op_sel:[1,0,0]
	v_lshlrev_b32_e32 v96, 16, v82
	v_and_b32_e32 v97, 0xffff0000, v82
	v_pk_fma_f32 v[92:93], v[158:159], v[96:97], v[92:93] op_sel:[1,0,0]
	v_lshlrev_b32_e32 v134, 16, v135
	v_and_b32_e32 v135, 0xffff0000, v135
	v_pk_fma_f32 v[80:81], v[158:159], v[96:97], v[80:81] op_sel_hi:[0,1,1]
	v_pk_mul_f32 v[96:97], v[6:7], v[92:93]
	v_pk_mul_f32 v[92:93], v[12:13], v[92:93]
	v_lshlrev_b32_e32 v130, 16, v131
	v_and_b32_e32 v131, 0xffff0000, v131
	v_pk_fma_f32 v[96:97], v[12:13], v[80:81], v[96:97] neg_lo:[0,0,1] neg_hi:[0,0,1]
	v_pk_fma_f32 v[92:93], v[6:7], v[80:81], v[92:93]
	v_pk_fma_f32 v[80:81], v[144:145], v[134:135], 0 op_sel_hi:[0,1,0]
	v_pk_fma_f32 v[100:101], v[144:145], v[134:135], 0 op_sel:[1,0,0] op_sel_hi:[1,1,0]
	v_pk_fma_f32 v[80:81], v[146:147], v[130:131], v[80:81] op_sel_hi:[0,1,1]
	v_pk_fma_f32 v[100:101], v[146:147], v[130:131], v[100:101] op_sel:[1,0,0]
	v_lshlrev_b32_e32 v102, 16, v103
	v_and_b32_e32 v103, 0xffff0000, v103
	v_pk_fma_f32 v[80:81], v[148:149], v[102:103], v[80:81] op_sel_hi:[0,1,1]
	v_pk_fma_f32 v[100:101], v[148:149], v[102:103], v[100:101] op_sel:[1,0,0]
	v_lshlrev_b32_e32 v98, 16, v99
	v_and_b32_e32 v99, 0xffff0000, v99
	v_pk_fma_f32 v[80:81], v[150:151], v[98:99], v[80:81] op_sel_hi:[0,1,1]
	v_pk_fma_f32 v[98:99], v[150:151], v[98:99], v[100:101] op_sel:[1,0,0]
	v_lshlrev_b32_e32 v94, 16, v95
	v_and_b32_e32 v95, 0xffff0000, v95
	v_pk_fma_f32 v[80:81], v[152:153], v[94:95], v[80:81] op_sel_hi:[0,1,1]
	v_pk_fma_f32 v[94:95], v[152:153], v[94:95], v[98:99] op_sel:[1,0,0]
	v_lshlrev_b32_e32 v90, 16, v91
	v_and_b32_e32 v91, 0xffff0000, v91
	v_pk_fma_f32 v[80:81], v[154:155], v[90:91], v[80:81] op_sel_hi:[0,1,1]
	v_pk_fma_f32 v[90:91], v[154:155], v[90:91], v[94:95] op_sel:[1,0,0]
	v_lshlrev_b32_e32 v86, 16, v87
	v_and_b32_e32 v87, 0xffff0000, v87
	v_pk_fma_f32 v[80:81], v[156:157], v[86:87], v[80:81] op_sel_hi:[0,1,1]
	v_pk_fma_f32 v[86:87], v[156:157], v[86:87], v[90:91] op_sel:[1,0,0]
	v_lshlrev_b32_e32 v82, 16, v83
	v_and_b32_e32 v83, 0xffff0000, v83
	v_readlane_b32 s0, v253, 49
	v_pk_fma_f32 v[80:81], v[158:159], v[82:83], v[80:81] op_sel_hi:[0,1,1]
	v_pk_fma_f32 v[82:83], v[158:159], v[82:83], v[86:87] op_sel:[1,0,0]
	v_or_b32_e32 v0, s0, v172
	v_mov_b32_e32 v1, v193
	v_pk_mul_f32 v[86:87], v[2:3], v[82:83]
	v_lshlrev_b64 v[40:41], 12, v[0:1]
	v_pk_fma_f32 v[86:87], v[4:5], v[80:81], v[86:87] neg_lo:[0,0,1] neg_hi:[0,0,1]
	v_pk_mul_f32 v[82:83], v[4:5], v[82:83]
	v_mul_lo_u32 v1, v166, s6
	v_lshl_add_u64 v[40:41], v[162:163], 0, v[40:41]
	v_pk_fma_f32 v[90:91], v[2:3], v[80:81], v[82:83]
	v_cvt_pk_bf16_f32 v80, v178, v179
	v_cvt_pk_bf16_f32 v81, v84, v85
	v_cvt_pk_bf16_f32 v82, v96, v97
	v_cvt_pk_bf16_f32 v83, v86, v87
	v_add3_u32 v1, 0, v1, v192
	global_load_dwordx4 v[76:79], v[40:41], off sc1
	global_load_dwordx4 v[72:75], v[40:41], off offset:512 sc1
	global_load_dwordx4 v[60:63], v[40:41], off offset:1024 sc1
	global_load_dwordx4 v[56:59], v[40:41], off offset:1536 sc1
	global_load_dwordx4 v[52:55], v[40:41], off offset:2048 sc1
	global_load_dwordx4 v[48:51], v[40:41], off offset:2560 sc1
	global_load_dwordx4 v[44:47], v[40:41], off offset:3072 sc1
	s_nop 0
	global_load_dwordx4 v[40:43], v[40:41], off offset:3584 sc1
	ds_write_b128 v1, v[80:83]
	v_cvt_pk_bf16_f32 v80, v174, v175
	v_cvt_pk_bf16_f32 v81, v88, v89
	v_cvt_pk_bf16_f32 v82, v92, v93
	v_cvt_pk_bf16_f32 v83, v90, v91
	ds_write_b128 v1, v[80:83] offset:512
	v_lshlrev_b32_e32 v80, 16, v68
	v_and_b32_e32 v81, 0xffff0000, v68
	v_lshlrev_b32_e32 v84, 16, v64
	v_and_b32_e32 v85, 0xffff0000, v64
	v_pk_fma_f32 v[88:89], v[144:145], v[80:81], 0 op_sel_hi:[0,1,0]
	v_pk_fma_f32 v[80:81], v[144:145], v[80:81], 0 op_sel:[1,0,0] op_sel_hi:[1,1,0]
	v_pk_fma_f32 v[88:89], v[146:147], v[84:85], v[88:89] op_sel_hi:[0,1,1]
	v_pk_fma_f32 v[80:81], v[146:147], v[84:85], v[80:81] op_sel:[1,0,0]
	v_lshlrev_b32_e32 v84, 16, v36
	v_and_b32_e32 v85, 0xffff0000, v36
	v_pk_fma_f32 v[88:89], v[148:149], v[84:85], v[88:89] op_sel_hi:[0,1,1]
	v_pk_fma_f32 v[80:81], v[148:149], v[84:85], v[80:81] op_sel:[1,0,0]
	v_lshlrev_b32_e32 v84, 16, v32
	v_and_b32_e32 v85, 0xffff0000, v32
	v_pk_fma_f32 v[88:89], v[150:151], v[84:85], v[88:89] op_sel_hi:[0,1,1]
	v_pk_fma_f32 v[80:81], v[150:151], v[84:85], v[80:81] op_sel:[1,0,0]
	v_lshlrev_b32_e32 v84, 16, v28
	v_and_b32_e32 v85, 0xffff0000, v28
	v_pk_fma_f32 v[88:89], v[152:153], v[84:85], v[88:89] op_sel_hi:[0,1,1]
	v_pk_fma_f32 v[80:81], v[152:153], v[84:85], v[80:81] op_sel:[1,0,0]
	v_lshlrev_b32_e32 v84, 16, v24
	v_and_b32_e32 v85, 0xffff0000, v24
	v_pk_fma_f32 v[88:89], v[154:155], v[84:85], v[88:89] op_sel_hi:[0,1,1]
	v_pk_fma_f32 v[80:81], v[154:155], v[84:85], v[80:81] op_sel:[1,0,0]
	v_lshlrev_b32_e32 v84, 16, v20
	v_and_b32_e32 v85, 0xffff0000, v20
	v_pk_fma_f32 v[88:89], v[156:157], v[84:85], v[88:89] op_sel_hi:[0,1,1]
	v_pk_fma_f32 v[80:81], v[156:157], v[84:85], v[80:81] op_sel:[1,0,0]
	v_lshlrev_b32_e32 v84, 16, v16
	v_and_b32_e32 v85, 0xffff0000, v16
	v_pk_fma_f32 v[80:81], v[158:159], v[84:85], v[80:81] op_sel:[1,0,0]
	v_lshlrev_b32_e32 v68, 16, v69
	v_and_b32_e32 v69, 0xffff0000, v69
	v_pk_fma_f32 v[88:89], v[158:159], v[84:85], v[88:89] op_sel_hi:[0,1,1]
	v_pk_mul_f32 v[84:85], v[10:11], v[80:81]
	v_pk_mul_f32 v[80:81], v[160:161], v[80:81]
	v_lshlrev_b32_e32 v64, 16, v65
	v_and_b32_e32 v65, 0xffff0000, v65
	v_pk_fma_f32 v[84:85], v[160:161], v[88:89], v[84:85] neg_lo:[0,0,1] neg_hi:[0,0,1]
	v_pk_fma_f32 v[80:81], v[10:11], v[88:89], v[80:81]
	v_pk_fma_f32 v[88:89], v[144:145], v[68:69], 0 op_sel_hi:[0,1,0]
	v_pk_fma_f32 v[68:69], v[144:145], v[68:69], 0 op_sel:[1,0,0] op_sel_hi:[1,1,0]
	v_pk_fma_f32 v[88:89], v[146:147], v[64:65], v[88:89] op_sel_hi:[0,1,1]
	v_pk_fma_f32 v[64:65], v[146:147], v[64:65], v[68:69] op_sel:[1,0,0]
	v_lshlrev_b32_e32 v36, 16, v37
	v_and_b32_e32 v37, 0xffff0000, v37
	v_pk_fma_f32 v[68:69], v[148:149], v[36:37], v[88:89] op_sel_hi:[0,1,1]
	v_pk_fma_f32 v[36:37], v[148:149], v[36:37], v[64:65] op_sel:[1,0,0]
	v_lshlrev_b32_e32 v32, 16, v33
	v_and_b32_e32 v33, 0xffff0000, v33
	v_pk_fma_f32 v[64:65], v[150:151], v[32:33], v[68:69] op_sel_hi:[0,1,1]
	v_pk_fma_f32 v[32:33], v[150:151], v[32:33], v[36:37] op_sel:[1,0,0]
	v_lshlrev_b32_e32 v28, 16, v29
	v_and_b32_e32 v29, 0xffff0000, v29
	v_pk_fma_f32 v[36:37], v[152:153], v[28:29], v[64:65] op_sel_hi:[0,1,1]
	v_pk_fma_f32 v[28:29], v[152:153], v[28:29], v[32:33] op_sel:[1,0,0]
	v_lshlrev_b32_e32 v24, 16, v25
	v_and_b32_e32 v25, 0xffff0000, v25
	v_pk_fma_f32 v[32:33], v[154:155], v[24:25], v[36:37] op_sel_hi:[0,1,1]
	v_pk_fma_f32 v[24:25], v[154:155], v[24:25], v[28:29] op_sel:[1,0,0]
	v_lshlrev_b32_e32 v20, 16, v21
	v_and_b32_e32 v21, 0xffff0000, v21
	v_pk_fma_f32 v[28:29], v[156:157], v[20:21], v[32:33] op_sel_hi:[0,1,1]
	v_pk_fma_f32 v[20:21], v[156:157], v[20:21], v[24:25] op_sel:[1,0,0]
	v_lshlrev_b32_e32 v16, 16, v17
	v_and_b32_e32 v17, 0xffff0000, v17
	v_pk_fma_f32 v[24:25], v[158:159], v[16:17], v[28:29] op_sel_hi:[0,1,1]
	v_pk_fma_f32 v[16:17], v[158:159], v[16:17], v[20:21] op_sel:[1,0,0]
	v_lshlrev_b32_e32 v82, 16, v70
	v_and_b32_e32 v83, 0xffff0000, v70
	v_pk_mul_f32 v[20:21], v[14:15], v[16:17]
	v_pk_mul_f32 v[16:17], v[8:9], v[16:17]
	v_lshlrev_b32_e32 v86, 16, v66
	v_and_b32_e32 v87, 0xffff0000, v66
	v_pk_fma_f32 v[20:21], v[8:9], v[24:25], v[20:21] neg_lo:[0,0,1] neg_hi:[0,0,1]
	v_pk_fma_f32 v[24:25], v[14:15], v[24:25], v[16:17]
	v_pk_fma_f32 v[16:17], v[144:145], v[82:83], 0 op_sel_hi:[0,1,0]
	v_pk_fma_f32 v[28:29], v[144:145], v[82:83], 0 op_sel:[1,0,0] op_sel_hi:[1,1,0]
	v_pk_fma_f32 v[16:17], v[146:147], v[86:87], v[16:17] op_sel_hi:[0,1,1]
	v_pk_fma_f32 v[28:29], v[146:147], v[86:87], v[28:29] op_sel:[1,0,0]
	v_lshlrev_b32_e32 v32, 16, v38
	v_and_b32_e32 v33, 0xffff0000, v38
	v_pk_fma_f32 v[16:17], v[148:149], v[32:33], v[16:17] op_sel_hi:[0,1,1]
	v_pk_fma_f32 v[28:29], v[148:149], v[32:33], v[28:29] op_sel:[1,0,0]
	v_lshlrev_b32_e32 v32, 16, v34
	v_and_b32_e32 v33, 0xffff0000, v34
	v_pk_fma_f32 v[16:17], v[150:151], v[32:33], v[16:17] op_sel_hi:[0,1,1]
	v_pk_fma_f32 v[28:29], v[150:151], v[32:33], v[28:29] op_sel:[1,0,0]
	v_lshlrev_b32_e32 v32, 16, v30
	v_and_b32_e32 v33, 0xffff0000, v30
	v_pk_fma_f32 v[16:17], v[152:153], v[32:33], v[16:17] op_sel_hi:[0,1,1]
	v_pk_fma_f32 v[28:29], v[152:153], v[32:33], v[28:29] op_sel:[1,0,0]
	v_lshlrev_b32_e32 v32, 16, v26
	v_and_b32_e32 v33, 0xffff0000, v26
	v_pk_fma_f32 v[16:17], v[154:155], v[32:33], v[16:17] op_sel_hi:[0,1,1]
	v_pk_fma_f32 v[28:29], v[154:155], v[32:33], v[28:29] op_sel:[1,0,0]
	v_lshlrev_b32_e32 v32, 16, v22
	v_and_b32_e32 v33, 0xffff0000, v22
	v_pk_fma_f32 v[16:17], v[156:157], v[32:33], v[16:17] op_sel_hi:[0,1,1]
	v_pk_fma_f32 v[28:29], v[156:157], v[32:33], v[28:29] op_sel:[1,0,0]
	v_lshlrev_b32_e32 v32, 16, v18
	v_and_b32_e32 v33, 0xffff0000, v18
	v_pk_fma_f32 v[28:29], v[158:159], v[32:33], v[28:29] op_sel:[1,0,0]
	v_lshlrev_b32_e32 v70, 16, v71
	v_and_b32_e32 v71, 0xffff0000, v71
	v_pk_fma_f32 v[16:17], v[158:159], v[32:33], v[16:17] op_sel_hi:[0,1,1]
	v_pk_mul_f32 v[32:33], v[6:7], v[28:29]
	v_pk_mul_f32 v[28:29], v[12:13], v[28:29]
	v_lshlrev_b32_e32 v66, 16, v67
	v_and_b32_e32 v67, 0xffff0000, v67
	v_pk_fma_f32 v[32:33], v[12:13], v[16:17], v[32:33] neg_lo:[0,0,1] neg_hi:[0,0,1]
	v_pk_fma_f32 v[28:29], v[6:7], v[16:17], v[28:29]
	v_pk_fma_f32 v[16:17], v[144:145], v[70:71], 0 op_sel_hi:[0,1,0]
	v_pk_fma_f32 v[36:37], v[144:145], v[70:71], 0 op_sel:[1,0,0] op_sel_hi:[1,1,0]
	v_pk_fma_f32 v[16:17], v[146:147], v[66:67], v[16:17] op_sel_hi:[0,1,1]
	v_pk_fma_f32 v[36:37], v[146:147], v[66:67], v[36:37] op_sel:[1,0,0]
	v_lshlrev_b32_e32 v38, 16, v39
	v_and_b32_e32 v39, 0xffff0000, v39
	v_pk_fma_f32 v[16:17], v[148:149], v[38:39], v[16:17] op_sel_hi:[0,1,1]
	v_pk_fma_f32 v[36:37], v[148:149], v[38:39], v[36:37] op_sel:[1,0,0]
	v_lshlrev_b32_e32 v34, 16, v35
	v_and_b32_e32 v35, 0xffff0000, v35
	v_pk_fma_f32 v[16:17], v[150:151], v[34:35], v[16:17] op_sel_hi:[0,1,1]
	v_pk_fma_f32 v[34:35], v[150:151], v[34:35], v[36:37] op_sel:[1,0,0]
	v_lshlrev_b32_e32 v30, 16, v31
	v_and_b32_e32 v31, 0xffff0000, v31
	v_pk_fma_f32 v[16:17], v[152:153], v[30:31], v[16:17] op_sel_hi:[0,1,1]
	v_pk_fma_f32 v[30:31], v[152:153], v[30:31], v[34:35] op_sel:[1,0,0]
	v_lshlrev_b32_e32 v26, 16, v27
	v_and_b32_e32 v27, 0xffff0000, v27
	v_pk_fma_f32 v[16:17], v[154:155], v[26:27], v[16:17] op_sel_hi:[0,1,1]
	v_pk_fma_f32 v[26:27], v[154:155], v[26:27], v[30:31] op_sel:[1,0,0]
	v_lshlrev_b32_e32 v22, 16, v23
	v_and_b32_e32 v23, 0xffff0000, v23
	v_pk_fma_f32 v[16:17], v[156:157], v[22:23], v[16:17] op_sel_hi:[0,1,1]
	v_pk_fma_f32 v[22:23], v[156:157], v[22:23], v[26:27] op_sel:[1,0,0]
	v_lshlrev_b32_e32 v18, 16, v19
	v_and_b32_e32 v19, 0xffff0000, v19
	v_pk_fma_f32 v[16:17], v[158:159], v[18:19], v[16:17] op_sel_hi:[0,1,1]
	v_pk_fma_f32 v[18:19], v[158:159], v[18:19], v[22:23] op_sel:[1,0,0]
	v_mul_lo_u32 v1, v164, s6
	v_pk_mul_f32 v[22:23], v[2:3], v[18:19]
	v_pk_mul_f32 v[18:19], v[4:5], v[18:19]
	v_pk_fma_f32 v[22:23], v[4:5], v[16:17], v[22:23] neg_lo:[0,0,1] neg_hi:[0,0,1]
	v_pk_fma_f32 v[26:27], v[2:3], v[16:17], v[18:19]
	v_cvt_pk_bf16_f32 v16, v84, v85
	v_cvt_pk_bf16_f32 v17, v20, v21
	v_cvt_pk_bf16_f32 v18, v32, v33
	v_cvt_pk_bf16_f32 v19, v22, v23
	v_add3_u32 v1, 0, v1, v192
	v_readlane_b32 s0, v253, 50
	ds_write_b128 v1, v[16:19]
	v_cvt_pk_bf16_f32 v16, v80, v81
	v_cvt_pk_bf16_f32 v17, v24, v25
	v_cvt_pk_bf16_f32 v18, v28, v29
	v_cvt_pk_bf16_f32 v19, v26, v27
	v_or_b32_e32 v166, s0, v172
	ds_write_b128 v1, v[16:19] offset:512
	v_lshlrev_b64 v[16:17], 12, v[166:167]
	v_readlane_b32 s0, v253, 52
	v_lshl_add_u64 v[16:17], v[162:163], 0, v[16:17]
	global_load_dwordx4 v[132:135], v[16:17], off sc1
	global_load_dwordx4 v[128:131], v[16:17], off offset:512 sc1
	global_load_dwordx4 v[100:103], v[16:17], off offset:1024 sc1
	global_load_dwordx4 v[96:99], v[16:17], off offset:1536 sc1
	global_load_dwordx4 v[92:95], v[16:17], off offset:2048 sc1
	global_load_dwordx4 v[88:91], v[16:17], off offset:2560 sc1
	global_load_dwordx4 v[84:87], v[16:17], off offset:3072 sc1
	global_load_dwordx4 v[80:83], v[16:17], off offset:3584 sc1
	v_or_b32_e32 v164, s0, v172
	v_lshlrev_b64 v[16:17], 12, v[164:165]
	v_lshl_add_u64 v[16:17], v[162:163], 0, v[16:17]
	s_waitcnt vmcnt(23)
	v_lshlrev_b32_e32 v162, 16, v140
	v_and_b32_e32 v163, 0xffff0000, v140
	s_waitcnt vmcnt(22)
	v_lshlrev_b32_e32 v174, 16, v136
	v_and_b32_e32 v175, 0xffff0000, v136
	v_pk_fma_f32 v[178:179], v[144:145], v[162:163], 0 op_sel_hi:[0,1,0]
	v_pk_fma_f32 v[162:163], v[144:145], v[162:163], 0 op_sel:[1,0,0] op_sel_hi:[1,1,0]
	v_pk_fma_f32 v[178:179], v[146:147], v[174:175], v[178:179] op_sel_hi:[0,1,1]
	v_pk_fma_f32 v[162:163], v[146:147], v[174:175], v[162:163] op_sel:[1,0,0]
	s_waitcnt vmcnt(21)
	v_lshlrev_b32_e32 v174, 16, v124
	v_and_b32_e32 v175, 0xffff0000, v124
	v_pk_fma_f32 v[178:179], v[148:149], v[174:175], v[178:179] op_sel_hi:[0,1,1]
	v_pk_fma_f32 v[162:163], v[148:149], v[174:175], v[162:163] op_sel:[1,0,0]
	s_waitcnt vmcnt(20)
	v_lshlrev_b32_e32 v174, 16, v120
	v_and_b32_e32 v175, 0xffff0000, v120
	v_pk_fma_f32 v[178:179], v[150:151], v[174:175], v[178:179] op_sel_hi:[0,1,1]
	v_pk_fma_f32 v[162:163], v[150:151], v[174:175], v[162:163] op_sel:[1,0,0]
	s_waitcnt vmcnt(19)
	v_lshlrev_b32_e32 v174, 16, v116
	v_and_b32_e32 v175, 0xffff0000, v116
	v_pk_fma_f32 v[178:179], v[152:153], v[174:175], v[178:179] op_sel_hi:[0,1,1]
	v_pk_fma_f32 v[162:163], v[152:153], v[174:175], v[162:163] op_sel:[1,0,0]
	s_waitcnt vmcnt(18)
	v_lshlrev_b32_e32 v174, 16, v112
	v_and_b32_e32 v175, 0xffff0000, v112
	v_pk_fma_f32 v[178:179], v[154:155], v[174:175], v[178:179] op_sel_hi:[0,1,1]
	v_pk_fma_f32 v[162:163], v[154:155], v[174:175], v[162:163] op_sel:[1,0,0]
	s_waitcnt vmcnt(17)
	v_lshlrev_b32_e32 v174, 16, v108
	v_and_b32_e32 v175, 0xffff0000, v108
	v_pk_fma_f32 v[178:179], v[156:157], v[174:175], v[178:179] op_sel_hi:[0,1,1]
	v_pk_fma_f32 v[162:163], v[156:157], v[174:175], v[162:163] op_sel:[1,0,0]
	s_waitcnt vmcnt(16)
	v_lshlrev_b32_e32 v174, 16, v104
	v_and_b32_e32 v175, 0xffff0000, v104
	v_pk_fma_f32 v[162:163], v[158:159], v[174:175], v[162:163] op_sel:[1,0,0]
	v_lshlrev_b32_e32 v140, 16, v141
	v_and_b32_e32 v141, 0xffff0000, v141
	v_pk_fma_f32 v[178:179], v[158:159], v[174:175], v[178:179] op_sel_hi:[0,1,1]
	v_pk_mul_f32 v[174:175], v[10:11], v[162:163]
	v_pk_mul_f32 v[162:163], v[160:161], v[162:163]
	v_lshlrev_b32_e32 v136, 16, v137
	v_and_b32_e32 v137, 0xffff0000, v137
	v_pk_fma_f32 v[174:175], v[160:161], v[178:179], v[174:175] neg_lo:[0,0,1] neg_hi:[0,0,1]
	v_pk_fma_f32 v[162:163], v[10:11], v[178:179], v[162:163]
	v_pk_fma_f32 v[178:179], v[144:145], v[140:141], 0 op_sel_hi:[0,1,0]
	v_pk_fma_f32 v[140:141], v[144:145], v[140:141], 0 op_sel:[1,0,0] op_sel_hi:[1,1,0]
	v_pk_fma_f32 v[178:179], v[146:147], v[136:137], v[178:179] op_sel_hi:[0,1,1]
	v_pk_fma_f32 v[136:137], v[146:147], v[136:137], v[140:141] op_sel:[1,0,0]
	v_lshlrev_b32_e32 v124, 16, v125
	v_and_b32_e32 v125, 0xffff0000, v125
	v_pk_fma_f32 v[140:141], v[148:149], v[124:125], v[178:179] op_sel_hi:[0,1,1]
	v_pk_fma_f32 v[124:125], v[148:149], v[124:125], v[136:137] op_sel:[1,0,0]
	v_lshlrev_b32_e32 v120, 16, v121
	v_and_b32_e32 v121, 0xffff0000, v121
	v_pk_fma_f32 v[136:137], v[150:151], v[120:121], v[140:141] op_sel_hi:[0,1,1]
	v_pk_fma_f32 v[120:121], v[150:151], v[120:121], v[124:125] op_sel:[1,0,0]
	v_lshlrev_b32_e32 v116, 16, v117
	v_and_b32_e32 v117, 0xffff0000, v117
	v_pk_fma_f32 v[124:125], v[152:153], v[116:117], v[136:137] op_sel_hi:[0,1,1]
	v_pk_fma_f32 v[116:117], v[152:153], v[116:117], v[120:121] op_sel:[1,0,0]
	v_lshlrev_b32_e32 v112, 16, v113
	v_and_b32_e32 v113, 0xffff0000, v113
	v_pk_fma_f32 v[120:121], v[154:155], v[112:113], v[124:125] op_sel_hi:[0,1,1]
	v_pk_fma_f32 v[112:113], v[154:155], v[112:113], v[116:117] op_sel:[1,0,0]
	v_lshlrev_b32_e32 v108, 16, v109
	v_and_b32_e32 v109, 0xffff0000, v109
	v_pk_fma_f32 v[116:117], v[156:157], v[108:109], v[120:121] op_sel_hi:[0,1,1]
	v_pk_fma_f32 v[108:109], v[156:157], v[108:109], v[112:113] op_sel:[1,0,0]
	v_lshlrev_b32_e32 v104, 16, v105
	v_and_b32_e32 v105, 0xffff0000, v105
	v_pk_fma_f32 v[112:113], v[158:159], v[104:105], v[116:117] op_sel_hi:[0,1,1]
	v_pk_fma_f32 v[104:105], v[158:159], v[104:105], v[108:109] op_sel:[1,0,0]
	v_lshlrev_b32_e32 v172, 16, v142
	v_and_b32_e32 v173, 0xffff0000, v142
	v_pk_mul_f32 v[108:109], v[14:15], v[104:105]
	v_pk_mul_f32 v[104:105], v[8:9], v[104:105]
	v_lshlrev_b32_e32 v176, 16, v138
	v_and_b32_e32 v177, 0xffff0000, v138
	v_pk_fma_f32 v[108:109], v[8:9], v[112:113], v[108:109] neg_lo:[0,0,1] neg_hi:[0,0,1]
	v_pk_fma_f32 v[112:113], v[14:15], v[112:113], v[104:105]
	v_pk_fma_f32 v[104:105], v[144:145], v[172:173], 0 op_sel_hi:[0,1,0]
	v_pk_fma_f32 v[116:117], v[144:145], v[172:173], 0 op_sel:[1,0,0] op_sel_hi:[1,1,0]
	v_pk_fma_f32 v[104:105], v[146:147], v[176:177], v[104:105] op_sel_hi:[0,1,1]
	v_pk_fma_f32 v[116:117], v[146:147], v[176:177], v[116:117] op_sel:[1,0,0]
	v_lshlrev_b32_e32 v120, 16, v126
	v_and_b32_e32 v121, 0xffff0000, v126
	v_pk_fma_f32 v[104:105], v[148:149], v[120:121], v[104:105] op_sel_hi:[0,1,1]
	v_pk_fma_f32 v[116:117], v[148:149], v[120:121], v[116:117] op_sel:[1,0,0]
	v_lshlrev_b32_e32 v120, 16, v122
	v_and_b32_e32 v121, 0xffff0000, v122
	v_pk_fma_f32 v[104:105], v[150:151], v[120:121], v[104:105] op_sel_hi:[0,1,1]
	v_pk_fma_f32 v[116:117], v[150:151], v[120:121], v[116:117] op_sel:[1,0,0]
	v_lshlrev_b32_e32 v120, 16, v118
	v_and_b32_e32 v121, 0xffff0000, v118
	v_pk_fma_f32 v[104:105], v[152:153], v[120:121], v[104:105] op_sel_hi:[0,1,1]
	v_pk_fma_f32 v[116:117], v[152:153], v[120:121], v[116:117] op_sel:[1,0,0]
	v_lshlrev_b32_e32 v120, 16, v114
	v_and_b32_e32 v121, 0xffff0000, v114
	v_pk_fma_f32 v[104:105], v[154:155], v[120:121], v[104:105] op_sel_hi:[0,1,1]
	v_pk_fma_f32 v[116:117], v[154:155], v[120:121], v[116:117] op_sel:[1,0,0]
	v_lshlrev_b32_e32 v120, 16, v110
	v_and_b32_e32 v121, 0xffff0000, v110
	v_pk_fma_f32 v[104:105], v[156:157], v[120:121], v[104:105] op_sel_hi:[0,1,1]
	v_pk_fma_f32 v[116:117], v[156:157], v[120:121], v[116:117] op_sel:[1,0,0]
	v_lshlrev_b32_e32 v120, 16, v106
	v_and_b32_e32 v121, 0xffff0000, v106
	v_pk_fma_f32 v[116:117], v[158:159], v[120:121], v[116:117] op_sel:[1,0,0]
	v_lshlrev_b32_e32 v142, 16, v143
	v_and_b32_e32 v143, 0xffff0000, v143
	v_pk_fma_f32 v[104:105], v[158:159], v[120:121], v[104:105] op_sel_hi:[0,1,1]
	v_pk_mul_f32 v[120:121], v[6:7], v[116:117]
	v_pk_mul_f32 v[116:117], v[12:13], v[116:117]
	v_lshlrev_b32_e32 v138, 16, v139
	v_and_b32_e32 v139, 0xffff0000, v139
	v_pk_fma_f32 v[120:121], v[12:13], v[104:105], v[120:121] neg_lo:[0,0,1] neg_hi:[0,0,1]
	v_pk_fma_f32 v[116:117], v[6:7], v[104:105], v[116:117]
	v_pk_fma_f32 v[104:105], v[144:145], v[142:143], 0 op_sel_hi:[0,1,0]
	v_pk_fma_f32 v[124:125], v[144:145], v[142:143], 0 op_sel:[1,0,0] op_sel_hi:[1,1,0]
	v_pk_fma_f32 v[104:105], v[146:147], v[138:139], v[104:105] op_sel_hi:[0,1,1]
	v_pk_fma_f32 v[124:125], v[146:147], v[138:139], v[124:125] op_sel:[1,0,0]
	v_lshlrev_b32_e32 v126, 16, v127
	v_and_b32_e32 v127, 0xffff0000, v127
	v_pk_fma_f32 v[104:105], v[148:149], v[126:127], v[104:105] op_sel_hi:[0,1,1]
	v_pk_fma_f32 v[124:125], v[148:149], v[126:127], v[124:125] op_sel:[1,0,0]
	v_lshlrev_b32_e32 v122, 16, v123
	v_and_b32_e32 v123, 0xffff0000, v123
	v_pk_fma_f32 v[104:105], v[150:151], v[122:123], v[104:105] op_sel_hi:[0,1,1]
	v_pk_fma_f32 v[122:123], v[150:151], v[122:123], v[124:125] op_sel:[1,0,0]
	v_lshlrev_b32_e32 v118, 16, v119
	v_and_b32_e32 v119, 0xffff0000, v119
	v_pk_fma_f32 v[104:105], v[152:153], v[118:119], v[104:105] op_sel_hi:[0,1,1]
	v_pk_fma_f32 v[118:119], v[152:153], v[118:119], v[122:123] op_sel:[1,0,0]
	v_lshlrev_b32_e32 v114, 16, v115
	v_and_b32_e32 v115, 0xffff0000, v115
	v_pk_fma_f32 v[104:105], v[154:155], v[114:115], v[104:105] op_sel_hi:[0,1,1]
	v_pk_fma_f32 v[114:115], v[154:155], v[114:115], v[118:119] op_sel:[1,0,0]
	v_lshlrev_b32_e32 v110, 16, v111
	v_and_b32_e32 v111, 0xffff0000, v111
	v_pk_fma_f32 v[104:105], v[156:157], v[110:111], v[104:105] op_sel_hi:[0,1,1]
	v_pk_fma_f32 v[110:111], v[156:157], v[110:111], v[114:115] op_sel:[1,0,0]
	v_lshlrev_b32_e32 v106, 16, v107
	v_and_b32_e32 v107, 0xffff0000, v107
	v_pk_fma_f32 v[104:105], v[158:159], v[106:107], v[104:105] op_sel_hi:[0,1,1]
	v_pk_fma_f32 v[106:107], v[158:159], v[106:107], v[110:111] op_sel:[1,0,0]
	v_mul_lo_u32 v1, v168, s6
	v_pk_mul_f32 v[110:111], v[2:3], v[106:107]
	v_pk_mul_f32 v[106:107], v[4:5], v[106:107]
	v_pk_fma_f32 v[110:111], v[4:5], v[104:105], v[110:111] neg_lo:[0,0,1] neg_hi:[0,0,1]
	v_pk_fma_f32 v[114:115], v[2:3], v[104:105], v[106:107]
	v_cvt_pk_bf16_f32 v104, v174, v175
	v_cvt_pk_bf16_f32 v105, v108, v109
	v_cvt_pk_bf16_f32 v106, v120, v121
	v_cvt_pk_bf16_f32 v107, v110, v111
	v_add3_u32 v1, 0, v1, v192
	global_load_dwordx4 v[68:71], v[16:17], off sc1
	global_load_dwordx4 v[64:67], v[16:17], off offset:512 sc1
	global_load_dwordx4 v[36:39], v[16:17], off offset:1024 sc1
	global_load_dwordx4 v[32:35], v[16:17], off offset:1536 sc1
	global_load_dwordx4 v[28:31], v[16:17], off offset:2048 sc1
	global_load_dwordx4 v[24:27], v[16:17], off offset:2560 sc1
	global_load_dwordx4 v[20:23], v[16:17], off offset:3072 sc1
	s_nop 0
	global_load_dwordx4 v[16:19], v[16:17], off offset:3584 sc1
	ds_write_b128 v1, v[104:107]
	v_cvt_pk_bf16_f32 v104, v162, v163
	v_cvt_pk_bf16_f32 v105, v112, v113
	v_cvt_pk_bf16_f32 v106, v116, v117
	v_cvt_pk_bf16_f32 v107, v114, v115
	ds_write_b128 v1, v[104:107] offset:512
	s_waitcnt vmcnt(23)
	v_lshlrev_b32_e32 v104, 16, v76
	v_and_b32_e32 v105, 0xffff0000, v76
	s_waitcnt vmcnt(22)
	v_lshlrev_b32_e32 v108, 16, v72
	v_and_b32_e32 v109, 0xffff0000, v72
	v_pk_fma_f32 v[112:113], v[144:145], v[104:105], 0 op_sel_hi:[0,1,0]
	v_pk_fma_f32 v[104:105], v[144:145], v[104:105], 0 op_sel:[1,0,0] op_sel_hi:[1,1,0]
	v_pk_fma_f32 v[112:113], v[146:147], v[108:109], v[112:113] op_sel_hi:[0,1,1]
	v_pk_fma_f32 v[104:105], v[146:147], v[108:109], v[104:105] op_sel:[1,0,0]
	s_waitcnt vmcnt(21)
	v_lshlrev_b32_e32 v108, 16, v60
	v_and_b32_e32 v109, 0xffff0000, v60
	v_pk_fma_f32 v[112:113], v[148:149], v[108:109], v[112:113] op_sel_hi:[0,1,1]
	v_pk_fma_f32 v[104:105], v[148:149], v[108:109], v[104:105] op_sel:[1,0,0]
	s_waitcnt vmcnt(20)
	v_lshlrev_b32_e32 v108, 16, v56
	v_and_b32_e32 v109, 0xffff0000, v56
	v_pk_fma_f32 v[112:113], v[150:151], v[108:109], v[112:113] op_sel_hi:[0,1,1]
	v_pk_fma_f32 v[104:105], v[150:151], v[108:109], v[104:105] op_sel:[1,0,0]
	s_waitcnt vmcnt(19)
	v_lshlrev_b32_e32 v108, 16, v52
	v_and_b32_e32 v109, 0xffff0000, v52
	v_pk_fma_f32 v[112:113], v[152:153], v[108:109], v[112:113] op_sel_hi:[0,1,1]
	v_pk_fma_f32 v[104:105], v[152:153], v[108:109], v[104:105] op_sel:[1,0,0]
	s_waitcnt vmcnt(18)
	v_lshlrev_b32_e32 v108, 16, v48
	v_and_b32_e32 v109, 0xffff0000, v48
	v_pk_fma_f32 v[112:113], v[154:155], v[108:109], v[112:113] op_sel_hi:[0,1,1]
	v_pk_fma_f32 v[104:105], v[154:155], v[108:109], v[104:105] op_sel:[1,0,0]
	s_waitcnt vmcnt(17)
	v_lshlrev_b32_e32 v108, 16, v44
	v_and_b32_e32 v109, 0xffff0000, v44
	v_pk_fma_f32 v[112:113], v[156:157], v[108:109], v[112:113] op_sel_hi:[0,1,1]
	v_pk_fma_f32 v[104:105], v[156:157], v[108:109], v[104:105] op_sel:[1,0,0]
	s_waitcnt vmcnt(16)
	v_lshlrev_b32_e32 v108, 16, v40
	v_and_b32_e32 v109, 0xffff0000, v40
	v_pk_fma_f32 v[104:105], v[158:159], v[108:109], v[104:105] op_sel:[1,0,0]
	v_lshlrev_b32_e32 v76, 16, v77
	v_and_b32_e32 v77, 0xffff0000, v77
	v_pk_fma_f32 v[112:113], v[158:159], v[108:109], v[112:113] op_sel_hi:[0,1,1]
	v_pk_mul_f32 v[108:109], v[10:11], v[104:105]
	v_pk_mul_f32 v[104:105], v[160:161], v[104:105]
	v_lshlrev_b32_e32 v72, 16, v73
	v_and_b32_e32 v73, 0xffff0000, v73
	v_pk_fma_f32 v[108:109], v[160:161], v[112:113], v[108:109] neg_lo:[0,0,1] neg_hi:[0,0,1]
	v_pk_fma_f32 v[104:105], v[10:11], v[112:113], v[104:105]
	v_pk_fma_f32 v[112:113], v[144:145], v[76:77], 0 op_sel_hi:[0,1,0]
	v_pk_fma_f32 v[76:77], v[144:145], v[76:77], 0 op_sel:[1,0,0] op_sel_hi:[1,1,0]
	v_pk_fma_f32 v[112:113], v[146:147], v[72:73], v[112:113] op_sel_hi:[0,1,1]
	v_pk_fma_f32 v[72:73], v[146:147], v[72:73], v[76:77] op_sel:[1,0,0]
	v_lshlrev_b32_e32 v60, 16, v61
	v_and_b32_e32 v61, 0xffff0000, v61
	v_pk_fma_f32 v[76:77], v[148:149], v[60:61], v[112:113] op_sel_hi:[0,1,1]
	v_pk_fma_f32 v[60:61], v[148:149], v[60:61], v[72:73] op_sel:[1,0,0]
	v_lshlrev_b32_e32 v56, 16, v57
	v_and_b32_e32 v57, 0xffff0000, v57
	v_pk_fma_f32 v[72:73], v[150:151], v[56:57], v[76:77] op_sel_hi:[0,1,1]
	v_pk_fma_f32 v[56:57], v[150:151], v[56:57], v[60:61] op_sel:[1,0,0]
	v_lshlrev_b32_e32 v52, 16, v53
	v_and_b32_e32 v53, 0xffff0000, v53
	v_pk_fma_f32 v[60:61], v[152:153], v[52:53], v[72:73] op_sel_hi:[0,1,1]
	v_pk_fma_f32 v[52:53], v[152:153], v[52:53], v[56:57] op_sel:[1,0,0]
	v_lshlrev_b32_e32 v48, 16, v49
	v_and_b32_e32 v49, 0xffff0000, v49
	v_pk_fma_f32 v[56:57], v[154:155], v[48:49], v[60:61] op_sel_hi:[0,1,1]
	v_pk_fma_f32 v[48:49], v[154:155], v[48:49], v[52:53] op_sel:[1,0,0]
	v_lshlrev_b32_e32 v44, 16, v45
	v_and_b32_e32 v45, 0xffff0000, v45
	v_pk_fma_f32 v[52:53], v[156:157], v[44:45], v[56:57] op_sel_hi:[0,1,1]
	v_pk_fma_f32 v[44:45], v[156:157], v[44:45], v[48:49] op_sel:[1,0,0]
	v_lshlrev_b32_e32 v40, 16, v41
	v_and_b32_e32 v41, 0xffff0000, v41
	v_pk_fma_f32 v[48:49], v[158:159], v[40:41], v[52:53] op_sel_hi:[0,1,1]
	v_pk_fma_f32 v[40:41], v[158:159], v[40:41], v[44:45] op_sel:[1,0,0]
	v_lshlrev_b32_e32 v106, 16, v78
	v_and_b32_e32 v107, 0xffff0000, v78
	v_pk_mul_f32 v[44:45], v[14:15], v[40:41]
	v_pk_mul_f32 v[40:41], v[8:9], v[40:41]
	v_lshlrev_b32_e32 v110, 16, v74
	v_and_b32_e32 v111, 0xffff0000, v74
	v_pk_fma_f32 v[44:45], v[8:9], v[48:49], v[44:45] neg_lo:[0,0,1] neg_hi:[0,0,1]
	v_pk_fma_f32 v[48:49], v[14:15], v[48:49], v[40:41]
	v_pk_fma_f32 v[40:41], v[144:145], v[106:107], 0 op_sel_hi:[0,1,0]
	v_pk_fma_f32 v[52:53], v[144:145], v[106:107], 0 op_sel:[1,0,0] op_sel_hi:[1,1,0]
	v_pk_fma_f32 v[40:41], v[146:147], v[110:111], v[40:41] op_sel_hi:[0,1,1]
	v_pk_fma_f32 v[52:53], v[146:147], v[110:111], v[52:53] op_sel:[1,0,0]
	v_lshlrev_b32_e32 v56, 16, v62
	v_and_b32_e32 v57, 0xffff0000, v62
	v_pk_fma_f32 v[40:41], v[148:149], v[56:57], v[40:41] op_sel_hi:[0,1,1]
	v_pk_fma_f32 v[52:53], v[148:149], v[56:57], v[52:53] op_sel:[1,0,0]
	v_lshlrev_b32_e32 v56, 16, v58
	v_and_b32_e32 v57, 0xffff0000, v58
	v_pk_fma_f32 v[40:41], v[150:151], v[56:57], v[40:41] op_sel_hi:[0,1,1]
	v_pk_fma_f32 v[52:53], v[150:151], v[56:57], v[52:53] op_sel:[1,0,0]
	v_lshlrev_b32_e32 v56, 16, v54
	v_and_b32_e32 v57, 0xffff0000, v54
	v_pk_fma_f32 v[40:41], v[152:153], v[56:57], v[40:41] op_sel_hi:[0,1,1]
	v_pk_fma_f32 v[52:53], v[152:153], v[56:57], v[52:53] op_sel:[1,0,0]
	v_lshlrev_b32_e32 v56, 16, v50
	v_and_b32_e32 v57, 0xffff0000, v50
	v_pk_fma_f32 v[40:41], v[154:155], v[56:57], v[40:41] op_sel_hi:[0,1,1]
	v_pk_fma_f32 v[52:53], v[154:155], v[56:57], v[52:53] op_sel:[1,0,0]
	v_lshlrev_b32_e32 v56, 16, v46
	v_and_b32_e32 v57, 0xffff0000, v46
	v_pk_fma_f32 v[40:41], v[156:157], v[56:57], v[40:41] op_sel_hi:[0,1,1]
	v_pk_fma_f32 v[52:53], v[156:157], v[56:57], v[52:53] op_sel:[1,0,0]
	v_lshlrev_b32_e32 v56, 16, v42
	v_and_b32_e32 v57, 0xffff0000, v42
	v_pk_fma_f32 v[52:53], v[158:159], v[56:57], v[52:53] op_sel:[1,0,0]
	v_lshlrev_b32_e32 v78, 16, v79
	v_and_b32_e32 v79, 0xffff0000, v79
	v_pk_fma_f32 v[40:41], v[158:159], v[56:57], v[40:41] op_sel_hi:[0,1,1]
	v_pk_mul_f32 v[56:57], v[6:7], v[52:53]
	v_pk_mul_f32 v[52:53], v[12:13], v[52:53]
	v_lshlrev_b32_e32 v74, 16, v75
	v_and_b32_e32 v75, 0xffff0000, v75
	v_pk_fma_f32 v[56:57], v[12:13], v[40:41], v[56:57] neg_lo:[0,0,1] neg_hi:[0,0,1]
	v_pk_fma_f32 v[52:53], v[6:7], v[40:41], v[52:53]
	v_pk_fma_f32 v[40:41], v[144:145], v[78:79], 0 op_sel_hi:[0,1,0]
	v_pk_fma_f32 v[60:61], v[144:145], v[78:79], 0 op_sel:[1,0,0] op_sel_hi:[1,1,0]
	v_pk_fma_f32 v[40:41], v[146:147], v[74:75], v[40:41] op_sel_hi:[0,1,1]
	v_pk_fma_f32 v[60:61], v[146:147], v[74:75], v[60:61] op_sel:[1,0,0]
	v_lshlrev_b32_e32 v62, 16, v63
	v_and_b32_e32 v63, 0xffff0000, v63
	v_pk_fma_f32 v[40:41], v[148:149], v[62:63], v[40:41] op_sel_hi:[0,1,1]
	v_pk_fma_f32 v[60:61], v[148:149], v[62:63], v[60:61] op_sel:[1,0,0]
	v_lshlrev_b32_e32 v58, 16, v59
	v_and_b32_e32 v59, 0xffff0000, v59
	v_pk_fma_f32 v[40:41], v[150:151], v[58:59], v[40:41] op_sel_hi:[0,1,1]
	v_pk_fma_f32 v[58:59], v[150:151], v[58:59], v[60:61] op_sel:[1,0,0]
	v_lshlrev_b32_e32 v54, 16, v55
	v_and_b32_e32 v55, 0xffff0000, v55
	v_pk_fma_f32 v[40:41], v[152:153], v[54:55], v[40:41] op_sel_hi:[0,1,1]
	v_pk_fma_f32 v[54:55], v[152:153], v[54:55], v[58:59] op_sel:[1,0,0]
	v_lshlrev_b32_e32 v50, 16, v51
	v_and_b32_e32 v51, 0xffff0000, v51
	v_pk_fma_f32 v[40:41], v[154:155], v[50:51], v[40:41] op_sel_hi:[0,1,1]
	v_pk_fma_f32 v[50:51], v[154:155], v[50:51], v[54:55] op_sel:[1,0,0]
	v_lshlrev_b32_e32 v46, 16, v47
	v_and_b32_e32 v47, 0xffff0000, v47
	v_pk_fma_f32 v[40:41], v[156:157], v[46:47], v[40:41] op_sel_hi:[0,1,1]
	v_pk_fma_f32 v[46:47], v[156:157], v[46:47], v[50:51] op_sel:[1,0,0]
	v_lshlrev_b32_e32 v42, 16, v43
	v_and_b32_e32 v43, 0xffff0000, v43
	v_pk_fma_f32 v[40:41], v[158:159], v[42:43], v[40:41] op_sel_hi:[0,1,1]
	v_pk_fma_f32 v[42:43], v[158:159], v[42:43], v[46:47] op_sel:[1,0,0]
	v_mul_lo_u32 v0, v0, s6
	v_pk_mul_f32 v[46:47], v[2:3], v[42:43]
	v_pk_mul_f32 v[42:43], v[4:5], v[42:43]
	v_pk_fma_f32 v[46:47], v[4:5], v[40:41], v[46:47] neg_lo:[0,0,1] neg_hi:[0,0,1]
	v_pk_fma_f32 v[50:51], v[2:3], v[40:41], v[42:43]
	v_cvt_pk_bf16_f32 v40, v108, v109
	v_cvt_pk_bf16_f32 v41, v44, v45
	v_cvt_pk_bf16_f32 v42, v56, v57
	v_cvt_pk_bf16_f32 v43, v46, v47
	v_add3_u32 v0, 0, v0, v192
	ds_write_b128 v0, v[40:43]
	v_cvt_pk_bf16_f32 v40, v104, v105
	v_cvt_pk_bf16_f32 v41, v48, v49
	v_cvt_pk_bf16_f32 v42, v52, v53
	v_cvt_pk_bf16_f32 v43, v50, v51
	ds_write_b128 v0, v[40:43] offset:512
	s_waitcnt vmcnt(15)
	v_lshlrev_b32_e32 v0, 16, v132
	v_and_b32_e32 v1, 0xffff0000, v132
	s_waitcnt vmcnt(14)
	v_lshlrev_b32_e32 v46, 16, v128
	v_and_b32_e32 v47, 0xffff0000, v128
	v_pk_fma_f32 v[54:55], v[144:145], v[0:1], 0 op_sel_hi:[0,1,0]
	v_pk_fma_f32 v[0:1], v[144:145], v[0:1], 0 op_sel:[1,0,0] op_sel_hi:[1,1,0]
	v_pk_fma_f32 v[54:55], v[146:147], v[46:47], v[54:55] op_sel_hi:[0,1,1]
	v_pk_fma_f32 v[0:1], v[146:147], v[46:47], v[0:1] op_sel:[1,0,0]
	s_waitcnt vmcnt(13)
	v_lshlrev_b32_e32 v46, 16, v100
	v_and_b32_e32 v47, 0xffff0000, v100
	v_pk_fma_f32 v[54:55], v[148:149], v[46:47], v[54:55] op_sel_hi:[0,1,1]
	v_pk_fma_f32 v[0:1], v[148:149], v[46:47], v[0:1] op_sel:[1,0,0]
	s_waitcnt vmcnt(12)
	v_lshlrev_b32_e32 v46, 16, v96
	v_and_b32_e32 v47, 0xffff0000, v96
	v_pk_fma_f32 v[54:55], v[150:151], v[46:47], v[54:55] op_sel_hi:[0,1,1]
	v_pk_fma_f32 v[0:1], v[150:151], v[46:47], v[0:1] op_sel:[1,0,0]
	s_waitcnt vmcnt(11)
	v_lshlrev_b32_e32 v46, 16, v92
	v_and_b32_e32 v47, 0xffff0000, v92
	v_pk_fma_f32 v[54:55], v[152:153], v[46:47], v[54:55] op_sel_hi:[0,1,1]
	v_pk_fma_f32 v[0:1], v[152:153], v[46:47], v[0:1] op_sel:[1,0,0]
	s_waitcnt vmcnt(10)
	v_lshlrev_b32_e32 v46, 16, v88
	v_and_b32_e32 v47, 0xffff0000, v88
	v_pk_fma_f32 v[54:55], v[154:155], v[46:47], v[54:55] op_sel_hi:[0,1,1]
	v_pk_fma_f32 v[0:1], v[154:155], v[46:47], v[0:1] op_sel:[1,0,0]
	s_waitcnt vmcnt(9)
	v_lshlrev_b32_e32 v46, 16, v84
	v_and_b32_e32 v47, 0xffff0000, v84
	v_pk_fma_f32 v[54:55], v[156:157], v[46:47], v[54:55] op_sel_hi:[0,1,1]
	v_pk_fma_f32 v[0:1], v[156:157], v[46:47], v[0:1] op_sel:[1,0,0]
	s_waitcnt vmcnt(8)
	v_lshlrev_b32_e32 v46, 16, v80
	v_and_b32_e32 v47, 0xffff0000, v80
	v_pk_fma_f32 v[0:1], v[158:159], v[46:47], v[0:1] op_sel:[1,0,0]
	v_lshlrev_b32_e32 v40, 16, v133
	v_and_b32_e32 v41, 0xffff0000, v133
	v_pk_fma_f32 v[54:55], v[158:159], v[46:47], v[54:55] op_sel_hi:[0,1,1]
	v_pk_mul_f32 v[46:47], v[10:11], v[0:1]
	v_pk_mul_f32 v[0:1], v[160:161], v[0:1]
	v_lshlrev_b32_e32 v48, 16, v129
	v_and_b32_e32 v49, 0xffff0000, v129
	v_pk_fma_f32 v[46:47], v[160:161], v[54:55], v[46:47] neg_lo:[0,0,1] neg_hi:[0,0,1]
	v_pk_fma_f32 v[0:1], v[10:11], v[54:55], v[0:1]
	v_pk_fma_f32 v[54:55], v[144:145], v[40:41], 0 op_sel_hi:[0,1,0]
	v_pk_fma_f32 v[40:41], v[144:145], v[40:41], 0 op_sel:[1,0,0] op_sel_hi:[1,1,0]
	v_pk_fma_f32 v[54:55], v[146:147], v[48:49], v[54:55] op_sel_hi:[0,1,1]
	v_pk_fma_f32 v[40:41], v[146:147], v[48:49], v[40:41] op_sel:[1,0,0]
	v_lshlrev_b32_e32 v48, 16, v101
	v_and_b32_e32 v49, 0xffff0000, v101
	v_pk_fma_f32 v[54:55], v[148:149], v[48:49], v[54:55] op_sel_hi:[0,1,1]
	v_pk_fma_f32 v[40:41], v[148:149], v[48:49], v[40:41] op_sel:[1,0,0]
	v_lshlrev_b32_e32 v48, 16, v97
	v_and_b32_e32 v49, 0xffff0000, v97
	v_pk_fma_f32 v[54:55], v[150:151], v[48:49], v[54:55] op_sel_hi:[0,1,1]
	v_pk_fma_f32 v[40:41], v[150:151], v[48:49], v[40:41] op_sel:[1,0,0]
	v_lshlrev_b32_e32 v48, 16, v93
	v_and_b32_e32 v49, 0xffff0000, v93
	v_pk_fma_f32 v[54:55], v[152:153], v[48:49], v[54:55] op_sel_hi:[0,1,1]
	v_pk_fma_f32 v[40:41], v[152:153], v[48:49], v[40:41] op_sel:[1,0,0]
	v_lshlrev_b32_e32 v48, 16, v89
	v_and_b32_e32 v49, 0xffff0000, v89
	v_pk_fma_f32 v[54:55], v[154:155], v[48:49], v[54:55] op_sel_hi:[0,1,1]
	v_pk_fma_f32 v[40:41], v[154:155], v[48:49], v[40:41] op_sel:[1,0,0]
	v_lshlrev_b32_e32 v48, 16, v85
	v_and_b32_e32 v49, 0xffff0000, v85
	v_pk_fma_f32 v[54:55], v[156:157], v[48:49], v[54:55] op_sel_hi:[0,1,1]
	v_pk_fma_f32 v[40:41], v[156:157], v[48:49], v[40:41] op_sel:[1,0,0]
	v_lshlrev_b32_e32 v48, 16, v81
	v_and_b32_e32 v49, 0xffff0000, v81
	v_pk_fma_f32 v[40:41], v[158:159], v[48:49], v[40:41] op_sel:[1,0,0]
	v_lshlrev_b32_e32 v42, 16, v134
	v_and_b32_e32 v43, 0xffff0000, v134
	v_pk_fma_f32 v[54:55], v[158:159], v[48:49], v[54:55] op_sel_hi:[0,1,1]
	v_pk_mul_f32 v[48:49], v[14:15], v[40:41]
	v_pk_mul_f32 v[40:41], v[8:9], v[40:41]
	v_lshlrev_b32_e32 v50, 16, v130
	v_and_b32_e32 v51, 0xffff0000, v130
	v_pk_fma_f32 v[48:49], v[8:9], v[54:55], v[48:49] neg_lo:[0,0,1] neg_hi:[0,0,1]
	v_pk_fma_f32 v[54:55], v[14:15], v[54:55], v[40:41]
	v_pk_fma_f32 v[40:41], v[144:145], v[42:43], 0 op_sel_hi:[0,1,0]
	v_pk_fma_f32 v[42:43], v[144:145], v[42:43], 0 op_sel:[1,0,0] op_sel_hi:[1,1,0]
	v_pk_fma_f32 v[40:41], v[146:147], v[50:51], v[40:41] op_sel_hi:[0,1,1]
	v_pk_fma_f32 v[42:43], v[146:147], v[50:51], v[42:43] op_sel:[1,0,0]
	v_lshlrev_b32_e32 v50, 16, v102
	v_and_b32_e32 v51, 0xffff0000, v102
	v_pk_fma_f32 v[40:41], v[148:149], v[50:51], v[40:41] op_sel_hi:[0,1,1]
	v_pk_fma_f32 v[42:43], v[148:149], v[50:51], v[42:43] op_sel:[1,0,0]
	v_lshlrev_b32_e32 v50, 16, v98
	v_and_b32_e32 v51, 0xffff0000, v98
	v_pk_fma_f32 v[40:41], v[150:151], v[50:51], v[40:41] op_sel_hi:[0,1,1]
	v_pk_fma_f32 v[42:43], v[150:151], v[50:51], v[42:43] op_sel:[1,0,0]
	v_lshlrev_b32_e32 v50, 16, v94
	v_and_b32_e32 v51, 0xffff0000, v94
	v_pk_fma_f32 v[40:41], v[152:153], v[50:51], v[40:41] op_sel_hi:[0,1,1]
	v_pk_fma_f32 v[42:43], v[152:153], v[50:51], v[42:43] op_sel:[1,0,0]
	v_lshlrev_b32_e32 v50, 16, v90
	v_and_b32_e32 v51, 0xffff0000, v90
	v_pk_fma_f32 v[40:41], v[154:155], v[50:51], v[40:41] op_sel_hi:[0,1,1]
	v_pk_fma_f32 v[42:43], v[154:155], v[50:51], v[42:43] op_sel:[1,0,0]
	v_lshlrev_b32_e32 v50, 16, v86
	v_and_b32_e32 v51, 0xffff0000, v86
	v_pk_fma_f32 v[40:41], v[156:157], v[50:51], v[40:41] op_sel_hi:[0,1,1]
	v_pk_fma_f32 v[42:43], v[156:157], v[50:51], v[42:43] op_sel:[1,0,0]
	v_lshlrev_b32_e32 v50, 16, v82
	v_and_b32_e32 v51, 0xffff0000, v82
	v_pk_fma_f32 v[42:43], v[158:159], v[50:51], v[42:43] op_sel:[1,0,0]
	v_lshlrev_b32_e32 v44, 16, v135
	v_and_b32_e32 v45, 0xffff0000, v135
	v_pk_fma_f32 v[40:41], v[158:159], v[50:51], v[40:41] op_sel_hi:[0,1,1]
	v_pk_mul_f32 v[50:51], v[6:7], v[42:43]
	v_pk_mul_f32 v[42:43], v[12:13], v[42:43]
	v_lshlrev_b32_e32 v52, 16, v131
	v_and_b32_e32 v53, 0xffff0000, v131
	v_pk_fma_f32 v[50:51], v[12:13], v[40:41], v[50:51] neg_lo:[0,0,1] neg_hi:[0,0,1]
	v_pk_fma_f32 v[56:57], v[6:7], v[40:41], v[42:43]
	v_pk_fma_f32 v[40:41], v[144:145], v[44:45], 0 op_sel_hi:[0,1,0]
	v_pk_fma_f32 v[42:43], v[144:145], v[44:45], 0 op_sel:[1,0,0] op_sel_hi:[1,1,0]
	v_pk_fma_f32 v[40:41], v[146:147], v[52:53], v[40:41] op_sel_hi:[0,1,1]
	v_pk_fma_f32 v[42:43], v[146:147], v[52:53], v[42:43] op_sel:[1,0,0]
	v_lshlrev_b32_e32 v44, 16, v103
	v_and_b32_e32 v45, 0xffff0000, v103
	v_pk_fma_f32 v[40:41], v[148:149], v[44:45], v[40:41] op_sel_hi:[0,1,1]
	v_pk_fma_f32 v[42:43], v[148:149], v[44:45], v[42:43] op_sel:[1,0,0]
	v_lshlrev_b32_e32 v44, 16, v99
	v_and_b32_e32 v45, 0xffff0000, v99
	v_pk_fma_f32 v[40:41], v[150:151], v[44:45], v[40:41] op_sel_hi:[0,1,1]
	v_pk_fma_f32 v[42:43], v[150:151], v[44:45], v[42:43] op_sel:[1,0,0]
	v_lshlrev_b32_e32 v44, 16, v95
	v_and_b32_e32 v45, 0xffff0000, v95
	v_pk_fma_f32 v[40:41], v[152:153], v[44:45], v[40:41] op_sel_hi:[0,1,1]
	v_pk_fma_f32 v[42:43], v[152:153], v[44:45], v[42:43] op_sel:[1,0,0]
	v_lshlrev_b32_e32 v44, 16, v91
	v_and_b32_e32 v45, 0xffff0000, v91
	v_pk_fma_f32 v[40:41], v[154:155], v[44:45], v[40:41] op_sel_hi:[0,1,1]
	v_pk_fma_f32 v[42:43], v[154:155], v[44:45], v[42:43] op_sel:[1,0,0]
	v_lshlrev_b32_e32 v44, 16, v87
	v_and_b32_e32 v45, 0xffff0000, v87
	v_pk_fma_f32 v[40:41], v[156:157], v[44:45], v[40:41] op_sel_hi:[0,1,1]
	v_pk_fma_f32 v[42:43], v[156:157], v[44:45], v[42:43] op_sel:[1,0,0]
	v_lshlrev_b32_e32 v44, 16, v83
	v_and_b32_e32 v45, 0xffff0000, v83
	v_pk_fma_f32 v[42:43], v[158:159], v[44:45], v[42:43] op_sel:[1,0,0]
	v_pk_fma_f32 v[40:41], v[158:159], v[44:45], v[40:41] op_sel_hi:[0,1,1]
	v_pk_mul_f32 v[44:45], v[2:3], v[42:43]
	v_pk_mul_f32 v[42:43], v[4:5], v[42:43]
	v_pk_fma_f32 v[44:45], v[4:5], v[40:41], v[44:45] neg_lo:[0,0,1] neg_hi:[0,0,1]
	v_pk_fma_f32 v[52:53], v[2:3], v[40:41], v[42:43]
	v_cvt_pk_bf16_f32 v43, v44, v45
	v_mul_lo_u32 v44, v166, s6
	v_cvt_pk_bf16_f32 v40, v46, v47
	v_cvt_pk_bf16_f32 v41, v48, v49
	v_cvt_pk_bf16_f32 v42, v50, v51
	v_add3_u32 v44, 0, v44, v192
	ds_write_b128 v44, v[40:43]
	v_cvt_pk_bf16_f32 v40, v0, v1
	s_waitcnt vmcnt(7)
	v_lshlrev_b32_e32 v0, 16, v68
	v_and_b32_e32 v1, 0xffff0000, v68
	v_cvt_pk_bf16_f32 v41, v54, v55
	s_waitcnt vmcnt(6)
	v_lshlrev_b32_e32 v46, 16, v64
	v_and_b32_e32 v47, 0xffff0000, v64
	v_pk_fma_f32 v[54:55], v[144:145], v[0:1], 0 op_sel_hi:[0,1,0]
	v_pk_fma_f32 v[0:1], v[144:145], v[0:1], 0 op_sel:[1,0,0] op_sel_hi:[1,1,0]
	v_pk_fma_f32 v[54:55], v[146:147], v[46:47], v[54:55] op_sel_hi:[0,1,1]
	v_pk_fma_f32 v[0:1], v[146:147], v[46:47], v[0:1] op_sel:[1,0,0]
	s_waitcnt vmcnt(5)
	v_lshlrev_b32_e32 v46, 16, v36
	v_and_b32_e32 v47, 0xffff0000, v36
	v_pk_fma_f32 v[54:55], v[148:149], v[46:47], v[54:55] op_sel_hi:[0,1,1]
	v_pk_fma_f32 v[0:1], v[148:149], v[46:47], v[0:1] op_sel:[1,0,0]
	s_waitcnt vmcnt(4)
	v_lshlrev_b32_e32 v46, 16, v32
	v_and_b32_e32 v47, 0xffff0000, v32
	v_pk_fma_f32 v[54:55], v[150:151], v[46:47], v[54:55] op_sel_hi:[0,1,1]
	v_pk_fma_f32 v[0:1], v[150:151], v[46:47], v[0:1] op_sel:[1,0,0]
	s_waitcnt vmcnt(3)
	v_lshlrev_b32_e32 v46, 16, v28
	v_and_b32_e32 v47, 0xffff0000, v28
	v_pk_fma_f32 v[54:55], v[152:153], v[46:47], v[54:55] op_sel_hi:[0,1,1]
	v_pk_fma_f32 v[0:1], v[152:153], v[46:47], v[0:1] op_sel:[1,0,0]
	s_waitcnt vmcnt(2)
	v_lshlrev_b32_e32 v46, 16, v24
	v_and_b32_e32 v47, 0xffff0000, v24
	v_pk_fma_f32 v[54:55], v[154:155], v[46:47], v[54:55] op_sel_hi:[0,1,1]
	v_pk_fma_f32 v[0:1], v[154:155], v[46:47], v[0:1] op_sel:[1,0,0]
	s_waitcnt vmcnt(1)
	v_lshlrev_b32_e32 v46, 16, v20
	v_and_b32_e32 v47, 0xffff0000, v20
	v_pk_fma_f32 v[54:55], v[156:157], v[46:47], v[54:55] op_sel_hi:[0,1,1]
	v_pk_fma_f32 v[0:1], v[156:157], v[46:47], v[0:1] op_sel:[1,0,0]
	s_waitcnt vmcnt(0)
	v_lshlrev_b32_e32 v46, 16, v16
	v_and_b32_e32 v47, 0xffff0000, v16
	v_cvt_pk_bf16_f32 v42, v56, v57
	v_cvt_pk_bf16_f32 v43, v52, v53
	v_pk_fma_f32 v[0:1], v[158:159], v[46:47], v[0:1] op_sel:[1,0,0]
	ds_write_b128 v44, v[40:43] offset:512
	v_lshlrev_b32_e32 v40, 16, v69
	v_and_b32_e32 v41, 0xffff0000, v69
	v_pk_fma_f32 v[54:55], v[158:159], v[46:47], v[54:55] op_sel_hi:[0,1,1]
	v_pk_mul_f32 v[46:47], v[10:11], v[0:1]
	v_pk_mul_f32 v[0:1], v[160:161], v[0:1]
	v_lshlrev_b32_e32 v48, 16, v65
	v_and_b32_e32 v49, 0xffff0000, v65
	v_pk_fma_f32 v[10:11], v[10:11], v[54:55], v[0:1]
	v_pk_fma_f32 v[0:1], v[144:145], v[40:41], 0 op_sel_hi:[0,1,0]
	v_pk_fma_f32 v[40:41], v[144:145], v[40:41], 0 op_sel:[1,0,0] op_sel_hi:[1,1,0]
	v_pk_fma_f32 v[0:1], v[146:147], v[48:49], v[0:1] op_sel_hi:[0,1,1]
	v_pk_fma_f32 v[40:41], v[146:147], v[48:49], v[40:41] op_sel:[1,0,0]
	v_lshlrev_b32_e32 v36, 16, v37
	v_and_b32_e32 v37, 0xffff0000, v37
	v_pk_fma_f32 v[0:1], v[148:149], v[36:37], v[0:1] op_sel_hi:[0,1,1]
	v_pk_fma_f32 v[36:37], v[148:149], v[36:37], v[40:41] op_sel:[1,0,0]
	v_lshlrev_b32_e32 v32, 16, v33
	v_and_b32_e32 v33, 0xffff0000, v33
	v_pk_fma_f32 v[0:1], v[150:151], v[32:33], v[0:1] op_sel_hi:[0,1,1]
	v_pk_fma_f32 v[32:33], v[150:151], v[32:33], v[36:37] op_sel:[1,0,0]
	v_lshlrev_b32_e32 v28, 16, v29
	v_and_b32_e32 v29, 0xffff0000, v29
	v_pk_fma_f32 v[0:1], v[152:153], v[28:29], v[0:1] op_sel_hi:[0,1,1]
	v_pk_fma_f32 v[28:29], v[152:153], v[28:29], v[32:33] op_sel:[1,0,0]
	v_lshlrev_b32_e32 v24, 16, v25
	v_and_b32_e32 v25, 0xffff0000, v25
	v_pk_fma_f32 v[0:1], v[154:155], v[24:25], v[0:1] op_sel_hi:[0,1,1]
; #define GAS __attribute__((address_space(1)))
; __device__ __forceinline__ void b_unit(Frame& F, int u, bool dry) {
;     ...
;     __syncthreads();
;     const int fr = lane & 15, fq = lane >> 4;
;     f32x4 ur[2][8], ui[2][8];
;     {
;         const bf16x8 Wr = *(const GAS bf16x8*)(ws_ + WS_W16F + (size_t)lane * 16), Wi = *(const GAS bf16x8*)(ws_ + WS_W16F + 1024 + (size_t)lane * 16);
	v_pk_fma_f32 v[24:25], v[154:155], v[24:25], v[28:29] op_sel:[1,0,0]
	v_lshlrev_b32_e32 v20, 16, v21
	v_and_b32_e32 v21, 0xffff0000, v21
	v_pk_fma_f32 v[0:1], v[156:157], v[20:21], v[0:1] op_sel_hi:[0,1,1]
	v_pk_fma_f32 v[20:21], v[156:157], v[20:21], v[24:25] op_sel:[1,0,0]
	v_lshlrev_b32_e32 v16, 16, v17
	v_and_b32_e32 v17, 0xffff0000, v17
	v_pk_fma_f32 v[0:1], v[158:159], v[16:17], v[0:1] op_sel_hi:[0,1,1]
	v_pk_fma_f32 v[16:17], v[158:159], v[16:17], v[20:21] op_sel:[1,0,0]
	v_lshlrev_b32_e32 v42, 16, v70
	v_pk_mul_f32 v[20:21], v[14:15], v[16:17]
	v_and_b32_e32 v43, 0xffff0000, v70
	v_pk_fma_f32 v[20:21], v[8:9], v[0:1], v[20:21] neg_lo:[0,0,1] neg_hi:[0,0,1]
	v_pk_mul_f32 v[8:9], v[8:9], v[16:17]
	v_lshlrev_b32_e32 v50, 16, v66
	v_and_b32_e32 v51, 0xffff0000, v66
	v_pk_fma_f32 v[8:9], v[14:15], v[0:1], v[8:9]
	v_pk_fma_f32 v[0:1], v[144:145], v[42:43], 0 op_sel_hi:[0,1,0]
	v_pk_fma_f32 v[14:15], v[144:145], v[42:43], 0 op_sel:[1,0,0] op_sel_hi:[1,1,0]
	v_pk_fma_f32 v[0:1], v[146:147], v[50:51], v[0:1] op_sel_hi:[0,1,1]
	v_pk_fma_f32 v[14:15], v[146:147], v[50:51], v[14:15] op_sel:[1,0,0]
	v_lshlrev_b32_e32 v16, 16, v38
	v_and_b32_e32 v17, 0xffff0000, v38
	v_pk_fma_f32 v[0:1], v[148:149], v[16:17], v[0:1] op_sel_hi:[0,1,1]
	v_pk_fma_f32 v[14:15], v[148:149], v[16:17], v[14:15] op_sel:[1,0,0]
	v_lshlrev_b32_e32 v16, 16, v34
	v_and_b32_e32 v17, 0xffff0000, v34
	v_pk_fma_f32 v[0:1], v[150:151], v[16:17], v[0:1] op_sel_hi:[0,1,1]
	v_pk_fma_f32 v[14:15], v[150:151], v[16:17], v[14:15] op_sel:[1,0,0]
	v_lshlrev_b32_e32 v16, 16, v30
	v_and_b32_e32 v17, 0xffff0000, v30
	v_pk_fma_f32 v[0:1], v[152:153], v[16:17], v[0:1] op_sel_hi:[0,1,1]
	v_pk_fma_f32 v[14:15], v[152:153], v[16:17], v[14:15] op_sel:[1,0,0]
	v_lshlrev_b32_e32 v16, 16, v26
	v_and_b32_e32 v17, 0xffff0000, v26
	v_pk_fma_f32 v[0:1], v[154:155], v[16:17], v[0:1] op_sel_hi:[0,1,1]
	v_pk_fma_f32 v[14:15], v[154:155], v[16:17], v[14:15] op_sel:[1,0,0]
	v_lshlrev_b32_e32 v16, 16, v22
	v_and_b32_e32 v17, 0xffff0000, v22
	v_pk_fma_f32 v[0:1], v[156:157], v[16:17], v[0:1] op_sel_hi:[0,1,1]
	v_pk_fma_f32 v[14:15], v[156:157], v[16:17], v[14:15] op_sel:[1,0,0]
	v_lshlrev_b32_e32 v16, 16, v18
	v_and_b32_e32 v17, 0xffff0000, v18
	v_pk_fma_f32 v[14:15], v[158:159], v[16:17], v[14:15] op_sel:[1,0,0]
	v_pk_fma_f32 v[0:1], v[158:159], v[16:17], v[0:1] op_sel_hi:[0,1,1]
	v_pk_mul_f32 v[16:17], v[6:7], v[14:15]
	v_lshlrev_b32_e32 v44, 16, v71
	v_and_b32_e32 v45, 0xffff0000, v71
	v_pk_fma_f32 v[16:17], v[12:13], v[0:1], v[16:17] neg_lo:[0,0,1] neg_hi:[0,0,1]
	v_pk_mul_f32 v[12:13], v[12:13], v[14:15]
	v_lshlrev_b32_e32 v52, 16, v67
	v_and_b32_e32 v53, 0xffff0000, v67
	v_pk_fma_f32 v[6:7], v[6:7], v[0:1], v[12:13]
	v_pk_fma_f32 v[0:1], v[144:145], v[44:45], 0 op_sel_hi:[0,1,0]
	v_pk_fma_f32 v[12:13], v[144:145], v[44:45], 0 op_sel:[1,0,0] op_sel_hi:[1,1,0]
	v_pk_fma_f32 v[0:1], v[146:147], v[52:53], v[0:1] op_sel_hi:[0,1,1]
	v_pk_fma_f32 v[12:13], v[146:147], v[52:53], v[12:13] op_sel:[1,0,0]
	v_lshlrev_b32_e32 v14, 16, v39
	v_and_b32_e32 v15, 0xffff0000, v39
	v_pk_fma_f32 v[0:1], v[148:149], v[14:15], v[0:1] op_sel_hi:[0,1,1]
	v_pk_fma_f32 v[12:13], v[148:149], v[14:15], v[12:13] op_sel:[1,0,0]
	v_lshlrev_b32_e32 v14, 16, v35
	v_and_b32_e32 v15, 0xffff0000, v35
	v_pk_fma_f32 v[0:1], v[150:151], v[14:15], v[0:1] op_sel_hi:[0,1,1]
	v_pk_fma_f32 v[12:13], v[150:151], v[14:15], v[12:13] op_sel:[1,0,0]
	v_lshlrev_b32_e32 v14, 16, v31
	v_and_b32_e32 v15, 0xffff0000, v31
	v_pk_fma_f32 v[0:1], v[152:153], v[14:15], v[0:1] op_sel_hi:[0,1,1]
	v_pk_fma_f32 v[12:13], v[152:153], v[14:15], v[12:13] op_sel:[1,0,0]
	v_lshlrev_b32_e32 v14, 16, v27
	v_and_b32_e32 v15, 0xffff0000, v27
	v_pk_fma_f32 v[0:1], v[154:155], v[14:15], v[0:1] op_sel_hi:[0,1,1]
	v_pk_fma_f32 v[12:13], v[154:155], v[14:15], v[12:13] op_sel:[1,0,0]
	v_lshlrev_b32_e32 v14, 16, v23
	v_and_b32_e32 v15, 0xffff0000, v23
	v_pk_fma_f32 v[0:1], v[156:157], v[14:15], v[0:1] op_sel_hi:[0,1,1]
	v_pk_fma_f32 v[12:13], v[156:157], v[14:15], v[12:13] op_sel:[1,0,0]
	v_lshlrev_b32_e32 v14, 16, v19
	v_and_b32_e32 v15, 0xffff0000, v19
	v_pk_fma_f32 v[12:13], v[158:159], v[14:15], v[12:13] op_sel:[1,0,0]
	v_pk_fma_f32 v[0:1], v[158:159], v[14:15], v[0:1] op_sel_hi:[0,1,1]
	v_pk_mul_f32 v[14:15], v[2:3], v[12:13]
	v_pk_fma_f32 v[46:47], v[160:161], v[54:55], v[46:47] neg_lo:[0,0,1] neg_hi:[0,0,1]
	v_pk_fma_f32 v[14:15], v[4:5], v[0:1], v[14:15] neg_lo:[0,0,1] neg_hi:[0,0,1]
	v_pk_mul_f32 v[4:5], v[4:5], v[12:13]
	v_mul_lo_u32 v12, v164, s6
	v_pk_fma_f32 v[4:5], v[2:3], v[0:1], v[4:5]
	v_cvt_pk_bf16_f32 v0, v46, v47
	v_cvt_pk_bf16_f32 v1, v20, v21
	v_cvt_pk_bf16_f32 v2, v16, v17
	v_cvt_pk_bf16_f32 v3, v14, v15
	v_add3_u32 v12, 0, v12, v192
	ds_write_b128 v12, v[0:3]
	v_cvt_pk_bf16_f32 v0, v10, v11
	v_cvt_pk_bf16_f32 v1, v8, v9
	v_cvt_pk_bf16_f32 v2, v6, v7
	v_cvt_pk_bf16_f32 v3, v4, v5
	v_lshlrev_b32_e32 v192, 4, v171
	ds_write_b128 v12, v[0:3] offset:512
	v_lshl_add_u64 v[0:1], s[2:3], 0, v[192:193]
	v_add_co_u32_e32 v4, vcc, s7, v0
	s_waitcnt lgkmcnt(0)
	s_nop 0
	v_addc_co_u32_e32 v5, vcc, 0, v1, vcc
	s_barrier
; #define LAS __attribute__((address_space(3)))
; #define GAS __attribute__((address_space(1)))
; __device__ __forceinline__ unsigned cvtpk(float lo, float hi) { f32x2 v = {lo, hi}; bf16x2_t b = __builtin_convertvector(v, bf16x2_t); return __builtin_bit_cast(unsigned, b); }
; __device__ __forceinline__ void b_unit(Frame& F, int u, bool dry) {
;     ...
;     {
;         const bf16x8 Wr = *(const GAS bf16x8*)(ws_ + WS_W16F + (size_t)lane * 16), Wi = *(const GAS bf16x8*)(ws_ + WS_W16F + 1024 + (size_t)lane * 16);
;         f32x2 t2[4];
; #pragma unroll
;         for (int j = 0; j < 4; ++j) t2[j] = *(const GAS f32x2*)(ws_ + WS_TW2 + (size_t)(lane * 4 + j) * 8);
;         const f32x4 zero4 = (f32x4){0.f, 0.f, 0.f, 0.f};
;         const unsigned rbase = (unsigned)(size_t)Bt + (unsigned)(16 * w) * 1040u + (unsigned)(fq >> 1) * 512u + (unsigned)(16 * (8 * (fq & 1) + (fr >> 2)) + 4 * (fr & 3)) * 2u;
;         u32x2 q0[16], q1[16];
;     ...
;         BU_TR8(0); BU_TR8(8);
;     ...
;         LAS unsigned char* vrow = Bt + (size_t)(16 * w) * 1040 + 64 * fr + 8 * fq;
; #pragma unroll
;         for (int i = 0; i < 16; ++i) {
;             u32x4 f4; f4.x = q0[i].x; f4.y = q0[i].y; f4.z = q1[i].x; f4.w = q1[i].y;
;             const bf16x8 frag = __builtin_bit_cast(bf16x8, f4);
;             const f32x4 dr = __builtin_amdgcn_mfma_f32_16x16x32_bf16(frag, Wr, zero4, 0, 0, 0), di = __builtin_amdgcn_mfma_f32_16x16x32_bf16(frag, Wi, zero4, 0, 0, 0);
;             float vr[4], vi[4];
; #pragma unroll
;             for (int j = 0; j < 4; ++j) { vr[j] = dr[j] * t2[j].x + di[j] * t2[j].y; vi[j] = di[j] * t2[j].x - dr[j] * t2[j].y; }
;             u32x2 o; o.x = cvtpk(vr[0], vr[1]); o.y = cvtpk(vr[2], vr[3]); *(LAS u32x2*)(vrow + i * 1040) = o;
;             o.x = cvtpk(vi[0], vi[1]); o.y = cvtpk(vi[2], vi[3]); *(LAS u32x2*)(vrow + i * 1040 + 32) = o;
;         }
	global_load_dwordx4 v[0:3], v[4:5], off
	s_nop 0
	global_load_dwordx4 v[4:7], v[4:5], off offset:1024
	v_lshlrev_b32_e32 v8, 5, v171
	v_mov_b32_e32 v9, v193
	v_lshl_add_u64 v[8:9], s[2:3], 0, v[8:9]
	s_mov_b64 s[0:1], 0x1d90800
	v_lshl_add_u64 v[10:11], v[8:9], 0, s[0:1]
	v_add_co_u32_e32 v8, vcc, s7, v8
	v_lshrrev_b32_e32 v17, 1, v170
	s_nop 0
	v_addc_co_u32_e32 v9, vcc, 0, v9, vcc
	global_load_dwordx4 v[12:15], v[8:9], off offset:2048
	s_nop 0
	global_load_dwordx4 v[8:11], v[10:11], off offset:16
	v_bfe_u32 v18, v170, 2, 2
	v_and_b32_e32 v76, 24, v17
	v_and_or_b32 v17, v17, 8, v18
	v_lshlrev_b32_e32 v18, 3, v170
	v_and_b32_e32 v18, 24, v18
	v_readlane_b32 s0, v253, 54
	v_and_b32_e32 v16, 0x200, v192
	v_lshlrev_b32_e32 v17, 5, v17
	v_add_u32_e32 v18, s0, v18
	v_add3_u32 v64, v18, v16, v17
	ds_read_b64_tr_b16 v[82:83], v64 offset:0
	ds_read_b64_tr_b16 v[84:85], v64 offset:0+128
	ds_read_b64_tr_b16 v[78:79], v64 offset:0+1040
	ds_read_b64_tr_b16 v[80:81], v64 offset:0+1040+128
	ds_read_b64_tr_b16 v[72:73], v64 offset:0+2080
	ds_read_b64_tr_b16 v[74:75], v64 offset:0+2080+128
	ds_read_b64_tr_b16 v[68:69], v64 offset:0+3120
	ds_read_b64_tr_b16 v[70:71], v64 offset:0+3120+128
	ds_read_b64_tr_b16 v[60:61], v64 offset:0+4160
	ds_read_b64_tr_b16 v[62:63], v64 offset:0+4160+128
	ds_read_b64_tr_b16 v[56:57], v64 offset:0+5200
	ds_read_b64_tr_b16 v[58:59], v64 offset:0+5200+128
	ds_read_b64_tr_b16 v[52:53], v64 offset:0+6240
	ds_read_b64_tr_b16 v[54:55], v64 offset:0+6240+128
	ds_read_b64_tr_b16 v[48:49], v64 offset:0+7280
	ds_read_b64_tr_b16 v[50:51], v64 offset:0+7280+128
	s_waitcnt lgkmcnt(0)
	v_and_b32_e32 v77, 15, v170
	s_waitcnt vmcnt(3)
	v_mfma_f32_16x16x32_bf16 v[86:89], v[82:85], v[0:3], 0
	ds_read_b64_tr_b16 v[44:45], v64 offset:0x2080
	ds_read_b64_tr_b16 v[46:47], v64 offset:0x2080+128
	ds_read_b64_tr_b16 v[40:41], v64 offset:0x2080+1040
	ds_read_b64_tr_b16 v[42:43], v64 offset:0x2080+1040+128
	ds_read_b64_tr_b16 v[36:37], v64 offset:0x2080+2080
	ds_read_b64_tr_b16 v[38:39], v64 offset:0x2080+2080+128
	ds_read_b64_tr_b16 v[32:33], v64 offset:0x2080+3120
	ds_read_b64_tr_b16 v[34:35], v64 offset:0x2080+3120+128
	ds_read_b64_tr_b16 v[28:29], v64 offset:0x2080+4160
	ds_read_b64_tr_b16 v[30:31], v64 offset:0x2080+4160+128
	ds_read_b64_tr_b16 v[24:25], v64 offset:0x2080+5200
	ds_read_b64_tr_b16 v[26:27], v64 offset:0x2080+5200+128
	ds_read_b64_tr_b16 v[20:21], v64 offset:0x2080+6240
	ds_read_b64_tr_b16 v[22:23], v64 offset:0x2080+6240+128
	ds_read_b64_tr_b16 v[16:17], v64 offset:0x2080+7280
	ds_read_b64_tr_b16 v[18:19], v64 offset:0x2080+7280+128
	s_waitcnt lgkmcnt(0)
	v_lshlrev_b32_e32 v64, 6, v77
	v_add3_u32 v66, s0, v64, v76
	s_waitcnt vmcnt(2)
	v_mfma_f32_16x16x32_bf16 v[82:85], v[82:85], v[4:7], 0
	v_add_u32_e32 v67, 0x800, v66
	v_readlane_b32 s0, v253, 60
	v_lshlrev_b32_e32 v192, 1, v76
	s_waitcnt vmcnt(1)
	v_mov_b32_e32 v65, v14
	v_mov_b32_e32 v14, v13
	v_mov_b32_e32 v64, v12
	s_nop 0
	v_pk_mul_f32 v[12:13], v[14:15], v[82:83]
	s_nop 0
	v_pk_fma_f32 v[90:91], v[64:65], v[86:87], v[12:13]
	v_pk_mul_f32 v[12:13], v[14:15], v[86:87]
	s_nop 0
	v_pk_fma_f32 v[82:83], v[64:65], v[82:83], v[12:13] neg_lo:[0,0,1] neg_hi:[0,0,1]
	s_waitcnt vmcnt(0)
	v_mov_b32_e32 v13, v10
	v_mov_b32_e32 v10, v9
	v_mov_b32_e32 v12, v8
	v_pk_mul_f32 v[8:9], v[10:11], v[84:85]
	v_pk_mul_f32 v[86:87], v[10:11], v[88:89]
	v_pk_fma_f32 v[8:9], v[12:13], v[88:89], v[8:9]
	v_pk_fma_f32 v[84:85], v[12:13], v[84:85], v[86:87] neg_lo:[0,0,1] neg_hi:[0,0,1]
	v_cvt_pk_bf16_f32 v87, v8, v9
	v_cvt_pk_bf16_f32 v8, v82, v83
	v_cvt_pk_bf16_f32 v9, v84, v85
	v_mfma_f32_16x16x32_bf16 v[82:85], v[78:81], v[0:3], 0
	v_cvt_pk_bf16_f32 v86, v90, v91
	ds_write2_b64 v66, v[86:87], v[8:9] offset1:4
	v_mfma_f32_16x16x32_bf16 v[78:81], v[78:81], v[4:7], 0
	s_nop 7
	v_pk_mul_f32 v[8:9], v[14:15], v[78:79]
	s_nop 0
	v_pk_fma_f32 v[8:9], v[64:65], v[82:83], v[8:9]
	v_pk_mul_f32 v[82:83], v[14:15], v[82:83]
	v_cvt_pk_bf16_f32 v8, v8, v9
	v_pk_fma_f32 v[78:79], v[64:65], v[78:79], v[82:83] neg_lo:[0,0,1] neg_hi:[0,0,1]
	v_pk_mul_f32 v[82:83], v[10:11], v[80:81]
	v_cvt_pk_bf16_f32 v78, v78, v79
	v_pk_fma_f32 v[82:83], v[12:13], v[84:85], v[82:83]
	v_pk_mul_f32 v[84:85], v[10:11], v[84:85]
	v_cvt_pk_bf16_f32 v9, v82, v83
	v_pk_fma_f32 v[80:81], v[12:13], v[80:81], v[84:85] neg_lo:[0,0,1] neg_hi:[0,0,1]
	s_nop 0
	v_cvt_pk_bf16_f32 v79, v80, v81
	ds_write2_b64 v66, v[8:9], v[78:79] offset0:130 offset1:134
	v_mfma_f32_16x16x32_bf16 v[78:81], v[72:75], v[0:3], 0
	v_mfma_f32_16x16x32_bf16 v[72:75], v[72:75], v[4:7], 0
	s_nop 7
	v_pk_mul_f32 v[8:9], v[14:15], v[72:73]
	s_nop 0
	v_pk_fma_f32 v[8:9], v[64:65], v[78:79], v[8:9]
	v_pk_mul_f32 v[78:79], v[14:15], v[78:79]
	v_cvt_pk_bf16_f32 v8, v8, v9
	v_pk_fma_f32 v[72:73], v[64:65], v[72:73], v[78:79] neg_lo:[0,0,1] neg_hi:[0,0,1]
	v_pk_mul_f32 v[78:79], v[10:11], v[74:75]
	v_cvt_pk_bf16_f32 v72, v72, v73
	v_pk_fma_f32 v[78:79], v[12:13], v[80:81], v[78:79]
	v_pk_mul_f32 v[80:81], v[10:11], v[80:81]
	v_cvt_pk_bf16_f32 v9, v78, v79
	v_pk_fma_f32 v[74:75], v[12:13], v[74:75], v[80:81] neg_lo:[0,0,1] neg_hi:[0,0,1]
	s_nop 0
	v_cvt_pk_bf16_f32 v73, v74, v75
	ds_write2_b64 v67, v[8:9], v[72:73] offset0:4 offset1:8
	v_mfma_f32_16x16x32_bf16 v[72:75], v[68:71], v[0:3], 0
	v_mfma_f32_16x16x32_bf16 v[68:71], v[68:71], v[4:7], 0
	s_nop 7
	v_pk_mul_f32 v[8:9], v[14:15], v[68:69]
	s_nop 0
	v_pk_fma_f32 v[8:9], v[64:65], v[72:73], v[8:9]
	v_pk_mul_f32 v[72:73], v[14:15], v[72:73]
	v_cvt_pk_bf16_f32 v8, v8, v9
	v_pk_fma_f32 v[68:69], v[64:65], v[68:69], v[72:73] neg_lo:[0,0,1] neg_hi:[0,0,1]
	v_pk_mul_f32 v[72:73], v[10:11], v[70:71]
	v_cvt_pk_bf16_f32 v68, v68, v69
; #define LAS __attribute__((address_space(3)))
; __device__ __forceinline__ unsigned cvtpk(float lo, float hi) { f32x2 v = {lo, hi}; bf16x2_t b = __builtin_convertvector(v, bf16x2_t); return __builtin_bit_cast(unsigned, b); }
; __device__ __forceinline__ void b_unit(Frame& F, int u, bool dry) {
;     ...
; #pragma unroll
;         for (int i = 0; i < 16; ++i) {
;             u32x4 f4; f4.x = q0[i].x; f4.y = q0[i].y; f4.z = q1[i].x; f4.w = q1[i].y;
;             const bf16x8 frag = __builtin_bit_cast(bf16x8, f4);
;             const f32x4 dr = __builtin_amdgcn_mfma_f32_16x16x32_bf16(frag, Wr, zero4, 0, 0, 0), di = __builtin_amdgcn_mfma_f32_16x16x32_bf16(frag, Wi, zero4, 0, 0, 0);
;             float vr[4], vi[4];
; #pragma unroll
;             for (int j = 0; j < 4; ++j) { vr[j] = dr[j] * t2[j].x + di[j] * t2[j].y; vi[j] = di[j] * t2[j].x - dr[j] * t2[j].y; }
;             u32x2 o; o.x = cvtpk(vr[0], vr[1]); o.y = cvtpk(vr[2], vr[3]); *(LAS u32x2*)(vrow + i * 1040) = o;
;             o.x = cvtpk(vi[0], vi[1]); o.y = cvtpk(vi[2], vi[3]); *(LAS u32x2*)(vrow + i * 1040 + 32) = o;
;         }
	v_pk_fma_f32 v[72:73], v[12:13], v[74:75], v[72:73]
	v_pk_mul_f32 v[74:75], v[10:11], v[74:75]
	v_cvt_pk_bf16_f32 v9, v72, v73
	v_pk_fma_f32 v[70:71], v[12:13], v[70:71], v[74:75] neg_lo:[0,0,1] neg_hi:[0,0,1]
	s_nop 0
	v_cvt_pk_bf16_f32 v69, v70, v71
	ds_write2_b64 v67, v[8:9], v[68:69] offset0:134 offset1:138
	v_mfma_f32_16x16x32_bf16 v[68:71], v[60:63], v[0:3], 0
	v_add_u32_e32 v67, 0x1000, v66
	v_mfma_f32_16x16x32_bf16 v[60:63], v[60:63], v[4:7], 0
	s_nop 7
	v_pk_mul_f32 v[8:9], v[14:15], v[60:61]
	s_nop 0
	v_pk_fma_f32 v[8:9], v[64:65], v[68:69], v[8:9]
	v_pk_mul_f32 v[68:69], v[14:15], v[68:69]
	v_cvt_pk_bf16_f32 v8, v8, v9
	v_pk_fma_f32 v[60:61], v[64:65], v[60:61], v[68:69] neg_lo:[0,0,1] neg_hi:[0,0,1]
	v_pk_mul_f32 v[68:69], v[10:11], v[62:63]
	v_cvt_pk_bf16_f32 v60, v60, v61
	v_pk_fma_f32 v[68:69], v[12:13], v[70:71], v[68:69]
	v_pk_mul_f32 v[70:71], v[10:11], v[70:71]
	v_cvt_pk_bf16_f32 v9, v68, v69
	v_pk_fma_f32 v[62:63], v[12:13], v[62:63], v[70:71] neg_lo:[0,0,1] neg_hi:[0,0,1]
	s_nop 0
	v_cvt_pk_bf16_f32 v61, v62, v63
	ds_write2_b64 v67, v[8:9], v[60:61] offset0:8 offset1:12
	v_mfma_f32_16x16x32_bf16 v[60:63], v[56:59], v[0:3], 0
	v_mfma_f32_16x16x32_bf16 v[56:59], v[56:59], v[4:7], 0
	s_nop 7
	v_pk_mul_f32 v[8:9], v[14:15], v[56:57]
	s_nop 0
	v_pk_fma_f32 v[8:9], v[64:65], v[60:61], v[8:9]
	v_pk_mul_f32 v[60:61], v[14:15], v[60:61]
	v_cvt_pk_bf16_f32 v8, v8, v9
	v_pk_fma_f32 v[56:57], v[64:65], v[56:57], v[60:61] neg_lo:[0,0,1] neg_hi:[0,0,1]
	v_pk_mul_f32 v[60:61], v[10:11], v[58:59]
	v_cvt_pk_bf16_f32 v56, v56, v57
	v_pk_fma_f32 v[60:61], v[12:13], v[62:63], v[60:61]
	v_pk_mul_f32 v[62:63], v[10:11], v[62:63]
	v_cvt_pk_bf16_f32 v9, v60, v61
	v_pk_fma_f32 v[58:59], v[12:13], v[58:59], v[62:63] neg_lo:[0,0,1] neg_hi:[0,0,1]
	s_nop 0
	v_cvt_pk_bf16_f32 v57, v58, v59
	ds_write2_b64 v67, v[8:9], v[56:57] offset0:138 offset1:142
	v_mfma_f32_16x16x32_bf16 v[56:59], v[52:55], v[0:3], 0
	v_mfma_f32_16x16x32_bf16 v[52:55], v[52:55], v[4:7], 0
	s_nop 7
	v_pk_mul_f32 v[8:9], v[14:15], v[52:53]
	s_nop 0
	v_pk_fma_f32 v[8:9], v[64:65], v[56:57], v[8:9]
	v_pk_mul_f32 v[56:57], v[14:15], v[56:57]
	v_cvt_pk_bf16_f32 v8, v8, v9
	v_pk_fma_f32 v[52:53], v[64:65], v[52:53], v[56:57] neg_lo:[0,0,1] neg_hi:[0,0,1]
	v_pk_mul_f32 v[56:57], v[10:11], v[54:55]
	v_cvt_pk_bf16_f32 v52, v52, v53
	v_pk_fma_f32 v[56:57], v[12:13], v[58:59], v[56:57]
	v_pk_mul_f32 v[58:59], v[10:11], v[58:59]
	v_cvt_pk_bf16_f32 v9, v56, v57
	v_pk_fma_f32 v[54:55], v[12:13], v[54:55], v[58:59] neg_lo:[0,0,1] neg_hi:[0,0,1]
	v_add_u32_e32 v56, 0x1800, v66
	v_cvt_pk_bf16_f32 v53, v54, v55
	ds_write2_b64 v56, v[8:9], v[52:53] offset0:12 offset1:16
	v_mfma_f32_16x16x32_bf16 v[52:55], v[48:51], v[0:3], 0
	v_mfma_f32_16x16x32_bf16 v[48:51], v[48:51], v[4:7], 0
	s_nop 7
	v_pk_mul_f32 v[8:9], v[14:15], v[48:49]
	s_nop 0
	v_pk_fma_f32 v[8:9], v[64:65], v[52:53], v[8:9]
	v_pk_mul_f32 v[52:53], v[14:15], v[52:53]
	v_cvt_pk_bf16_f32 v8, v8, v9
	v_pk_fma_f32 v[48:49], v[64:65], v[48:49], v[52:53] neg_lo:[0,0,1] neg_hi:[0,0,1]
	v_pk_mul_f32 v[52:53], v[10:11], v[50:51]
	v_cvt_pk_bf16_f32 v48, v48, v49
	v_pk_fma_f32 v[52:53], v[12:13], v[54:55], v[52:53]
	v_pk_mul_f32 v[54:55], v[10:11], v[54:55]
	v_cvt_pk_bf16_f32 v9, v52, v53
	v_pk_fma_f32 v[50:51], v[12:13], v[50:51], v[54:55] neg_lo:[0,0,1] neg_hi:[0,0,1]
	v_mov_b32_e32 v52, 0x1c700
	v_cvt_pk_bf16_f32 v49, v50, v51
	ds_write2_b64 v56, v[8:9], v[48:49] offset0:142 offset1:146
	v_mfma_f32_16x16x32_bf16 v[48:51], v[44:47], v[0:3], 0
	v_mad_u32_u24 v134, v77, s6, v52
	v_mfma_f32_16x16x32_bf16 v[44:47], v[44:47], v[4:7], 0
	s_nop 7
	v_pk_mul_f32 v[8:9], v[14:15], v[44:45]
	s_nop 0
	v_pk_fma_f32 v[8:9], v[64:65], v[48:49], v[8:9]
	v_pk_mul_f32 v[48:49], v[14:15], v[48:49]
	v_cvt_pk_bf16_f32 v8, v8, v9
	v_pk_fma_f32 v[44:45], v[64:65], v[44:45], v[48:49] neg_lo:[0,0,1] neg_hi:[0,0,1]
	v_pk_mul_f32 v[48:49], v[10:11], v[46:47]
	v_cvt_pk_bf16_f32 v44, v44, v45
	v_pk_fma_f32 v[48:49], v[12:13], v[50:51], v[48:49]
	v_pk_mul_f32 v[50:51], v[10:11], v[50:51]
	v_cvt_pk_bf16_f32 v9, v48, v49
	v_pk_fma_f32 v[46:47], v[12:13], v[46:47], v[50:51] neg_lo:[0,0,1] neg_hi:[0,0,1]
	v_add_u32_e32 v48, 0x2000, v66
	v_cvt_pk_bf16_f32 v45, v46, v47
	ds_write2_b64 v48, v[8:9], v[44:45] offset0:16 offset1:20
	v_mfma_f32_16x16x32_bf16 v[44:47], v[40:43], v[0:3], 0
	v_mfma_f32_16x16x32_bf16 v[40:43], v[40:43], v[4:7], 0
	s_nop 7
	v_pk_mul_f32 v[8:9], v[14:15], v[40:41]
	s_nop 0
	v_pk_fma_f32 v[8:9], v[64:65], v[44:45], v[8:9]
	v_pk_mul_f32 v[44:45], v[14:15], v[44:45]
	v_cvt_pk_bf16_f32 v8, v8, v9
	v_pk_fma_f32 v[40:41], v[64:65], v[40:41], v[44:45] neg_lo:[0,0,1] neg_hi:[0,0,1]
	v_pk_mul_f32 v[44:45], v[10:11], v[42:43]
	v_cvt_pk_bf16_f32 v40, v40, v41
	v_pk_fma_f32 v[44:45], v[12:13], v[46:47], v[44:45]
	v_pk_mul_f32 v[46:47], v[10:11], v[46:47]
	v_cvt_pk_bf16_f32 v9, v44, v45
	v_pk_fma_f32 v[42:43], v[12:13], v[42:43], v[46:47] neg_lo:[0,0,1] neg_hi:[0,0,1]
	s_nop 0
	v_cvt_pk_bf16_f32 v41, v42, v43
	ds_write2_b64 v48, v[8:9], v[40:41] offset0:146 offset1:150
	v_mfma_f32_16x16x32_bf16 v[40:43], v[36:39], v[0:3], 0
	v_mfma_f32_16x16x32_bf16 v[36:39], v[36:39], v[4:7], 0
	s_nop 7
	v_pk_mul_f32 v[8:9], v[14:15], v[36:37]
	s_nop 0
	v_pk_fma_f32 v[8:9], v[64:65], v[40:41], v[8:9]
	v_pk_mul_f32 v[40:41], v[14:15], v[40:41]
	v_cvt_pk_bf16_f32 v8, v8, v9
	v_pk_fma_f32 v[36:37], v[64:65], v[36:37], v[40:41] neg_lo:[0,0,1] neg_hi:[0,0,1]
	v_pk_mul_f32 v[40:41], v[10:11], v[38:39]
	v_cvt_pk_bf16_f32 v36, v36, v37
	v_pk_fma_f32 v[40:41], v[12:13], v[42:43], v[40:41]
	v_pk_mul_f32 v[42:43], v[10:11], v[42:43]
	v_cvt_pk_bf16_f32 v9, v40, v41
; #define LAS __attribute__((address_space(3)))
; __device__ __forceinline__ unsigned cvtpk(float lo, float hi) { f32x2 v = {lo, hi}; bf16x2_t b = __builtin_convertvector(v, bf16x2_t); return __builtin_bit_cast(unsigned, b); }
; __device__ __forceinline__ void b_unit(Frame& F, int u, bool dry) {
;     ...
;             u32x2 o; o.x = cvtpk(vr[0], vr[1]); o.y = cvtpk(vr[2], vr[3]); *(LAS u32x2*)(vrow + i * 1040) = o;
;             o.x = cvtpk(vi[0], vi[1]); o.y = cvtpk(vi[2], vi[3]); *(LAS u32x2*)(vrow + i * 1040 + 32) = o;
;         }
;         __syncthreads();
; #pragma unroll
;         for (int cc = 0; cc < 2; ++cc)
; #pragma unroll
;             for (int lb = 0; lb < 8; ++lb) {
;                 const bf16x8 frag = *(const LAS bf16x8*)(Bt + (size_t)(16 * lb + fr) * 1040 + 64 * (2 * w + cc) + 16 * fq);
;                 ur[cc][lb] = __builtin_amdgcn_mfma_f32_16x16x32_bf16(frag, Wr, zero4, 0, 0, 0);
;                 ui[cc][lb] = __builtin_amdgcn_mfma_f32_16x16x32_bf16(frag, Wi, zero4, 0, 0, 0);
;             }
	v_pk_fma_f32 v[38:39], v[12:13], v[38:39], v[42:43] neg_lo:[0,0,1] neg_hi:[0,0,1]
	v_add_u32_e32 v40, 0x2800, v66
	v_cvt_pk_bf16_f32 v37, v38, v39
	ds_write2_b64 v40, v[8:9], v[36:37] offset0:20 offset1:24
	v_mfma_f32_16x16x32_bf16 v[36:39], v[32:35], v[0:3], 0
	v_mfma_f32_16x16x32_bf16 v[32:35], v[32:35], v[4:7], 0
	s_nop 7
	v_pk_mul_f32 v[8:9], v[14:15], v[32:33]
	s_nop 0
	v_pk_fma_f32 v[8:9], v[64:65], v[36:37], v[8:9]
	v_pk_mul_f32 v[36:37], v[14:15], v[36:37]
	v_cvt_pk_bf16_f32 v8, v8, v9
	v_pk_fma_f32 v[32:33], v[64:65], v[32:33], v[36:37] neg_lo:[0,0,1] neg_hi:[0,0,1]
	v_pk_mul_f32 v[36:37], v[10:11], v[34:35]
	v_cvt_pk_bf16_f32 v32, v32, v33
	v_pk_fma_f32 v[36:37], v[12:13], v[38:39], v[36:37]
	v_pk_mul_f32 v[38:39], v[10:11], v[38:39]
	v_cvt_pk_bf16_f32 v9, v36, v37
	v_pk_fma_f32 v[34:35], v[12:13], v[34:35], v[38:39] neg_lo:[0,0,1] neg_hi:[0,0,1]
	s_nop 0
	v_cvt_pk_bf16_f32 v33, v34, v35
	ds_write2_b64 v40, v[8:9], v[32:33] offset0:150 offset1:154
	v_mfma_f32_16x16x32_bf16 v[32:35], v[28:31], v[0:3], 0
	v_mov_b32_e32 v40, 0x14500
	v_mad_u32_u24 v118, v77, s6, v40
	v_mfma_f32_16x16x32_bf16 v[28:31], v[28:31], v[4:7], 0
	s_nop 7
	v_pk_mul_f32 v[8:9], v[14:15], v[28:29]
	s_nop 0
	v_pk_fma_f32 v[8:9], v[64:65], v[32:33], v[8:9]
	v_pk_mul_f32 v[32:33], v[14:15], v[32:33]
	v_cvt_pk_bf16_f32 v8, v8, v9
	v_pk_fma_f32 v[28:29], v[64:65], v[28:29], v[32:33] neg_lo:[0,0,1] neg_hi:[0,0,1]
	v_pk_mul_f32 v[32:33], v[10:11], v[30:31]
	v_cvt_pk_bf16_f32 v28, v28, v29
	v_pk_fma_f32 v[32:33], v[12:13], v[34:35], v[32:33]
	v_pk_mul_f32 v[34:35], v[10:11], v[34:35]
	v_cvt_pk_bf16_f32 v9, v32, v33
	v_pk_fma_f32 v[30:31], v[12:13], v[30:31], v[34:35] neg_lo:[0,0,1] neg_hi:[0,0,1]
	v_add_u32_e32 v32, 0x3000, v66
	v_cvt_pk_bf16_f32 v29, v30, v31
	ds_write2_b64 v32, v[8:9], v[28:29] offset0:24 offset1:28
	v_mfma_f32_16x16x32_bf16 v[28:31], v[24:27], v[0:3], 0
	v_mfma_f32_16x16x32_bf16 v[24:27], v[24:27], v[4:7], 0
	s_nop 7
	v_pk_mul_f32 v[8:9], v[14:15], v[24:25]
	s_nop 0
	v_pk_fma_f32 v[8:9], v[64:65], v[28:29], v[8:9]
	v_pk_mul_f32 v[28:29], v[14:15], v[28:29]
	v_cvt_pk_bf16_f32 v8, v8, v9
	v_pk_fma_f32 v[24:25], v[64:65], v[24:25], v[28:29] neg_lo:[0,0,1] neg_hi:[0,0,1]
	v_pk_mul_f32 v[28:29], v[10:11], v[26:27]
	v_cvt_pk_bf16_f32 v24, v24, v25
	v_pk_fma_f32 v[28:29], v[12:13], v[30:31], v[28:29]
	v_pk_mul_f32 v[30:31], v[10:11], v[30:31]
	v_cvt_pk_bf16_f32 v9, v28, v29
	v_pk_fma_f32 v[26:27], v[12:13], v[26:27], v[30:31] neg_lo:[0,0,1] neg_hi:[0,0,1]
	s_nop 0
	v_cvt_pk_bf16_f32 v25, v26, v27
	ds_write2_b64 v32, v[8:9], v[24:25] offset0:154 offset1:158
	v_mfma_f32_16x16x32_bf16 v[24:27], v[20:23], v[0:3], 0
	v_mfma_f32_16x16x32_bf16 v[20:23], v[20:23], v[4:7], 0
	s_nop 7
	v_pk_mul_f32 v[8:9], v[14:15], v[20:21]
	s_nop 0
	v_pk_fma_f32 v[8:9], v[64:65], v[24:25], v[8:9]
	v_pk_mul_f32 v[24:25], v[14:15], v[24:25]
	v_cvt_pk_bf16_f32 v8, v8, v9
	v_pk_fma_f32 v[20:21], v[64:65], v[20:21], v[24:25] neg_lo:[0,0,1] neg_hi:[0,0,1]
	v_pk_mul_f32 v[24:25], v[10:11], v[22:23]
	v_cvt_pk_bf16_f32 v20, v20, v21
	v_pk_fma_f32 v[24:25], v[12:13], v[26:27], v[24:25]
	v_pk_mul_f32 v[26:27], v[10:11], v[26:27]
	v_cvt_pk_bf16_f32 v9, v24, v25
	v_pk_fma_f32 v[22:23], v[12:13], v[22:23], v[26:27] neg_lo:[0,0,1] neg_hi:[0,0,1]
	v_add_u32_e32 v24, 0x3800, v66
	v_cvt_pk_bf16_f32 v21, v22, v23
	ds_write2_b64 v24, v[8:9], v[20:21] offset0:28 offset1:32
	v_mfma_f32_16x16x32_bf16 v[20:23], v[16:19], v[0:3], 0
	v_mfma_f32_16x16x32_bf16 v[16:19], v[16:19], v[4:7], 0
	s_nop 7
	v_pk_mul_f32 v[8:9], v[14:15], v[16:17]
	v_pk_mul_f32 v[14:15], v[14:15], v[20:21]
	v_pk_fma_f32 v[8:9], v[64:65], v[20:21], v[8:9]
	v_pk_fma_f32 v[14:15], v[64:65], v[16:17], v[14:15] neg_lo:[0,0,1] neg_hi:[0,0,1]
	v_pk_mul_f32 v[16:17], v[10:11], v[18:19]
	v_pk_mul_f32 v[10:11], v[10:11], v[22:23]
	v_pk_fma_f32 v[16:17], v[12:13], v[22:23], v[16:17]
	v_pk_fma_f32 v[10:11], v[12:13], v[18:19], v[10:11] neg_lo:[0,0,1] neg_hi:[0,0,1]
	v_cvt_pk_bf16_f32 v8, v8, v9
	v_cvt_pk_bf16_f32 v9, v16, v17
	v_cvt_pk_bf16_f32 v12, v14, v15
	v_cvt_pk_bf16_f32 v13, v10, v11
	ds_write2_b64 v24, v[8:9], v[12:13] offset0:158 offset1:162
	v_and_b32_e32 v8, 48, v170
	v_mov_b32_e32 v16, 0x10400
	v_add_u32_e32 v78, s0, v8
	v_mad_u32_u24 v110, v77, s6, v16
	v_add_u32_e32 v16, v78, v110
	v_add_u32_e32 v40, v78, v118
	s_waitcnt lgkmcnt(0)
	s_barrier
; #define LAS __attribute__((address_space(3)))
; #define GAS __attribute__((address_space(1)))
; __device__ __forceinline__ unsigned cvtpk(float lo, float hi) { f32x2 v = {lo, hi}; bf16x2_t b = __builtin_convertvector(v, bf16x2_t); return __builtin_bit_cast(unsigned, b); }
; __device__ __forceinline__ void b_unit(Frame& F, int u, bool dry) {
;     ...
; #pragma unroll
;         for (int cc = 0; cc < 2; ++cc)
; #pragma unroll
;             for (int lb = 0; lb < 8; ++lb) {
;                 const bf16x8 frag = *(const LAS bf16x8*)(Bt + (size_t)(16 * lb + fr) * 1040 + 64 * (2 * w + cc) + 16 * fq);
;                 ur[cc][lb] = __builtin_amdgcn_mfma_f32_16x16x32_bf16(frag, Wr, zero4, 0, 0, 0);
;                 ui[cc][lb] = __builtin_amdgcn_mfma_f32_16x16x32_bf16(frag, Wi, zero4, 0, 0, 0);
;             }
;     }
;     bf16x8 yr[2][4], yi[2][4];
; #pragma unroll
;     for (int mb = 0; mb < 2; ++mb)
; #pragma unroll
;         for (int t = 0; t < 4; ++t) {
;             u32x4 p; p.x = cvtpk(ur[mb][2 * t][0], ur[mb][2 * t][1]); p.y = cvtpk(ur[mb][2 * t][2], ur[mb][2 * t][3]); p.z = cvtpk(ur[mb][2 * t + 1][0], ur[mb][2 * t + 1][1]); p.w = cvtpk(ur[mb][2 * t + 1][2], ur[mb][2 * t + 1][3]);
;             yr[mb][t] = __builtin_bit_cast(bf16x8, p);
;             p.x = cvtpk(ui[mb][2 * t][0], ui[mb][2 * t][1]); p.y = cvtpk(ui[mb][2 * t][2], ui[mb][2 * t][3]); p.z = cvtpk(ui[mb][2 * t + 1][0], ui[mb][2 * t + 1][1]); p.w = cvtpk(ui[mb][2 * t + 1][2], ui[mb][2 * t + 1][3]);
;             yi[mb][t] = __builtin_bit_cast(bf16x8, p);
;         }
;     bf16_t* SBG = (bf16_t*)(ws_ + WS_SBG);
;     __syncthreads();
;     {   const GAS u32x4* src = (const GAS u32x4*)(ws_ + WS_GT) + (w * 64 + lane); u32x4 tv[8];
; #pragma unroll
;         for (int i = 0; i < 8; ++i) tv[i] = src[i * 512];
; #pragma unroll
;         for (int i = 0; i < 8; ++i) *(LAS u32x4*)(Bt + (size_t)(i * 512 + w * 64 + lane) * 16) = tv[i]; }
	v_or_b32_e32 v228, s70, v171
	v_ashrrev_i32_e32 v229, 31, v228
	v_lshl_add_u64 v[228:229], v[228:229], 4, s[2:3]
	s_mov_b64 s[98:99], 0x1dd4040
	v_lshl_add_u64 v[230:231], v[228:229], 0, s[98:99]
	s_mov_b64 s[98:99], 0x2000
	global_load_dwordx4 v[196:199], v[230:231], off
	v_lshl_add_u64 v[230:231], v[230:231], 0, s[98:99]
	global_load_dwordx4 v[200:203], v[230:231], off
	v_lshl_add_u64 v[230:231], v[230:231], 0, s[98:99]
	global_load_dwordx4 v[204:207], v[230:231], off
	v_lshl_add_u64 v[230:231], v[230:231], 0, s[98:99]
	global_load_dwordx4 v[208:211], v[230:231], off
	v_lshl_add_u64 v[230:231], v[230:231], 0, s[98:99]
	global_load_dwordx4 v[212:215], v[230:231], off
	v_lshl_add_u64 v[230:231], v[230:231], 0, s[98:99]
	global_load_dwordx4 v[216:219], v[230:231], off
	v_lshl_add_u64 v[230:231], v[230:231], 0, s[98:99]
	global_load_dwordx4 v[220:223], v[230:231], off
	v_lshl_add_u64 v[230:231], v[230:231], 0, s[98:99]
	global_load_dwordx4 v[224:227], v[230:231], off
	s_nop 0
	s_nop 0
	s_nop 0
	s_nop 0
	s_nop 0
	s_nop 0
	s_nop 0
	s_nop 0
	ds_read_b128 v[16:19], v16
	ds_read_b128 v[40:43], v40
	s_waitcnt lgkmcnt(0)
	v_mfma_f32_16x16x32_bf16 v[64:67], v[40:43], v[0:3], 0
	v_add_u32_e32 v52, v78, v134
	ds_read_b128 v[52:55], v52
	v_mad_u32_u24 v102, v77, s6, v78
	v_mfma_f32_16x16x32_bf16 v[56:59], v[40:43], v[4:7], 0
	v_mov_b32_e32 v40, 0x18600
	v_mad_u32_u24 v126, v77, s6, v40
	v_add_u32_e32 v40, v78, v126
	ds_read_b128 v[40:43], v40
	ds_read_b128 v[8:11], v102
	s_waitcnt lgkmcnt(2)
	v_mfma_f32_16x16x32_bf16 v[72:75], v[52:55], v[0:3], 0
	v_add_u32_e32 v135, 64, v78
	ds_read_b128 v[12:15], v102 offset:49920
	s_mov_b32 s0, 0x1dd6000
	v_mfma_f32_16x16x32_bf16 v[68:71], v[52:55], v[4:7], 0
	ds_read_b128 v[52:55], v102 offset:64
	s_waitcnt lgkmcnt(2)
	v_mfma_f32_16x16x32_bf16 v[36:39], v[8:11], v[0:3], 0
	v_mfma_f32_16x16x32_bf16 v[20:23], v[8:11], v[4:7], 0
	ds_read_b128 v[8:11], v102 offset:16640
	s_waitcnt lgkmcnt(1)
	v_mfma_f32_16x16x32_bf16 v[78:81], v[52:55], v[0:3], 0
	v_mfma_f32_16x16x32_bf16 v[82:85], v[52:55], v[4:7], 0
	ds_read_b128 v[52:55], v102 offset:16704
	s_waitcnt lgkmcnt(1)
	v_mfma_f32_16x16x32_bf16 v[48:51], v[8:11], v[0:3], 0
	v_mfma_f32_16x16x32_bf16 v[24:27], v[8:11], v[4:7], 0
	ds_read_b128 v[8:11], v102 offset:33280
	s_waitcnt lgkmcnt(1)
	v_mfma_f32_16x16x32_bf16 v[86:89], v[52:55], v[0:3], 0
	v_mfma_f32_16x16x32_bf16 v[90:93], v[52:55], v[4:7], 0
	ds_read_b128 v[52:55], v102 offset:33344
	s_waitcnt lgkmcnt(0)
	v_mfma_f32_16x16x32_bf16 v[94:97], v[52:55], v[0:3], 0
	v_mfma_f32_16x16x32_bf16 v[98:101], v[52:55], v[4:7], 0
	ds_read_b128 v[52:55], v102 offset:49984
	s_waitcnt lgkmcnt(0)
	v_mfma_f32_16x16x32_bf16 v[102:105], v[52:55], v[0:3], 0
	v_mfma_f32_16x16x32_bf16 v[106:109], v[52:55], v[4:7], 0
	v_add_u32_e32 v52, v135, v110
	ds_read_b128 v[52:55], v52
	s_waitcnt lgkmcnt(0)
	v_mfma_f32_16x16x32_bf16 v[110:113], v[52:55], v[0:3], 0
	v_mfma_f32_16x16x32_bf16 v[114:117], v[52:55], v[4:7], 0
	v_add_u32_e32 v52, v135, v118
	ds_read_b128 v[52:55], v52
	s_waitcnt lgkmcnt(0)
	v_mfma_f32_16x16x32_bf16 v[118:121], v[52:55], v[0:3], 0
	v_mfma_f32_16x16x32_bf16 v[122:125], v[52:55], v[4:7], 0
	v_add_u32_e32 v52, v135, v126
	ds_read_b128 v[52:55], v52
	s_waitcnt lgkmcnt(0)
	v_mfma_f32_16x16x32_bf16 v[126:129], v[52:55], v[0:3], 0
	v_mfma_f32_16x16x32_bf16 v[130:133], v[52:55], v[4:7], 0
	v_add_u32_e32 v52, v135, v134
	ds_read_b128 v[52:55], v52
	s_waitcnt lgkmcnt(0)
	v_mfma_f32_16x16x32_bf16 v[44:47], v[16:19], v[0:3], 0
	s_barrier
	v_mfma_f32_16x16x32_bf16 v[60:63], v[40:43], v[0:3], 0
	v_mfma_f32_16x16x32_bf16 v[40:43], v[40:43], v[4:7], 0
	v_mfma_f32_16x16x32_bf16 v[134:137], v[52:55], v[0:3], 0
	v_mfma_f32_16x16x32_bf16 v[138:141], v[52:55], v[4:7], 0
	v_cvt_pk_bf16_f32 v54, v48, v49
	v_cvt_pk_bf16_f32 v48, v20, v21
	s_nop 0
	v_cvt_pk_bf16_f32 v20, v44, v45
	v_cvt_pk_bf16_f32 v44, v98, v99
	v_or_b32_e32 v98, s70, v171
	v_ashrrev_i32_e32 v99, 31, v98
	v_mfma_f32_16x16x32_bf16 v[28:31], v[8:11], v[0:3], 0
	v_cvt_pk_bf16_f32 v49, v22, v23
	v_cvt_pk_bf16_f32 v22, v64, v65
	v_cvt_pk_bf16_f32 v53, v38, v39
	v_mfma_f32_16x16x32_bf16 v[32:35], v[12:15], v[0:3], 0
	v_cvt_pk_bf16_f32 v0, v40, v41
	v_cvt_pk_bf16_f32 v40, v94, v95
	v_lshl_add_u64 v[94:95], v[98:99], 4, s[2:3]
	v_mfma_f32_16x16x32_bf16 v[8:11], v[8:11], v[4:7], 0
	v_add_co_u32_e32 v64, vcc, s8, v94
	v_cvt_pk_bf16_f32 v2, v68, v69
	s_nop 0
	v_addc_co_u32_e32 v65, vcc, 0, v95, vcc
	v_mfma_f32_16x16x32_bf16 v[16:19], v[16:19], v[4:7], 0
	v_add_co_u32_e32 v68, vcc, s0, v94
	s_mov_b32 s0, 0x1dd8000
	s_nop 0
	v_addc_co_u32_e32 v69, vcc, 0, v95, vcc
	v_cvt_pk_bf16_f32 v38, v32, v33
	v_cvt_pk_bf16_f32 v33, v10, v11
	v_cvt_pk_bf16_f32 v10, v72, v73
	v_add_co_u32_e32 v72, vcc, s0, v94
	s_mov_b32 s0, 0x1dda000
	s_nop 0
	v_addc_co_u32_e32 v73, vcc, 0, v95, vcc
	v_cvt_pk_bf16_f32 v16, v16, v17
	v_cvt_pk_bf16_f32 v17, v18, v19
	v_cvt_pk_bf16_f32 v18, v56, v57
	v_cvt_pk_bf16_f32 v56, v78, v79
	v_add_co_u32_e32 v78, vcc, s0, v94
	s_mov_b32 s0, 0x1ddc000
	s_nop 0
	v_addc_co_u32_e32 v79, vcc, 0, v95, vcc
	v_cvt_pk_bf16_f32 v32, v8, v9
	v_cvt_pk_bf16_f32 v8, v60, v61
	v_cvt_pk_bf16_f32 v60, v82, v83
	v_add_co_u32_e32 v82, vcc, s0, v94
	v_cvt_pk_bf16_f32 v23, v66, v67
	s_nop 0
	s_nop 0
	v_addc_co_u32_e32 v83, vcc, 0, v95, vcc
	s_mov_b32 s0, 0x1dde000
	v_cvt_pk_bf16_f32 v19, v58, v59
	v_cvt_pk_bf16_f32 v3, v70, v71
	v_cvt_pk_bf16_f32 v58, v86, v87
	s_nop 0
	s_nop 0
	v_add_co_u32_e32 v86, vcc, s0, v94
	v_cvt_pk_bf16_f32 v11, v74, v75
	s_nop 0
	s_nop 0
	v_addc_co_u32_e32 v87, vcc, 0, v95, vcc
	s_mov_b32 s0, 0x1de0000
	v_cvt_pk_bf16_f32 v9, v62, v63
	v_cvt_pk_bf16_f32 v57, v80, v81
	v_cvt_pk_bf16_f32 v62, v90, v91
	s_nop 0
	s_nop 0
	v_add_co_u32_e32 v90, vcc, s0, v94
	v_cvt_pk_bf16_f32 v61, v84, v85
	s_nop 0
	s_nop 0
	v_addc_co_u32_e32 v91, vcc, 0, v95, vcc
	s_mov_b32 s0, 0x1de2000
	v_cvt_pk_bf16_f32 v59, v88, v89
	s_nop 0
	s_nop 0
	v_add_co_u32_e32 v94, vcc, s0, v94
	v_cvt_pk_bf16_f32 v63, v92, v93
	s_nop 0
	s_nop 0
	v_addc_co_u32_e32 v95, vcc, 0, v95, vcc
	v_cvt_pk_bf16_f32 v41, v96, v97
	s_nop 0
	s_nop 0
	v_lshl_add_u32 v98, v98, 4, 0
	v_readlane_b32 s0, v253, 51
	s_waitcnt vmcnt(0)
; #define LAS __attribute__((address_space(3)))
; #define GAS __attribute__((address_space(1)))
; __device__ __forceinline__ void b_unit(Frame& F, int u, bool dry) {
;     ...
;     {   const GAS u32x4* src = (const GAS u32x4*)(ws_ + WS_GT) + (w * 64 + lane); u32x4 tv[8];
; #pragma unroll
;         for (int i = 0; i < 8; ++i) tv[i] = src[i * 512];
; #pragma unroll
;         for (int i = 0; i < 8; ++i) *(LAS u32x4*)(Bt + (size_t)(i * 512 + w * 64 + lane) * 16) = tv[i]; }
;     u32x4 sbq[4][2];
; #pragma unroll
;     for (int p = 0; p < 4; ++p)
; #pragma unroll
;         for (int mb = 0; mb < 2; ++mb) { const int k1 = 2 * w + mb + 16 * fr; const size_t tok = (size_t)b * SEQ + 8 * k1 + k2; sbq[p][mb] = *(const GAS u32x4*)(SBG + tok * 512 + g * 128 + 32 * p + 8 * fq); }
;     __syncthreads();
;     const LAS unsigned char* XF = Bt + (size_t)(fq * 16 + fr) * 16;
; #pragma unroll
;     for (int p = 0; p < 4; ++p) {
;         f32x4 o3[2][2];
; #pragma unroll
;         for (int h = 0; h < 2; ++h) { const int lb = 2 * p + h;
;             o3[h][0] = (f32x4){0.f, 0.f, 0.f, 0.f}; o3[h][1] = (f32x4){0.f, 0.f, 0.f, 0.f};
; #pragma unroll
;             for (int t = 0; t < 4; ++t) {
;                 const bf16x8 xc = *(const LAS bf16x8*)(XF + (size_t)((lb * 4 + t) * 2 + 0) * 1024), xs = *(const LAS bf16x8*)(XF + (size_t)((lb * 4 + t) * 2 + 1) * 1024);
; #pragma unroll
;                 for (int mb = 0; mb < 2; ++mb) { o3[h][mb] = __builtin_amdgcn_mfma_f32_16x16x32_bf16(xc, yr[mb][t], o3[h][mb], 0, 0, 0); o3[h][mb] = __builtin_amdgcn_mfma_f32_16x16x32_bf16(xs, yi[mb][t], o3[h][mb], 0, 0, 0); }
;             }
;         }
	ds_write_b128 v98, v[196:199]
	s_nop 0
	ds_write_b128 v98, v[200:203] offset:8192
	s_nop 0
	ds_write_b128 v98, v[204:207] offset:16384
	s_nop 0
	ds_write_b128 v98, v[208:211] offset:24576
	s_nop 0
	ds_write_b128 v98, v[212:215] offset:32768
	s_nop 0
	ds_write_b128 v98, v[216:219] offset:40960
	s_nop 0
	ds_write_b128 v98, v[220:223] offset:49152
	s_nop 0
	ds_write_b128 v98, v[224:227] offset:57344
	v_lshl_add_u32 v64, v77, 7, s0
	v_readlane_b32 s0, v254, 31
	s_add_u32 s0, s2, s0
	s_addc_u32 s1, s3, 0
	v_lshl_add_u64 v[66:67], s[0:1], 0, v[192:193]
	s_mov_b64 s[0:1], 0xa000000
	v_lshl_add_u64 v[66:67], v[66:67], 0, s[0:1]
	v_readlane_b32 s0, v254, 21
	v_mov_b32_e32 v65, v193
	v_readlane_b32 s1, v254, 22
	v_or_b32_e32 v192, 8, v64
	v_cvt_pk_bf16_f32 v45, v100, v101
	v_lshl_add_u64 v[68:69], s[0:1], 0, v[64:65]
	v_lshlrev_b64 v[68:69], 10, v[68:69]
	v_lshl_add_u64 v[98:99], v[66:67], 0, v[68:69]
	global_load_dwordx4 v[92:95], v[98:99], off sc1
	v_lshl_add_u64 v[64:65], s[0:1], 0, v[192:193]
	v_lshlrev_b32_e32 v100, 4, v170
	v_lshlrev_b64 v[64:65], 10, v[64:65]
	v_and_b32_e32 v100, 0x3f0, v100
	v_lshl_add_u64 v[96:97], v[66:67], 0, v[64:65]
	v_add_u32_e32 v100, 0, v100
	v_cvt_pk_bf16_f32 v21, v46, v47
	v_cvt_pk_bf16_f32 v1, v42, v43
	v_cvt_pk_bf16_f32 v42, v102, v103
	v_cvt_pk_bf16_f32 v43, v104, v105
	v_cvt_pk_bf16_f32 v46, v106, v107
	v_cvt_pk_bf16_f32 v47, v108, v109
	global_load_dwordx4 v[88:91], v[96:97], off sc1
	global_load_dwordx4 v[84:87], v[98:99], off offset:64 sc1
	global_load_dwordx4 v[80:83], v[96:97], off offset:64 sc1
	global_load_dwordx4 v[76:79], v[98:99], off offset:128 sc1
	global_load_dwordx4 v[72:75], v[96:97], off offset:128 sc1
	global_load_dwordx4 v[68:71], v[98:99], off offset:192 sc1
	global_load_dwordx4 v[64:67], v[96:97], off offset:192 sc1
	s_waitcnt lgkmcnt(0)
	s_barrier
	ds_read_b128 v[102:105], v100
	ds_read_b128 v[106:109], v100 offset:1024
	v_cvt_pk_bf16_f32 v52, v36, v37
	v_cvt_pk_bf16_f32 v55, v50, v51
	v_cvt_pk_bf16_f32 v50, v24, v25
	v_cvt_pk_bf16_f32 v24, v110, v111
	v_cvt_pk_bf16_f32 v25, v112, v113
	s_waitcnt lgkmcnt(1)
	v_mfma_f32_16x16x32_bf16 v[110:113], v[102:105], v[52:55], 0
	v_cvt_pk_bf16_f32 v51, v26, v27
	v_cvt_pk_bf16_f32 v36, v28, v29
	v_cvt_pk_bf16_f32 v28, v114, v115
	v_mfma_f32_16x16x32_bf16 v[102:105], v[102:105], v[56:59], 0
	v_cvt_pk_bf16_f32 v29, v116, v117
	v_cvt_pk_bf16_f32 v37, v30, v31
	v_cvt_pk_bf16_f32 v39, v34, v35
	s_waitcnt lgkmcnt(0)
	v_mfma_f32_16x16x32_bf16 v[110:113], v[106:109], v[48:51], v[110:113]
	v_cvt_pk_bf16_f32 v26, v118, v119
	v_cvt_pk_bf16_f32 v27, v120, v121
	v_cvt_pk_bf16_f32 v30, v122, v123
	v_mfma_f32_16x16x32_bf16 v[102:105], v[106:109], v[60:63], v[102:105]
	ds_read_b128 v[106:109], v100 offset:2048
	ds_read_b128 v[114:117], v100 offset:3072
	v_cvt_pk_bf16_f32 v31, v124, v125
	s_mov_b32 s0, 0x3b000000
	v_mfma_f32_16x16x32_bf16 v[12:15], v[12:15], v[4:7], 0
	v_cvt_pk_bf16_f32 v4, v130, v131
	v_cvt_pk_bf16_f32 v5, v132, v133
	v_cvt_pk_bf16_f32 v6, v138, v139
	s_waitcnt lgkmcnt(1)
	v_mfma_f32_16x16x32_bf16 v[110:113], v[106:109], v[36:39], v[110:113]
	v_cvt_pk_bf16_f32 v7, v140, v141
	s_nop 1
	v_cvt_pk_bf16_f32 v34, v12, v13
	v_cvt_pk_bf16_f32 v35, v14, v15
	v_mfma_f32_16x16x32_bf16 v[102:105], v[106:109], v[40:43], v[102:105]
	v_cvt_pk_bf16_f32 v12, v126, v127
	v_cvt_pk_bf16_f32 v13, v128, v129
	v_cvt_pk_bf16_f32 v14, v134, v135
	s_waitcnt lgkmcnt(0)
	v_mfma_f32_16x16x32_bf16 v[110:113], v[114:117], v[32:35], v[110:113]
	v_cvt_pk_bf16_f32 v15, v136, v137
	v_mfma_f32_16x16x32_bf16 v[102:105], v[114:117], v[44:47], v[102:105]
	ds_read_b128 v[106:109], v100 offset:4096
	ds_read_b128 v[114:117], v100 offset:5120
	s_waitcnt lgkmcnt(1)
	v_mfma_f32_16x16x32_bf16 v[110:113], v[106:109], v[20:23], v[110:113]
	v_mfma_f32_16x16x32_bf16 v[102:105], v[106:109], v[24:27], v[102:105]
	s_waitcnt lgkmcnt(0)
	v_mfma_f32_16x16x32_bf16 v[110:113], v[114:117], v[16:19], v[110:113]
	v_mfma_f32_16x16x32_bf16 v[102:105], v[114:117], v[28:31], v[102:105]
	ds_read_b128 v[106:109], v100 offset:6144
	ds_read_b128 v[114:117], v100 offset:7168
	s_waitcnt lgkmcnt(1)
	v_mfma_f32_16x16x32_bf16 v[110:113], v[106:109], v[8:11], v[110:113]
	v_mfma_f32_16x16x32_bf16 v[102:105], v[106:109], v[12:15], v[102:105]
	s_waitcnt lgkmcnt(0)
	v_mfma_f32_16x16x32_bf16 v[110:113], v[114:117], v[0:3], v[110:113]
	v_mfma_f32_16x16x32_bf16 v[102:105], v[114:117], v[4:7], v[102:105]
	ds_read_b128 v[106:109], v100 offset:8192
	ds_read_b128 v[114:117], v100 offset:9216
	s_nop 4
	v_pk_mul_f32 v[110:111], v[110:111], s[0:1] op_sel_hi:[1,0]
	v_pk_mul_f32 v[112:113], v[112:113], s[0:1] op_sel_hi:[1,0]
	s_waitcnt lgkmcnt(1)
	v_mfma_f32_16x16x32_bf16 v[118:121], v[106:109], v[52:55], 0
	v_mfma_f32_16x16x32_bf16 v[106:109], v[106:109], v[56:59], 0
	s_waitcnt lgkmcnt(0)
	v_mfma_f32_16x16x32_bf16 v[118:121], v[114:117], v[48:51], v[118:121]
	v_mfma_f32_16x16x32_bf16 v[106:109], v[114:117], v[60:63], v[106:109]
	ds_read_b128 v[114:117], v100 offset:10240
	ds_read_b128 v[122:125], v100 offset:11264
	s_waitcnt lgkmcnt(1)
	v_mfma_f32_16x16x32_bf16 v[118:121], v[114:117], v[36:39], v[118:121]
	v_mfma_f32_16x16x32_bf16 v[106:109], v[114:117], v[40:43], v[106:109]
	s_waitcnt lgkmcnt(0)
	v_mfma_f32_16x16x32_bf16 v[118:121], v[122:125], v[32:35], v[118:121]
	v_mfma_f32_16x16x32_bf16 v[106:109], v[122:125], v[44:47], v[106:109]
	ds_read_b128 v[114:117], v100 offset:12288
	ds_read_b128 v[122:125], v100 offset:13312
	s_waitcnt lgkmcnt(1)
	v_mfma_f32_16x16x32_bf16 v[118:121], v[114:117], v[20:23], v[118:121]
	v_mfma_f32_16x16x32_bf16 v[106:109], v[114:117], v[24:27], v[106:109]
	s_waitcnt lgkmcnt(0)
; #define LAS __attribute__((address_space(3)))
; #define GAS __attribute__((address_space(1)))
; __device__ __forceinline__ unsigned cvtpk(float lo, float hi) { f32x2 v = {lo, hi}; bf16x2_t b = __builtin_convertvector(v, bf16x2_t); return __builtin_bit_cast(unsigned, b); }
; __device__ __forceinline__ float bflo(unsigned w) { return __uint_as_float(w << 16); }
; __device__ __forceinline__ float bfhi(unsigned w) { return __uint_as_float(w & 0xffff0000u); }
; __device__ __forceinline__ void b_unit(Frame& F, int u, bool dry) {
;     ...
;     for (int p = 0; p < 4; ++p) {
;         f32x4 o3[2][2];
; #pragma unroll
;         for (int h = 0; h < 2; ++h) { const int lb = 2 * p + h;
;             o3[h][0] = (f32x4){0.f, 0.f, 0.f, 0.f}; o3[h][1] = (f32x4){0.f, 0.f, 0.f, 0.f};
; #pragma unroll
;             for (int t = 0; t < 4; ++t) {
;                 const bf16x8 xc = *(const LAS bf16x8*)(XF + (size_t)((lb * 4 + t) * 2 + 0) * 1024), xs = *(const LAS bf16x8*)(XF + (size_t)((lb * 4 + t) * 2 + 1) * 1024);
; #pragma unroll
;                 for (int mb = 0; mb < 2; ++mb) { o3[h][mb] = __builtin_amdgcn_mfma_f32_16x16x32_bf16(xc, yr[mb][t], o3[h][mb], 0, 0, 0); o3[h][mb] = __builtin_amdgcn_mfma_f32_16x16x32_bf16(xs, yi[mb][t], o3[h][mb], 0, 0, 0); }
;             }
;         }
; #pragma unroll
;         for (int mb = 0; mb < 2; ++mb) { const int k1 = 2 * w + mb + 16 * fr; const size_t tok = (size_t)b * SEQ + 8 * k1 + k2; const u32x4 sb = sbq[p][mb]; const f32x4 a0 = o3[0][mb] * 0.001953125f, a1 = o3[1][mb] * 0.001953125f;
;             u32x4 o; o.x = cvtpk(bflo(sb.x) * a0[0], bfhi(sb.x) * a0[1]); o.y = cvtpk(bflo(sb.y) * a0[2], bfhi(sb.y) * a0[3]); o.z = cvtpk(bflo(sb.z) * a1[0], bfhi(sb.z) * a1[1]); o.w = cvtpk(bflo(sb.w) * a1[2], bfhi(sb.w) * a1[3]);
;             if (!dry) *(GAS u32x4*)(SBG + tok * 512 + g * 128 + 32 * p + 8 * fq) = o; }
	v_mfma_f32_16x16x32_bf16 v[118:121], v[122:125], v[16:19], v[118:121]
	v_mfma_f32_16x16x32_bf16 v[106:109], v[122:125], v[28:31], v[106:109]
	ds_read_b128 v[114:117], v100 offset:14336
	ds_read_b128 v[122:125], v100 offset:15360
	s_waitcnt lgkmcnt(1)
	v_mfma_f32_16x16x32_bf16 v[118:121], v[114:117], v[8:11], v[118:121]
	s_waitcnt lgkmcnt(0)
	v_mfma_f32_16x16x32_bf16 v[118:121], v[122:125], v[0:3], v[118:121]
	v_mfma_f32_16x16x32_bf16 v[106:109], v[114:117], v[12:15], v[106:109]
	v_mfma_f32_16x16x32_bf16 v[106:109], v[122:125], v[4:7], v[106:109]
	s_nop 5
	v_mul_f32_e64 v116, v118, s0
	v_mul_f32_e64 v117, v119, s0
	s_waitcnt vmcnt(7)
	v_lshlrev_b32_e32 v118, 16, v92
	v_and_b32_e32 v119, 0xffff0000, v92
	v_pk_mul_f32 v[110:111], v[110:111], v[118:119]
	v_pk_mul_f32 v[114:115], v[120:121], s[0:1] op_sel_hi:[1,0]
	v_cvt_pk_bf16_f32 v92, v110, v111
	v_lshlrev_b32_e32 v110, 16, v93
	v_and_b32_e32 v111, 0xffff0000, v93
	v_pk_mul_f32 v[110:111], v[112:113], v[110:111]
	s_nop 0
	v_cvt_pk_bf16_f32 v93, v110, v111
	v_lshlrev_b32_e32 v110, 16, v94
	v_and_b32_e32 v111, 0xffff0000, v94
	v_pk_mul_f32 v[110:111], v[116:117], v[110:111]
	s_nop 0
	v_cvt_pk_bf16_f32 v94, v110, v111
	v_lshlrev_b32_e32 v110, 16, v95
	v_and_b32_e32 v111, 0xffff0000, v95
	v_pk_mul_f32 v[110:111], v[114:115], v[110:111]
	s_nop 0
	v_cvt_pk_bf16_f32 v95, v110, v111
	global_store_dwordx4 v[98:99], v[92:95], off
	s_nop 1
	v_pk_mul_f32 v[92:93], v[104:105], s[0:1] op_sel_hi:[1,0]
	v_pk_mul_f32 v[94:95], v[102:103], s[0:1] op_sel_hi:[1,0]
	v_pk_mul_f32 v[104:105], v[106:107], s[0:1] op_sel_hi:[1,0]
	s_waitcnt vmcnt(7)
	v_lshlrev_b32_e32 v106, 16, v88
	v_and_b32_e32 v107, 0xffff0000, v88
	v_pk_mul_f32 v[94:95], v[94:95], v[106:107]
	v_pk_mul_f32 v[102:103], v[108:109], s[0:1] op_sel_hi:[1,0]
	v_cvt_pk_bf16_f32 v88, v94, v95
	v_lshlrev_b32_e32 v94, 16, v89
	v_and_b32_e32 v95, 0xffff0000, v89
	v_pk_mul_f32 v[92:93], v[92:93], v[94:95]
	s_nop 0
	v_cvt_pk_bf16_f32 v89, v92, v93
	v_lshlrev_b32_e32 v92, 16, v90
	v_and_b32_e32 v93, 0xffff0000, v90
	v_pk_mul_f32 v[92:93], v[104:105], v[92:93]
	s_nop 0
	v_cvt_pk_bf16_f32 v90, v92, v93
	v_lshlrev_b32_e32 v92, 16, v91
	v_and_b32_e32 v93, 0xffff0000, v91
	v_pk_mul_f32 v[92:93], v[102:103], v[92:93]
	s_nop 0
	v_cvt_pk_bf16_f32 v91, v92, v93
	global_store_dwordx4 v[96:97], v[88:91], off
	ds_read_b128 v[88:91], v100 offset:16384
	ds_read_b128 v[92:95], v100 offset:17408
	s_waitcnt lgkmcnt(1)
	v_mfma_f32_16x16x32_bf16 v[102:105], v[88:91], v[52:55], 0
	v_mfma_f32_16x16x32_bf16 v[88:91], v[88:91], v[56:59], 0
	s_waitcnt lgkmcnt(0)
	v_mfma_f32_16x16x32_bf16 v[102:105], v[92:95], v[48:51], v[102:105]
	v_mfma_f32_16x16x32_bf16 v[88:91], v[92:95], v[60:63], v[88:91]
	ds_read_b128 v[92:95], v100 offset:18432
	ds_read_b128 v[106:109], v100 offset:19456
	s_waitcnt lgkmcnt(1)
	v_mfma_f32_16x16x32_bf16 v[102:105], v[92:95], v[36:39], v[102:105]
	v_mfma_f32_16x16x32_bf16 v[88:91], v[92:95], v[40:43], v[88:91]
	s_waitcnt lgkmcnt(0)
	v_mfma_f32_16x16x32_bf16 v[102:105], v[106:109], v[32:35], v[102:105]
	v_mfma_f32_16x16x32_bf16 v[88:91], v[106:109], v[44:47], v[88:91]
	ds_read_b128 v[92:95], v100 offset:20480
	ds_read_b128 v[106:109], v100 offset:21504
	s_waitcnt lgkmcnt(1)
	v_mfma_f32_16x16x32_bf16 v[102:105], v[92:95], v[20:23], v[102:105]
	v_mfma_f32_16x16x32_bf16 v[88:91], v[92:95], v[24:27], v[88:91]
	s_waitcnt lgkmcnt(0)
	v_mfma_f32_16x16x32_bf16 v[102:105], v[106:109], v[16:19], v[102:105]
	v_mfma_f32_16x16x32_bf16 v[88:91], v[106:109], v[28:31], v[88:91]
	ds_read_b128 v[92:95], v100 offset:22528
	ds_read_b128 v[106:109], v100 offset:23552
	s_waitcnt lgkmcnt(1)
	v_mfma_f32_16x16x32_bf16 v[102:105], v[92:95], v[8:11], v[102:105]
	v_mfma_f32_16x16x32_bf16 v[88:91], v[92:95], v[12:15], v[88:91]
	s_waitcnt lgkmcnt(0)
	v_mfma_f32_16x16x32_bf16 v[102:105], v[106:109], v[0:3], v[102:105]
	v_mfma_f32_16x16x32_bf16 v[88:91], v[106:109], v[4:7], v[88:91]
	ds_read_b128 v[92:95], v100 offset:24576
	ds_read_b128 v[106:109], v100 offset:25600
	s_nop 4
	v_pk_mul_f32 v[102:103], v[102:103], s[0:1] op_sel_hi:[1,0]
	v_pk_mul_f32 v[104:105], v[104:105], s[0:1] op_sel_hi:[1,0]
	s_waitcnt lgkmcnt(1)
	v_mfma_f32_16x16x32_bf16 v[110:113], v[92:95], v[52:55], 0
	v_mfma_f32_16x16x32_bf16 v[92:95], v[92:95], v[56:59], 0
	s_waitcnt lgkmcnt(0)
	v_mfma_f32_16x16x32_bf16 v[110:113], v[106:109], v[48:51], v[110:113]
	v_mfma_f32_16x16x32_bf16 v[92:95], v[106:109], v[60:63], v[92:95]
	ds_read_b128 v[106:109], v100 offset:26624
	ds_read_b128 v[114:117], v100 offset:27648
	s_waitcnt lgkmcnt(1)
	v_mfma_f32_16x16x32_bf16 v[110:113], v[106:109], v[36:39], v[110:113]
	v_mfma_f32_16x16x32_bf16 v[92:95], v[106:109], v[40:43], v[92:95]
	s_waitcnt lgkmcnt(0)
	v_mfma_f32_16x16x32_bf16 v[110:113], v[114:117], v[32:35], v[110:113]
	v_mfma_f32_16x16x32_bf16 v[92:95], v[114:117], v[44:47], v[92:95]
	ds_read_b128 v[106:109], v100 offset:28672
	ds_read_b128 v[114:117], v100 offset:29696
	s_waitcnt lgkmcnt(1)
	v_mfma_f32_16x16x32_bf16 v[110:113], v[106:109], v[20:23], v[110:113]
	v_mfma_f32_16x16x32_bf16 v[92:95], v[106:109], v[24:27], v[92:95]
	s_waitcnt lgkmcnt(0)
	v_mfma_f32_16x16x32_bf16 v[110:113], v[114:117], v[16:19], v[110:113]
	v_mfma_f32_16x16x32_bf16 v[92:95], v[114:117], v[28:31], v[92:95]
	ds_read_b128 v[106:109], v100 offset:30720
	ds_read_b128 v[114:117], v100 offset:31744
	s_waitcnt lgkmcnt(1)
	v_mfma_f32_16x16x32_bf16 v[110:113], v[106:109], v[8:11], v[110:113]
	s_waitcnt lgkmcnt(0)
	v_mfma_f32_16x16x32_bf16 v[110:113], v[114:117], v[0:3], v[110:113]
	v_mfma_f32_16x16x32_bf16 v[92:95], v[106:109], v[12:15], v[92:95]
	v_mfma_f32_16x16x32_bf16 v[92:95], v[114:117], v[4:7], v[92:95]
	s_nop 5
	v_mul_f32_e64 v108, v110, s0
	v_mul_f32_e64 v109, v111, s0
	s_waitcnt vmcnt(7)
; #define LAS __attribute__((address_space(3)))
; #define GAS __attribute__((address_space(1)))
; __device__ __forceinline__ unsigned cvtpk(float lo, float hi) { f32x2 v = {lo, hi}; bf16x2_t b = __builtin_convertvector(v, bf16x2_t); return __builtin_bit_cast(unsigned, b); }
; __device__ __forceinline__ float bflo(unsigned w) { return __uint_as_float(w << 16); }
; __device__ __forceinline__ float bfhi(unsigned w) { return __uint_as_float(w & 0xffff0000u); }
; __device__ __forceinline__ void b_unit(Frame& F, int u, bool dry) {
;     ...
;     for (int p = 0; p < 4; ++p) {
;         f32x4 o3[2][2];
; #pragma unroll
;         for (int h = 0; h < 2; ++h) { const int lb = 2 * p + h;
;             o3[h][0] = (f32x4){0.f, 0.f, 0.f, 0.f}; o3[h][1] = (f32x4){0.f, 0.f, 0.f, 0.f};
; #pragma unroll
;             for (int t = 0; t < 4; ++t) {
;                 const bf16x8 xc = *(const LAS bf16x8*)(XF + (size_t)((lb * 4 + t) * 2 + 0) * 1024), xs = *(const LAS bf16x8*)(XF + (size_t)((lb * 4 + t) * 2 + 1) * 1024);
; #pragma unroll
;                 for (int mb = 0; mb < 2; ++mb) { o3[h][mb] = __builtin_amdgcn_mfma_f32_16x16x32_bf16(xc, yr[mb][t], o3[h][mb], 0, 0, 0); o3[h][mb] = __builtin_amdgcn_mfma_f32_16x16x32_bf16(xs, yi[mb][t], o3[h][mb], 0, 0, 0); }
;             }
;         }
; #pragma unroll
;         for (int mb = 0; mb < 2; ++mb) { const int k1 = 2 * w + mb + 16 * fr; const size_t tok = (size_t)b * SEQ + 8 * k1 + k2; const u32x4 sb = sbq[p][mb]; const f32x4 a0 = o3[0][mb] * 0.001953125f, a1 = o3[1][mb] * 0.001953125f;
;             u32x4 o; o.x = cvtpk(bflo(sb.x) * a0[0], bfhi(sb.x) * a0[1]); o.y = cvtpk(bflo(sb.y) * a0[2], bfhi(sb.y) * a0[3]); o.z = cvtpk(bflo(sb.z) * a1[0], bfhi(sb.z) * a1[1]); o.w = cvtpk(bflo(sb.w) * a1[2], bfhi(sb.w) * a1[3]);
;             if (!dry) *(GAS u32x4*)(SBG + tok * 512 + g * 128 + 32 * p + 8 * fq) = o; }
	v_lshlrev_b32_e32 v110, 16, v84
	v_and_b32_e32 v111, 0xffff0000, v84
	v_pk_mul_f32 v[102:103], v[102:103], v[110:111]
	v_pk_mul_f32 v[106:107], v[112:113], s[0:1] op_sel_hi:[1,0]
	v_cvt_pk_bf16_f32 v84, v102, v103
	v_lshlrev_b32_e32 v102, 16, v85
	v_and_b32_e32 v103, 0xffff0000, v85
	v_pk_mul_f32 v[102:103], v[104:105], v[102:103]
	s_nop 0
	v_cvt_pk_bf16_f32 v85, v102, v103
	v_lshlrev_b32_e32 v102, 16, v86
	v_and_b32_e32 v103, 0xffff0000, v86
	v_pk_mul_f32 v[102:103], v[108:109], v[102:103]
	s_nop 0
	v_cvt_pk_bf16_f32 v86, v102, v103
	v_lshlrev_b32_e32 v102, 16, v87
	v_and_b32_e32 v103, 0xffff0000, v87
	v_pk_mul_f32 v[102:103], v[106:107], v[102:103]
	s_nop 0
	v_cvt_pk_bf16_f32 v87, v102, v103
	global_store_dwordx4 v[98:99], v[84:87], off offset:64
	s_nop 1
	v_pk_mul_f32 v[84:85], v[90:91], s[0:1] op_sel_hi:[1,0]
	v_pk_mul_f32 v[86:87], v[88:89], s[0:1] op_sel_hi:[1,0]
	v_pk_mul_f32 v[90:91], v[92:93], s[0:1] op_sel_hi:[1,0]
	s_waitcnt vmcnt(7)
	v_lshlrev_b32_e32 v92, 16, v80
	v_and_b32_e32 v93, 0xffff0000, v80
	v_pk_mul_f32 v[86:87], v[86:87], v[92:93]
	v_pk_mul_f32 v[88:89], v[94:95], s[0:1] op_sel_hi:[1,0]
	v_cvt_pk_bf16_f32 v80, v86, v87
	v_lshlrev_b32_e32 v86, 16, v81
	v_and_b32_e32 v87, 0xffff0000, v81
	v_pk_mul_f32 v[84:85], v[84:85], v[86:87]
	s_nop 0
	v_cvt_pk_bf16_f32 v81, v84, v85
	v_lshlrev_b32_e32 v84, 16, v82
	v_and_b32_e32 v85, 0xffff0000, v82
	v_pk_mul_f32 v[84:85], v[90:91], v[84:85]
	s_nop 0
	v_cvt_pk_bf16_f32 v82, v84, v85
	v_lshlrev_b32_e32 v84, 16, v83
	v_and_b32_e32 v85, 0xffff0000, v83
	v_pk_mul_f32 v[84:85], v[88:89], v[84:85]
	s_nop 0
	v_cvt_pk_bf16_f32 v83, v84, v85
	global_store_dwordx4 v[96:97], v[80:83], off offset:64
	ds_read_b128 v[80:83], v100 offset:32768
	ds_read_b128 v[84:87], v100 offset:33792
	s_waitcnt lgkmcnt(1)
	v_mfma_f32_16x16x32_bf16 v[88:91], v[80:83], v[52:55], 0
	v_mfma_f32_16x16x32_bf16 v[80:83], v[80:83], v[56:59], 0
	s_waitcnt lgkmcnt(0)
	v_mfma_f32_16x16x32_bf16 v[88:91], v[84:87], v[48:51], v[88:91]
	v_mfma_f32_16x16x32_bf16 v[80:83], v[84:87], v[60:63], v[80:83]
	ds_read_b128 v[84:87], v100 offset:34816
	ds_read_b128 v[92:95], v100 offset:35840
	s_waitcnt lgkmcnt(1)
	v_mfma_f32_16x16x32_bf16 v[88:91], v[84:87], v[36:39], v[88:91]
	v_mfma_f32_16x16x32_bf16 v[80:83], v[84:87], v[40:43], v[80:83]
	s_waitcnt lgkmcnt(0)
	v_mfma_f32_16x16x32_bf16 v[88:91], v[92:95], v[32:35], v[88:91]
	v_mfma_f32_16x16x32_bf16 v[80:83], v[92:95], v[44:47], v[80:83]
	ds_read_b128 v[84:87], v100 offset:36864
	ds_read_b128 v[92:95], v100 offset:37888
	s_waitcnt lgkmcnt(1)
	v_mfma_f32_16x16x32_bf16 v[88:91], v[84:87], v[20:23], v[88:91]
	v_mfma_f32_16x16x32_bf16 v[80:83], v[84:87], v[24:27], v[80:83]
	s_waitcnt lgkmcnt(0)
	v_mfma_f32_16x16x32_bf16 v[88:91], v[92:95], v[16:19], v[88:91]
	v_mfma_f32_16x16x32_bf16 v[80:83], v[92:95], v[28:31], v[80:83]
	ds_read_b128 v[92:95], v100 offset:38912
	ds_read_b128 v[102:105], v100 offset:39936
	s_waitcnt lgkmcnt(1)
	v_mfma_f32_16x16x32_bf16 v[84:87], v[92:95], v[8:11], v[88:91]
	v_mfma_f32_16x16x32_bf16 v[80:83], v[92:95], v[12:15], v[80:83]
	s_nop 1
	ds_read_b128 v[88:91], v100 offset:40960
	ds_read_b128 v[92:95], v100 offset:41984
	s_waitcnt lgkmcnt(2)
	v_mfma_f32_16x16x32_bf16 v[84:87], v[102:105], v[0:3], v[84:87]
	v_mfma_f32_16x16x32_bf16 v[80:83], v[102:105], v[4:7], v[80:83]
	s_waitcnt lgkmcnt(1)
	v_mfma_f32_16x16x32_bf16 v[102:105], v[88:91], v[52:55], 0
	s_nop 4
	v_mul_f32_e64 v84, v84, s0
	v_mul_f32_e64 v85, v85, s0
	v_pk_mul_f32 v[86:87], v[86:87], s[0:1] op_sel_hi:[1,0]
	v_mfma_f32_16x16x32_bf16 v[88:91], v[88:91], v[56:59], 0
	s_waitcnt lgkmcnt(0)
	v_mfma_f32_16x16x32_bf16 v[102:105], v[92:95], v[48:51], v[102:105]
	v_mfma_f32_16x16x32_bf16 v[88:91], v[92:95], v[60:63], v[88:91]
	ds_read_b128 v[92:95], v100 offset:43008
	ds_read_b128 v[106:109], v100 offset:44032
	s_waitcnt lgkmcnt(1)
	v_mfma_f32_16x16x32_bf16 v[102:105], v[92:95], v[36:39], v[102:105]
	v_mfma_f32_16x16x32_bf16 v[88:91], v[92:95], v[40:43], v[88:91]
	s_waitcnt lgkmcnt(0)
	v_mfma_f32_16x16x32_bf16 v[102:105], v[106:109], v[32:35], v[102:105]
	v_mfma_f32_16x16x32_bf16 v[88:91], v[106:109], v[44:47], v[88:91]
	ds_read_b128 v[92:95], v100 offset:45056
	ds_read_b128 v[106:109], v100 offset:46080
	s_waitcnt lgkmcnt(1)
	v_mfma_f32_16x16x32_bf16 v[102:105], v[92:95], v[20:23], v[102:105]
	v_mfma_f32_16x16x32_bf16 v[88:91], v[92:95], v[24:27], v[88:91]
	s_waitcnt lgkmcnt(0)
	v_mfma_f32_16x16x32_bf16 v[102:105], v[106:109], v[16:19], v[102:105]
	v_mfma_f32_16x16x32_bf16 v[88:91], v[106:109], v[28:31], v[88:91]
	ds_read_b128 v[92:95], v100 offset:47104
	ds_read_b128 v[106:109], v100 offset:48128
	s_waitcnt lgkmcnt(1)
	v_mfma_f32_16x16x32_bf16 v[102:105], v[92:95], v[8:11], v[102:105]
	s_waitcnt lgkmcnt(0)
	v_mfma_f32_16x16x32_bf16 v[102:105], v[106:109], v[0:3], v[102:105]
	v_mfma_f32_16x16x32_bf16 v[88:91], v[92:95], v[12:15], v[88:91]
	v_mfma_f32_16x16x32_bf16 v[88:91], v[106:109], v[4:7], v[88:91]
	s_nop 5
	v_mul_f32_e64 v94, v102, s0
	v_mul_f32_e64 v95, v103, s0
	s_waitcnt vmcnt(7)
	v_lshlrev_b32_e32 v102, 16, v76
	v_and_b32_e32 v103, 0xffff0000, v76
	v_pk_mul_f32 v[84:85], v[84:85], v[102:103]
	v_pk_mul_f32 v[92:93], v[104:105], s[0:1] op_sel_hi:[1,0]
	v_cvt_pk_bf16_f32 v76, v84, v85
	v_lshlrev_b32_e32 v84, 16, v77
	v_and_b32_e32 v85, 0xffff0000, v77
	v_pk_mul_f32 v[84:85], v[86:87], v[84:85]
	s_nop 0
	v_cvt_pk_bf16_f32 v77, v84, v85
	v_lshlrev_b32_e32 v84, 16, v78
	v_and_b32_e32 v85, 0xffff0000, v78
	v_pk_mul_f32 v[84:85], v[94:95], v[84:85]
	s_nop 0
	v_cvt_pk_bf16_f32 v78, v84, v85
	v_lshlrev_b32_e32 v84, 16, v79
	v_and_b32_e32 v85, 0xffff0000, v79
	v_pk_mul_f32 v[84:85], v[92:93], v[84:85]
	s_nop 0
	v_cvt_pk_bf16_f32 v79, v84, v85
	global_store_dwordx4 v[98:99], v[76:79], off offset:128
	s_waitcnt vmcnt(7)
; #define LAS __attribute__((address_space(3)))
; #define GAS __attribute__((address_space(1)))
; __device__ __forceinline__ unsigned cvtpk(float lo, float hi) { f32x2 v = {lo, hi}; bf16x2_t b = __builtin_convertvector(v, bf16x2_t); return __builtin_bit_cast(unsigned, b); }
; __device__ __forceinline__ float bflo(unsigned w) { return __uint_as_float(w << 16); }
; __device__ __forceinline__ float bfhi(unsigned w) { return __uint_as_float(w & 0xffff0000u); }
; __device__ __forceinline__ void b_unit(Frame& F, int u, bool dry) {
;     ...
;     for (int p = 0; p < 4; ++p) {
;         f32x4 o3[2][2];
; #pragma unroll
;         for (int h = 0; h < 2; ++h) { const int lb = 2 * p + h;
;             o3[h][0] = (f32x4){0.f, 0.f, 0.f, 0.f}; o3[h][1] = (f32x4){0.f, 0.f, 0.f, 0.f};
; #pragma unroll
;             for (int t = 0; t < 4; ++t) {
;                 const bf16x8 xc = *(const LAS bf16x8*)(XF + (size_t)((lb * 4 + t) * 2 + 0) * 1024), xs = *(const LAS bf16x8*)(XF + (size_t)((lb * 4 + t) * 2 + 1) * 1024);
; #pragma unroll
;                 for (int mb = 0; mb < 2; ++mb) { o3[h][mb] = __builtin_amdgcn_mfma_f32_16x16x32_bf16(xc, yr[mb][t], o3[h][mb], 0, 0, 0); o3[h][mb] = __builtin_amdgcn_mfma_f32_16x16x32_bf16(xs, yi[mb][t], o3[h][mb], 0, 0, 0); }
;             }
;         }
; #pragma unroll
;         for (int mb = 0; mb < 2; ++mb) { const int k1 = 2 * w + mb + 16 * fr; const size_t tok = (size_t)b * SEQ + 8 * k1 + k2; const u32x4 sb = sbq[p][mb]; const f32x4 a0 = o3[0][mb] * 0.001953125f, a1 = o3[1][mb] * 0.001953125f;
;             u32x4 o; o.x = cvtpk(bflo(sb.x) * a0[0], bfhi(sb.x) * a0[1]); o.y = cvtpk(bflo(sb.y) * a0[2], bfhi(sb.y) * a0[3]); o.z = cvtpk(bflo(sb.z) * a1[0], bfhi(sb.z) * a1[1]); o.w = cvtpk(bflo(sb.w) * a1[2], bfhi(sb.w) * a1[3]);
;             if (!dry) *(GAS u32x4*)(SBG + tok * 512 + g * 128 + 32 * p + 8 * fq) = o; }
;     }
;     __syncthreads();
	v_lshlrev_b32_e32 v84, 16, v72
	v_and_b32_e32 v85, 0xffff0000, v72
	v_pk_mul_f32 v[78:79], v[80:81], s[0:1] op_sel_hi:[1,0]
	v_pk_mul_f32 v[76:77], v[82:83], s[0:1] op_sel_hi:[1,0]
	v_pk_mul_f32 v[78:79], v[78:79], v[84:85]
	v_pk_mul_f32 v[82:83], v[88:89], s[0:1] op_sel_hi:[1,0]
	v_cvt_pk_bf16_f32 v72, v78, v79
	v_lshlrev_b32_e32 v78, 16, v73
	v_and_b32_e32 v79, 0xffff0000, v73
	v_pk_mul_f32 v[76:77], v[76:77], v[78:79]
	v_pk_mul_f32 v[80:81], v[90:91], s[0:1] op_sel_hi:[1,0]
	v_cvt_pk_bf16_f32 v73, v76, v77
	v_lshlrev_b32_e32 v76, 16, v74
	v_and_b32_e32 v77, 0xffff0000, v74
	v_pk_mul_f32 v[76:77], v[82:83], v[76:77]
	s_nop 0
	v_cvt_pk_bf16_f32 v74, v76, v77
	v_lshlrev_b32_e32 v76, 16, v75
	v_and_b32_e32 v77, 0xffff0000, v75
	v_pk_mul_f32 v[76:77], v[80:81], v[76:77]
	s_nop 0
	v_cvt_pk_bf16_f32 v75, v76, v77
	global_store_dwordx4 v[96:97], v[72:75], off offset:128
	ds_read_b128 v[72:75], v100 offset:49152
	ds_read_b128 v[76:79], v100 offset:50176
	s_waitcnt lgkmcnt(1)
	v_mfma_f32_16x16x32_bf16 v[80:83], v[72:75], v[52:55], 0
	v_mfma_f32_16x16x32_bf16 v[72:75], v[72:75], v[56:59], 0
	s_waitcnt lgkmcnt(0)
	v_mfma_f32_16x16x32_bf16 v[80:83], v[76:79], v[48:51], v[80:83]
	v_mfma_f32_16x16x32_bf16 v[72:75], v[76:79], v[60:63], v[72:75]
	ds_read_b128 v[76:79], v100 offset:51200
	ds_read_b128 v[84:87], v100 offset:52224
	s_waitcnt lgkmcnt(1)
	v_mfma_f32_16x16x32_bf16 v[80:83], v[76:79], v[36:39], v[80:83]
	v_mfma_f32_16x16x32_bf16 v[72:75], v[76:79], v[40:43], v[72:75]
	s_waitcnt lgkmcnt(0)
	v_mfma_f32_16x16x32_bf16 v[80:83], v[84:87], v[32:35], v[80:83]
	v_mfma_f32_16x16x32_bf16 v[72:75], v[84:87], v[44:47], v[72:75]
	ds_read_b128 v[76:79], v100 offset:53248
	ds_read_b128 v[84:87], v100 offset:54272
	s_waitcnt lgkmcnt(1)
	v_mfma_f32_16x16x32_bf16 v[80:83], v[76:79], v[20:23], v[80:83]
	v_mfma_f32_16x16x32_bf16 v[72:75], v[76:79], v[24:27], v[72:75]
	s_waitcnt lgkmcnt(0)
	v_mfma_f32_16x16x32_bf16 v[80:83], v[84:87], v[16:19], v[80:83]
	v_mfma_f32_16x16x32_bf16 v[72:75], v[84:87], v[28:31], v[72:75]
	ds_read_b128 v[84:87], v100 offset:55296
	ds_read_b128 v[88:91], v100 offset:56320
	s_waitcnt lgkmcnt(1)
	v_mfma_f32_16x16x32_bf16 v[76:79], v[84:87], v[8:11], v[80:83]
	v_mfma_f32_16x16x32_bf16 v[72:75], v[84:87], v[12:15], v[72:75]
	s_nop 1
	ds_read_b128 v[80:83], v100 offset:57344
	ds_read_b128 v[84:87], v100 offset:58368
	s_waitcnt lgkmcnt(1)
	v_mfma_f32_16x16x32_bf16 v[52:55], v[80:83], v[52:55], 0
	s_waitcnt lgkmcnt(0)
	v_mfma_f32_16x16x32_bf16 v[48:51], v[84:87], v[48:51], v[52:55]
	v_mfma_f32_16x16x32_bf16 v[52:55], v[80:83], v[56:59], 0
	v_mfma_f32_16x16x32_bf16 v[52:55], v[84:87], v[60:63], v[52:55]
	ds_read_b128 v[56:59], v100 offset:59392
	ds_read_b128 v[60:63], v100 offset:60416
	s_waitcnt lgkmcnt(1)
	v_mfma_f32_16x16x32_bf16 v[36:39], v[56:59], v[36:39], v[48:51]
	s_waitcnt lgkmcnt(0)
	v_mfma_f32_16x16x32_bf16 v[32:35], v[60:63], v[32:35], v[36:39]
	v_mfma_f32_16x16x32_bf16 v[36:39], v[56:59], v[40:43], v[52:55]
	v_mfma_f32_16x16x32_bf16 v[36:39], v[60:63], v[44:47], v[36:39]
	ds_read_b128 v[40:43], v100 offset:61440
	ds_read_b128 v[44:47], v100 offset:62464
	v_mov_b32_e32 v53, v193
	s_waitcnt lgkmcnt(1)
	v_mfma_f32_16x16x32_bf16 v[20:23], v[40:43], v[20:23], v[32:35]
	s_waitcnt lgkmcnt(0)
	v_mfma_f32_16x16x32_bf16 v[16:19], v[44:47], v[16:19], v[20:23]
	v_mfma_f32_16x16x32_bf16 v[20:23], v[40:43], v[24:27], v[36:39]
	v_mfma_f32_16x16x32_bf16 v[20:23], v[44:47], v[28:31], v[20:23]
	ds_read_b128 v[24:27], v100 offset:63488
	ds_read_b128 v[28:31], v100 offset:64512
	s_waitcnt lgkmcnt(1)
	v_mfma_f32_16x16x32_bf16 v[8:11], v[24:27], v[8:11], v[16:19]
	v_mfma_f32_16x16x32_bf16 v[76:79], v[88:91], v[0:3], v[76:79]
	s_waitcnt lgkmcnt(0)
	v_mfma_f32_16x16x32_bf16 v[0:3], v[28:31], v[0:3], v[8:11]
	v_mfma_f32_16x16x32_bf16 v[8:11], v[24:27], v[12:15], v[20:23]
	v_mfma_f32_16x16x32_bf16 v[72:75], v[88:91], v[4:7], v[72:75]
	s_nop 5
	v_mul_f32_e64 v12, v2, s0
	v_mul_f32_e64 v13, v3, s0
	v_pk_mul_f32 v[2:3], v[0:1], s[0:1] op_sel_hi:[1,0]
	s_waitcnt vmcnt(7)
	v_lshlrev_b32_e32 v0, 16, v68
	v_mfma_f32_16x16x32_bf16 v[4:7], v[28:31], v[4:7], v[8:11]
	v_and_b32_e32 v1, 0xffff0000, v68
	s_nop 1
	v_pk_mul_f32 v[10:11], v[76:77], s[0:1] op_sel_hi:[1,0]
	v_pk_mul_f32 v[8:9], v[78:79], s[0:1] op_sel_hi:[1,0]
	v_pk_mul_f32 v[0:1], v[10:11], v[0:1]
	v_lshlrev_b32_e32 v10, 16, v69
	v_and_b32_e32 v11, 0xffff0000, v69
	v_pk_mul_f32 v[8:9], v[8:9], v[10:11]
	v_cvt_pk_bf16_f32 v0, v0, v1
	v_cvt_pk_bf16_f32 v1, v8, v9
	v_lshlrev_b32_e32 v8, 16, v70
	v_and_b32_e32 v9, 0xffff0000, v70
	v_pk_mul_f32 v[2:3], v[2:3], v[8:9]
	v_lshlrev_b32_e32 v8, 16, v71
	v_and_b32_e32 v9, 0xffff0000, v71
	v_pk_mul_f32 v[8:9], v[12:13], v[8:9]
	v_cvt_pk_bf16_f32 v2, v2, v3
	v_cvt_pk_bf16_f32 v3, v8, v9
	global_store_dwordx4 v[98:99], v[0:3], off offset:192
	s_waitcnt vmcnt(7)
	v_lshlrev_b32_e32 v8, 16, v64
	v_and_b32_e32 v9, 0xffff0000, v64
	v_pk_mul_f32 v[0:1], v[72:73], s[0:1] op_sel_hi:[1,0]
	v_pk_mul_f32 v[2:3], v[74:75], s[0:1] op_sel_hi:[1,0]
	v_pk_mul_f32 v[0:1], v[0:1], v[8:9]
	v_lshlrev_b32_e32 v8, 16, v65
	v_and_b32_e32 v9, 0xffff0000, v65
	v_pk_mul_f32 v[2:3], v[2:3], v[8:9]
	v_pk_mul_f32 v[4:5], v[4:5], s[0:1] op_sel_hi:[1,0]
	v_cvt_pk_bf16_f32 v0, v0, v1
	v_cvt_pk_bf16_f32 v1, v2, v3
	v_lshlrev_b32_e32 v2, 16, v66
	v_and_b32_e32 v3, 0xffff0000, v66
	v_pk_mul_f32 v[6:7], v[6:7], s[0:1] op_sel_hi:[1,0]
	v_pk_mul_f32 v[2:3], v[4:5], v[2:3]
	v_lshlrev_b32_e32 v4, 16, v67
	v_and_b32_e32 v5, 0xffff0000, v67
	v_pk_mul_f32 v[4:5], v[6:7], v[4:5]
	v_cvt_pk_bf16_f32 v2, v2, v3
	v_cvt_pk_bf16_f32 v3, v4, v5
	v_readlane_b32 s0, v253, 55
	global_store_dwordx4 v[96:97], v[0:3], off offset:192
	s_barrier
; #define LAS __attribute__((address_space(3)))
; #define GAS __attribute__((address_space(1)))
; __device__ __forceinline__ int otid(int wave) { return wave * 64 + olane(); }
; __device__ __forceinline__ float bflo(unsigned w) { return __uint_as_float(w << 16); }
; __device__ __forceinline__ float bfhi(unsigned w) { return __uint_as_float(w & 0xffff0000u); }
; __device__ __forceinline__ void a_unit(Frame& F, int L, int u, bool dry) {
;     ...
;     const int w = F.wave, lane = otid(F.wave) & 63, tg = lane & 15, cr = lane >> 4, fr = lane & 15, fq = lane >> 4;
;     const bf16_t* gvt = (const bf16_t*)(ws_ + WS_GVT) + (size_t)((b * 16 + chunk) * 512) * 128;
;     LAS unsigned char* VT = F.lds + w * 17408;
;     LAS float* part = (LAS float*)(F.lds + 139264);
;     const bf16_t* Wh = (const bf16_t*)(ws_ + WS_AWS) + (size_t)((L * 8 + w) * 2 + qh) * 8192 + (size_t)lane * 8;
;     float s[8], q[8];
; #pragma unroll
;     for (int j = 0; j < 8; ++j) { s[j] = 0.f; q[j] = 0.f; }
;     u32x4 raw[16];
;     {
; #pragma unroll
;         for (int i = 0; i < 16; ++i) raw[i] = *(const GAS u32x4*)(gvt + (size_t)(64 * w + 4 * i + cr) * 128 + 8 * tg);
; #pragma unroll
;         for (int i = 0; i < 16; ++i)
; #pragma unroll
;             for (int jj = 0; jj < 4; ++jj) { const float lo = bflo(raw[i][jj]), hi = bfhi(raw[i][jj]); s[2 * jj] += lo; q[2 * jj] = fmaf(lo, lo, q[2 * jj]); s[2 * jj + 1] += hi; q[2 * jj + 1] = fmaf(hi, hi, q[2 * jj + 1]); }
	v_mbcnt_lo_u32_b32 v176, -1, 0
	v_mbcnt_hi_u32_b32 v176, -1, v176
	v_readlane_b32 s1, v253, 56
	v_bfe_u32 v173, v176, 4, 2
	v_and_b32_e32 v190, 15, v176
	s_add_u32 s0, s28, s0
	s_addc_u32 s1, s29, s1
	v_or_b32_e32 v0, s70, v173
	v_lshlrev_b32_e32 v52, 4, v190
	v_lshl_add_u64 v[2:3], s[0:1], 0, v[52:53]
	s_mov_b64 s[0:1], 0x6000000
	v_ashrrev_i32_e32 v1, 31, v0
	v_lshl_add_u64 v[2:3], v[2:3], 0, s[0:1]
	v_lshlrev_b64 v[4:5], 8, v[0:1]
	v_lshl_add_u64 v[4:5], v[2:3], 0, v[4:5]
	global_load_dwordx4 v[56:59], v[4:5], off sc1
	v_or_b32_e32 v4, 4, v0
	v_ashrrev_i32_e32 v5, 31, v4
	v_lshlrev_b64 v[4:5], 8, v[4:5]
	v_lshl_add_u64 v[4:5], v[2:3], 0, v[4:5]
	global_load_dwordx4 v[60:63], v[4:5], off sc1
	v_or_b32_e32 v4, 8, v0
	v_ashrrev_i32_e32 v5, 31, v4
	v_lshlrev_b64 v[4:5], 8, v[4:5]
	v_lshl_add_u64 v[4:5], v[2:3], 0, v[4:5]
	global_load_dwordx4 v[70:73], v[4:5], off sc1
	v_or_b32_e32 v4, 12, v0
	v_ashrrev_i32_e32 v5, 31, v4
	v_lshlrev_b64 v[4:5], 8, v[4:5]
	v_lshl_add_u64 v[4:5], v[2:3], 0, v[4:5]
	global_load_dwordx4 v[48:51], v[4:5], off sc1
	v_or_b32_e32 v4, 16, v0
	v_ashrrev_i32_e32 v5, 31, v4
	v_lshlrev_b64 v[4:5], 8, v[4:5]
	v_lshl_add_u64 v[4:5], v[2:3], 0, v[4:5]
	global_load_dwordx4 v[44:47], v[4:5], off sc1
	v_or_b32_e32 v4, 20, v0
	v_ashrrev_i32_e32 v5, 31, v4
	v_lshlrev_b64 v[4:5], 8, v[4:5]
	v_lshl_add_u64 v[4:5], v[2:3], 0, v[4:5]
	global_load_dwordx4 v[40:43], v[4:5], off sc1
	v_or_b32_e32 v4, 24, v0
	v_ashrrev_i32_e32 v5, 31, v4
	v_lshlrev_b64 v[4:5], 8, v[4:5]
	v_lshl_add_u64 v[4:5], v[2:3], 0, v[4:5]
	global_load_dwordx4 v[36:39], v[4:5], off sc1
	v_or_b32_e32 v4, 28, v0
	v_ashrrev_i32_e32 v5, 31, v4
	v_lshlrev_b64 v[4:5], 8, v[4:5]
	v_lshl_add_u64 v[4:5], v[2:3], 0, v[4:5]
	global_load_dwordx4 v[32:35], v[4:5], off sc1
	v_or_b32_e32 v4, 32, v0
	v_ashrrev_i32_e32 v5, 31, v4
	v_lshlrev_b64 v[4:5], 8, v[4:5]
	v_lshl_add_u64 v[4:5], v[2:3], 0, v[4:5]
	global_load_dwordx4 v[28:31], v[4:5], off sc1
	v_or_b32_e32 v4, 36, v0
	v_ashrrev_i32_e32 v5, 31, v4
	v_lshlrev_b64 v[4:5], 8, v[4:5]
	v_lshl_add_u64 v[4:5], v[2:3], 0, v[4:5]
	global_load_dwordx4 v[24:27], v[4:5], off sc1
	v_or_b32_e32 v4, 40, v0
	v_ashrrev_i32_e32 v5, 31, v4
	v_lshlrev_b64 v[4:5], 8, v[4:5]
	v_lshl_add_u64 v[4:5], v[2:3], 0, v[4:5]
	global_load_dwordx4 v[20:23], v[4:5], off sc1
	v_or_b32_e32 v4, 44, v0
	v_ashrrev_i32_e32 v5, 31, v4
	v_lshlrev_b64 v[4:5], 8, v[4:5]
	v_lshl_add_u64 v[4:5], v[2:3], 0, v[4:5]
	global_load_dwordx4 v[16:19], v[4:5], off sc1
	v_or_b32_e32 v4, 48, v0
	v_ashrrev_i32_e32 v5, 31, v4
	v_lshlrev_b64 v[4:5], 8, v[4:5]
	v_lshl_add_u64 v[4:5], v[2:3], 0, v[4:5]
	global_load_dwordx4 v[12:15], v[4:5], off sc1
	v_or_b32_e32 v4, 52, v0
	v_ashrrev_i32_e32 v5, 31, v4
	v_lshlrev_b64 v[4:5], 8, v[4:5]
	v_lshl_add_u64 v[4:5], v[2:3], 0, v[4:5]
	global_load_dwordx4 v[8:11], v[4:5], off sc1
	v_or_b32_e32 v4, 56, v0
	v_ashrrev_i32_e32 v5, 31, v4
	v_or_b32_e32 v0, 60, v0
	v_lshlrev_b64 v[4:5], 8, v[4:5]
	v_ashrrev_i32_e32 v1, 31, v0
	v_lshl_add_u64 v[4:5], v[2:3], 0, v[4:5]
	v_lshlrev_b64 v[0:1], 8, v[0:1]
	global_load_dwordx4 v[4:7], v[4:5], off sc1
	v_lshl_add_u64 v[0:1], v[2:3], 0, v[0:1]
	global_load_dwordx4 v[0:3], v[0:1], off sc1
	v_and_b32_e32 v162, 63, v176
	v_cmp_gt_u32_e32 vcc, 16, v162
	s_waitcnt vmcnt(15)
	v_lshlrev_b32_e32 v64, 16, v57
	v_lshlrev_b32_e32 v156, 16, v56
	v_and_b32_e32 v157, 0xffff0000, v56
	v_and_b32_e32 v65, 0xffff0000, v57
	v_add_f32_e32 v68, 0, v64
	v_lshlrev_b32_e32 v56, 16, v58
	s_waitcnt vmcnt(14)
	v_lshlrev_b32_e32 v54, 16, v60
	v_and_b32_e32 v55, 0xffff0000, v60
	v_lshlrev_b32_e32 v60, 16, v61
	v_add_f32_e32 v66, 0, v156
	v_add_f32_e32 v69, 0, v65
	v_and_b32_e32 v57, 0xffff0000, v58
	v_add_f32_e32 v74, 0, v56
	v_lshlrev_b32_e32 v58, 16, v59
	v_and_b32_e32 v61, 0xffff0000, v61
	v_add_f32_e32 v80, v68, v60
	v_lshlrev_b32_e32 v68, 16, v62
	v_add_f32_e32 v67, 0, v157
	v_add_f32_e32 v75, 0, v57
	v_add_f32_e32 v76, 0, v58
	v_add_f32_e32 v66, v66, v54
	v_add_f32_e32 v81, v69, v61
	v_and_b32_e32 v69, 0xffff0000, v62
	v_add_f32_e32 v62, v74, v68
	v_lshlrev_b32_e32 v74, 16, v63
	s_waitcnt vmcnt(13)
	v_lshlrev_b32_e32 v78, 16, v70
	v_and_b32_e32 v59, 0xffff0000, v59
	v_add_f32_e32 v67, v67, v55
	v_add_f32_e32 v84, v75, v69
	v_and_b32_e32 v75, 0xffff0000, v63
	v_add_f32_e32 v63, v76, v74
	v_and_b32_e32 v79, 0xffff0000, v70
	v_add_f32_e32 v66, v66, v78
	v_lshlrev_b32_e32 v82, 16, v71
	v_lshlrev_b32_e32 v90, 16, v72
	v_lshlrev_b32_e32 v98, 16, v73
	s_waitcnt vmcnt(12)
	v_lshlrev_b32_e32 v100, 16, v48
	v_add_f32_e32 v77, 0, v59
	v_add_f32_e32 v67, v67, v79
	v_and_b32_e32 v83, 0xffff0000, v71
	v_add_f32_e32 v70, v80, v82
	v_add_f32_e32 v62, v62, v90
	v_add_f32_e32 v63, v63, v98
	v_and_b32_e32 v101, 0xffff0000, v48
	v_add_f32_e32 v48, v66, v100
	v_lshlrev_b32_e32 v114, 16, v49
	v_lshlrev_b32_e32 v126, 16, v50
	v_lshlrev_b32_e32 v136, 16, v51
	s_waitcnt vmcnt(11)
	v_lshlrev_b32_e32 v130, 16, v44
	v_add_f32_e32 v76, v77, v75
	v_add_f32_e32 v71, v81, v83
	v_and_b32_e32 v91, 0xffff0000, v72
	v_and_b32_e32 v99, 0xffff0000, v73
	v_add_f32_e32 v66, v67, v101
	v_and_b32_e32 v115, 0xffff0000, v49
	v_add_f32_e32 v49, v70, v114
	v_and_b32_e32 v127, 0xffff0000, v50
	v_add_f32_e32 v50, v62, v126
	v_and_b32_e32 v137, 0xffff0000, v51
	v_add_f32_e32 v51, v63, v136
	v_and_b32_e32 v131, 0xffff0000, v44
	v_add_f32_e32 v44, v48, v130
	v_lshlrev_b32_e32 v138, 16, v45
	v_lshlrev_b32_e32 v144, 16, v46
	v_lshlrev_b32_e32 v118, 16, v47
	s_waitcnt vmcnt(10)
; __device__ __forceinline__ float bflo(unsigned w) { return __uint_as_float(w << 16); }
; __device__ __forceinline__ float bfhi(unsigned w) { return __uint_as_float(w & 0xffff0000u); }
; __device__ __forceinline__ void a_unit(Frame& F, int L, int u, bool dry) {
;     ...
;         for (int i = 0; i < 16; ++i)
; #pragma unroll
;             for (int jj = 0; jj < 4; ++jj) { const float lo = bflo(raw[i][jj]), hi = bfhi(raw[i][jj]); s[2 * jj] += lo; q[2 * jj] = fmaf(lo, lo, q[2 * jj]); s[2 * jj + 1] += hi; q[2 * jj + 1] = fmaf(hi, hi, q[2 * jj + 1]); }
	v_lshlrev_b32_e32 v120, 16, v40
	v_fma_f32 v158, v58, v58, 0
	v_add_f32_e32 v72, v84, v91
	v_add_f32_e32 v73, v76, v99
	v_add_f32_e32 v67, v71, v115
	v_add_f32_e32 v48, v66, v131
	v_and_b32_e32 v139, 0xffff0000, v45
	v_add_f32_e32 v45, v49, v138
	v_and_b32_e32 v145, 0xffff0000, v46
	v_add_f32_e32 v46, v50, v144
	v_and_b32_e32 v119, 0xffff0000, v47
	v_add_f32_e32 v47, v51, v118
	v_and_b32_e32 v121, 0xffff0000, v40
	v_add_f32_e32 v40, v44, v120
	v_lshlrev_b32_e32 v132, 16, v41
	v_lshlrev_b32_e32 v140, 16, v42
	v_lshlrev_b32_e32 v112, 16, v43
	s_waitcnt vmcnt(9)
	v_lshlrev_b32_e32 v116, 16, v36
	v_fma_f32 v165, v156, v156, 0
	v_fma_f32 v164, v157, v157, 0
	v_fma_f32 v163, v64, v64, 0
	v_fma_f32 v161, v65, v65, 0
	v_fma_f32 v160, v56, v56, 0
	v_fma_f32 v159, v57, v57, 0
	v_fmac_f32_e32 v158, v74, v74
	v_add_f32_e32 v62, v72, v127
	v_add_f32_e32 v63, v73, v137
	v_add_f32_e32 v49, v67, v139
	v_add_f32_e32 v44, v48, v121
	v_and_b32_e32 v133, 0xffff0000, v41
	v_add_f32_e32 v41, v45, v132
	v_and_b32_e32 v141, 0xffff0000, v42
	v_add_f32_e32 v42, v46, v140
	v_and_b32_e32 v113, 0xffff0000, v43
	v_add_f32_e32 v43, v47, v112
	v_and_b32_e32 v117, 0xffff0000, v36
	v_add_f32_e32 v36, v40, v116
	v_lshlrev_b32_e32 v128, 16, v37
	v_lshlrev_b32_e32 v96, 16, v38
	v_lshlrev_b32_e32 v108, 16, v39
	s_waitcnt vmcnt(8)
	v_lshlrev_b32_e32 v110, 16, v32
	v_fma_f32 v53, v59, v59, 0
	v_fmac_f32_e32 v165, v54, v54
	v_fmac_f32_e32 v164, v55, v55
	v_fmac_f32_e32 v163, v60, v60
	v_fmac_f32_e32 v161, v61, v61
	v_fmac_f32_e32 v160, v68, v68
	v_fmac_f32_e32 v159, v69, v69
	v_fmac_f32_e32 v158, v98, v98
	v_add_f32_e32 v50, v62, v145
	v_add_f32_e32 v51, v63, v119
	v_add_f32_e32 v45, v49, v133
	v_add_f32_e32 v40, v44, v117
	v_and_b32_e32 v129, 0xffff0000, v37
	v_add_f32_e32 v37, v41, v128
	v_and_b32_e32 v97, 0xffff0000, v38
	v_add_f32_e32 v38, v42, v96
	v_and_b32_e32 v109, 0xffff0000, v39
	v_add_f32_e32 v39, v43, v108
	v_and_b32_e32 v111, 0xffff0000, v32
	v_add_f32_e32 v32, v36, v110
	v_lshlrev_b32_e32 v86, 16, v33
	v_lshlrev_b32_e32 v92, 16, v34
	v_lshlrev_b32_e32 v104, 16, v35
	s_waitcnt vmcnt(7)
	v_lshlrev_b32_e32 v102, 16, v28
	v_fmac_f32_e32 v53, v75, v75
	v_fmac_f32_e32 v165, v78, v78
	v_fmac_f32_e32 v164, v79, v79
	v_fmac_f32_e32 v163, v82, v82
	v_fmac_f32_e32 v161, v83, v83
	v_fmac_f32_e32 v160, v90, v90
	v_fmac_f32_e32 v159, v91, v91
	v_fmac_f32_e32 v158, v136, v136
	v_add_f32_e32 v46, v50, v141
	v_add_f32_e32 v47, v51, v113
	v_add_f32_e32 v41, v45, v129
	v_add_f32_e32 v36, v40, v111
	v_and_b32_e32 v87, 0xffff0000, v33
	v_add_f32_e32 v33, v37, v86
	v_and_b32_e32 v93, 0xffff0000, v34
	v_add_f32_e32 v34, v38, v92
	v_and_b32_e32 v105, 0xffff0000, v35
	v_add_f32_e32 v35, v39, v104
	v_and_b32_e32 v103, 0xffff0000, v28
	v_add_f32_e32 v28, v32, v102
	v_lshlrev_b32_e32 v194, 16, v29
	v_lshlrev_b32_e32 v32, 16, v30
	v_lshlrev_b32_e32 v244, 16, v31
	v_fmac_f32_e32 v53, v99, v99
	v_fmac_f32_e32 v165, v100, v100
	v_fmac_f32_e32 v164, v101, v101
	v_fmac_f32_e32 v163, v114, v114
	v_fmac_f32_e32 v161, v115, v115
	v_fmac_f32_e32 v160, v126, v126
	v_fmac_f32_e32 v159, v127, v127
	v_fmac_f32_e32 v158, v118, v118
	v_add_f32_e32 v42, v46, v97
	v_add_f32_e32 v43, v47, v109
	v_add_f32_e32 v37, v41, v87
	v_add_f32_e32 v36, v36, v103
	v_and_b32_e32 v195, 0xffff0000, v29
	v_add_f32_e32 v29, v33, v194
	v_and_b32_e32 v33, 0xffff0000, v30
	v_add_f32_e32 v30, v34, v32
	v_and_b32_e32 v245, 0xffff0000, v31
	v_add_f32_e32 v31, v35, v244
	s_waitcnt vmcnt(6)
	v_lshlrev_b32_e32 v34, 16, v24
	v_and_b32_e32 v35, 0xffff0000, v24
	v_fmac_f32_e32 v53, v137, v137
	v_fmac_f32_e32 v165, v130, v130
	v_fmac_f32_e32 v164, v131, v131
	v_fmac_f32_e32 v163, v138, v138
	v_fmac_f32_e32 v161, v139, v139
	v_fmac_f32_e32 v160, v144, v144
	v_fmac_f32_e32 v159, v145, v145
	v_fmac_f32_e32 v158, v112, v112
	v_add_f32_e32 v38, v42, v93
	v_add_f32_e32 v39, v43, v105
	v_add_f32_e32 v40, v37, v195
	v_add_f32_e32 v24, v28, v34
	v_add_f32_e32 v28, v36, v35
	v_lshlrev_b32_e32 v36, 16, v25
	v_and_b32_e32 v37, 0xffff0000, v25
	v_fmac_f32_e32 v53, v119, v119
	v_fmac_f32_e32 v165, v120, v120
	v_fmac_f32_e32 v164, v121, v121
	v_fmac_f32_e32 v163, v132, v132
	v_fmac_f32_e32 v161, v133, v133
	v_fmac_f32_e32 v160, v140, v140
	v_fmac_f32_e32 v159, v141, v141
	v_fmac_f32_e32 v158, v108, v108
	v_add_f32_e32 v41, v38, v33
	v_add_f32_e32 v42, v39, v245
	v_add_f32_e32 v25, v29, v36
	v_add_f32_e32 v29, v40, v37
	v_lshlrev_b32_e32 v38, 16, v26
	v_and_b32_e32 v39, 0xffff0000, v26
	v_lshlrev_b32_e32 v40, 16, v27
	v_fmac_f32_e32 v53, v113, v113
	v_fmac_f32_e32 v165, v116, v116
	v_fmac_f32_e32 v164, v117, v117
	v_fmac_f32_e32 v163, v128, v128
	v_fmac_f32_e32 v161, v129, v129
	v_fmac_f32_e32 v160, v96, v96
	v_fmac_f32_e32 v159, v97, v97
	v_fmac_f32_e32 v158, v104, v104
	v_add_f32_e32 v26, v30, v38
	v_add_f32_e32 v30, v41, v39
	v_and_b32_e32 v41, 0xffff0000, v27
	v_add_f32_e32 v27, v31, v40
	s_waitcnt vmcnt(5)
	v_lshlrev_b32_e32 v48, 16, v23
	v_fmac_f32_e32 v53, v109, v109
	v_fmac_f32_e32 v165, v110, v110
	v_fmac_f32_e32 v164, v111, v111
	v_fmac_f32_e32 v163, v86, v86
	v_fmac_f32_e32 v161, v87, v87
	v_fmac_f32_e32 v160, v92, v92
	v_fmac_f32_e32 v159, v93, v93
	v_fmac_f32_e32 v158, v244, v244
	v_add_f32_e32 v31, v42, v41
	v_lshlrev_b32_e32 v42, 16, v20
	v_and_b32_e32 v43, 0xffff0000, v20
	v_lshlrev_b32_e32 v44, 16, v21
	v_and_b32_e32 v45, 0xffff0000, v21
	v_lshlrev_b32_e32 v46, 16, v22
	v_and_b32_e32 v47, 0xffff0000, v22
	v_and_b32_e32 v49, 0xffff0000, v23
	v_add_f32_e32 v23, v27, v48
	s_waitcnt vmcnt(4)
; __device__ __forceinline__ float bflo(unsigned w) { return __uint_as_float(w << 16); }
; __device__ __forceinline__ float bfhi(unsigned w) { return __uint_as_float(w & 0xffff0000u); }
; __device__ __forceinline__ void a_unit(Frame& F, int L, int u, bool dry) {
;     ...
;         for (int i = 0; i < 16; ++i)
; #pragma unroll
;             for (int jj = 0; jj < 4; ++jj) { const float lo = bflo(raw[i][jj]), hi = bfhi(raw[i][jj]); s[2 * jj] += lo; q[2 * jj] = fmaf(lo, lo, q[2 * jj]); s[2 * jj + 1] += hi; q[2 * jj + 1] = fmaf(hi, hi, q[2 * jj + 1]); }
	v_lshlrev_b32_e32 v76, 16, v19
	v_fmac_f32_e32 v53, v105, v105
	v_fmac_f32_e32 v165, v102, v102
	v_fmac_f32_e32 v164, v103, v103
	v_fmac_f32_e32 v163, v194, v194
	v_fmac_f32_e32 v161, v195, v195
	v_fmac_f32_e32 v160, v32, v32
	v_fmac_f32_e32 v159, v33, v33
	v_fmac_f32_e32 v158, v40, v40
	v_add_f32_e32 v20, v24, v42
	v_add_f32_e32 v24, v28, v43
	v_add_f32_e32 v21, v25, v44
	v_add_f32_e32 v25, v29, v45
	v_add_f32_e32 v22, v26, v46
	v_add_f32_e32 v26, v30, v47
	v_lshlrev_b32_e32 v50, 16, v16
	v_and_b32_e32 v51, 0xffff0000, v16
	v_lshlrev_b32_e32 v62, 16, v17
	v_and_b32_e32 v63, 0xffff0000, v17
	v_lshlrev_b32_e32 v70, 16, v18
	v_and_b32_e32 v71, 0xffff0000, v18
	v_and_b32_e32 v77, 0xffff0000, v19
	v_add_f32_e32 v19, v23, v76
	s_waitcnt vmcnt(3)
	v_lshlrev_b32_e32 v84, 16, v15
	v_fmac_f32_e32 v53, v245, v245
	v_fmac_f32_e32 v165, v34, v34
	v_fmac_f32_e32 v164, v35, v35
	v_fmac_f32_e32 v163, v36, v36
	v_fmac_f32_e32 v161, v37, v37
	v_fmac_f32_e32 v160, v38, v38
	v_fmac_f32_e32 v159, v39, v39
	v_fmac_f32_e32 v158, v48, v48
	v_add_f32_e32 v27, v31, v49
	v_add_f32_e32 v16, v20, v50
	v_add_f32_e32 v20, v24, v51
	v_add_f32_e32 v17, v21, v62
	v_add_f32_e32 v21, v25, v63
	v_add_f32_e32 v18, v22, v70
	v_add_f32_e32 v22, v26, v71
	v_lshlrev_b32_e32 v66, 16, v12
	v_and_b32_e32 v67, 0xffff0000, v12
	v_lshlrev_b32_e32 v72, 16, v13
	v_and_b32_e32 v73, 0xffff0000, v13
	v_lshlrev_b32_e32 v80, 16, v14
	v_and_b32_e32 v81, 0xffff0000, v14
	v_and_b32_e32 v85, 0xffff0000, v15
	v_add_f32_e32 v15, v19, v84
	s_waitcnt vmcnt(2)
	v_lshlrev_b32_e32 v122, 16, v11
	v_fmac_f32_e32 v53, v41, v41
	v_fmac_f32_e32 v165, v42, v42
	v_fmac_f32_e32 v164, v43, v43
	v_fmac_f32_e32 v163, v44, v44
	v_fmac_f32_e32 v161, v45, v45
	v_fmac_f32_e32 v160, v46, v46
	v_fmac_f32_e32 v159, v47, v47
	v_fmac_f32_e32 v158, v76, v76
	v_add_f32_e32 v23, v27, v77
	v_add_f32_e32 v12, v16, v66
	v_add_f32_e32 v16, v20, v67
	v_add_f32_e32 v13, v17, v72
	v_add_f32_e32 v17, v21, v73
	v_add_f32_e32 v14, v18, v80
	v_add_f32_e32 v18, v22, v81
	v_lshlrev_b32_e32 v88, 16, v8
	v_and_b32_e32 v89, 0xffff0000, v8
	v_lshlrev_b32_e32 v94, 16, v9
	v_and_b32_e32 v95, 0xffff0000, v9
	v_lshlrev_b32_e32 v106, 16, v10
	v_and_b32_e32 v107, 0xffff0000, v10
	v_and_b32_e32 v123, 0xffff0000, v11
	v_add_f32_e32 v11, v15, v122
	s_waitcnt vmcnt(1)
	v_lshlrev_b32_e32 v146, 16, v7
	v_fmac_f32_e32 v53, v49, v49
	v_fmac_f32_e32 v165, v50, v50
	v_fmac_f32_e32 v164, v51, v51
	v_fmac_f32_e32 v163, v62, v62
	v_fmac_f32_e32 v161, v63, v63
	v_fmac_f32_e32 v160, v70, v70
	v_fmac_f32_e32 v159, v71, v71
	v_fmac_f32_e32 v158, v84, v84
	v_add_f32_e32 v19, v23, v85
	v_add_f32_e32 v8, v12, v88
	v_add_f32_e32 v12, v16, v89
	v_add_f32_e32 v9, v13, v94
	v_add_f32_e32 v13, v17, v95
	v_add_f32_e32 v10, v14, v106
	v_add_f32_e32 v14, v18, v107
	v_lshlrev_b32_e32 v124, 16, v4
	v_and_b32_e32 v125, 0xffff0000, v4
	v_lshlrev_b32_e32 v134, 16, v5
	v_and_b32_e32 v135, 0xffff0000, v5
	v_lshlrev_b32_e32 v142, 16, v6
	v_and_b32_e32 v143, 0xffff0000, v6
	v_and_b32_e32 v147, 0xffff0000, v7
	v_add_f32_e32 v7, v11, v146
	s_waitcnt vmcnt(0)
; #define LAS __attribute__((address_space(3)))
; __device__ __forceinline__ float xsum16(float v) { float a = v, b = v; asm("s_nop 1\n\tv_permlane16_swap_b32 %0, %1" : "+v"(a), "+v"(b)); return a + b; }
; __device__ __forceinline__ float xsum32(float v) { float a = v, b = v; asm("s_nop 1\n\tv_permlane32_swap_b32 %0, %1" : "+v"(a), "+v"(b)); return a + b; }
; __device__ __forceinline__ float bflo(unsigned w) { return __uint_as_float(w << 16); }
; __device__ __forceinline__ float bfhi(unsigned w) { return __uint_as_float(w & 0xffff0000u); }
; __device__ __forceinline__ void a_unit(Frame& F, int L, int u, bool dry) {
;     ...
;             for (int jj = 0; jj < 4; ++jj) { const float lo = bflo(raw[i][jj]), hi = bfhi(raw[i][jj]); s[2 * jj] += lo; q[2 * jj] = fmaf(lo, lo, q[2 * jj]); s[2 * jj + 1] += hi; q[2 * jj + 1] = fmaf(hi, hi, q[2 * jj + 1]); }
;     }
; #pragma unroll
;     for (int j = 0; j < 8; ++j) { s[j] = xsum32(xsum16(s[j])); q[j] = xsum32(xsum16(q[j])); }
;     if (cr == 0) {
; #pragma unroll
;         for (int j = 0; j < 8; ++j) *(LAS f32x2*)(part + (w * 128 + 8 * tg + j) * 2) = (f32x2){s[j], q[j]};
;     }
	v_lshlrev_b32_e32 v154, 16, v3
	v_fmac_f32_e32 v53, v77, v77
	v_fmac_f32_e32 v165, v66, v66
	v_fmac_f32_e32 v164, v67, v67
	v_fmac_f32_e32 v163, v72, v72
	v_fmac_f32_e32 v161, v73, v73
	v_fmac_f32_e32 v160, v80, v80
	v_fmac_f32_e32 v159, v81, v81
	v_fmac_f32_e32 v158, v122, v122
	v_add_f32_e32 v15, v19, v123
	v_add_f32_e32 v4, v8, v124
	v_add_f32_e32 v8, v12, v125
	v_add_f32_e32 v5, v9, v134
	v_add_f32_e32 v9, v13, v135
	v_add_f32_e32 v6, v10, v142
	v_add_f32_e32 v10, v14, v143
	v_lshlrev_b32_e32 v148, 16, v0
	v_and_b32_e32 v149, 0xffff0000, v0
	v_lshlrev_b32_e32 v150, 16, v1
	v_and_b32_e32 v151, 0xffff0000, v1
	v_lshlrev_b32_e32 v152, 16, v2
	v_and_b32_e32 v153, 0xffff0000, v2
	v_add_f32_e32 v24, v7, v154
	v_fmac_f32_e32 v53, v85, v85
	v_fmac_f32_e32 v165, v88, v88
	v_fmac_f32_e32 v164, v89, v89
	v_fmac_f32_e32 v163, v94, v94
	v_fmac_f32_e32 v161, v95, v95
	v_fmac_f32_e32 v160, v106, v106
	v_fmac_f32_e32 v159, v107, v107
	v_fmac_f32_e32 v158, v146, v146
	v_add_f32_e32 v11, v15, v147
	v_add_f32_e32 v0, v4, v148
	v_add_f32_e32 v4, v8, v149
	v_add_f32_e32 v8, v5, v150
	v_add_f32_e32 v12, v9, v151
	v_add_f32_e32 v16, v6, v152
	v_add_f32_e32 v20, v10, v153
	v_and_b32_e32 v155, 0xffff0000, v3
	v_mov_b32_e32 v25, v24
	v_fmac_f32_e32 v53, v123, v123
	v_fmac_f32_e32 v165, v124, v124
	v_fmac_f32_e32 v164, v125, v125
	v_fmac_f32_e32 v163, v134, v134
	v_fmac_f32_e32 v161, v135, v135
	v_fmac_f32_e32 v160, v142, v142
	v_fmac_f32_e32 v159, v143, v143
	v_fmac_f32_e32 v158, v154, v154
	v_add_f32_e32 v28, v11, v155
	v_mov_b32_e32 v1, v0
	v_mov_b32_e32 v5, v4
	v_mov_b32_e32 v9, v8
	v_mov_b32_e32 v13, v12
	v_mov_b32_e32 v17, v16
	v_mov_b32_e32 v21, v20
	s_nop 1
	v_permlane16_swap_b32 v24, v25
	v_fmac_f32_e32 v53, v147, v147
	v_fmac_f32_e32 v165, v148, v148
	v_fmac_f32_e32 v164, v149, v149
	v_fmac_f32_e32 v163, v150, v150
	v_fmac_f32_e32 v161, v151, v151
	v_fmac_f32_e32 v160, v152, v152
	v_fmac_f32_e32 v159, v153, v153
	s_nop 1
	v_permlane16_swap_b32 v0, v1
	s_nop 1
	v_permlane16_swap_b32 v4, v5
	s_nop 1
	v_permlane16_swap_b32 v8, v9
	s_nop 1
	v_permlane16_swap_b32 v12, v13
	s_nop 1
	v_permlane16_swap_b32 v16, v17
	s_nop 1
	v_permlane16_swap_b32 v20, v21
	v_add_f32_e32 v24, v24, v25
	v_mov_b32_e32 v25, v158
	v_mov_b32_e32 v29, v28
	v_fmac_f32_e32 v53, v155, v155
	v_add_f32_e32 v0, v0, v1
	v_mov_b32_e32 v1, v165
	v_add_f32_e32 v4, v4, v5
	v_mov_b32_e32 v5, v164
	v_add_f32_e32 v8, v8, v9
	v_mov_b32_e32 v9, v163
	v_add_f32_e32 v12, v12, v13
	v_mov_b32_e32 v13, v161
	v_add_f32_e32 v16, v16, v17
	v_mov_b32_e32 v17, v160
	v_add_f32_e32 v20, v20, v21
	v_mov_b32_e32 v21, v159
	s_nop 1
	v_permlane16_swap_b32 v158, v25
	s_nop 1
	v_permlane16_swap_b32 v28, v29
	s_nop 1
	v_permlane16_swap_b32 v165, v1
	s_nop 1
	v_permlane16_swap_b32 v164, v5
	s_nop 1
	v_permlane16_swap_b32 v163, v9
	s_nop 1
	v_permlane16_swap_b32 v161, v13
	s_nop 1
	v_permlane16_swap_b32 v160, v17
	s_nop 1
	v_permlane16_swap_b32 v159, v21
	s_nop 0
	v_add_f32_e32 v25, v158, v25
	v_add_f32_e32 v158, v28, v29
	v_mov_b32_e32 v28, v53
	v_add_f32_e32 v1, v165, v1
	v_add_f32_e32 v5, v164, v5
	v_add_f32_e32 v9, v163, v9
	v_add_f32_e32 v13, v161, v13
	v_add_f32_e32 v17, v160, v17
	v_add_f32_e32 v21, v159, v21
	s_nop 1
	v_permlane16_swap_b32 v53, v28
	v_mov_b32_e32 v2, v0
	v_add_f32_e32 v159, v53, v28
	v_mov_b32_e32 v3, v1
	v_mov_b32_e32 v6, v4
	v_mov_b32_e32 v7, v5
	v_mov_b32_e32 v10, v8
	v_mov_b32_e32 v11, v9
	v_mov_b32_e32 v14, v12
	v_mov_b32_e32 v15, v13
	v_mov_b32_e32 v18, v16
	v_mov_b32_e32 v19, v17
	v_mov_b32_e32 v22, v20
	v_mov_b32_e32 v23, v21
	v_mov_b32_e32 v26, v24
	v_mov_b32_e32 v27, v25
	v_mov_b32_e32 v160, v158
	v_mov_b32_e32 v161, v159
	s_nop 1
	v_permlane32_swap_b32 v0, v2
	s_nop 1
	v_permlane32_swap_b32 v1, v3
	s_nop 1
	v_permlane32_swap_b32 v4, v6
	s_nop 1
	v_permlane32_swap_b32 v5, v7
	s_nop 1
	v_permlane32_swap_b32 v8, v10
	s_nop 1
	v_permlane32_swap_b32 v9, v11
	s_nop 1
	v_permlane32_swap_b32 v12, v14
	s_nop 1
	v_permlane32_swap_b32 v13, v15
	s_nop 1
	v_permlane32_swap_b32 v16, v18
	s_nop 1
	v_permlane32_swap_b32 v17, v19
	s_nop 1
	v_permlane32_swap_b32 v20, v22
	s_nop 1
	v_permlane32_swap_b32 v21, v23
	s_nop 1
	v_permlane32_swap_b32 v24, v26
	s_nop 1
	v_permlane32_swap_b32 v25, v27
	s_nop 1
	v_permlane32_swap_b32 v158, v160
	s_nop 1
	v_permlane32_swap_b32 v159, v161
	s_and_saveexec_b64 s[0:1], vcc
	s_cbranch_execz .LBB0_471
	v_lshlrev_b32_e32 v28, 3, v190
	v_readlane_b32 s2, v253, 59
	v_pk_add_f32 v[2:3], v[0:1], v[2:3]
	v_pk_add_f32 v[4:5], v[4:5], v[6:7]
	v_or_b32_e32 v0, s2, v28
	v_lshl_add_u32 v0, v0, 3, 0
	v_add_u32_e32 v0, 0x22000, v0
	v_pk_add_f32 v[160:161], v[158:159], v[160:161]
	v_pk_add_f32 v[158:159], v[24:25], v[26:27]
	v_pk_add_f32 v[20:21], v[20:21], v[22:23]
	v_pk_add_f32 v[18:19], v[16:17], v[18:19]
	v_pk_add_f32 v[12:13], v[12:13], v[14:15]
	v_pk_add_f32 v[10:11], v[8:9], v[10:11]
	ds_write_b128 v0, v[2:5]
	ds_write_b128 v0, v[10:13] offset:16
	ds_write_b128 v0, v[18:21] offset:32
	ds_write_b128 v0, v[158:161] offset:48

; #define GAS __attribute__((address_space(1)))
; __device__ __forceinline__ int otid(int wave) { return wave * 64 + olane(); }
; __device__ __forceinline__ void c_unit(Frame& F, int L, int u, bool dry) {
;     ...
;     const int b = u >> 5, t0 = 64 * (u & 31), tid = otid(F.wave), cp = tid & 255, th = tid >> 8;
;     const bf16_t* H = (const bf16_t*)(ws_ + WS_H) + (size_t)b * SEQ * 512 + 2 * cp;
;     bf16_t* SCG = (bf16_t*)(ws_ + WS_SCG) + (size_t)b * SEQ * 512 + 2 * cp;
;     const float* cw = kin(8) + (size_t)L * CONVW * 512 + 2 * cp;
;     f32x2 wv[CONVW];
; #pragma unroll
;     for (int j = 0; j < CONVW; ++j) wv[j] = *(const GAS f32x2*)(cw + j * 512);
;     const f32x2 cbv = *(const GAS f32x2*)(kin(9) + L * 512 + 2 * cp);
;     const f32x2 gv = *(const GAS f32x2*)(kin(10) + L * 512 + 2 * cp), bv = *(const GAS f32x2*)(kin(11) + L * 512 + 2 * cp);
;     const int tb0 = t0 + 32 * th;
;     unsigned hv[62], sc[32];
; #pragma unroll
;     for (int i = 0; i < 62; ++i) { const int tl = tb0 + i - 15; hv[i] = 0u; if (tl >= 0 && tl < SEQ) hv[i] = *(const GAS unsigned*)(H + (size_t)tl * 512); }
; #pragma unroll
;     for (int t = 0; t < 32; ++t) sc[t] = *(const GAS unsigned*)(SCG + (size_t)(tb0 + t) * 512);
.LBB0_561:
	s_or_b64 exec, exec, s[0:1]
	v_readlane_b32 s0, v254, 33
	v_readlane_b32 s1, v254, 34
	s_add_u32 s0, s2, s0
	s_addc_u32 s1, s3, s1
	v_mov_b32_e32 v49, v193
	v_lshl_add_u64 v[48:49], s[0:1], 0, v[48:49]
	s_mov_b64 s[0:1], 0xb000000
	v_ashrrev_i32_e32 v41, 31, v40
	v_lshl_add_u64 v[148:149], v[48:49], 0, s[0:1]
	v_lshlrev_b64 v[48:49], 10, v[40:41]
	v_lshl_add_u64 v[218:219], v[148:149], 0, v[48:49]
	v_or_b32_e32 v48, 1, v40
	v_ashrrev_i32_e32 v49, 31, v48
	v_lshlrev_b64 v[48:49], 10, v[48:49]
	v_lshl_add_u64 v[212:213], v[148:149], 0, v[48:49]
	v_or_b32_e32 v48, 2, v40
	v_ashrrev_i32_e32 v49, 31, v48
	v_lshlrev_b64 v[48:49], 10, v[48:49]
	v_lshl_add_u64 v[208:209], v[148:149], 0, v[48:49]
	v_or_b32_e32 v48, 3, v40
	v_ashrrev_i32_e32 v49, 31, v48
	v_lshlrev_b64 v[48:49], 10, v[48:49]
	v_lshl_add_u64 v[204:205], v[148:149], 0, v[48:49]
	v_or_b32_e32 v48, 4, v40
	v_ashrrev_i32_e32 v49, 31, v48
	v_lshlrev_b64 v[48:49], 10, v[48:49]
	v_lshl_add_u64 v[180:181], v[148:149], 0, v[48:49]
	v_or_b32_e32 v48, 5, v40
	v_ashrrev_i32_e32 v49, 31, v48
	v_lshlrev_b64 v[48:49], 10, v[48:49]
	v_lshl_add_u64 v[178:179], v[148:149], 0, v[48:49]
	v_or_b32_e32 v48, 6, v40
	v_ashrrev_i32_e32 v49, 31, v48
	v_lshlrev_b64 v[48:49], 10, v[48:49]
	v_lshl_add_u64 v[176:177], v[148:149], 0, v[48:49]
	v_or_b32_e32 v48, 7, v40
	v_ashrrev_i32_e32 v49, 31, v48
	v_lshlrev_b64 v[48:49], 10, v[48:49]
	v_lshl_add_u64 v[174:175], v[148:149], 0, v[48:49]
	v_or_b32_e32 v48, 8, v40
	v_ashrrev_i32_e32 v49, 31, v48
	v_lshlrev_b64 v[48:49], 10, v[48:49]
	v_lshl_add_u64 v[172:173], v[148:149], 0, v[48:49]
	v_or_b32_e32 v48, 9, v40
	v_ashrrev_i32_e32 v49, 31, v48
	v_lshlrev_b64 v[48:49], 10, v[48:49]
	v_lshl_add_u64 v[170:171], v[148:149], 0, v[48:49]
	v_or_b32_e32 v48, 10, v40
	v_ashrrev_i32_e32 v49, 31, v48
	v_lshlrev_b64 v[48:49], 10, v[48:49]
	v_lshl_add_u64 v[156:157], v[148:149], 0, v[48:49]
	v_or_b32_e32 v48, 11, v40
	v_ashrrev_i32_e32 v49, 31, v48
	v_lshlrev_b64 v[48:49], 10, v[48:49]
	v_lshl_add_u64 v[140:141], v[148:149], 0, v[48:49]
	v_or_b32_e32 v48, 12, v40
	v_ashrrev_i32_e32 v49, 31, v48
	v_lshlrev_b64 v[48:49], 10, v[48:49]
	v_lshl_add_u64 v[122:123], v[148:149], 0, v[48:49]
	v_or_b32_e32 v48, 13, v40
	v_ashrrev_i32_e32 v49, 31, v48
	v_lshlrev_b64 v[48:49], 10, v[48:49]
	v_lshl_add_u64 v[120:121], v[148:149], 0, v[48:49]
	v_or_b32_e32 v48, 14, v40
	v_ashrrev_i32_e32 v49, 31, v48
	v_lshlrev_b64 v[48:49], 10, v[48:49]
	v_lshl_add_u64 v[116:117], v[148:149], 0, v[48:49]
	v_or_b32_e32 v48, 15, v40
	v_ashrrev_i32_e32 v49, 31, v48
	v_lshlrev_b64 v[48:49], 10, v[48:49]
	v_lshl_add_u64 v[114:115], v[148:149], 0, v[48:49]
	v_or_b32_e32 v48, 16, v40
	v_ashrrev_i32_e32 v49, 31, v48
	v_lshlrev_b64 v[48:49], 10, v[48:49]
	v_lshl_add_u64 v[98:99], v[148:149], 0, v[48:49]
	v_or_b32_e32 v48, 17, v40
	v_ashrrev_i32_e32 v49, 31, v48
	v_lshlrev_b64 v[48:49], 10, v[48:49]
	v_lshl_add_u64 v[96:97], v[148:149], 0, v[48:49]
	v_or_b32_e32 v48, 18, v40
	v_ashrrev_i32_e32 v49, 31, v48
	v_lshlrev_b64 v[48:49], 10, v[48:49]
	v_lshl_add_u64 v[94:95], v[148:149], 0, v[48:49]
	v_or_b32_e32 v48, 19, v40
	v_ashrrev_i32_e32 v49, 31, v48
	v_lshlrev_b64 v[48:49], 10, v[48:49]
	v_lshl_add_u64 v[92:93], v[148:149], 0, v[48:49]
	v_or_b32_e32 v48, 20, v40
	v_ashrrev_i32_e32 v49, 31, v48
	v_lshlrev_b64 v[48:49], 10, v[48:49]
	v_lshl_add_u64 v[90:91], v[148:149], 0, v[48:49]
	v_or_b32_e32 v48, 21, v40
	v_ashrrev_i32_e32 v49, 31, v48
	v_lshlrev_b64 v[48:49], 10, v[48:49]
	v_lshl_add_u64 v[88:89], v[148:149], 0, v[48:49]
	v_or_b32_e32 v48, 22, v40
	v_ashrrev_i32_e32 v49, 31, v48
	v_lshlrev_b64 v[48:49], 10, v[48:49]
	v_lshl_add_u64 v[86:87], v[148:149], 0, v[48:49]
	v_or_b32_e32 v48, 23, v40
	v_ashrrev_i32_e32 v49, 31, v48
	v_lshlrev_b64 v[48:49], 10, v[48:49]
	v_lshl_add_u64 v[84:85], v[148:149], 0, v[48:49]
	v_or_b32_e32 v48, 24, v40
	v_ashrrev_i32_e32 v49, 31, v48
	v_lshlrev_b64 v[48:49], 10, v[48:49]
	v_lshl_add_u64 v[82:83], v[148:149], 0, v[48:49]
	v_or_b32_e32 v48, 25, v40
	v_ashrrev_i32_e32 v49, 31, v48
	v_lshlrev_b64 v[48:49], 10, v[48:49]
	v_lshl_add_u64 v[80:81], v[148:149], 0, v[48:49]
	v_or_b32_e32 v48, 26, v40
	global_load_dword v247, v[218:219], off sc1
	global_load_dword v244, v[212:213], off sc1
	v_ashrrev_i32_e32 v49, 31, v48
	v_lshlrev_b64 v[48:49], 10, v[48:49]
	v_lshl_add_u64 v[76:77], v[148:149], 0, v[48:49]
	v_or_b32_e32 v48, 27, v40
	v_ashrrev_i32_e32 v49, 31, v48
	v_lshlrev_b64 v[48:49], 10, v[48:49]
	v_lshl_add_u64 v[74:75], v[148:149], 0, v[48:49]
	v_or_b32_e32 v48, 28, v40
	v_ashrrev_i32_e32 v49, 31, v48
	v_lshlrev_b64 v[48:49], 10, v[48:49]
	v_lshl_add_u64 v[64:65], v[148:149], 0, v[48:49]
	v_or_b32_e32 v48, 29, v40
	v_ashrrev_i32_e32 v49, 31, v48
	v_lshlrev_b64 v[48:49], 10, v[48:49]
	v_lshl_add_u64 v[62:63], v[148:149], 0, v[48:49]
	v_or_b32_e32 v48, 30, v40
	v_or_b32_e32 v40, 31, v40
	v_ashrrev_i32_e32 v49, 31, v48
	v_ashrrev_i32_e32 v41, 31, v40
	v_lshlrev_b64 v[48:49], 10, v[48:49]
	v_lshlrev_b64 v[40:41], 10, v[40:41]
	v_lshl_add_u64 v[48:49], v[148:149], 0, v[48:49]
	v_lshl_add_u64 v[40:41], v[148:149], 0, v[40:41]
	s_waitcnt vmcnt(2)
; #define GAS __attribute__((address_space(1)))
; __device__ __forceinline__ unsigned cvtpk(float lo, float hi) { f32x2 v = {lo, hi}; bf16x2_t b = __builtin_convertvector(v, bf16x2_t); return __builtin_bit_cast(unsigned, b); }
; __device__ __forceinline__ float bflo(unsigned w) { return __uint_as_float(w << 16); }
; __device__ __forceinline__ float bfhi(unsigned w) { return __uint_as_float(w & 0xffff0000u); }
; __device__ __forceinline__ float fsilu(float x) { return x * fsigmoid(x); }
; __device__ __forceinline__ void c_unit(Frame& F, int L, int u, bool dry) {
;     ...
;         for (int i = 0; i < 46; ++i) {
;             const float h0 = bflo(hv[16 * sub + i]), h1 = bfhi(hv[16 * sub + i]);
; #pragma unroll
;             for (int t = 0; t < 16; ++t) { const int j = i - t; if (j >= 0 && j < CONVW) { acc[t].x = fmaf(h0, wv[j].x, acc[t].x); acc[t].y = fmaf(h1, wv[j].y, acc[t].y); } }
;         }
; #pragma unroll
;         for (int t = 0; t < 16; ++t) {
;             float s = acc[t].x + acc[t].y, qq = acc[t].x * acc[t].x + acc[t].y * acc[t].y;
;             s = half_wave_sum(s); qq = half_wave_sum(qq);
;             const float mu = __builtin_ldexpf(s, -6), rstd = rsqrtf(fmaxf(__builtin_ldexpf(qq, -6) - mu * mu, 0.f) + LN_EPS);
;             const float h0 = (acc[t].x - mu) * rstd * gv.x + bv.x, h1 = (acc[t].y - mu) * rstd * gv.y + bv.y;
;             const unsigned ov = cvtpk(fsilu(h0) * bflo(sc[16 * sub + t]), fsilu(h1) * bfhi(sc[16 * sub + t])); if (!dry) *(GAS unsigned*)(SCG + (size_t)(tb + t) * 512) = ov;
	v_and_b32_e32 v149, 0xffff0000, v101
	v_lshlrev_b32_e32 v148, 16, v101
	v_lshlrev_b32_e32 v222, 16, v100
	v_and_b32_e32 v223, 0xffff0000, v100
	v_pk_fma_f32 v[100:101], v[148:149], v[66:67], v[78:79]
	v_lshlrev_b32_e32 v220, 16, v103
	v_and_b32_e32 v221, 0xffff0000, v103
	v_pk_fma_f32 v[100:101], v[222:223], v[68:69], v[100:101]
	v_lshlrev_b32_e32 v216, 16, v102
	v_and_b32_e32 v217, 0xffff0000, v102
	v_pk_fma_f32 v[100:101], v[220:221], v[70:71], v[100:101]
	v_lshlrev_b32_e32 v214, 16, v107
	v_pk_fma_f32 v[100:101], v[216:217], v[72:73], v[100:101]
	v_and_b32_e32 v215, 0xffff0000, v107
	v_lshlrev_b32_e32 v210, 16, v105
	v_and_b32_e32 v211, 0xffff0000, v105
	v_pk_fma_f32 v[100:101], v[214:215], v[36:37], v[100:101]
	v_lshlrev_b32_e32 v206, 16, v112
	v_and_b32_e32 v207, 0xffff0000, v112
	v_pk_fma_f32 v[100:101], v[210:211], v[38:39], v[100:101]
	v_lshlrev_b32_e32 v200, 16, v111
	v_and_b32_e32 v201, 0xffff0000, v111
	v_pk_fma_f32 v[100:101], v[206:207], v[42:43], v[100:101]
	v_lshlrev_b32_e32 v198, 16, v126
	v_and_b32_e32 v199, 0xffff0000, v126
	v_pk_fma_f32 v[100:101], v[200:201], v[60:61], v[100:101]
	v_lshlrev_b32_e32 v196, 16, v124
	v_and_b32_e32 v197, 0xffff0000, v124
	v_pk_fma_f32 v[100:101], v[198:199], v[44:45], v[100:101]
	v_lshlrev_b32_e32 v190, 16, v131
	v_and_b32_e32 v191, 0xffff0000, v131
	v_pk_fma_f32 v[100:101], v[196:197], v[46:47], v[100:101]
	v_lshlrev_b32_e32 v188, 16, v130
	v_and_b32_e32 v189, 0xffff0000, v130
	v_pk_fma_f32 v[100:101], v[190:191], v[54:55], v[100:101]
	v_lshlrev_b32_e32 v186, 16, v139
	v_and_b32_e32 v187, 0xffff0000, v139
	v_pk_fma_f32 v[100:101], v[188:189], v[58:59], v[100:101]
	v_lshlrev_b32_e32 v184, 16, v138
	v_and_b32_e32 v185, 0xffff0000, v138
	v_pk_fma_f32 v[100:101], v[186:187], v[50:51], v[100:101]
	v_lshlrev_b32_e32 v182, 16, v142
	v_and_b32_e32 v183, 0xffff0000, v142
	v_pk_fma_f32 v[100:101], v[184:185], v[52:53], v[100:101]
	v_lshlrev_b32_e32 v202, 16, v134
	v_pk_fma_f32 v[100:101], v[182:183], v[56:57], v[100:101]
	v_and_b32_e32 v203, 0xffff0000, v134
	v_lshlrev_b32_e32 v154, 16, v129
	v_and_b32_e32 v155, 0xffff0000, v129
	v_pk_fma_f32 v[100:101], v[202:203], v[22:23], v[100:101]
	v_lshlrev_b32_e32 v152, 16, v128
	v_and_b32_e32 v153, 0xffff0000, v128
	v_pk_fma_f32 v[100:101], v[154:155], v[26:27], v[100:101]
	v_lshlrev_b32_e32 v150, 16, v127
	v_and_b32_e32 v151, 0xffff0000, v127
	v_pk_fma_f32 v[100:101], v[152:153], v[28:29], v[100:101]
	v_lshlrev_b32_e32 v148, 16, v137
	v_and_b32_e32 v149, 0xffff0000, v137
	v_pk_fma_f32 v[100:101], v[150:151], v[30:31], v[100:101]
	v_lshlrev_b32_e32 v142, 16, v136
	v_and_b32_e32 v143, 0xffff0000, v136
	v_pk_fma_f32 v[100:101], v[148:149], v[34:35], v[100:101]
	v_lshlrev_b32_e32 v138, 16, v144
	v_and_b32_e32 v139, 0xffff0000, v144
	v_pk_fma_f32 v[100:101], v[142:143], v[32:33], v[100:101]
	v_lshlrev_b32_e32 v134, 16, v135
	v_and_b32_e32 v135, 0xffff0000, v135
	v_pk_fma_f32 v[100:101], v[138:139], v[18:19], v[100:101]
	v_lshlrev_b32_e32 v130, 16, v146
	v_and_b32_e32 v131, 0xffff0000, v146
	v_pk_fma_f32 v[100:101], v[134:135], v[20:21], v[100:101]
	v_lshlrev_b32_e32 v128, 16, v145
	v_and_b32_e32 v129, 0xffff0000, v145
	v_pk_fma_f32 v[100:101], v[130:131], v[24:25], v[100:101]
	v_lshlrev_b32_e32 v126, 16, v147
	v_and_b32_e32 v127, 0xffff0000, v147
	v_pk_fma_f32 v[100:101], v[128:129], v[16:17], v[100:101]
	v_lshlrev_b32_e32 v164, 16, v106
	v_pk_fma_f32 v[100:101], v[126:127], v[14:15], v[100:101]
	v_and_b32_e32 v165, 0xffff0000, v106
	v_lshlrev_b32_e32 v168, 16, v110
	v_and_b32_e32 v169, 0xffff0000, v110
	v_pk_fma_f32 v[100:101], v[164:165], v[2:3], v[100:101]
	v_lshlrev_b32_e32 v166, 16, v109
	v_and_b32_e32 v167, 0xffff0000, v109
	v_pk_fma_f32 v[100:101], v[168:169], v[10:11], v[100:101]
	v_lshlrev_b32_e32 v162, 16, v113
	v_and_b32_e32 v163, 0xffff0000, v113
	v_pk_fma_f32 v[100:101], v[166:167], v[4:5], v[100:101]
	v_lshlrev_b32_e32 v160, 16, v108
	v_and_b32_e32 v161, 0xffff0000, v108
	v_pk_fma_f32 v[100:101], v[162:163], v[6:7], v[100:101]
	v_pk_fma_f32 v[222:223], v[222:223], v[66:67], v[78:79]
	v_pk_fma_f32 v[100:101], v[160:161], v[12:13], v[100:101]
	v_pk_fma_f32 v[222:223], v[220:221], v[68:69], v[222:223]
	v_add_f32_e32 v105, v100, v101
	v_pk_mul_f32 v[106:107], v[100:101], v[100:101]
	v_pk_fma_f32 v[222:223], v[216:217], v[70:71], v[222:223]
	v_add_f32_dpp v105, v105, v105 quad_perm:[1,0,3,2] row_mask:0xf bank_mask:0xf bound_ctrl:1
	v_add_f32_e32 v106, v106, v107
	v_pk_fma_f32 v[222:223], v[214:215], v[72:73], v[222:223]
	v_add_f32_dpp v105, v105, v105 quad_perm:[2,3,0,1] row_mask:0xf bank_mask:0xf bound_ctrl:1
	v_add_f32_dpp v106, v106, v106 quad_perm:[1,0,3,2] row_mask:0xf bank_mask:0xf bound_ctrl:1
	v_pk_fma_f32 v[222:223], v[210:211], v[36:37], v[222:223]
	v_add_f32_dpp v105, v105, v105 row_half_mirror row_mask:0xf bank_mask:0xf bound_ctrl:1
	v_add_f32_dpp v106, v106, v106 quad_perm:[2,3,0,1] row_mask:0xf bank_mask:0xf bound_ctrl:1
	v_pk_fma_f32 v[222:223], v[206:207], v[38:39], v[222:223]
	v_add_f32_dpp v105, v105, v105 row_mirror row_mask:0xf bank_mask:0xf bound_ctrl:1
	v_mov_b32_e32 v107, v105
	v_add_f32_dpp v106, v106, v106 row_half_mirror row_mask:0xf bank_mask:0xf bound_ctrl:1
	s_nop 1
	v_permlane16_swap_b32 v105, v107
	v_pk_fma_f32 v[222:223], v[200:201], v[42:43], v[222:223]
	v_add_f32_e32 v105, v105, v107
	v_add_f32_dpp v106, v106, v106 row_mirror row_mask:0xf bank_mask:0xf bound_ctrl:1
	v_mov_b32_e32 v107, v106
	s_nop 1
	v_permlane16_swap_b32 v106, v107
	v_ldexp_f32 v194, v105, -6
	v_add_f32_e32 v106, v106, v107
	v_ldexp_f32 v105, v106, -6
	v_fma_f32 v105, -v194, v194, v105
	v_pk_fma_f32 v[222:223], v[198:199], v[60:61], v[222:223]
; #define GAS __attribute__((address_space(1)))
; __device__ __forceinline__ unsigned cvtpk(float lo, float hi) { f32x2 v = {lo, hi}; bf16x2_t b = __builtin_convertvector(v, bf16x2_t); return __builtin_bit_cast(unsigned, b); }
; __device__ __forceinline__ float bflo(unsigned w) { return __uint_as_float(w << 16); }
; __device__ __forceinline__ float bfhi(unsigned w) { return __uint_as_float(w & 0xffff0000u); }
; __device__ __forceinline__ float fsilu(float x) { return x * fsigmoid(x); }
; __device__ __forceinline__ void c_unit(Frame& F, int L, int u, bool dry) {
;     ...
; #pragma unroll
;         for (int t = 0; t < 16; ++t) {
;             float s = acc[t].x + acc[t].y, qq = acc[t].x * acc[t].x + acc[t].y * acc[t].y;
;             s = half_wave_sum(s); qq = half_wave_sum(qq);
;             const float mu = __builtin_ldexpf(s, -6), rstd = rsqrtf(fmaxf(__builtin_ldexpf(qq, -6) - mu * mu, 0.f) + LN_EPS);
;             const float h0 = (acc[t].x - mu) * rstd * gv.x + bv.x, h1 = (acc[t].y - mu) * rstd * gv.y + bv.y;
;             const unsigned ov = cvtpk(fsilu(h0) * bflo(sc[16 * sub + t]), fsilu(h1) * bfhi(sc[16 * sub + t])); if (!dry) *(GAS unsigned*)(SCG + (size_t)(tb + t) * 512) = ov;
	v_max_f32_e32 v105, 0, v105
	v_pk_fma_f32 v[222:223], v[196:197], v[44:45], v[222:223]
	v_add_f32_e32 v105, 0x3727c5ac, v105
	s_mov_b32 s0, 0x800000
	v_pk_fma_f32 v[222:223], v[190:191], v[46:47], v[222:223]
	v_mul_f32_e32 v106, 0x4b800000, v105
	v_cmp_gt_f32_e32 vcc, s0, v105
	v_pk_fma_f32 v[222:223], v[188:189], v[54:55], v[222:223]
	v_and_b32_e32 v107, 0xffff0000, v104
	v_cndmask_b32_e32 v105, v105, v106, vcc
	v_pk_fma_f32 v[222:223], v[186:187], v[58:59], v[222:223]
	v_rsq_f32_e32 v105, v105
	v_pk_fma_f32 v[222:223], v[184:185], v[50:51], v[222:223]
	v_lshlrev_b32_e32 v106, 16, v104
	v_pk_fma_f32 v[222:223], v[182:183], v[52:53], v[222:223]
	v_mul_f32_e32 v104, 0x45800000, v105
	v_pk_fma_f32 v[222:223], v[202:203], v[56:57], v[222:223]
	v_pk_add_f32 v[100:101], v[100:101], v[194:195] op_sel_hi:[1,0] neg_lo:[0,1] neg_hi:[0,1]
	v_pk_fma_f32 v[222:223], v[154:155], v[22:23], v[222:223]
	v_cndmask_b32_e32 v104, v105, v104, vcc
	v_pk_fma_f32 v[222:223], v[152:153], v[26:27], v[222:223]
	v_pk_mul_f32 v[100:101], v[100:101], v[104:105] op_sel_hi:[1,0]
	v_pk_fma_f32 v[222:223], v[150:151], v[28:29], v[222:223]
	v_pk_fma_f32 v[194:195], v[0:1], v[100:101], v[8:9]
	v_pk_fma_f32 v[222:223], v[148:149], v[30:31], v[222:223]
	v_mul_f32_e32 v100, 0xbfb8aa3b, v194
	v_pk_fma_f32 v[222:223], v[142:143], v[34:35], v[222:223]
	v_mul_f32_e32 v101, 0xbfb8aa3b, v195
	v_pk_fma_f32 v[222:223], v[138:139], v[32:33], v[222:223]
	v_exp_f32_e32 v100, v100
	v_exp_f32_e32 v101, v101
	v_pk_fma_f32 v[222:223], v[134:135], v[18:19], v[222:223]
	v_lshlrev_b32_e32 v158, 16, v125
	v_pk_fma_f32 v[222:223], v[130:131], v[20:21], v[222:223]
	v_add_f32_e32 v100, 1.0, v100
	v_pk_fma_f32 v[222:223], v[128:129], v[24:25], v[222:223]
	v_add_f32_e32 v101, 1.0, v101
	v_pk_fma_f32 v[222:223], v[126:127], v[16:17], v[222:223]
	v_and_b32_e32 v159, 0xffff0000, v125
	v_pk_fma_f32 v[222:223], v[164:165], v[14:15], v[222:223]
	v_lshlrev_b32_e32 v124, 16, v243
	v_and_b32_e32 v125, 0xffff0000, v243
	v_lshlrev_b32_e32 v112, 16, v242
	v_and_b32_e32 v113, 0xffff0000, v242
	v_rcp_f32_e32 v242, v100
	v_rcp_f32_e32 v243, v101
	v_pk_fma_f32 v[222:223], v[168:169], v[2:3], v[222:223]
	v_lshlrev_b32_e32 v104, 16, v241
	v_pk_fma_f32 v[222:223], v[166:167], v[10:11], v[222:223]
	v_and_b32_e32 v105, 0xffff0000, v241
	v_pk_fma_f32 v[222:223], v[162:163], v[4:5], v[222:223]
	v_lshlrev_b32_e32 v100, 16, v240
	v_pk_fma_f32 v[222:223], v[160:161], v[6:7], v[222:223]
	v_and_b32_e32 v101, 0xffff0000, v240
	v_pk_mul_f32 v[194:195], v[194:195], v[242:243]
	s_waitcnt vmcnt(1)
	v_lshlrev_b32_e32 v240, 16, v247
	v_and_b32_e32 v241, 0xffff0000, v247
	v_pk_fma_f32 v[222:223], v[158:159], v[12:13], v[222:223]
	v_pk_mul_f32 v[194:195], v[194:195], v[240:241]
	v_add_f32_e32 v242, v222, v223
	v_pk_mul_f32 v[240:241], v[222:223], v[222:223]
	v_pk_fma_f32 v[220:221], v[220:221], v[66:67], v[78:79]
	v_add_f32_e32 v240, v240, v241
	v_add_f32_dpp v241, v242, v242 quad_perm:[1,0,3,2] row_mask:0xf bank_mask:0xf bound_ctrl:1
	v_pk_fma_f32 v[220:221], v[216:217], v[68:69], v[220:221]
	v_add_f32_dpp v240, v240, v240 quad_perm:[1,0,3,2] row_mask:0xf bank_mask:0xf bound_ctrl:1
	v_add_f32_dpp v241, v241, v241 quad_perm:[2,3,0,1] row_mask:0xf bank_mask:0xf bound_ctrl:1
	v_pk_fma_f32 v[220:221], v[214:215], v[70:71], v[220:221]
	v_add_f32_dpp v240, v240, v240 quad_perm:[2,3,0,1] row_mask:0xf bank_mask:0xf bound_ctrl:1
	v_add_f32_dpp v241, v241, v241 row_half_mirror row_mask:0xf bank_mask:0xf bound_ctrl:1
	v_pk_fma_f32 v[220:221], v[210:211], v[72:73], v[220:221]
	v_add_f32_dpp v240, v240, v240 row_half_mirror row_mask:0xf bank_mask:0xf bound_ctrl:1
	v_add_f32_dpp v241, v241, v241 row_mirror row_mask:0xf bank_mask:0xf bound_ctrl:1
	v_mov_b32_e32 v242, v241
	s_nop 1
	v_permlane16_swap_b32 v241, v242
	v_add_f32_dpp v240, v240, v240 row_mirror row_mask:0xf bank_mask:0xf bound_ctrl:1
	v_add_f32_e32 v241, v241, v242
	v_mov_b32_e32 v242, v240
	s_nop 1
	v_permlane16_swap_b32 v240, v242
	v_pk_fma_f32 v[220:221], v[206:207], v[36:37], v[220:221]
	v_add_f32_e32 v242, v240, v242
	v_pk_fma_f32 v[220:221], v[200:201], v[38:39], v[220:221]
	v_ldexp_f32 v240, v241, -6
	v_ldexp_f32 v241, v242, -6
	v_pk_fma_f32 v[220:221], v[198:199], v[42:43], v[220:221]
	v_fma_f32 v242, -v240, v240, v241
	v_pk_add_f32 v[240:241], v[222:223], v[240:241] op_sel_hi:[1,0] neg_lo:[0,1] neg_hi:[0,1]
	global_load_dword v222, v[208:209], off sc1
	global_load_dword v247, v[180:181], off sc1
	v_pk_fma_f32 v[220:221], v[196:197], v[60:61], v[220:221]
	v_max_f32_e32 v223, 0, v242
	v_pk_fma_f32 v[220:221], v[190:191], v[44:45], v[220:221]
	v_add_f32_e32 v223, 0x3727c5ac, v223
	v_pk_fma_f32 v[220:221], v[188:189], v[46:47], v[220:221]
	v_mul_f32_e32 v242, 0x4b800000, v223
	v_pk_fma_f32 v[220:221], v[186:187], v[54:55], v[220:221]
	v_cmp_gt_f32_e32 vcc, s0, v223
	v_pk_fma_f32 v[220:221], v[184:185], v[58:59], v[220:221]
	v_lshlrev_b32_e32 v146, 16, v119
	v_pk_fma_f32 v[220:221], v[182:183], v[50:51], v[220:221]
	v_cndmask_b32_e32 v223, v223, v242, vcc
	v_pk_fma_f32 v[220:221], v[202:203], v[52:53], v[220:221]
	v_rsq_f32_e32 v223, v223
	v_pk_fma_f32 v[220:221], v[154:155], v[56:57], v[220:221]
	v_cvt_pk_bf16_f32 v242, v194, v195
	v_pk_fma_f32 v[220:221], v[152:153], v[22:23], v[220:221]
	v_mul_f32_e32 v194, 0x45800000, v223
	v_pk_fma_f32 v[220:221], v[150:151], v[26:27], v[220:221]
	v_cndmask_b32_e32 v194, v223, v194, vcc
	v_pk_fma_f32 v[220:221], v[148:149], v[28:29], v[220:221]
	v_pk_mul_f32 v[194:195], v[240:241], v[194:195] op_sel_hi:[1,0]
	v_pk_fma_f32 v[220:221], v[142:143], v[30:31], v[220:221]
	v_pk_fma_f32 v[194:195], v[0:1], v[194:195], v[8:9]
	v_pk_fma_f32 v[220:221], v[138:139], v[34:35], v[220:221]
	v_mul_f32_e32 v223, 0xbfb8aa3b, v194
	v_pk_fma_f32 v[220:221], v[134:135], v[32:33], v[220:221]
	v_exp_f32_e32 v223, v223
	v_pk_fma_f32 v[220:221], v[130:131], v[18:19], v[220:221]
	v_mul_f32_e32 v240, 0xbfb8aa3b, v195
	v_pk_fma_f32 v[220:221], v[128:129], v[20:21], v[220:221]
	v_exp_f32_e32 v240, v240
	v_pk_fma_f32 v[220:221], v[126:127], v[24:25], v[220:221]
	v_and_b32_e32 v147, 0xffff0000, v119
	v_pk_fma_f32 v[220:221], v[164:165], v[16:17], v[220:221]
	global_store_dword v[218:219], v242, off
	v_pk_fma_f32 v[220:221], v[168:169], v[14:15], v[220:221]
	v_add_f32_e32 v218, 1.0, v223
	v_pk_fma_f32 v[220:221], v[166:167], v[2:3], v[220:221]
	v_add_f32_e32 v219, 1.0, v240
	v_pk_fma_f32 v[220:221], v[162:163], v[10:11], v[220:221]
	v_rcp_f32_e32 v218, v218
	v_pk_fma_f32 v[220:221], v[160:161], v[4:5], v[220:221]
	v_rcp_f32_e32 v219, v219
	v_pk_fma_f32 v[220:221], v[158:159], v[6:7], v[220:221]
	v_lshlrev_b32_e32 v110, 16, v252
	v_pk_fma_f32 v[220:221], v[146:147], v[12:13], v[220:221]
	v_pk_mul_f32 v[194:195], v[194:195], v[218:219]
	v_add_f32_e32 v223, v220, v221
	v_pk_mul_f32 v[240:241], v[220:221], v[220:221]
	s_waitcnt vmcnt(3)
; #define GAS __attribute__((address_space(1)))
; __device__ __forceinline__ unsigned cvtpk(float lo, float hi) { f32x2 v = {lo, hi}; bf16x2_t b = __builtin_convertvector(v, bf16x2_t); return __builtin_bit_cast(unsigned, b); }
; __device__ __forceinline__ float bflo(unsigned w) { return __uint_as_float(w << 16); }
; __device__ __forceinline__ float bfhi(unsigned w) { return __uint_as_float(w & 0xffff0000u); }
; __device__ __forceinline__ float fsilu(float x) { return x * fsigmoid(x); }
; __device__ __forceinline__ void c_unit(Frame& F, int L, int u, bool dry) {
;     ...
;         for (int i = 0; i < 46; ++i) {
;             const float h0 = bflo(hv[16 * sub + i]), h1 = bfhi(hv[16 * sub + i]);
; #pragma unroll
;             for (int t = 0; t < 16; ++t) { const int j = i - t; if (j >= 0 && j < CONVW) { acc[t].x = fmaf(h0, wv[j].x, acc[t].x); acc[t].y = fmaf(h1, wv[j].y, acc[t].y); } }
;         }
; #pragma unroll
;         for (int t = 0; t < 16; ++t) {
;             float s = acc[t].x + acc[t].y, qq = acc[t].x * acc[t].x + acc[t].y * acc[t].y;
;             s = half_wave_sum(s); qq = half_wave_sum(qq);
;             const float mu = __builtin_ldexpf(s, -6), rstd = rsqrtf(fmaxf(__builtin_ldexpf(qq, -6) - mu * mu, 0.f) + LN_EPS);
;             const float h0 = (acc[t].x - mu) * rstd * gv.x + bv.x, h1 = (acc[t].y - mu) * rstd * gv.y + bv.y;
;             const unsigned ov = cvtpk(fsilu(h0) * bflo(sc[16 * sub + t]), fsilu(h1) * bfhi(sc[16 * sub + t])); if (!dry) *(GAS unsigned*)(SCG + (size_t)(tb + t) * 512) = ov;
	v_lshlrev_b32_e32 v218, 16, v244
	v_add_f32_dpp v223, v223, v223 quad_perm:[1,0,3,2] row_mask:0xf bank_mask:0xf bound_ctrl:1
	v_add_f32_e32 v240, v240, v241
	v_and_b32_e32 v219, 0xffff0000, v244
	v_add_f32_dpp v223, v223, v223 quad_perm:[2,3,0,1] row_mask:0xf bank_mask:0xf bound_ctrl:1
	v_add_f32_dpp v240, v240, v240 quad_perm:[1,0,3,2] row_mask:0xf bank_mask:0xf bound_ctrl:1
	v_pk_mul_f32 v[218:219], v[194:195], v[218:219]
	v_add_f32_dpp v223, v223, v223 row_half_mirror row_mask:0xf bank_mask:0xf bound_ctrl:1
	v_add_f32_dpp v240, v240, v240 quad_perm:[2,3,0,1] row_mask:0xf bank_mask:0xf bound_ctrl:1
	v_and_b32_e32 v111, 0xffff0000, v252
	v_add_f32_dpp v223, v223, v223 row_mirror row_mask:0xf bank_mask:0xf bound_ctrl:1
	v_mov_b32_e32 v241, v223
	v_add_f32_dpp v240, v240, v240 row_half_mirror row_mask:0xf bank_mask:0xf bound_ctrl:1
	s_nop 1
	v_permlane16_swap_b32 v223, v241
	global_load_dword v252, v[204:205], off sc1
	v_add_f32_e32 v223, v223, v241
	v_add_f32_dpp v240, v240, v240 row_mirror row_mask:0xf bank_mask:0xf bound_ctrl:1
	v_mov_b32_e32 v241, v240
	s_nop 1
	v_permlane16_swap_b32 v240, v241
	v_ldexp_f32 v194, v223, -6
	v_add_f32_e32 v240, v240, v241
	v_ldexp_f32 v195, v240, -6
	v_fma_f32 v195, -v194, v194, v195
	v_max_f32_e32 v195, 0, v195
	v_add_f32_e32 v195, 0x3727c5ac, v195
	v_mul_f32_e32 v223, 0x4b800000, v195
	v_cmp_gt_f32_e32 vcc, s0, v195
	v_lshlrev_b32_e32 v144, 16, v132
	v_and_b32_e32 v145, 0xffff0000, v132
	v_cndmask_b32_e32 v195, v195, v223, vcc
	v_cvt_pk_bf16_f32 v223, v218, v219
	global_store_dword v[212:213], v223, off
	v_pk_fma_f32 v[212:213], v[216:217], v[66:67], v[78:79]
	v_rsq_f32_e32 v195, v195
	v_pk_fma_f32 v[212:213], v[214:215], v[68:69], v[212:213]
	v_lshlrev_b32_e32 v136, 16, v118
	v_pk_fma_f32 v[212:213], v[210:211], v[70:71], v[212:213]
	v_pk_add_f32 v[220:221], v[220:221], v[194:195] op_sel_hi:[1,0] neg_lo:[0,1] neg_hi:[0,1]
	v_pk_fma_f32 v[212:213], v[206:207], v[72:73], v[212:213]
	v_mul_f32_e32 v194, 0x45800000, v195
	v_pk_fma_f32 v[212:213], v[200:201], v[36:37], v[212:213]
	v_cndmask_b32_e32 v194, v195, v194, vcc
	v_pk_fma_f32 v[212:213], v[198:199], v[38:39], v[212:213]
	v_pk_mul_f32 v[194:195], v[220:221], v[194:195] op_sel_hi:[1,0]
	v_pk_fma_f32 v[212:213], v[196:197], v[42:43], v[212:213]
	v_pk_fma_f32 v[194:195], v[0:1], v[194:195], v[8:9]
	v_pk_fma_f32 v[212:213], v[190:191], v[60:61], v[212:213]
	v_mul_f32_e32 v220, 0xbfb8aa3b, v194
	v_pk_fma_f32 v[212:213], v[188:189], v[44:45], v[212:213]
	v_mul_f32_e32 v221, 0xbfb8aa3b, v195
	v_pk_fma_f32 v[212:213], v[186:187], v[46:47], v[212:213]
	v_exp_f32_e32 v220, v220
	v_pk_fma_f32 v[212:213], v[184:185], v[54:55], v[212:213]
	v_exp_f32_e32 v221, v221
	v_pk_fma_f32 v[212:213], v[182:183], v[58:59], v[212:213]
	v_add_f32_e32 v218, 1.0, v220
	v_pk_fma_f32 v[212:213], v[202:203], v[50:51], v[212:213]
	v_add_f32_e32 v219, 1.0, v221
	v_pk_fma_f32 v[212:213], v[154:155], v[52:53], v[212:213]
	v_rcp_f32_e32 v218, v218
	v_pk_fma_f32 v[212:213], v[152:153], v[56:57], v[212:213]
	v_rcp_f32_e32 v219, v219
	v_pk_fma_f32 v[212:213], v[150:151], v[22:23], v[212:213]
	v_and_b32_e32 v137, 0xffff0000, v118
	v_pk_fma_f32 v[212:213], v[148:149], v[26:27], v[212:213]
	v_pk_mul_f32 v[194:195], v[194:195], v[218:219]
	v_pk_fma_f32 v[212:213], v[142:143], v[28:29], v[212:213]
	v_lshlrev_b32_e32 v118, 16, v245
	v_pk_fma_f32 v[212:213], v[138:139], v[30:31], v[212:213]
	v_and_b32_e32 v119, 0xffff0000, v245
	v_pk_fma_f32 v[212:213], v[134:135], v[34:35], v[212:213]
	v_lshlrev_b32_e32 v108, 16, v251
	v_pk_fma_f32 v[212:213], v[130:131], v[32:33], v[212:213]
	v_and_b32_e32 v109, 0xffff0000, v251
	v_pk_fma_f32 v[212:213], v[128:129], v[18:19], v[212:213]
	v_lshlrev_b32_e32 v102, 16, v246
	v_pk_fma_f32 v[212:213], v[126:127], v[20:21], v[212:213]
	v_and_b32_e32 v103, 0xffff0000, v246
	v_pk_fma_f32 v[212:213], v[164:165], v[24:25], v[212:213]
	global_load_dword v246, v[178:179], off sc1
	global_load_dword v245, v[176:177], off sc1
	global_load_dword v240, v[174:175], off sc1
	global_load_dword v251, v[172:173], off sc1
	global_load_dword v242, v[170:171], off sc1
	global_load_dword v243, v[156:157], off sc1
	global_load_dword v241, v[140:141], off sc1
	global_load_dword v223, v[122:123], off sc1
	v_pk_fma_f32 v[212:213], v[168:169], v[16:17], v[212:213]
	v_lshlrev_b32_e32 v132, 16, v133
	v_pk_fma_f32 v[212:213], v[166:167], v[14:15], v[212:213]
	v_and_b32_e32 v133, 0xffff0000, v133
	v_pk_fma_f32 v[212:213], v[162:163], v[2:3], v[212:213]
	s_waitcnt vmcnt(6)
; #define GAS __attribute__((address_space(1)))
; __device__ __forceinline__ unsigned cvtpk(float lo, float hi) { f32x2 v = {lo, hi}; bf16x2_t b = __builtin_convertvector(v, bf16x2_t); return __builtin_bit_cast(unsigned, b); }
; __device__ __forceinline__ float bflo(unsigned w) { return __uint_as_float(w << 16); }
; __device__ __forceinline__ float bfhi(unsigned w) { return __uint_as_float(w & 0xffff0000u); }
; __device__ __forceinline__ float fsilu(float x) { return x * fsigmoid(x); }
; __device__ __forceinline__ void c_unit(Frame& F, int L, int u, bool dry) {
;     ...
;         for (int i = 0; i < 46; ++i) {
;             const float h0 = bflo(hv[16 * sub + i]), h1 = bfhi(hv[16 * sub + i]);
; #pragma unroll
;             for (int t = 0; t < 16; ++t) { const int j = i - t; if (j >= 0 && j < CONVW) { acc[t].x = fmaf(h0, wv[j].x, acc[t].x); acc[t].y = fmaf(h1, wv[j].y, acc[t].y); } }
;         }
; #pragma unroll
;         for (int t = 0; t < 16; ++t) {
;             float s = acc[t].x + acc[t].y, qq = acc[t].x * acc[t].x + acc[t].y * acc[t].y;
;             s = half_wave_sum(s); qq = half_wave_sum(qq);
;             const float mu = __builtin_ldexpf(s, -6), rstd = rsqrtf(fmaxf(__builtin_ldexpf(qq, -6) - mu * mu, 0.f) + LN_EPS);
;             const float h0 = (acc[t].x - mu) * rstd * gv.x + bv.x, h1 = (acc[t].y - mu) * rstd * gv.y + bv.y;
;             const unsigned ov = cvtpk(fsilu(h0) * bflo(sc[16 * sub + t]), fsilu(h1) * bfhi(sc[16 * sub + t])); if (!dry) *(GAS unsigned*)(SCG + (size_t)(tb + t) * 512) = ov;
	v_lshlrev_b32_e32 v244, 16, v245
	v_pk_fma_f32 v[212:213], v[160:161], v[10:11], v[212:213]
	v_and_b32_e32 v245, 0xffff0000, v245
	v_pk_fma_f32 v[212:213], v[158:159], v[4:5], v[212:213]
	s_nop 0
	v_pk_fma_f32 v[212:213], v[146:147], v[6:7], v[212:213]
	s_nop 0
	v_pk_fma_f32 v[212:213], v[144:145], v[12:13], v[212:213]
	s_nop 0
	v_add_f32_e32 v218, v212, v213
	v_pk_mul_f32 v[216:217], v[212:213], v[212:213]
	s_nop 0
	v_add_f32_e32 v216, v216, v217
	v_add_f32_dpp v217, v218, v218 quad_perm:[1,0,3,2] row_mask:0xf bank_mask:0xf bound_ctrl:1
	s_nop 0
	v_add_f32_dpp v216, v216, v216 quad_perm:[1,0,3,2] row_mask:0xf bank_mask:0xf bound_ctrl:1
	v_add_f32_dpp v217, v217, v217 quad_perm:[2,3,0,1] row_mask:0xf bank_mask:0xf bound_ctrl:1
	s_nop 0
	v_add_f32_dpp v216, v216, v216 quad_perm:[2,3,0,1] row_mask:0xf bank_mask:0xf bound_ctrl:1
	v_add_f32_dpp v217, v217, v217 row_half_mirror row_mask:0xf bank_mask:0xf bound_ctrl:1
	s_nop 0
	v_add_f32_dpp v216, v216, v216 row_half_mirror row_mask:0xf bank_mask:0xf bound_ctrl:1
	v_add_f32_dpp v217, v217, v217 row_mirror row_mask:0xf bank_mask:0xf bound_ctrl:1
	v_mov_b32_e32 v218, v217
	s_nop 1
	v_permlane16_swap_b32 v217, v218
	v_add_f32_dpp v216, v216, v216 row_mirror row_mask:0xf bank_mask:0xf bound_ctrl:1
	v_add_f32_e32 v218, v217, v218
	v_mov_b32_e32 v217, v216
	s_nop 1
	v_permlane16_swap_b32 v216, v217
	s_nop 0
	v_add_f32_e32 v219, v216, v217
	v_lshlrev_b32_e32 v216, 16, v222
	v_and_b32_e32 v217, 0xffff0000, v222
	v_pk_mul_f32 v[194:195], v[194:195], v[216:217]
	v_ldexp_f32 v216, v218, -6
	v_ldexp_f32 v217, v219, -6
	v_fma_f32 v217, -v216, v216, v217
	v_max_f32_e32 v217, 0, v217
	v_add_f32_e32 v217, 0x3727c5ac, v217
	v_mul_f32_e32 v218, 0x4b800000, v217
	v_cmp_gt_f32_e32 vcc, s0, v217
	global_load_dword v222, v[120:121], off sc1
	global_load_dword v220, v[116:117], off sc1
	v_cndmask_b32_e32 v217, v217, v218, vcc
	v_rsq_f32_e32 v217, v217
	global_load_dword v221, v[114:115], off sc1
	global_load_dword v219, v[98:99], off sc1
	global_load_dword v218, v[96:97], off sc1
	v_pk_add_f32 v[212:213], v[212:213], v[216:217] op_sel_hi:[1,0] neg_lo:[0,1] neg_hi:[0,1]
	v_mul_f32_e32 v216, 0x45800000, v217
	v_cndmask_b32_e32 v216, v217, v216, vcc
	v_pk_mul_f32 v[212:213], v[212:213], v[216:217] op_sel_hi:[1,0]
	v_cvt_pk_bf16_f32 v216, v194, v195
	v_pk_fma_f32 v[194:195], v[0:1], v[212:213], v[8:9]
	global_store_dword v[208:209], v216, off
	v_mul_f32_e32 v212, 0xbfb8aa3b, v194
	v_exp_f32_e32 v212, v212
	v_mul_f32_e32 v208, 0xbfb8aa3b, v195
	v_exp_f32_e32 v209, v208
	global_load_dword v217, v[94:95], off sc1
	global_load_dword v216, v[92:93], off sc1
	v_add_f32_e32 v208, 1.0, v212
	v_pk_fma_f32 v[212:213], v[214:215], v[66:67], v[78:79]
	v_add_f32_e32 v209, 1.0, v209
	v_pk_fma_f32 v[212:213], v[210:211], v[68:69], v[212:213]
	v_rcp_f32_e32 v208, v208
	v_pk_fma_f32 v[212:213], v[206:207], v[70:71], v[212:213]
	v_rcp_f32_e32 v209, v209
	v_pk_fma_f32 v[212:213], v[200:201], v[72:73], v[212:213]
	global_load_dword v215, v[80:81], off sc1
	v_pk_fma_f32 v[212:213], v[198:199], v[36:37], v[212:213]
	v_pk_mul_f32 v[194:195], v[194:195], v[208:209]
	v_pk_fma_f32 v[212:213], v[196:197], v[38:39], v[212:213]
	v_lshlrev_b32_e32 v208, 16, v252
	v_pk_fma_f32 v[212:213], v[190:191], v[42:43], v[212:213]
	v_and_b32_e32 v209, 0xffff0000, v252
	v_pk_fma_f32 v[212:213], v[188:189], v[60:61], v[212:213]
	v_pk_mul_f32 v[194:195], v[194:195], v[208:209]
	v_pk_fma_f32 v[212:213], v[186:187], v[44:45], v[212:213]
	v_cvt_pk_bf16_f32 v194, v194, v195
	v_pk_fma_f32 v[212:213], v[184:185], v[46:47], v[212:213]
	global_store_dword v[204:205], v194, off
	v_pk_fma_f32 v[212:213], v[182:183], v[54:55], v[212:213]
	s_nop 0
	v_pk_fma_f32 v[212:213], v[202:203], v[58:59], v[212:213]
	s_nop 0
	v_pk_fma_f32 v[212:213], v[154:155], v[50:51], v[212:213]
	s_nop 0
	v_pk_fma_f32 v[212:213], v[152:153], v[52:53], v[212:213]
	s_nop 0
	v_pk_fma_f32 v[212:213], v[150:151], v[56:57], v[212:213]
	s_nop 0
	v_pk_fma_f32 v[212:213], v[148:149], v[22:23], v[212:213]
	s_nop 0
	v_pk_fma_f32 v[212:213], v[142:143], v[26:27], v[212:213]
	s_nop 0
	v_pk_fma_f32 v[212:213], v[138:139], v[28:29], v[212:213]
	s_nop 0
	v_pk_fma_f32 v[212:213], v[134:135], v[30:31], v[212:213]
	s_nop 0
	v_pk_fma_f32 v[212:213], v[130:131], v[34:35], v[212:213]
	s_nop 0
	v_pk_fma_f32 v[212:213], v[128:129], v[32:33], v[212:213]
	s_nop 0
	v_pk_fma_f32 v[212:213], v[126:127], v[18:19], v[212:213]
	s_nop 0
	v_pk_fma_f32 v[212:213], v[164:165], v[20:21], v[212:213]
	s_nop 0
	v_pk_fma_f32 v[212:213], v[168:169], v[24:25], v[212:213]
	s_nop 0
	v_pk_fma_f32 v[212:213], v[166:167], v[16:17], v[212:213]
	s_nop 0
	v_pk_fma_f32 v[212:213], v[162:163], v[14:15], v[212:213]
	s_nop 0
	v_pk_fma_f32 v[208:209], v[160:161], v[2:3], v[212:213]
	s_nop 0
	v_pk_fma_f32 v[208:209], v[158:159], v[10:11], v[208:209]
	s_nop 0
	v_pk_fma_f32 v[208:209], v[146:147], v[4:5], v[208:209]
	s_nop 0
	v_pk_fma_f32 v[208:209], v[144:145], v[6:7], v[208:209]
	s_nop 0
	v_pk_fma_f32 v[208:209], v[136:137], v[12:13], v[208:209]
	s_nop 0
	v_add_f32_e32 v214, v208, v209
	v_pk_mul_f32 v[212:213], v[208:209], v[208:209]
	s_nop 0
	v_add_f32_e32 v212, v212, v213
	v_add_f32_dpp v213, v214, v214 quad_perm:[1,0,3,2] row_mask:0xf bank_mask:0xf bound_ctrl:1
	s_nop 0
	v_add_f32_dpp v212, v212, v212 quad_perm:[1,0,3,2] row_mask:0xf bank_mask:0xf bound_ctrl:1
	v_add_f32_dpp v213, v213, v213 quad_perm:[2,3,0,1] row_mask:0xf bank_mask:0xf bound_ctrl:1
	s_nop 0
	v_add_f32_dpp v212, v212, v212 quad_perm:[2,3,0,1] row_mask:0xf bank_mask:0xf bound_ctrl:1
	v_add_f32_dpp v213, v213, v213 row_half_mirror row_mask:0xf bank_mask:0xf bound_ctrl:1
	s_nop 0
; #define GAS __attribute__((address_space(1)))
; __device__ __forceinline__ unsigned cvtpk(float lo, float hi) { f32x2 v = {lo, hi}; bf16x2_t b = __builtin_convertvector(v, bf16x2_t); return __builtin_bit_cast(unsigned, b); }
; __device__ __forceinline__ float bflo(unsigned w) { return __uint_as_float(w << 16); }
; __device__ __forceinline__ float bfhi(unsigned w) { return __uint_as_float(w & 0xffff0000u); }
; __device__ __forceinline__ float fsilu(float x) { return x * fsigmoid(x); }
; __device__ __forceinline__ void c_unit(Frame& F, int L, int u, bool dry) {
;     ...
;         for (int i = 0; i < 46; ++i) {
;             const float h0 = bflo(hv[16 * sub + i]), h1 = bfhi(hv[16 * sub + i]);
; #pragma unroll
;             for (int t = 0; t < 16; ++t) { const int j = i - t; if (j >= 0 && j < CONVW) { acc[t].x = fmaf(h0, wv[j].x, acc[t].x); acc[t].y = fmaf(h1, wv[j].y, acc[t].y); } }
;         }
; #pragma unroll
;         for (int t = 0; t < 16; ++t) {
;             float s = acc[t].x + acc[t].y, qq = acc[t].x * acc[t].x + acc[t].y * acc[t].y;
;             s = half_wave_sum(s); qq = half_wave_sum(qq);
;             const float mu = __builtin_ldexpf(s, -6), rstd = rsqrtf(fmaxf(__builtin_ldexpf(qq, -6) - mu * mu, 0.f) + LN_EPS);
;             const float h0 = (acc[t].x - mu) * rstd * gv.x + bv.x, h1 = (acc[t].y - mu) * rstd * gv.y + bv.y;
;             const unsigned ov = cvtpk(fsilu(h0) * bflo(sc[16 * sub + t]), fsilu(h1) * bfhi(sc[16 * sub + t])); if (!dry) *(GAS unsigned*)(SCG + (size_t)(tb + t) * 512) = ov;
	v_add_f32_dpp v212, v212, v212 row_half_mirror row_mask:0xf bank_mask:0xf bound_ctrl:1
	v_add_f32_dpp v213, v213, v213 row_mirror row_mask:0xf bank_mask:0xf bound_ctrl:1
	v_mov_b32_e32 v214, v213
	s_nop 1
	v_permlane16_swap_b32 v213, v214
	v_add_f32_dpp v212, v212, v212 row_mirror row_mask:0xf bank_mask:0xf bound_ctrl:1
	v_add_f32_e32 v213, v213, v214
	v_mov_b32_e32 v214, v212
	s_nop 1
	v_permlane16_swap_b32 v212, v214
	s_nop 0
	v_add_f32_e32 v214, v212, v214
	v_ldexp_f32 v212, v213, -6
	v_ldexp_f32 v213, v214, -6
	v_fma_f32 v213, -v212, v212, v213
	v_max_f32_e32 v213, 0, v213
	v_add_f32_e32 v213, 0x3727c5ac, v213
	v_mul_f32_e32 v214, 0x4b800000, v213
	v_cmp_gt_f32_e32 vcc, s0, v213
	s_nop 1
	v_cndmask_b32_e32 v213, v213, v214, vcc
	v_rsq_f32_e32 v213, v213
	global_load_dword v214, v[90:91], off sc1
	v_pk_add_f32 v[208:209], v[208:209], v[212:213] op_sel_hi:[1,0] neg_lo:[0,1] neg_hi:[0,1]
	v_mul_f32_e32 v212, 0x45800000, v213
	v_cndmask_b32_e32 v212, v213, v212, vcc
	v_pk_mul_f32 v[208:209], v[208:209], v[212:213] op_sel_hi:[1,0]
	global_load_dword v212, v[88:89], off sc1
	v_pk_fma_f32 v[208:209], v[0:1], v[208:209], v[8:9]
	s_nop 0
	v_mul_f32_e32 v195, 0xbfb8aa3b, v208
	v_mul_f32_e32 v194, 0xbfb8aa3b, v209
	v_exp_f32_e32 v195, v195
	v_exp_f32_e32 v204, v194
	v_add_f32_e32 v194, 1.0, v195
	v_add_f32_e32 v195, 1.0, v204
	v_pk_fma_f32 v[204:205], v[210:211], v[66:67], v[78:79]
	v_rcp_f32_e32 v194, v194
	v_pk_fma_f32 v[204:205], v[206:207], v[68:69], v[204:205]
	v_rcp_f32_e32 v195, v195
	v_pk_fma_f32 v[204:205], v[200:201], v[70:71], v[204:205]
	v_pk_fma_f32 v[206:207], v[206:207], v[66:67], v[78:79]
	v_pk_fma_f32 v[204:205], v[198:199], v[72:73], v[204:205]
	v_pk_mul_f32 v[194:195], v[208:209], v[194:195]
	v_pk_fma_f32 v[204:205], v[196:197], v[36:37], v[204:205]
	v_lshlrev_b32_e32 v208, 16, v247
	v_pk_fma_f32 v[204:205], v[190:191], v[38:39], v[204:205]
	v_and_b32_e32 v209, 0xffff0000, v247
	v_pk_fma_f32 v[204:205], v[188:189], v[42:43], v[204:205]
	v_pk_mul_f32 v[194:195], v[194:195], v[208:209]
	v_pk_fma_f32 v[204:205], v[186:187], v[60:61], v[204:205]
	v_cvt_pk_bf16_f32 v194, v194, v195
	v_pk_fma_f32 v[204:205], v[184:185], v[44:45], v[204:205]
	global_store_dword v[180:181], v194, off
	v_pk_fma_f32 v[204:205], v[182:183], v[46:47], v[204:205]
	v_pk_fma_f32 v[206:207], v[200:201], v[68:69], v[206:207]
	v_pk_fma_f32 v[204:205], v[202:203], v[54:55], v[204:205]
	v_pk_fma_f32 v[206:207], v[198:199], v[70:71], v[206:207]
	v_pk_fma_f32 v[204:205], v[154:155], v[58:59], v[204:205]
	v_pk_fma_f32 v[206:207], v[196:197], v[72:73], v[206:207]
	v_pk_fma_f32 v[204:205], v[152:153], v[50:51], v[204:205]
	v_pk_fma_f32 v[206:207], v[190:191], v[36:37], v[206:207]
	v_pk_fma_f32 v[204:205], v[150:151], v[52:53], v[204:205]
	v_pk_fma_f32 v[206:207], v[188:189], v[38:39], v[206:207]
	v_pk_fma_f32 v[204:205], v[148:149], v[56:57], v[204:205]
	v_pk_fma_f32 v[206:207], v[186:187], v[42:43], v[206:207]
	v_pk_fma_f32 v[204:205], v[142:143], v[22:23], v[204:205]
	v_pk_fma_f32 v[206:207], v[184:185], v[60:61], v[206:207]
	v_pk_fma_f32 v[204:205], v[138:139], v[26:27], v[204:205]
	v_pk_fma_f32 v[206:207], v[182:183], v[44:45], v[206:207]
	v_pk_fma_f32 v[204:205], v[134:135], v[28:29], v[204:205]
	v_pk_fma_f32 v[206:207], v[202:203], v[46:47], v[206:207]
	v_pk_fma_f32 v[204:205], v[130:131], v[30:31], v[204:205]
	v_pk_fma_f32 v[206:207], v[154:155], v[54:55], v[206:207]
	v_pk_fma_f32 v[204:205], v[128:129], v[34:35], v[204:205]
	v_pk_fma_f32 v[206:207], v[152:153], v[58:59], v[206:207]
	v_pk_fma_f32 v[204:205], v[126:127], v[32:33], v[204:205]
	v_pk_fma_f32 v[206:207], v[150:151], v[50:51], v[206:207]
	v_pk_fma_f32 v[204:205], v[164:165], v[18:19], v[204:205]
	v_pk_fma_f32 v[206:207], v[148:149], v[52:53], v[206:207]
	v_pk_fma_f32 v[204:205], v[168:169], v[20:21], v[204:205]
	v_pk_fma_f32 v[206:207], v[142:143], v[56:57], v[206:207]
	v_pk_fma_f32 v[204:205], v[166:167], v[24:25], v[204:205]
	v_pk_fma_f32 v[206:207], v[138:139], v[22:23], v[206:207]
	v_pk_fma_f32 v[204:205], v[162:163], v[16:17], v[204:205]
	v_pk_fma_f32 v[206:207], v[134:135], v[26:27], v[206:207]
	v_pk_fma_f32 v[204:205], v[160:161], v[14:15], v[204:205]
	v_pk_fma_f32 v[206:207], v[130:131], v[28:29], v[206:207]
	v_pk_fma_f32 v[204:205], v[158:159], v[2:3], v[204:205]
	v_pk_fma_f32 v[206:207], v[128:129], v[30:31], v[206:207]
	v_pk_fma_f32 v[204:205], v[146:147], v[10:11], v[204:205]
	v_pk_fma_f32 v[206:207], v[126:127], v[34:35], v[206:207]
	v_pk_fma_f32 v[204:205], v[144:145], v[4:5], v[204:205]
	v_pk_fma_f32 v[206:207], v[164:165], v[32:33], v[206:207]
	v_pk_fma_f32 v[204:205], v[136:137], v[6:7], v[204:205]
	v_pk_fma_f32 v[206:207], v[168:169], v[18:19], v[206:207]
	v_pk_fma_f32 v[204:205], v[132:133], v[12:13], v[204:205]
	v_pk_fma_f32 v[206:207], v[166:167], v[20:21], v[206:207]
	v_add_f32_e32 v210, v204, v205
	v_pk_mul_f32 v[208:209], v[204:205], v[204:205]
	v_pk_fma_f32 v[206:207], v[162:163], v[24:25], v[206:207]
	v_add_f32_e32 v208, v208, v209
	v_add_f32_dpp v209, v210, v210 quad_perm:[1,0,3,2] row_mask:0xf bank_mask:0xf bound_ctrl:1
	v_pk_fma_f32 v[206:207], v[160:161], v[16:17], v[206:207]
	v_add_f32_dpp v208, v208, v208 quad_perm:[1,0,3,2] row_mask:0xf bank_mask:0xf bound_ctrl:1
	v_add_f32_dpp v209, v209, v209 quad_perm:[2,3,0,1] row_mask:0xf bank_mask:0xf bound_ctrl:1
	v_pk_fma_f32 v[206:207], v[158:159], v[14:15], v[206:207]
	v_add_f32_dpp v208, v208, v208 quad_perm:[2,3,0,1] row_mask:0xf bank_mask:0xf bound_ctrl:1
	v_add_f32_dpp v209, v209, v209 row_half_mirror row_mask:0xf bank_mask:0xf bound_ctrl:1
	global_load_dword v211, v[86:87], off sc1
; #define GAS __attribute__((address_space(1)))
; __device__ __forceinline__ unsigned cvtpk(float lo, float hi) { f32x2 v = {lo, hi}; bf16x2_t b = __builtin_convertvector(v, bf16x2_t); return __builtin_bit_cast(unsigned, b); }
; __device__ __forceinline__ float bflo(unsigned w) { return __uint_as_float(w << 16); }
; __device__ __forceinline__ float bfhi(unsigned w) { return __uint_as_float(w & 0xffff0000u); }
; __device__ __forceinline__ float fsilu(float x) { return x * fsigmoid(x); }
; __device__ __forceinline__ void c_unit(Frame& F, int L, int u, bool dry) {
;     ...
;         for (int i = 0; i < 46; ++i) {
;             const float h0 = bflo(hv[16 * sub + i]), h1 = bfhi(hv[16 * sub + i]);
; #pragma unroll
;             for (int t = 0; t < 16; ++t) { const int j = i - t; if (j >= 0 && j < CONVW) { acc[t].x = fmaf(h0, wv[j].x, acc[t].x); acc[t].y = fmaf(h1, wv[j].y, acc[t].y); } }
;         }
; #pragma unroll
;         for (int t = 0; t < 16; ++t) {
;             float s = acc[t].x + acc[t].y, qq = acc[t].x * acc[t].x + acc[t].y * acc[t].y;
;             s = half_wave_sum(s); qq = half_wave_sum(qq);
;             const float mu = __builtin_ldexpf(s, -6), rstd = rsqrtf(fmaxf(__builtin_ldexpf(qq, -6) - mu * mu, 0.f) + LN_EPS);
;             const float h0 = (acc[t].x - mu) * rstd * gv.x + bv.x, h1 = (acc[t].y - mu) * rstd * gv.y + bv.y;
;             const unsigned ov = cvtpk(fsilu(h0) * bflo(sc[16 * sub + t]), fsilu(h1) * bfhi(sc[16 * sub + t])); if (!dry) *(GAS unsigned*)(SCG + (size_t)(tb + t) * 512) = ov;
	v_add_f32_dpp v208, v208, v208 row_half_mirror row_mask:0xf bank_mask:0xf bound_ctrl:1
	v_add_f32_dpp v209, v209, v209 row_mirror row_mask:0xf bank_mask:0xf bound_ctrl:1
	v_mov_b32_e32 v210, v209
	s_nop 1
	v_permlane16_swap_b32 v209, v210
	v_add_f32_dpp v208, v208, v208 row_mirror row_mask:0xf bank_mask:0xf bound_ctrl:1
	v_add_f32_e32 v209, v209, v210
	v_mov_b32_e32 v210, v208
	s_nop 1
	v_permlane16_swap_b32 v208, v210
	v_ldexp_f32 v194, v209, -6
	v_add_f32_e32 v208, v208, v210
	v_ldexp_f32 v180, v208, -6
	v_fma_f32 v180, -v194, v194, v180
	v_max_f32_e32 v180, 0, v180
	v_add_f32_e32 v180, 0x3727c5ac, v180
	v_mul_f32_e32 v181, 0x4b800000, v180
	v_cmp_gt_f32_e32 vcc, s0, v180
	v_pk_add_f32 v[194:195], v[204:205], v[194:195] op_sel_hi:[1,0] neg_lo:[0,1] neg_hi:[0,1]
	v_lshlrev_b32_e32 v204, 16, v246
	v_cndmask_b32_e32 v181, v180, v181, vcc
	v_rsq_f32_e32 v208, v181
	global_load_dword v210, v[84:85], off sc1
	v_lshlrev_b32_e32 v180, 16, v239
	v_and_b32_e32 v181, 0xffff0000, v239
	v_mul_f32_e32 v205, 0x45800000, v208
	v_cndmask_b32_e32 v208, v208, v205, vcc
	v_pk_mul_f32 v[194:195], v[194:195], v[208:209] op_sel_hi:[1,0]
	s_nop 0
	v_pk_fma_f32 v[194:195], v[0:1], v[194:195], v[8:9]
	s_nop 0
	v_mul_f32_e32 v205, 0xbfb8aa3b, v194
	v_exp_f32_e32 v208, v205
	v_mul_f32_e32 v205, 0xbfb8aa3b, v195
	v_exp_f32_e32 v209, v205
	v_and_b32_e32 v205, 0xffff0000, v246
	v_add_f32_e32 v208, 1.0, v208
	v_rcp_f32_e32 v246, v208
	v_add_f32_e32 v208, 1.0, v209
	v_rcp_f32_e32 v247, v208
	global_load_dword v209, v[82:83], off sc1
	v_pk_mul_f32 v[194:195], v[194:195], v[246:247]
	s_nop 0
	v_pk_mul_f32 v[194:195], v[194:195], v[204:205]
	v_pk_fma_f32 v[204:205], v[146:147], v[2:3], v[206:207]
	s_nop 0
	v_pk_fma_f32 v[204:205], v[144:145], v[10:11], v[204:205]
	s_nop 0
	v_pk_fma_f32 v[204:205], v[136:137], v[4:5], v[204:205]
	s_nop 0
	v_pk_fma_f32 v[204:205], v[132:133], v[6:7], v[204:205]
	s_nop 0
	v_pk_fma_f32 v[204:205], v[124:125], v[12:13], v[204:205]
	s_nop 0
	v_add_f32_e32 v208, v204, v205
	v_pk_mul_f32 v[206:207], v[204:205], v[204:205]
	s_nop 0
	v_add_f32_e32 v206, v206, v207
	v_add_f32_dpp v207, v208, v208 quad_perm:[1,0,3,2] row_mask:0xf bank_mask:0xf bound_ctrl:1
	s_nop 0
	v_add_f32_dpp v206, v206, v206 quad_perm:[1,0,3,2] row_mask:0xf bank_mask:0xf bound_ctrl:1
	v_add_f32_dpp v207, v207, v207 quad_perm:[2,3,0,1] row_mask:0xf bank_mask:0xf bound_ctrl:1
	s_nop 0
	v_add_f32_dpp v206, v206, v206 quad_perm:[2,3,0,1] row_mask:0xf bank_mask:0xf bound_ctrl:1
	v_add_f32_dpp v207, v207, v207 row_half_mirror row_mask:0xf bank_mask:0xf bound_ctrl:1
	s_nop 0
	v_add_f32_dpp v206, v206, v206 row_half_mirror row_mask:0xf bank_mask:0xf bound_ctrl:1
	v_add_f32_dpp v207, v207, v207 row_mirror row_mask:0xf bank_mask:0xf bound_ctrl:1
	v_mov_b32_e32 v208, v207
	s_nop 1
	v_permlane16_swap_b32 v207, v208
	v_add_f32_dpp v206, v206, v206 row_mirror row_mask:0xf bank_mask:0xf bound_ctrl:1
	v_add_f32_e32 v207, v207, v208
	v_mov_b32_e32 v208, v206
	s_nop 1
	v_permlane16_swap_b32 v206, v208
	s_nop 0
	v_add_f32_e32 v208, v206, v208
	v_ldexp_f32 v206, v207, -6
	v_ldexp_f32 v207, v208, -6
	v_fma_f32 v207, -v206, v206, v207
	v_max_f32_e32 v207, 0, v207
	v_add_f32_e32 v207, 0x3727c5ac, v207
	v_mul_f32_e32 v208, 0x4b800000, v207
	v_cmp_gt_f32_e32 vcc, s0, v207
	s_nop 1
	v_cndmask_b32_e32 v207, v207, v208, vcc
	v_rsq_f32_e32 v207, v207
	global_load_dword v213, v[76:77], off sc1
	global_load_dword v208, v[74:75], off sc1
	v_pk_add_f32 v[204:205], v[204:205], v[206:207] op_sel_hi:[1,0] neg_lo:[0,1] neg_hi:[0,1]
	v_cvt_pk_bf16_f32 v206, v194, v195
	v_mul_f32_e32 v194, 0x45800000, v207
	v_cndmask_b32_e32 v194, v207, v194, vcc
	v_pk_mul_f32 v[194:195], v[204:205], v[194:195] op_sel_hi:[1,0]
	global_store_dword v[178:179], v206, off
	v_pk_fma_f32 v[194:195], v[0:1], v[194:195], v[8:9]
	s_nop 0
	v_mul_f32_e32 v204, 0xbfb8aa3b, v194
	v_mul_f32_e32 v205, 0xbfb8aa3b, v195
	v_exp_f32_e32 v204, v204
	v_exp_f32_e32 v205, v205
	v_add_f32_e32 v178, 1.0, v204
	v_add_f32_e32 v179, 1.0, v205
	v_rcp_f32_e32 v178, v178
	v_rcp_f32_e32 v179, v179
	global_load_dword v207, v[64:65], off sc1
	global_load_dword v206, v[62:63], off sc1
	global_load_dword v204, v[48:49], off sc1
	global_load_dword v205, v[40:41], off sc1
	v_pk_mul_f32 v[194:195], v[194:195], v[178:179]
	v_pk_fma_f32 v[178:179], v[200:201], v[66:67], v[78:79]
	v_pk_fma_f32 v[200:201], v[202:203], v[66:67], v[78:79]
	v_pk_fma_f32 v[178:179], v[198:199], v[68:69], v[178:179]
	v_pk_fma_f32 v[198:199], v[198:199], v[66:67], v[78:79]
	v_pk_fma_f32 v[178:179], v[196:197], v[70:71], v[178:179]
	v_pk_fma_f32 v[198:199], v[196:197], v[68:69], v[198:199]
	v_pk_fma_f32 v[178:179], v[190:191], v[72:73], v[178:179]
	v_pk_fma_f32 v[196:197], v[196:197], v[66:67], v[78:79]
	v_pk_fma_f32 v[178:179], v[188:189], v[36:37], v[178:179]
	v_pk_fma_f32 v[198:199], v[190:191], v[70:71], v[198:199]
	v_pk_fma_f32 v[178:179], v[186:187], v[38:39], v[178:179]
	v_pk_fma_f32 v[196:197], v[190:191], v[68:69], v[196:197]
	v_pk_fma_f32 v[178:179], v[184:185], v[42:43], v[178:179]
	v_pk_fma_f32 v[190:191], v[190:191], v[66:67], v[78:79]
	v_pk_fma_f32 v[178:179], v[182:183], v[60:61], v[178:179]
	v_pk_fma_f32 v[198:199], v[188:189], v[72:73], v[198:199]
	v_pk_fma_f32 v[196:197], v[188:189], v[70:71], v[196:197]
	v_pk_fma_f32 v[190:191], v[188:189], v[68:69], v[190:191]
	v_pk_fma_f32 v[188:189], v[188:189], v[66:67], v[78:79]
	v_pk_fma_f32 v[178:179], v[202:203], v[44:45], v[178:179]
	v_pk_fma_f32 v[196:197], v[186:187], v[72:73], v[196:197]
	v_pk_fma_f32 v[190:191], v[186:187], v[70:71], v[190:191]
	v_pk_fma_f32 v[188:189], v[186:187], v[68:69], v[188:189]
; __device__ __forceinline__ float bflo(unsigned w) { return __uint_as_float(w << 16); }
; __device__ __forceinline__ float bfhi(unsigned w) { return __uint_as_float(w & 0xffff0000u); }
; __device__ __forceinline__ void c_unit(Frame& F, int L, int u, bool dry) {
;     ...
;         for (int i = 0; i < 46; ++i) {
;             const float h0 = bflo(hv[16 * sub + i]), h1 = bfhi(hv[16 * sub + i]);
; #pragma unroll
;             for (int t = 0; t < 16; ++t) { const int j = i - t; if (j >= 0 && j < CONVW) { acc[t].x = fmaf(h0, wv[j].x, acc[t].x); acc[t].y = fmaf(h1, wv[j].y, acc[t].y); } }
	v_pk_fma_f32 v[198:199], v[186:187], v[36:37], v[198:199]
	v_pk_fma_f32 v[186:187], v[186:187], v[66:67], v[78:79]
	v_pk_fma_f32 v[178:179], v[154:155], v[46:47], v[178:179]
	v_pk_fma_f32 v[190:191], v[184:185], v[72:73], v[190:191]
	v_pk_fma_f32 v[188:189], v[184:185], v[70:71], v[188:189]
	v_pk_fma_f32 v[186:187], v[184:185], v[68:69], v[186:187]
	v_pk_fma_f32 v[198:199], v[184:185], v[38:39], v[198:199]
	v_pk_fma_f32 v[196:197], v[184:185], v[36:37], v[196:197]
	v_pk_fma_f32 v[184:185], v[184:185], v[66:67], v[78:79]
	v_pk_fma_f32 v[178:179], v[152:153], v[54:55], v[178:179]
	v_pk_fma_f32 v[188:189], v[182:183], v[72:73], v[188:189]
	v_pk_fma_f32 v[186:187], v[182:183], v[70:71], v[186:187]
	v_pk_fma_f32 v[184:185], v[182:183], v[68:69], v[184:185]
	v_pk_fma_f32 v[198:199], v[182:183], v[42:43], v[198:199]
	v_pk_fma_f32 v[196:197], v[182:183], v[38:39], v[196:197]
	v_pk_fma_f32 v[190:191], v[182:183], v[36:37], v[190:191]
	v_pk_fma_f32 v[182:183], v[182:183], v[66:67], v[78:79]
	v_pk_fma_f32 v[178:179], v[150:151], v[58:59], v[178:179]
	v_pk_fma_f32 v[182:183], v[202:203], v[68:69], v[182:183]
	v_pk_fma_f32 v[178:179], v[148:149], v[50:51], v[178:179]
	v_pk_fma_f32 v[182:183], v[154:155], v[70:71], v[182:183]
	v_pk_fma_f32 v[178:179], v[142:143], v[52:53], v[178:179]
	v_pk_fma_f32 v[182:183], v[152:153], v[72:73], v[182:183]
	v_pk_fma_f32 v[178:179], v[138:139], v[56:57], v[178:179]
	v_pk_fma_f32 v[182:183], v[150:151], v[36:37], v[182:183]
	v_pk_fma_f32 v[178:179], v[134:135], v[22:23], v[178:179]
	v_pk_fma_f32 v[182:183], v[148:149], v[38:39], v[182:183]
	v_pk_fma_f32 v[178:179], v[130:131], v[26:27], v[178:179]
	v_pk_fma_f32 v[198:199], v[202:203], v[60:61], v[198:199]
	v_pk_fma_f32 v[182:183], v[142:143], v[42:43], v[182:183]
	v_pk_fma_f32 v[178:179], v[128:129], v[28:29], v[178:179]
	v_pk_fma_f32 v[198:199], v[154:155], v[44:45], v[198:199]
	v_pk_fma_f32 v[182:183], v[138:139], v[60:61], v[182:183]
	v_pk_fma_f32 v[178:179], v[126:127], v[30:31], v[178:179]
	v_pk_fma_f32 v[198:199], v[152:153], v[46:47], v[198:199]
	v_pk_fma_f32 v[182:183], v[134:135], v[44:45], v[182:183]
	v_pk_fma_f32 v[178:179], v[164:165], v[34:35], v[178:179]
	v_pk_fma_f32 v[198:199], v[150:151], v[54:55], v[198:199]
	v_pk_fma_f32 v[182:183], v[130:131], v[46:47], v[182:183]
	v_pk_fma_f32 v[178:179], v[168:169], v[32:33], v[178:179]
	v_pk_fma_f32 v[198:199], v[148:149], v[58:59], v[198:199]
	v_pk_fma_f32 v[182:183], v[128:129], v[54:55], v[182:183]
	v_pk_fma_f32 v[178:179], v[166:167], v[18:19], v[178:179]
	v_pk_fma_f32 v[200:201], v[154:155], v[68:69], v[200:201]
	v_pk_fma_f32 v[198:199], v[142:143], v[50:51], v[198:199]
	v_pk_fma_f32 v[182:183], v[126:127], v[58:59], v[182:183]
	v_pk_fma_f32 v[178:179], v[162:163], v[20:21], v[178:179]
	v_pk_fma_f32 v[200:201], v[152:153], v[70:71], v[200:201]
	v_pk_fma_f32 v[198:199], v[138:139], v[52:53], v[198:199]
	v_pk_fma_f32 v[182:183], v[164:165], v[50:51], v[182:183]
	v_pk_fma_f32 v[178:179], v[160:161], v[24:25], v[178:179]
	v_pk_fma_f32 v[200:201], v[150:151], v[72:73], v[200:201]
	v_pk_fma_f32 v[198:199], v[134:135], v[56:57], v[198:199]
	v_pk_fma_f32 v[182:183], v[168:169], v[52:53], v[182:183]
	v_pk_fma_f32 v[178:179], v[158:159], v[16:17], v[178:179]
	v_pk_fma_f32 v[246:247], v[166:167], v[56:57], v[182:183]
	v_pk_fma_f32 v[182:183], v[148:149], v[36:37], v[200:201]
	v_pk_fma_f32 v[200:201], v[146:147], v[14:15], v[178:179]
	v_pk_fma_f32 v[178:179], v[130:131], v[22:23], v[198:199]
	v_pk_fma_f32 v[196:197], v[202:203], v[42:43], v[196:197]
	v_pk_fma_f32 v[178:179], v[128:129], v[26:27], v[178:179]
	v_pk_fma_f32 v[196:197], v[154:155], v[60:61], v[196:197]
	v_pk_fma_f32 v[178:179], v[126:127], v[28:29], v[178:179]
	v_pk_fma_f32 v[196:197], v[152:153], v[44:45], v[196:197]
	v_pk_fma_f32 v[178:179], v[164:165], v[30:31], v[178:179]
	v_pk_fma_f32 v[196:197], v[150:151], v[46:47], v[196:197]
	v_pk_fma_f32 v[178:179], v[168:169], v[34:35], v[178:179]
	v_pk_fma_f32 v[196:197], v[148:149], v[54:55], v[196:197]
	v_pk_fma_f32 v[178:179], v[166:167], v[32:33], v[178:179]
	v_pk_fma_f32 v[196:197], v[142:143], v[58:59], v[196:197]
	v_pk_fma_f32 v[178:179], v[162:163], v[18:19], v[178:179]
	v_pk_fma_f32 v[196:197], v[138:139], v[50:51], v[196:197]
	v_pk_fma_f32 v[178:179], v[160:161], v[20:21], v[178:179]
	v_pk_fma_f32 v[196:197], v[134:135], v[52:53], v[196:197]
	v_pk_fma_f32 v[178:179], v[158:159], v[24:25], v[178:179]
	v_pk_fma_f32 v[196:197], v[130:131], v[56:57], v[196:197]
	v_pk_fma_f32 v[178:179], v[146:147], v[16:17], v[178:179]
	v_pk_fma_f32 v[190:191], v[202:203], v[38:39], v[190:191]
	v_pk_fma_f32 v[198:199], v[144:145], v[14:15], v[178:179]
	v_pk_fma_f32 v[178:179], v[128:129], v[22:23], v[196:197]
	v_pk_fma_f32 v[190:191], v[154:155], v[42:43], v[190:191]
	v_pk_fma_f32 v[178:179], v[126:127], v[26:27], v[178:179]
	v_pk_fma_f32 v[190:191], v[152:153], v[60:61], v[190:191]
	v_pk_fma_f32 v[178:179], v[164:165], v[28:29], v[178:179]
	v_pk_fma_f32 v[190:191], v[150:151], v[44:45], v[190:191]
	v_pk_fma_f32 v[178:179], v[168:169], v[30:31], v[178:179]
	v_pk_fma_f32 v[190:191], v[148:149], v[46:47], v[190:191]
	v_pk_fma_f32 v[178:179], v[166:167], v[34:35], v[178:179]
	v_pk_fma_f32 v[190:191], v[142:143], v[54:55], v[190:191]
	v_pk_fma_f32 v[178:179], v[162:163], v[32:33], v[178:179]
	v_pk_fma_f32 v[190:191], v[138:139], v[58:59], v[190:191]
	v_pk_fma_f32 v[178:179], v[160:161], v[18:19], v[178:179]
	v_pk_fma_f32 v[190:191], v[134:135], v[50:51], v[190:191]
	v_pk_fma_f32 v[178:179], v[158:159], v[20:21], v[178:179]
	v_pk_fma_f32 v[184:185], v[202:203], v[70:71], v[184:185]
	v_pk_fma_f32 v[190:191], v[130:131], v[52:53], v[190:191]
; #define GAS __attribute__((address_space(1)))
; __device__ __forceinline__ unsigned cvtpk(float lo, float hi) { f32x2 v = {lo, hi}; bf16x2_t b = __builtin_convertvector(v, bf16x2_t); return __builtin_bit_cast(unsigned, b); }
; __device__ __forceinline__ float bflo(unsigned w) { return __uint_as_float(w << 16); }
; __device__ __forceinline__ float bfhi(unsigned w) { return __uint_as_float(w & 0xffff0000u); }
; __device__ __forceinline__ float fsilu(float x) { return x * fsigmoid(x); }
; __device__ __forceinline__ void c_unit(Frame& F, int L, int u, bool dry) {
;     ...
; #pragma unroll
;         for (int t = 0; t < 16; ++t) {
;             float s = acc[t].x + acc[t].y, qq = acc[t].x * acc[t].x + acc[t].y * acc[t].y;
;             s = half_wave_sum(s); qq = half_wave_sum(qq);
;             const float mu = __builtin_ldexpf(s, -6), rstd = rsqrtf(fmaxf(__builtin_ldexpf(qq, -6) - mu * mu, 0.f) + LN_EPS);
;             const float h0 = (acc[t].x - mu) * rstd * gv.x + bv.x, h1 = (acc[t].y - mu) * rstd * gv.y + bv.y;
;             const unsigned ov = cvtpk(fsilu(h0) * bflo(sc[16 * sub + t]), fsilu(h1) * bfhi(sc[16 * sub + t])); if (!dry) *(GAS unsigned*)(SCG + (size_t)(tb + t) * 512) = ov;
	v_pk_fma_f32 v[178:179], v[146:147], v[24:25], v[178:179]
	v_pk_fma_f32 v[184:185], v[154:155], v[72:73], v[184:185]
	v_pk_fma_f32 v[188:189], v[202:203], v[36:37], v[188:189]
	v_pk_fma_f32 v[190:191], v[128:129], v[56:57], v[190:191]
	v_pk_fma_f32 v[178:179], v[144:145], v[16:17], v[178:179]
	v_pk_fma_f32 v[188:189], v[154:155], v[38:39], v[188:189]
	v_pk_fma_f32 v[184:185], v[152:153], v[36:37], v[184:185]
	v_pk_fma_f32 v[196:197], v[136:137], v[14:15], v[178:179]
	v_pk_fma_f32 v[178:179], v[126:127], v[22:23], v[190:191]
	v_pk_fma_f32 v[188:189], v[152:153], v[42:43], v[188:189]
	v_pk_fma_f32 v[184:185], v[150:151], v[38:39], v[184:185]
	v_pk_fma_f32 v[178:179], v[164:165], v[26:27], v[178:179]
	v_pk_fma_f32 v[188:189], v[150:151], v[60:61], v[188:189]
	v_pk_fma_f32 v[184:185], v[148:149], v[42:43], v[184:185]
	v_pk_fma_f32 v[178:179], v[168:169], v[28:29], v[178:179]
	v_pk_fma_f32 v[188:189], v[148:149], v[44:45], v[188:189]
	v_pk_fma_f32 v[184:185], v[142:143], v[60:61], v[184:185]
	v_pk_fma_f32 v[178:179], v[166:167], v[30:31], v[178:179]
	v_pk_fma_f32 v[188:189], v[142:143], v[46:47], v[188:189]
	v_pk_fma_f32 v[184:185], v[138:139], v[44:45], v[184:185]
	v_pk_fma_f32 v[178:179], v[162:163], v[34:35], v[178:179]
	v_pk_fma_f32 v[188:189], v[138:139], v[54:55], v[188:189]
	v_pk_fma_f32 v[184:185], v[134:135], v[46:47], v[184:185]
	v_pk_fma_f32 v[178:179], v[160:161], v[32:33], v[178:179]
	v_pk_fma_f32 v[188:189], v[134:135], v[58:59], v[188:189]
	v_pk_fma_f32 v[184:185], v[130:131], v[54:55], v[184:185]
	v_pk_fma_f32 v[178:179], v[158:159], v[18:19], v[178:179]
	v_pk_fma_f32 v[188:189], v[130:131], v[50:51], v[188:189]
	v_pk_fma_f32 v[184:185], v[128:129], v[58:59], v[184:185]
	v_pk_fma_f32 v[178:179], v[146:147], v[20:21], v[178:179]
	v_pk_fma_f32 v[188:189], v[128:129], v[52:53], v[188:189]
	v_pk_fma_f32 v[184:185], v[126:127], v[50:51], v[184:185]
	v_pk_fma_f32 v[178:179], v[144:145], v[24:25], v[178:179]
	v_pk_fma_f32 v[188:189], v[126:127], v[56:57], v[188:189]
	v_pk_fma_f32 v[184:185], v[164:165], v[52:53], v[184:185]
	v_pk_fma_f32 v[178:179], v[136:137], v[16:17], v[178:179]
	v_pk_fma_f32 v[186:187], v[202:203], v[72:73], v[186:187]
	v_pk_fma_f32 v[202:203], v[168:169], v[56:57], v[184:185]
	v_pk_fma_f32 v[184:185], v[132:133], v[14:15], v[178:179]
	v_pk_fma_f32 v[178:179], v[164:165], v[22:23], v[188:189]
	v_pk_mul_f32 v[188:189], v[194:195], v[244:245]
	v_pk_fma_f32 v[186:187], v[154:155], v[36:37], v[186:187]
	v_cvt_pk_bf16_f32 v188, v188, v189
	global_store_dword v[176:177], v188, off
	v_pk_fma_f32 v[176:177], v[144:145], v[2:3], v[200:201]
	v_pk_fma_f32 v[186:187], v[152:153], v[38:39], v[186:187]
	v_pk_fma_f32 v[176:177], v[136:137], v[10:11], v[176:177]
	v_pk_fma_f32 v[186:187], v[150:151], v[42:43], v[186:187]
	v_pk_fma_f32 v[176:177], v[132:133], v[4:5], v[176:177]
	v_pk_fma_f32 v[186:187], v[148:149], v[60:61], v[186:187]
	v_pk_fma_f32 v[176:177], v[124:125], v[6:7], v[176:177]
	v_pk_fma_f32 v[186:187], v[142:143], v[44:45], v[186:187]
	v_pk_fma_f32 v[176:177], v[118:119], v[12:13], v[176:177]
	v_pk_fma_f32 v[186:187], v[138:139], v[46:47], v[186:187]
	v_add_f32_e32 v194, v176, v177
	v_pk_mul_f32 v[190:191], v[176:177], v[176:177]
	v_pk_fma_f32 v[186:187], v[134:135], v[54:55], v[186:187]
	v_add_f32_e32 v190, v190, v191
	v_add_f32_dpp v191, v194, v194 quad_perm:[1,0,3,2] row_mask:0xf bank_mask:0xf bound_ctrl:1
	v_pk_fma_f32 v[186:187], v[130:131], v[58:59], v[186:187]
	v_add_f32_dpp v190, v190, v190 quad_perm:[1,0,3,2] row_mask:0xf bank_mask:0xf bound_ctrl:1
	v_add_f32_dpp v191, v191, v191 quad_perm:[2,3,0,1] row_mask:0xf bank_mask:0xf bound_ctrl:1
	v_pk_fma_f32 v[186:187], v[128:129], v[50:51], v[186:187]
	v_add_f32_dpp v190, v190, v190 quad_perm:[2,3,0,1] row_mask:0xf bank_mask:0xf bound_ctrl:1
	v_add_f32_dpp v191, v191, v191 row_half_mirror row_mask:0xf bank_mask:0xf bound_ctrl:1
	v_pk_fma_f32 v[186:187], v[126:127], v[52:53], v[186:187]
	v_add_f32_dpp v190, v190, v190 row_half_mirror row_mask:0xf bank_mask:0xf bound_ctrl:1
	v_add_f32_dpp v191, v191, v191 row_mirror row_mask:0xf bank_mask:0xf bound_ctrl:1
	v_mov_b32_e32 v194, v191
	s_nop 1
	v_permlane16_swap_b32 v191, v194
	v_add_f32_dpp v190, v190, v190 row_mirror row_mask:0xf bank_mask:0xf bound_ctrl:1
	v_add_f32_e32 v191, v191, v194
	v_mov_b32_e32 v194, v190
	s_nop 1
	v_permlane16_swap_b32 v190, v194
	v_pk_fma_f32 v[186:187], v[164:165], v[56:57], v[186:187]
	v_add_f32_e32 v194, v190, v194
	v_ldexp_f32 v190, v191, -6
	v_ldexp_f32 v191, v194, -6
	v_fma_f32 v191, -v190, v190, v191
	v_max_f32_e32 v191, 0, v191
	v_add_f32_e32 v191, 0x3727c5ac, v191
	v_pk_fma_f32 v[186:187], v[168:169], v[22:23], v[186:187]
	s_waitcnt vmcnt(29)
; #define GAS __attribute__((address_space(1)))
; __device__ __forceinline__ unsigned cvtpk(float lo, float hi) { f32x2 v = {lo, hi}; bf16x2_t b = __builtin_convertvector(v, bf16x2_t); return __builtin_bit_cast(unsigned, b); }
; __device__ __forceinline__ float bflo(unsigned w) { return __uint_as_float(w << 16); }
; __device__ __forceinline__ float bfhi(unsigned w) { return __uint_as_float(w & 0xffff0000u); }
; __device__ __forceinline__ float fsilu(float x) { return x * fsigmoid(x); }
; __device__ __forceinline__ void c_unit(Frame& F, int L, int u, bool dry) {
;     ...
; #pragma unroll
;         for (int t = 0; t < 16; ++t) {
;             float s = acc[t].x + acc[t].y, qq = acc[t].x * acc[t].x + acc[t].y * acc[t].y;
;             s = half_wave_sum(s); qq = half_wave_sum(qq);
;             const float mu = __builtin_ldexpf(s, -6), rstd = rsqrtf(fmaxf(__builtin_ldexpf(qq, -6) - mu * mu, 0.f) + LN_EPS);
;             const float h0 = (acc[t].x - mu) * rstd * gv.x + bv.x, h1 = (acc[t].y - mu) * rstd * gv.y + bv.y;
;             const unsigned ov = cvtpk(fsilu(h0) * bflo(sc[16 * sub + t]), fsilu(h1) * bfhi(sc[16 * sub + t])); if (!dry) *(GAS unsigned*)(SCG + (size_t)(tb + t) * 512) = ov;
	v_lshlrev_b32_e32 v188, 16, v240
	v_rsq_f32_e32 v191, v191
	v_pk_fma_f32 v[186:187], v[166:167], v[26:27], v[186:187]
	v_and_b32_e32 v189, 0xffff0000, v240
	v_pk_fma_f32 v[186:187], v[162:163], v[28:29], v[186:187]
	v_mov_b32_e32 v194, v191
	v_pk_add_f32 v[176:177], v[176:177], v[190:191] op_sel_hi:[1,0] neg_lo:[0,1] neg_hi:[0,1]
	v_pk_fma_f32 v[186:187], v[160:161], v[30:31], v[186:187]
	v_pk_mul_f32 v[176:177], v[176:177], v[194:195] op_sel_hi:[1,0]
	v_pk_fma_f32 v[186:187], v[158:159], v[34:35], v[186:187]
	v_pk_fma_f32 v[190:191], v[0:1], v[176:177], v[8:9]
	v_pk_fma_f32 v[186:187], v[146:147], v[32:33], v[186:187]
	v_mul_f32_e32 v176, 0xbfb8aa3b, v190
	v_exp_f32_e32 v194, v176
	v_mul_f32_e32 v176, 0xbfb8aa3b, v191
	v_exp_f32_e32 v195, v176
	v_pk_fma_f32 v[186:187], v[144:145], v[18:19], v[186:187]
	v_pk_fma_f32 v[184:185], v[124:125], v[2:3], v[184:185]
	v_pk_fma_f32 v[176:177], v[136:137], v[20:21], v[186:187]
	v_add_f32_e32 v186, 1.0, v194
	v_add_f32_e32 v187, 1.0, v195
	v_rcp_f32_e32 v186, v186
	v_rcp_f32_e32 v187, v187
	v_pk_fma_f32 v[184:185], v[118:119], v[10:11], v[184:185]
	v_pk_fma_f32 v[178:179], v[168:169], v[26:27], v[178:179]
	v_pk_fma_f32 v[184:185], v[112:113], v[4:5], v[184:185]
	v_pk_mul_f32 v[186:187], v[190:191], v[186:187]
	v_pk_fma_f32 v[184:185], v[110:111], v[6:7], v[184:185]
	v_pk_mul_f32 v[186:187], v[186:187], v[188:189]
	v_pk_fma_f32 v[188:189], v[166:167], v[22:23], v[202:203]
	v_cvt_pk_bf16_f32 v186, v186, v187
	global_store_dword v[174:175], v186, off
	v_pk_fma_f32 v[174:175], v[136:137], v[2:3], v[198:199]
	v_pk_fma_f32 v[188:189], v[162:163], v[26:27], v[188:189]
	v_pk_fma_f32 v[174:175], v[132:133], v[10:11], v[174:175]
	v_pk_fma_f32 v[188:189], v[160:161], v[28:29], v[188:189]
	v_pk_fma_f32 v[174:175], v[124:125], v[4:5], v[174:175]
	v_pk_fma_f32 v[188:189], v[158:159], v[30:31], v[188:189]
	v_pk_fma_f32 v[174:175], v[118:119], v[6:7], v[174:175]
	v_pk_fma_f32 v[188:189], v[146:147], v[34:35], v[188:189]
	v_pk_fma_f32 v[174:175], v[112:113], v[12:13], v[174:175]
	v_pk_fma_f32 v[188:189], v[144:145], v[32:33], v[188:189]
	v_add_f32_e32 v194, v174, v175
	v_pk_mul_f32 v[190:191], v[174:175], v[174:175]
	v_pk_fma_f32 v[188:189], v[136:137], v[18:19], v[188:189]
	v_add_f32_e32 v190, v190, v191
	v_add_f32_dpp v191, v194, v194 quad_perm:[1,0,3,2] row_mask:0xf bank_mask:0xf bound_ctrl:1
	s_waitcnt vmcnt(29)
	v_lshlrev_b32_e32 v186, 16, v251
	v_add_f32_dpp v190, v190, v190 quad_perm:[1,0,3,2] row_mask:0xf bank_mask:0xf bound_ctrl:1
	v_add_f32_dpp v191, v191, v191 quad_perm:[2,3,0,1] row_mask:0xf bank_mask:0xf bound_ctrl:1
	v_and_b32_e32 v187, 0xffff0000, v251
	v_add_f32_dpp v190, v190, v190 quad_perm:[2,3,0,1] row_mask:0xf bank_mask:0xf bound_ctrl:1
	v_add_f32_dpp v191, v191, v191 row_half_mirror row_mask:0xf bank_mask:0xf bound_ctrl:1
	v_pk_fma_f32 v[184:185], v[108:109], v[12:13], v[184:185]
	v_add_f32_dpp v190, v190, v190 row_half_mirror row_mask:0xf bank_mask:0xf bound_ctrl:1
	v_add_f32_dpp v191, v191, v191 row_mirror row_mask:0xf bank_mask:0xf bound_ctrl:1
	v_mov_b32_e32 v194, v191
	s_nop 1
	v_permlane16_swap_b32 v191, v194
	v_add_f32_dpp v190, v190, v190 row_mirror row_mask:0xf bank_mask:0xf bound_ctrl:1
	v_add_f32_e32 v191, v191, v194
	v_mov_b32_e32 v194, v190
	s_nop 1
	v_permlane16_swap_b32 v190, v194
	v_pk_fma_f32 v[178:179], v[166:167], v[28:29], v[178:179]
	v_add_f32_e32 v194, v190, v194
	v_ldexp_f32 v190, v191, -6
	v_ldexp_f32 v191, v194, -6
	v_fma_f32 v191, -v190, v190, v191
	v_max_f32_e32 v191, 0, v191
	v_add_f32_e32 v191, 0x3727c5ac, v191
	v_pk_fma_f32 v[178:179], v[162:163], v[30:31], v[178:179]
	v_pk_fma_f32 v[176:177], v[132:133], v[24:25], v[176:177]
	v_rsq_f32_e32 v191, v191
	v_pk_fma_f32 v[178:179], v[160:161], v[34:35], v[178:179]
	v_pk_fma_f32 v[176:177], v[124:125], v[16:17], v[176:177]
	v_pk_fma_f32 v[178:179], v[158:159], v[32:33], v[178:179]
	v_mov_b32_e32 v194, v191
	v_pk_add_f32 v[174:175], v[174:175], v[190:191] op_sel_hi:[1,0] neg_lo:[0,1] neg_hi:[0,1]
	v_pk_fma_f32 v[178:179], v[146:147], v[18:19], v[178:179]
	v_pk_mul_f32 v[174:175], v[174:175], v[194:195] op_sel_hi:[1,0]
	v_pk_fma_f32 v[178:179], v[144:145], v[20:21], v[178:179]
	v_pk_fma_f32 v[190:191], v[0:1], v[174:175], v[8:9]
	v_pk_fma_f32 v[178:179], v[136:137], v[24:25], v[178:179]
	v_mul_f32_e32 v174, 0xbfb8aa3b, v190
	v_exp_f32_e32 v194, v174
	v_mul_f32_e32 v174, 0xbfb8aa3b, v191
	v_exp_f32_e32 v195, v174
	v_pk_fma_f32 v[174:175], v[132:133], v[20:21], v[188:189]
	v_add_f32_e32 v188, 1.0, v194
	v_rcp_f32_e32 v188, v188
	v_add_f32_e32 v189, 1.0, v195
	v_rcp_f32_e32 v189, v189
	v_pk_fma_f32 v[178:179], v[132:133], v[16:17], v[178:179]
	v_pk_fma_f32 v[176:177], v[118:119], v[14:15], v[176:177]
	v_pk_fma_f32 v[178:179], v[124:125], v[14:15], v[178:179]
	v_pk_mul_f32 v[188:189], v[190:191], v[188:189]
	v_pk_fma_f32 v[178:179], v[118:119], v[2:3], v[178:179]
	v_pk_mul_f32 v[186:187], v[188:189], v[186:187]
	v_pk_fma_f32 v[188:189], v[162:163], v[22:23], v[246:247]
	v_cvt_pk_bf16_f32 v186, v186, v187
	global_store_dword v[172:173], v186, off
	v_pk_fma_f32 v[172:173], v[132:133], v[2:3], v[196:197]
	v_pk_fma_f32 v[188:189], v[160:161], v[26:27], v[188:189]
	v_pk_fma_f32 v[172:173], v[124:125], v[10:11], v[172:173]
	v_pk_fma_f32 v[188:189], v[158:159], v[28:29], v[188:189]
	v_pk_fma_f32 v[172:173], v[118:119], v[4:5], v[172:173]
	v_pk_fma_f32 v[188:189], v[146:147], v[30:31], v[188:189]
	v_pk_fma_f32 v[172:173], v[112:113], v[6:7], v[172:173]
	v_pk_fma_f32 v[188:189], v[144:145], v[34:35], v[188:189]
	v_pk_fma_f32 v[172:173], v[110:111], v[12:13], v[172:173]
	v_pk_fma_f32 v[188:189], v[136:137], v[32:33], v[188:189]
	v_add_f32_e32 v194, v172, v173
	v_pk_mul_f32 v[190:191], v[172:173], v[172:173]
	v_pk_fma_f32 v[188:189], v[132:133], v[18:19], v[188:189]
	v_add_f32_e32 v190, v190, v191
	v_add_f32_dpp v191, v194, v194 quad_perm:[1,0,3,2] row_mask:0xf bank_mask:0xf bound_ctrl:1
	s_waitcnt vmcnt(29)
; #define GAS __attribute__((address_space(1)))
; __device__ __forceinline__ unsigned cvtpk(float lo, float hi) { f32x2 v = {lo, hi}; bf16x2_t b = __builtin_convertvector(v, bf16x2_t); return __builtin_bit_cast(unsigned, b); }
; __device__ __forceinline__ float bflo(unsigned w) { return __uint_as_float(w << 16); }
; __device__ __forceinline__ float bfhi(unsigned w) { return __uint_as_float(w & 0xffff0000u); }
; __device__ __forceinline__ float fsilu(float x) { return x * fsigmoid(x); }
; __device__ __forceinline__ void c_unit(Frame& F, int L, int u, bool dry) {
;     ...
; #pragma unroll
;         for (int t = 0; t < 16; ++t) {
;             float s = acc[t].x + acc[t].y, qq = acc[t].x * acc[t].x + acc[t].y * acc[t].y;
;             s = half_wave_sum(s); qq = half_wave_sum(qq);
;             const float mu = __builtin_ldexpf(s, -6), rstd = rsqrtf(fmaxf(__builtin_ldexpf(qq, -6) - mu * mu, 0.f) + LN_EPS);
;             const float h0 = (acc[t].x - mu) * rstd * gv.x + bv.x, h1 = (acc[t].y - mu) * rstd * gv.y + bv.y;
;             const unsigned ov = cvtpk(fsilu(h0) * bflo(sc[16 * sub + t]), fsilu(h1) * bfhi(sc[16 * sub + t])); if (!dry) *(GAS unsigned*)(SCG + (size_t)(tb + t) * 512) = ov;
	v_lshlrev_b32_e32 v186, 16, v242
	v_add_f32_dpp v190, v190, v190 quad_perm:[1,0,3,2] row_mask:0xf bank_mask:0xf bound_ctrl:1
	v_add_f32_dpp v191, v191, v191 quad_perm:[2,3,0,1] row_mask:0xf bank_mask:0xf bound_ctrl:1
	v_and_b32_e32 v187, 0xffff0000, v242
	v_add_f32_dpp v190, v190, v190 quad_perm:[2,3,0,1] row_mask:0xf bank_mask:0xf bound_ctrl:1
	v_add_f32_dpp v191, v191, v191 row_half_mirror row_mask:0xf bank_mask:0xf bound_ctrl:1
	v_pk_fma_f32 v[178:179], v[112:113], v[10:11], v[178:179]
	v_add_f32_dpp v190, v190, v190 row_half_mirror row_mask:0xf bank_mask:0xf bound_ctrl:1
	v_add_f32_dpp v191, v191, v191 row_mirror row_mask:0xf bank_mask:0xf bound_ctrl:1
	v_mov_b32_e32 v194, v191
	s_nop 1
	v_permlane16_swap_b32 v191, v194
	v_add_f32_dpp v190, v190, v190 row_mirror row_mask:0xf bank_mask:0xf bound_ctrl:1
	v_add_f32_e32 v191, v191, v194
	v_mov_b32_e32 v194, v190
	s_nop 1
	v_permlane16_swap_b32 v190, v194
	v_pk_fma_f32 v[178:179], v[110:111], v[4:5], v[178:179]
	v_add_f32_e32 v194, v190, v194
	v_ldexp_f32 v190, v191, -6
	v_ldexp_f32 v191, v194, -6
	v_fma_f32 v191, -v190, v190, v191
	v_max_f32_e32 v191, 0, v191
	v_add_f32_e32 v191, 0x3727c5ac, v191
	v_pk_fma_f32 v[178:179], v[108:109], v[6:7], v[178:179]
	v_pk_fma_f32 v[176:177], v[112:113], v[2:3], v[176:177]
	v_rsq_f32_e32 v191, v191
	v_pk_fma_f32 v[178:179], v[102:103], v[12:13], v[178:179]
	v_pk_fma_f32 v[176:177], v[110:111], v[10:11], v[176:177]
	v_pk_fma_f32 v[174:175], v[124:125], v[24:25], v[174:175]
	v_mov_b32_e32 v194, v191
	v_pk_add_f32 v[172:173], v[172:173], v[190:191] op_sel_hi:[1,0] neg_lo:[0,1] neg_hi:[0,1]
	v_pk_fma_f32 v[176:177], v[108:109], v[4:5], v[176:177]
	v_pk_mul_f32 v[172:173], v[172:173], v[194:195] op_sel_hi:[1,0]
	v_pk_fma_f32 v[176:177], v[102:103], v[6:7], v[176:177]
	v_pk_fma_f32 v[190:191], v[0:1], v[172:173], v[8:9]
	v_pk_fma_f32 v[176:177], v[106:107], v[12:13], v[176:177]
	v_mul_f32_e32 v172, 0xbfb8aa3b, v190
	v_exp_f32_e32 v194, v172
	v_mul_f32_e32 v172, 0xbfb8aa3b, v191
	v_exp_f32_e32 v195, v172
	v_pk_fma_f32 v[172:173], v[124:125], v[20:21], v[188:189]
	v_add_f32_e32 v188, 1.0, v194
	v_rcp_f32_e32 v188, v188
	v_add_f32_e32 v189, 1.0, v195
	v_rcp_f32_e32 v189, v189
	v_pk_fma_f32 v[174:175], v[118:119], v[16:17], v[174:175]
	v_pk_fma_f32 v[172:173], v[118:119], v[24:25], v[172:173]
	v_pk_fma_f32 v[174:175], v[112:113], v[14:15], v[174:175]
	v_pk_mul_f32 v[188:189], v[190:191], v[188:189]
	v_add_f32_e32 v190, v178, v179
	v_pk_mul_f32 v[186:187], v[188:189], v[186:187]
	v_add_f32_e32 v188, v184, v185
	v_cvt_pk_bf16_f32 v186, v186, v187
	global_store_dword v[170:171], v186, off
	v_pk_mul_f32 v[186:187], v[184:185], v[184:185]
	s_waitcnt vmcnt(29)
	v_lshlrev_b32_e32 v170, 16, v243
	v_add_f32_e32 v186, v186, v187
	v_add_f32_dpp v187, v188, v188 quad_perm:[1,0,3,2] row_mask:0xf bank_mask:0xf bound_ctrl:1
	v_and_b32_e32 v171, 0xffff0000, v243
	v_add_f32_dpp v186, v186, v186 quad_perm:[1,0,3,2] row_mask:0xf bank_mask:0xf bound_ctrl:1
	v_add_f32_dpp v187, v187, v187 quad_perm:[2,3,0,1] row_mask:0xf bank_mask:0xf bound_ctrl:1
	v_pk_fma_f32 v[174:175], v[110:111], v[2:3], v[174:175]
	v_add_f32_dpp v186, v186, v186 quad_perm:[2,3,0,1] row_mask:0xf bank_mask:0xf bound_ctrl:1
	v_add_f32_dpp v187, v187, v187 row_half_mirror row_mask:0xf bank_mask:0xf bound_ctrl:1
	v_pk_fma_f32 v[174:175], v[108:109], v[10:11], v[174:175]
	v_add_f32_dpp v186, v186, v186 row_half_mirror row_mask:0xf bank_mask:0xf bound_ctrl:1
	v_add_f32_dpp v187, v187, v187 row_mirror row_mask:0xf bank_mask:0xf bound_ctrl:1
	v_mov_b32_e32 v188, v187
	s_nop 1
	v_permlane16_swap_b32 v187, v188
	v_add_f32_dpp v186, v186, v186 row_mirror row_mask:0xf bank_mask:0xf bound_ctrl:1
	v_add_f32_e32 v187, v187, v188
	v_mov_b32_e32 v188, v186
	s_nop 1
	v_permlane16_swap_b32 v186, v188
	v_pk_fma_f32 v[174:175], v[102:103], v[4:5], v[174:175]
	v_add_f32_e32 v188, v186, v188
	v_ldexp_f32 v186, v187, -6
	v_ldexp_f32 v187, v188, -6
	v_fma_f32 v187, -v186, v186, v187
	v_max_f32_e32 v187, 0, v187
	v_add_f32_e32 v187, 0x3727c5ac, v187
	v_pk_fma_f32 v[174:175], v[106:107], v[6:7], v[174:175]
	v_pk_fma_f32 v[172:173], v[112:113], v[16:17], v[172:173]
	v_rsq_f32_e32 v187, v187
	v_pk_fma_f32 v[174:175], v[104:105], v[12:13], v[174:175]
	v_pk_fma_f32 v[172:173], v[110:111], v[14:15], v[172:173]
	v_pk_fma_f32 v[182:183], v[142:143], v[38:39], v[182:183]
	v_mov_b32_e32 v188, v187
	v_pk_add_f32 v[184:185], v[184:185], v[186:187] op_sel_hi:[1,0] neg_lo:[0,1] neg_hi:[0,1]
	v_pk_fma_f32 v[182:183], v[138:139], v[42:43], v[182:183]
	v_pk_mul_f32 v[184:185], v[184:185], v[188:189] op_sel_hi:[1,0]
	v_pk_mul_f32 v[188:189], v[178:179], v[178:179]
	v_pk_fma_f32 v[184:185], v[0:1], v[184:185], v[8:9]
	v_add_f32_e32 v188, v188, v189
	v_add_f32_dpp v189, v190, v190 quad_perm:[1,0,3,2] row_mask:0xf bank_mask:0xf bound_ctrl:1
	v_mul_f32_e32 v186, 0xbfb8aa3b, v184
	v_add_f32_dpp v188, v188, v188 quad_perm:[1,0,3,2] row_mask:0xf bank_mask:0xf bound_ctrl:1
	v_add_f32_dpp v189, v189, v189 quad_perm:[2,3,0,1] row_mask:0xf bank_mask:0xf bound_ctrl:1
	v_mul_f32_e32 v187, 0xbfb8aa3b, v185
	v_add_f32_dpp v188, v188, v188 quad_perm:[2,3,0,1] row_mask:0xf bank_mask:0xf bound_ctrl:1
	v_add_f32_dpp v189, v189, v189 row_half_mirror row_mask:0xf bank_mask:0xf bound_ctrl:1
	v_exp_f32_e32 v186, v186
	v_add_f32_dpp v188, v188, v188 row_half_mirror row_mask:0xf bank_mask:0xf bound_ctrl:1
	v_add_f32_dpp v189, v189, v189 row_mirror row_mask:0xf bank_mask:0xf bound_ctrl:1
	v_mov_b32_e32 v190, v189
	s_nop 1
	v_permlane16_swap_b32 v189, v190
	v_add_f32_dpp v188, v188, v188 row_mirror row_mask:0xf bank_mask:0xf bound_ctrl:1
	v_add_f32_e32 v189, v189, v190
	v_mov_b32_e32 v190, v188
	s_nop 1
	v_permlane16_swap_b32 v188, v190
	v_exp_f32_e32 v187, v187
	v_add_f32_e32 v190, v188, v190
	v_ldexp_f32 v188, v189, -6
	v_ldexp_f32 v189, v190, -6
	v_fma_f32 v189, -v188, v188, v189
	v_max_f32_e32 v189, 0, v189
	v_add_f32_e32 v189, 0x3727c5ac, v189
	v_add_f32_e32 v186, 1.0, v186
	v_add_f32_e32 v187, 1.0, v187
	v_rcp_f32_e32 v186, v186
	v_rcp_f32_e32 v187, v187
	v_rsq_f32_e32 v189, v189
	v_pk_fma_f32 v[182:183], v[134:135], v[60:61], v[182:183]
	v_pk_mul_f32 v[184:185], v[184:185], v[186:187]
	v_pk_fma_f32 v[182:183], v[130:131], v[44:45], v[182:183]
	v_pk_mul_f32 v[170:171], v[184:185], v[170:171]
	v_mov_b32_e32 v184, v189
	v_pk_add_f32 v[178:179], v[178:179], v[188:189] op_sel_hi:[1,0] neg_lo:[0,1] neg_hi:[0,1]
	v_cvt_pk_bf16_f32 v186, v170, v171
	v_pk_mul_f32 v[178:179], v[178:179], v[184:185] op_sel_hi:[1,0]
	global_store_dword v[156:157], v186, off
	v_pk_fma_f32 v[178:179], v[0:1], v[178:179], v[8:9]
	s_waitcnt vmcnt(29)
; #define GAS __attribute__((address_space(1)))
; __device__ __forceinline__ unsigned cvtpk(float lo, float hi) { f32x2 v = {lo, hi}; bf16x2_t b = __builtin_convertvector(v, bf16x2_t); return __builtin_bit_cast(unsigned, b); }
; __device__ __forceinline__ float bflo(unsigned w) { return __uint_as_float(w << 16); }
; __device__ __forceinline__ float bfhi(unsigned w) { return __uint_as_float(w & 0xffff0000u); }
; __device__ __forceinline__ float fsilu(float x) { return x * fsigmoid(x); }
; __device__ __forceinline__ void c_unit(Frame& F, int L, int u, bool dry) {
;     ...
;         for (int i = 0; i < 46; ++i) {
;             const float h0 = bflo(hv[16 * sub + i]), h1 = bfhi(hv[16 * sub + i]);
; #pragma unroll
;             for (int t = 0; t < 16; ++t) { const int j = i - t; if (j >= 0 && j < CONVW) { acc[t].x = fmaf(h0, wv[j].x, acc[t].x); acc[t].y = fmaf(h1, wv[j].y, acc[t].y); } }
;         }
; #pragma unroll
;         for (int t = 0; t < 16; ++t) {
;             float s = acc[t].x + acc[t].y, qq = acc[t].x * acc[t].x + acc[t].y * acc[t].y;
;             s = half_wave_sum(s); qq = half_wave_sum(qq);
;             const float mu = __builtin_ldexpf(s, -6), rstd = rsqrtf(fmaxf(__builtin_ldexpf(qq, -6) - mu * mu, 0.f) + LN_EPS);
;             const float h0 = (acc[t].x - mu) * rstd * gv.x + bv.x, h1 = (acc[t].y - mu) * rstd * gv.y + bv.y;
;             const unsigned ov = cvtpk(fsilu(h0) * bflo(sc[16 * sub + t]), fsilu(h1) * bfhi(sc[16 * sub + t])); if (!dry) *(GAS unsigned*)(SCG + (size_t)(tb + t) * 512) = ov;
;         }
	v_lshlrev_b32_e32 v156, 16, v241
	v_mul_f32_e32 v184, 0xbfb8aa3b, v178
	v_mul_f32_e32 v185, 0xbfb8aa3b, v179
	v_exp_f32_e32 v184, v184
	v_exp_f32_e32 v185, v185
	v_and_b32_e32 v157, 0xffff0000, v241
	v_pk_fma_f32 v[182:183], v[128:129], v[46:47], v[182:183]
	v_add_f32_e32 v170, 1.0, v184
	v_add_f32_e32 v171, 1.0, v185
	v_rcp_f32_e32 v170, v170
	v_rcp_f32_e32 v171, v171
	v_add_f32_e32 v184, v176, v177
	v_pk_fma_f32 v[182:183], v[126:127], v[54:55], v[182:183]
	v_pk_mul_f32 v[170:171], v[178:179], v[170:171]
	v_pk_mul_f32 v[178:179], v[176:177], v[176:177]
	v_pk_mul_f32 v[156:157], v[170:171], v[156:157]
	v_add_f32_e32 v178, v178, v179
	v_add_f32_dpp v179, v184, v184 quad_perm:[1,0,3,2] row_mask:0xf bank_mask:0xf bound_ctrl:1
	v_cvt_pk_bf16_f32 v156, v156, v157
	v_add_f32_dpp v178, v178, v178 quad_perm:[1,0,3,2] row_mask:0xf bank_mask:0xf bound_ctrl:1
	v_add_f32_dpp v179, v179, v179 quad_perm:[2,3,0,1] row_mask:0xf bank_mask:0xf bound_ctrl:1
	global_store_dword v[140:141], v156, off
	v_add_f32_dpp v178, v178, v178 quad_perm:[2,3,0,1] row_mask:0xf bank_mask:0xf bound_ctrl:1
	v_add_f32_dpp v179, v179, v179 row_half_mirror row_mask:0xf bank_mask:0xf bound_ctrl:1
	v_pk_fma_f32 v[182:183], v[164:165], v[58:59], v[182:183]
	v_add_f32_dpp v178, v178, v178 row_half_mirror row_mask:0xf bank_mask:0xf bound_ctrl:1
	v_add_f32_dpp v179, v179, v179 row_mirror row_mask:0xf bank_mask:0xf bound_ctrl:1
	v_mov_b32_e32 v184, v179
	s_nop 1
	v_permlane16_swap_b32 v179, v184
	v_add_f32_dpp v178, v178, v178 row_mirror row_mask:0xf bank_mask:0xf bound_ctrl:1
	v_add_f32_e32 v179, v179, v184
	v_mov_b32_e32 v184, v178
	s_nop 1
	v_permlane16_swap_b32 v178, v184
	v_pk_fma_f32 v[182:183], v[168:169], v[50:51], v[182:183]
	v_add_f32_e32 v184, v178, v184
	v_ldexp_f32 v178, v179, -6
	v_ldexp_f32 v179, v184, -6
	v_fma_f32 v179, -v178, v178, v179
	v_max_f32_e32 v179, 0, v179
	v_add_f32_e32 v179, 0x3727c5ac, v179
	v_pk_fma_f32 v[182:183], v[166:167], v[52:53], v[182:183]
	s_nop 0
	v_rsq_f32_e32 v179, v179
	v_pk_fma_f32 v[182:183], v[162:163], v[56:57], v[182:183]
	v_mov_b32_e32 v140, v179
	v_pk_add_f32 v[156:157], v[176:177], v[178:179] op_sel_hi:[1,0] neg_lo:[0,1] neg_hi:[0,1]
	v_pk_mul_f32 v[176:177], v[174:175], v[174:175]
	v_pk_mul_f32 v[140:141], v[156:157], v[140:141] op_sel_hi:[1,0]
	v_add_f32_e32 v176, v176, v177
	v_pk_fma_f32 v[140:141], v[0:1], v[140:141], v[8:9]
	v_pk_fma_f32 v[182:183], v[160:161], v[22:23], v[182:183]
	v_mul_f32_e32 v156, 0xbfb8aa3b, v140
	v_exp_f32_e32 v157, v156
	v_mul_f32_e32 v156, 0xbfb8aa3b, v141
	v_exp_f32_e32 v171, v156
	v_add_f32_dpp v176, v176, v176 quad_perm:[1,0,3,2] row_mask:0xf bank_mask:0xf bound_ctrl:1
	v_add_f32_e32 v157, 1.0, v157
	v_rcp_f32_e32 v170, v157
	v_add_f32_e32 v157, 1.0, v171
	v_rcp_f32_e32 v171, v157
	v_add_f32_e32 v157, v174, v175
	v_add_f32_dpp v176, v176, v176 quad_perm:[2,3,0,1] row_mask:0xf bank_mask:0xf bound_ctrl:1
	s_waitcnt vmcnt(29)
	v_lshlrev_b32_e32 v156, 16, v223
	v_add_f32_dpp v157, v157, v157 quad_perm:[1,0,3,2] row_mask:0xf bank_mask:0xf bound_ctrl:1
	v_add_f32_dpp v176, v176, v176 row_half_mirror row_mask:0xf bank_mask:0xf bound_ctrl:1
	v_pk_mul_f32 v[140:141], v[140:141], v[170:171]
	v_add_f32_dpp v157, v157, v157 quad_perm:[2,3,0,1] row_mask:0xf bank_mask:0xf bound_ctrl:1
	v_add_f32_dpp v176, v176, v176 row_mirror row_mask:0xf bank_mask:0xf bound_ctrl:1
	v_pk_fma_f32 v[182:183], v[158:159], v[26:27], v[182:183]
	v_add_f32_dpp v157, v157, v157 row_half_mirror row_mask:0xf bank_mask:0xf bound_ctrl:1
	v_pk_fma_f32 v[182:183], v[146:147], v[28:29], v[182:183]
	s_nop 0
	v_add_f32_dpp v157, v157, v157 row_mirror row_mask:0xf bank_mask:0xf bound_ctrl:1
	v_mov_b32_e32 v177, v157
	s_nop 1
	v_permlane16_swap_b32 v157, v177
	v_pk_fma_f32 v[182:183], v[144:145], v[30:31], v[182:183]
	v_add_f32_e32 v157, v157, v177
	v_mov_b32_e32 v177, v176
	s_nop 1
	v_permlane16_swap_b32 v176, v177
	v_pk_fma_f32 v[182:183], v[136:137], v[34:35], v[182:183]
	v_add_f32_e32 v177, v176, v177
	v_ldexp_f32 v176, v157, -6
	v_ldexp_f32 v157, v177, -6
	v_fma_f32 v157, -v176, v176, v157
	v_max_f32_e32 v157, 0, v157
	v_add_f32_e32 v157, 0x3727c5ac, v157
	v_mul_f32_e32 v177, 0x4b800000, v157
	v_cmp_gt_f32_e32 vcc, s0, v157
	v_pk_fma_f32 v[182:183], v[132:133], v[32:33], v[182:183]
	s_nop 0
	v_cndmask_b32_e32 v157, v157, v177, vcc
	v_rsq_f32_e32 v177, v157
	v_and_b32_e32 v157, 0xffff0000, v223
	v_pk_mul_f32 v[140:141], v[140:141], v[156:157]
	v_pk_fma_f32 v[182:183], v[124:125], v[18:19], v[182:183]
	v_mul_f32_e32 v156, 0x45800000, v177
	v_cndmask_b32_e32 v156, v177, v156, vcc
	v_pk_add_f32 v[170:171], v[174:175], v[176:177] op_sel_hi:[1,0] neg_lo:[0,1] neg_hi:[0,1]
	v_cvt_pk_bf16_f32 v174, v140, v141
	v_pk_mul_f32 v[156:157], v[170:171], v[156:157] op_sel_hi:[1,0]
	global_store_dword v[122:123], v174, off
	v_pk_fma_f32 v[156:157], v[0:1], v[156:157], v[8:9]
	s_waitcnt vmcnt(29)
; #define GAS __attribute__((address_space(1)))
; __device__ __forceinline__ unsigned cvtpk(float lo, float hi) { f32x2 v = {lo, hi}; bf16x2_t b = __builtin_convertvector(v, bf16x2_t); return __builtin_bit_cast(unsigned, b); }
; __device__ __forceinline__ float bflo(unsigned w) { return __uint_as_float(w << 16); }
; __device__ __forceinline__ float bfhi(unsigned w) { return __uint_as_float(w & 0xffff0000u); }
; __device__ __forceinline__ float fsilu(float x) { return x * fsigmoid(x); }
; __device__ __forceinline__ void c_unit(Frame& F, int L, int u, bool dry) {
;     ...
;         for (int i = 0; i < 46; ++i) {
;             const float h0 = bflo(hv[16 * sub + i]), h1 = bfhi(hv[16 * sub + i]);
; #pragma unroll
;             for (int t = 0; t < 16; ++t) { const int j = i - t; if (j >= 0 && j < CONVW) { acc[t].x = fmaf(h0, wv[j].x, acc[t].x); acc[t].y = fmaf(h1, wv[j].y, acc[t].y); } }
;         }
; #pragma unroll
;         for (int t = 0; t < 16; ++t) {
;             float s = acc[t].x + acc[t].y, qq = acc[t].x * acc[t].x + acc[t].y * acc[t].y;
;             s = half_wave_sum(s); qq = half_wave_sum(qq);
;             const float mu = __builtin_ldexpf(s, -6), rstd = rsqrtf(fmaxf(__builtin_ldexpf(qq, -6) - mu * mu, 0.f) + LN_EPS);
;             const float h0 = (acc[t].x - mu) * rstd * gv.x + bv.x, h1 = (acc[t].y - mu) * rstd * gv.y + bv.y;
;             const unsigned ov = cvtpk(fsilu(h0) * bflo(sc[16 * sub + t]), fsilu(h1) * bfhi(sc[16 * sub + t])); if (!dry) *(GAS unsigned*)(SCG + (size_t)(tb + t) * 512) = ov;
;         }
	v_lshlrev_b32_e32 v122, 16, v222
	v_mul_f32_e32 v170, 0xbfb8aa3b, v156
	v_mul_f32_e32 v171, 0xbfb8aa3b, v157
	v_exp_f32_e32 v170, v170
	v_exp_f32_e32 v171, v171
	v_and_b32_e32 v123, 0xffff0000, v222
	v_pk_fma_f32 v[182:183], v[118:119], v[20:21], v[182:183]
	v_add_f32_e32 v140, 1.0, v170
	v_add_f32_e32 v141, 1.0, v171
	v_rcp_f32_e32 v140, v140
	v_rcp_f32_e32 v141, v141
	v_pk_fma_f32 v[182:183], v[112:113], v[24:25], v[182:183]
	v_pk_mul_f32 v[140:141], v[156:157], v[140:141]
	v_pk_fma_f32 v[156:157], v[108:109], v[2:3], v[172:173]
	v_pk_mul_f32 v[122:123], v[140:141], v[122:123]
	v_pk_fma_f32 v[156:157], v[102:103], v[10:11], v[156:157]
	v_cvt_pk_bf16_f32 v122, v122, v123
	v_pk_fma_f32 v[156:157], v[106:107], v[4:5], v[156:157]
	global_store_dword v[120:121], v122, off
	v_pk_fma_f32 v[156:157], v[104:105], v[6:7], v[156:157]
	v_pk_fma_f32 v[182:183], v[110:111], v[16:17], v[182:183]
	v_pk_fma_f32 v[156:157], v[100:101], v[12:13], v[156:157]
	v_pk_fma_f32 v[182:183], v[108:109], v[14:15], v[182:183]
	v_add_f32_e32 v172, v156, v157
	v_pk_mul_f32 v[170:171], v[156:157], v[156:157]
	s_nop 0
	v_add_f32_e32 v170, v170, v171
	v_add_f32_dpp v171, v172, v172 quad_perm:[1,0,3,2] row_mask:0xf bank_mask:0xf bound_ctrl:1
	s_nop 0
	v_add_f32_dpp v170, v170, v170 quad_perm:[1,0,3,2] row_mask:0xf bank_mask:0xf bound_ctrl:1
	v_add_f32_dpp v171, v171, v171 quad_perm:[2,3,0,1] row_mask:0xf bank_mask:0xf bound_ctrl:1
	s_nop 0
	v_add_f32_dpp v170, v170, v170 quad_perm:[2,3,0,1] row_mask:0xf bank_mask:0xf bound_ctrl:1
	v_add_f32_dpp v171, v171, v171 row_half_mirror row_mask:0xf bank_mask:0xf bound_ctrl:1
	s_nop 0
	v_add_f32_dpp v170, v170, v170 row_half_mirror row_mask:0xf bank_mask:0xf bound_ctrl:1
	v_add_f32_dpp v171, v171, v171 row_mirror row_mask:0xf bank_mask:0xf bound_ctrl:1
	v_mov_b32_e32 v172, v171
	s_nop 1
	v_permlane16_swap_b32 v171, v172
	v_add_f32_dpp v170, v170, v170 row_mirror row_mask:0xf bank_mask:0xf bound_ctrl:1
	v_add_f32_e32 v171, v171, v172
	v_mov_b32_e32 v172, v170
	s_nop 1
	v_permlane16_swap_b32 v170, v172
	s_nop 0
	v_add_f32_e32 v172, v170, v172
	v_ldexp_f32 v170, v171, -6
	v_ldexp_f32 v171, v172, -6
	v_fma_f32 v171, -v170, v170, v171
	v_max_f32_e32 v171, 0, v171
	v_add_f32_e32 v171, 0x3727c5ac, v171
	s_nop 1
	v_rsq_f32_e32 v171, v171
	s_nop 0
	v_mov_b32_e32 v120, v171
	v_pk_add_f32 v[122:123], v[156:157], v[170:171] op_sel_hi:[1,0] neg_lo:[0,1] neg_hi:[0,1]
	v_pk_fma_f32 v[156:157], v[102:103], v[2:3], v[182:183]
	v_pk_mul_f32 v[120:121], v[122:123], v[120:121] op_sel_hi:[1,0]
	v_pk_fma_f32 v[156:157], v[106:107], v[10:11], v[156:157]
	v_pk_fma_f32 v[120:121], v[0:1], v[120:121], v[8:9]
	v_pk_fma_f32 v[156:157], v[104:105], v[4:5], v[156:157]
	v_mul_f32_e32 v122, 0xbfb8aa3b, v120
	v_exp_f32_e32 v123, v122
	v_mul_f32_e32 v122, 0xbfb8aa3b, v121
	v_exp_f32_e32 v141, v122
	v_pk_fma_f32 v[156:157], v[100:101], v[6:7], v[156:157]
	v_add_f32_e32 v123, 1.0, v123
	v_rcp_f32_e32 v140, v123
	v_add_f32_e32 v123, 1.0, v141
	v_pk_fma_f32 v[156:157], v[180:181], v[12:13], v[156:157]
	v_rcp_f32_e32 v141, v123
	v_add_f32_e32 v123, v156, v157
	v_pk_mul_f32 v[170:171], v[156:157], v[156:157]
	s_waitcnt vmcnt(29)
	v_lshlrev_b32_e32 v122, 16, v220
	v_add_f32_dpp v123, v123, v123 quad_perm:[1,0,3,2] row_mask:0xf bank_mask:0xf bound_ctrl:1
	v_add_f32_e32 v170, v170, v171
	v_pk_mul_f32 v[120:121], v[120:121], v[140:141]
	v_add_f32_dpp v123, v123, v123 quad_perm:[2,3,0,1] row_mask:0xf bank_mask:0xf bound_ctrl:1
	v_add_f32_dpp v170, v170, v170 quad_perm:[1,0,3,2] row_mask:0xf bank_mask:0xf bound_ctrl:1
	s_nop 0
	v_add_f32_dpp v123, v123, v123 row_half_mirror row_mask:0xf bank_mask:0xf bound_ctrl:1
	v_add_f32_dpp v170, v170, v170 quad_perm:[2,3,0,1] row_mask:0xf bank_mask:0xf bound_ctrl:1
	s_nop 0
	v_add_f32_dpp v123, v123, v123 row_mirror row_mask:0xf bank_mask:0xf bound_ctrl:1
	v_mov_b32_e32 v171, v123
	v_add_f32_dpp v170, v170, v170 row_half_mirror row_mask:0xf bank_mask:0xf bound_ctrl:1
	s_nop 1
	v_permlane16_swap_b32 v123, v171
	s_nop 0
	v_add_f32_e32 v123, v123, v171
	v_add_f32_dpp v170, v170, v170 row_mirror row_mask:0xf bank_mask:0xf bound_ctrl:1
	v_mov_b32_e32 v171, v170
	s_nop 1
	v_permlane16_swap_b32 v170, v171
	s_nop 0
	v_add_f32_e32 v171, v170, v171
	v_ldexp_f32 v170, v123, -6
	v_ldexp_f32 v123, v171, -6
	v_fma_f32 v123, -v170, v170, v123
	v_max_f32_e32 v123, 0, v123
	v_add_f32_e32 v123, 0x3727c5ac, v123
	v_mul_f32_e32 v171, 0x4b800000, v123
	v_cmp_gt_f32_e32 vcc, s0, v123
	s_nop 1
	v_cndmask_b32_e32 v123, v123, v171, vcc
	v_rsq_f32_e32 v171, v123
	v_and_b32_e32 v123, 0xffff0000, v220
	v_pk_mul_f32 v[120:121], v[120:121], v[122:123]
	v_mul_f32_e32 v122, 0x45800000, v171
	v_cndmask_b32_e32 v122, v171, v122, vcc
	v_pk_add_f32 v[140:141], v[156:157], v[170:171] op_sel_hi:[1,0] neg_lo:[0,1] neg_hi:[0,1]
	v_cvt_pk_bf16_f32 v156, v120, v121
	v_pk_mul_f32 v[122:123], v[140:141], v[122:123] op_sel_hi:[1,0]
	global_store_dword v[116:117], v156, off
	v_pk_fma_f32 v[122:123], v[0:1], v[122:123], v[8:9]
	s_waitcnt vmcnt(29)
; #define GAS __attribute__((address_space(1)))
; __device__ __forceinline__ unsigned cvtpk(float lo, float hi) { f32x2 v = {lo, hi}; bf16x2_t b = __builtin_convertvector(v, bf16x2_t); return __builtin_bit_cast(unsigned, b); }
; __device__ __forceinline__ float bflo(unsigned w) { return __uint_as_float(w << 16); }
; __device__ __forceinline__ float bfhi(unsigned w) { return __uint_as_float(w & 0xffff0000u); }
; __device__ __forceinline__ float fsilu(float x) { return x * fsigmoid(x); }
; __device__ __forceinline__ void c_unit(Frame& F, int L, int u, bool dry) {
;     ...
;         for (int i = 0; i < 46; ++i) {
;             const float h0 = bflo(hv[16 * sub + i]), h1 = bfhi(hv[16 * sub + i]);
; #pragma unroll
;             for (int t = 0; t < 16; ++t) { const int j = i - t; if (j >= 0 && j < CONVW) { acc[t].x = fmaf(h0, wv[j].x, acc[t].x); acc[t].y = fmaf(h1, wv[j].y, acc[t].y); } }
;         }
; #pragma unroll
;         for (int t = 0; t < 16; ++t) {
;             float s = acc[t].x + acc[t].y, qq = acc[t].x * acc[t].x + acc[t].y * acc[t].y;
;             s = half_wave_sum(s); qq = half_wave_sum(qq);
;             const float mu = __builtin_ldexpf(s, -6), rstd = rsqrtf(fmaxf(__builtin_ldexpf(qq, -6) - mu * mu, 0.f) + LN_EPS);
;             const float h0 = (acc[t].x - mu) * rstd * gv.x + bv.x, h1 = (acc[t].y - mu) * rstd * gv.y + bv.y;
;             const unsigned ov = cvtpk(fsilu(h0) * bflo(sc[16 * sub + t]), fsilu(h1) * bfhi(sc[16 * sub + t])); if (!dry) *(GAS unsigned*)(SCG + (size_t)(tb + t) * 512) = ov;
	v_lshlrev_b32_e32 v116, 16, v221
	v_mul_f32_e32 v140, 0xbfb8aa3b, v122
	v_mul_f32_e32 v141, 0xbfb8aa3b, v123
	v_exp_f32_e32 v140, v140
	v_exp_f32_e32 v141, v141
	v_and_b32_e32 v117, 0xffff0000, v221
	v_pk_fma_f32 v[156:157], v[126:127], v[66:67], v[78:79]
	v_add_f32_e32 v120, 1.0, v140
	v_add_f32_e32 v121, 1.0, v141
	v_rcp_f32_e32 v120, v120
	v_rcp_f32_e32 v121, v121
	v_pk_fma_f32 v[140:141], v[142:143], v[66:67], v[78:79]
	v_pk_fma_f32 v[170:171], v[164:165], v[66:67], v[78:79]
	v_pk_fma_f32 v[140:141], v[138:139], v[68:69], v[140:141]
	v_pk_mul_f32 v[120:121], v[122:123], v[120:121]
	v_pk_fma_f32 v[122:123], v[148:149], v[66:67], v[78:79]
	v_pk_mul_f32 v[116:117], v[120:121], v[116:117]
	v_pk_fma_f32 v[122:123], v[142:143], v[68:69], v[122:123]
	v_cvt_pk_bf16_f32 v116, v116, v117
	v_pk_fma_f32 v[122:123], v[138:139], v[70:71], v[122:123]
	global_store_dword v[114:115], v116, off
	v_pk_fma_f32 v[122:123], v[134:135], v[72:73], v[122:123]
	v_pk_fma_f32 v[114:115], v[154:155], v[66:67], v[78:79]
	v_pk_fma_f32 v[122:123], v[130:131], v[36:37], v[122:123]
	v_pk_fma_f32 v[114:115], v[152:153], v[68:69], v[114:115]
	v_pk_fma_f32 v[122:123], v[128:129], v[38:39], v[122:123]
	v_pk_fma_f32 v[116:117], v[152:153], v[66:67], v[78:79]
	v_pk_fma_f32 v[122:123], v[126:127], v[42:43], v[122:123]
	v_pk_fma_f32 v[114:115], v[150:151], v[70:71], v[114:115]
	v_pk_fma_f32 v[122:123], v[164:165], v[60:61], v[122:123]
	v_pk_fma_f32 v[116:117], v[150:151], v[68:69], v[116:117]
	v_pk_fma_f32 v[122:123], v[168:169], v[44:45], v[122:123]
	v_pk_fma_f32 v[120:121], v[150:151], v[66:67], v[78:79]
	v_pk_fma_f32 v[122:123], v[166:167], v[46:47], v[122:123]
	v_pk_fma_f32 v[114:115], v[148:149], v[72:73], v[114:115]
	v_pk_fma_f32 v[122:123], v[162:163], v[54:55], v[122:123]
	v_pk_fma_f32 v[116:117], v[148:149], v[70:71], v[116:117]
	v_pk_fma_f32 v[120:121], v[148:149], v[68:69], v[120:121]
	v_pk_fma_f32 v[148:149], v[138:139], v[66:67], v[78:79]
	v_pk_fma_f32 v[122:123], v[160:161], v[58:59], v[122:123]
	v_pk_fma_f32 v[116:117], v[142:143], v[72:73], v[116:117]
	v_pk_fma_f32 v[120:121], v[142:143], v[70:71], v[120:121]
	v_pk_fma_f32 v[148:149], v[134:135], v[68:69], v[148:149]
	v_pk_fma_f32 v[114:115], v[142:143], v[36:37], v[114:115]
	v_pk_fma_f32 v[122:123], v[158:159], v[50:51], v[122:123]
	v_pk_fma_f32 v[120:121], v[138:139], v[72:73], v[120:121]
	v_pk_fma_f32 v[148:149], v[130:131], v[70:71], v[148:149]
	v_pk_fma_f32 v[114:115], v[138:139], v[38:39], v[114:115]
	v_pk_fma_f32 v[116:117], v[138:139], v[36:37], v[116:117]
	v_pk_fma_f32 v[122:123], v[146:147], v[52:53], v[122:123]
	v_pk_fma_f32 v[140:141], v[134:135], v[70:71], v[140:141]
	v_pk_fma_f32 v[148:149], v[128:129], v[72:73], v[148:149]
	v_pk_fma_f32 v[150:151], v[134:135], v[66:67], v[78:79]
	v_pk_fma_f32 v[152:153], v[130:131], v[66:67], v[78:79]
	v_pk_fma_f32 v[154:155], v[128:129], v[66:67], v[78:79]
	v_pk_fma_f32 v[114:115], v[134:135], v[42:43], v[114:115]
	v_pk_fma_f32 v[142:143], v[168:169], v[66:67], v[78:79]
	v_pk_fma_f32 v[116:117], v[134:135], v[38:39], v[116:117]
	v_pk_fma_f32 v[138:139], v[166:167], v[66:67], v[78:79]
	v_pk_fma_f32 v[120:121], v[134:135], v[36:37], v[120:121]
	v_pk_fma_f32 v[134:135], v[162:163], v[66:67], v[78:79]
	v_pk_fma_f32 v[178:179], v[144:145], v[56:57], v[122:123]
	v_pk_fma_f32 v[122:123], v[160:161], v[66:67], v[78:79]
	v_pk_fma_f32 v[66:67], v[158:159], v[66:67], v[78:79]
	v_pk_fma_f32 v[150:151], v[130:131], v[68:69], v[150:151]
	v_pk_fma_f32 v[152:153], v[128:129], v[68:69], v[152:153]
	v_pk_fma_f32 v[154:155], v[126:127], v[68:69], v[154:155]
	v_pk_fma_f32 v[156:157], v[164:165], v[68:69], v[156:157]
	v_pk_fma_f32 v[170:171], v[168:169], v[68:69], v[170:171]
	v_pk_fma_f32 v[142:143], v[166:167], v[68:69], v[142:143]
	v_pk_fma_f32 v[138:139], v[162:163], v[68:69], v[138:139]
	v_pk_fma_f32 v[134:135], v[160:161], v[68:69], v[134:135]
	v_pk_fma_f32 v[122:123], v[158:159], v[68:69], v[122:123]
	v_pk_fma_f32 v[66:67], v[146:147], v[68:69], v[66:67]
	v_pk_fma_f32 v[68:69], v[126:127], v[36:37], v[148:149]
	v_pk_fma_f32 v[150:151], v[128:129], v[70:71], v[150:151]
	v_pk_fma_f32 v[68:69], v[164:165], v[38:39], v[68:69]
	v_pk_fma_f32 v[150:151], v[126:127], v[72:73], v[150:151]
	v_pk_fma_f32 v[68:69], v[168:169], v[42:43], v[68:69]
	v_pk_fma_f32 v[152:153], v[126:127], v[70:71], v[152:153]
	v_pk_fma_f32 v[68:69], v[166:167], v[60:61], v[68:69]
	v_pk_fma_f32 v[152:153], v[164:165], v[72:73], v[152:153]
	v_pk_fma_f32 v[68:69], v[162:163], v[44:45], v[68:69]
	v_pk_fma_f32 v[142:143], v[162:163], v[70:71], v[142:143]
	v_pk_fma_f32 v[68:69], v[160:161], v[46:47], v[68:69]
	v_pk_fma_f32 v[172:173], v[160:161], v[72:73], v[142:143]
	v_pk_fma_f32 v[68:69], v[158:159], v[54:55], v[68:69]
	v_pk_fma_f32 v[154:155], v[164:165], v[70:71], v[154:155]
	v_pk_fma_f32 v[68:69], v[146:147], v[58:59], v[68:69]
	v_pk_fma_f32 v[154:155], v[168:169], v[72:73], v[154:155]
	v_pk_fma_f32 v[68:69], v[144:145], v[50:51], v[68:69]
	v_pk_fma_f32 v[138:139], v[160:161], v[70:71], v[138:139]
	v_pk_fma_f32 v[68:69], v[136:137], v[52:53], v[68:69]
	v_pk_fma_f32 v[174:175], v[158:159], v[72:73], v[138:139]
	v_pk_fma_f32 v[148:149], v[132:133], v[56:57], v[68:69]
	v_pk_fma_f32 v[68:69], v[164:165], v[36:37], v[150:151]
	v_pk_fma_f32 v[156:157], v[168:169], v[70:71], v[156:157]
	v_pk_fma_f32 v[68:69], v[168:169], v[38:39], v[68:69]
	v_pk_fma_f32 v[156:157], v[166:167], v[72:73], v[156:157]
	v_pk_fma_f32 v[68:69], v[166:167], v[42:43], v[68:69]
	v_pk_fma_f32 v[134:135], v[158:159], v[70:71], v[134:135]
	v_pk_fma_f32 v[68:69], v[162:163], v[60:61], v[68:69]
	v_pk_fma_f32 v[176:177], v[146:147], v[72:73], v[134:135]
; __device__ __forceinline__ float bflo(unsigned w) { return __uint_as_float(w << 16); }
; __device__ __forceinline__ float bfhi(unsigned w) { return __uint_as_float(w & 0xffff0000u); }
; __device__ __forceinline__ void c_unit(Frame& F, int L, int u, bool dry) {
;     ...
;         for (int i = 0; i < 46; ++i) {
;             const float h0 = bflo(hv[16 * sub + i]), h1 = bfhi(hv[16 * sub + i]);
; #pragma unroll
;             for (int t = 0; t < 16; ++t) { const int j = i - t; if (j >= 0 && j < CONVW) { acc[t].x = fmaf(h0, wv[j].x, acc[t].x); acc[t].y = fmaf(h1, wv[j].y, acc[t].y); } }
;         }
	v_pk_fma_f32 v[68:69], v[160:161], v[44:45], v[68:69]
	v_pk_fma_f32 v[170:171], v[166:167], v[70:71], v[170:171]
	v_pk_fma_f32 v[68:69], v[158:159], v[46:47], v[68:69]
	v_pk_fma_f32 v[170:171], v[162:163], v[72:73], v[170:171]
	v_pk_fma_f32 v[68:69], v[146:147], v[54:55], v[68:69]
	v_pk_fma_f32 v[140:141], v[130:131], v[72:73], v[140:141]
	v_pk_fma_f32 v[68:69], v[144:145], v[58:59], v[68:69]
	v_pk_fma_f32 v[114:115], v[130:131], v[60:61], v[114:115]
	v_pk_fma_f32 v[68:69], v[136:137], v[50:51], v[68:69]
	v_pk_fma_f32 v[116:117], v[130:131], v[42:43], v[116:117]
	v_pk_fma_f32 v[68:69], v[132:133], v[52:53], v[68:69]
	v_pk_fma_f32 v[120:121], v[130:131], v[38:39], v[120:121]
	v_pk_fma_f32 v[142:143], v[124:125], v[56:57], v[68:69]
	v_pk_fma_f32 v[68:69], v[168:169], v[36:37], v[152:153]
	v_pk_fma_f32 v[114:115], v[128:129], v[44:45], v[114:115]
	v_pk_fma_f32 v[68:69], v[166:167], v[38:39], v[68:69]
	v_pk_fma_f32 v[114:115], v[126:127], v[46:47], v[114:115]
	v_pk_fma_f32 v[68:69], v[162:163], v[42:43], v[68:69]
	v_pk_fma_f32 v[114:115], v[164:165], v[54:55], v[114:115]
	v_pk_fma_f32 v[68:69], v[160:161], v[60:61], v[68:69]
	v_pk_fma_f32 v[114:115], v[168:169], v[58:59], v[114:115]
	v_pk_fma_f32 v[68:69], v[158:159], v[44:45], v[68:69]
	v_pk_fma_f32 v[114:115], v[166:167], v[50:51], v[114:115]
	v_pk_fma_f32 v[68:69], v[146:147], v[46:47], v[68:69]
	v_pk_fma_f32 v[114:115], v[162:163], v[52:53], v[114:115]
	v_pk_fma_f32 v[68:69], v[144:145], v[54:55], v[68:69]
	v_pk_fma_f32 v[114:115], v[160:161], v[56:57], v[114:115]
	v_pk_fma_f32 v[68:69], v[136:137], v[58:59], v[68:69]
	v_pk_fma_f32 v[122:123], v[146:147], v[70:71], v[122:123]
	v_pk_fma_f32 v[68:69], v[132:133], v[50:51], v[68:69]
	v_pk_fma_f32 v[116:117], v[128:129], v[60:61], v[116:117]
	v_pk_fma_f32 v[68:69], v[124:125], v[52:53], v[68:69]
	v_pk_fma_f32 v[120:121], v[128:129], v[42:43], v[120:121]
	v_pk_fma_f32 v[138:139], v[118:119], v[56:57], v[68:69]
	v_pk_fma_f32 v[68:69], v[166:167], v[36:37], v[154:155]
	v_pk_fma_f32 v[182:183], v[144:145], v[72:73], v[122:123]
	v_pk_fma_f32 v[68:69], v[162:163], v[38:39], v[68:69]
	v_pk_fma_f32 v[122:123], v[128:129], v[36:37], v[140:141]
	v_pk_fma_f32 v[68:69], v[160:161], v[42:43], v[68:69]
	v_pk_fma_f32 v[116:117], v[126:127], v[44:45], v[116:117]
	v_pk_fma_f32 v[68:69], v[158:159], v[60:61], v[68:69]
	v_pk_fma_f32 v[116:117], v[164:165], v[46:47], v[116:117]
	v_pk_fma_f32 v[68:69], v[146:147], v[44:45], v[68:69]
	v_pk_fma_f32 v[116:117], v[168:169], v[54:55], v[116:117]
	v_pk_fma_f32 v[68:69], v[144:145], v[46:47], v[68:69]
	v_pk_fma_f32 v[116:117], v[166:167], v[58:59], v[116:117]
	v_pk_fma_f32 v[68:69], v[136:137], v[54:55], v[68:69]
	v_pk_fma_f32 v[116:117], v[162:163], v[50:51], v[116:117]
	v_pk_fma_f32 v[68:69], v[132:133], v[58:59], v[68:69]
	v_pk_fma_f32 v[116:117], v[160:161], v[52:53], v[116:117]
	v_pk_fma_f32 v[68:69], v[124:125], v[50:51], v[68:69]
	v_pk_fma_f32 v[116:117], v[158:159], v[56:57], v[116:117]
	v_pk_fma_f32 v[68:69], v[118:119], v[52:53], v[68:69]
	v_pk_fma_f32 v[120:121], v[126:127], v[60:61], v[120:121]
	v_pk_fma_f32 v[134:135], v[112:113], v[56:57], v[68:69]
	v_pk_fma_f32 v[68:69], v[162:163], v[36:37], v[156:157]
	v_pk_fma_f32 v[122:123], v[126:127], v[38:39], v[122:123]
	v_pk_fma_f32 v[68:69], v[160:161], v[38:39], v[68:69]
	v_pk_fma_f32 v[122:123], v[164:165], v[42:43], v[122:123]
	v_pk_fma_f32 v[68:69], v[158:159], v[42:43], v[68:69]
	v_pk_fma_f32 v[120:121], v[164:165], v[44:45], v[120:121]
	v_pk_fma_f32 v[68:69], v[146:147], v[60:61], v[68:69]
	v_pk_fma_f32 v[122:123], v[168:169], v[60:61], v[122:123]
	v_pk_fma_f32 v[68:69], v[144:145], v[44:45], v[68:69]
	v_pk_fma_f32 v[120:121], v[168:169], v[46:47], v[120:121]
	v_pk_fma_f32 v[68:69], v[136:137], v[46:47], v[68:69]
	v_pk_fma_f32 v[122:123], v[166:167], v[44:45], v[122:123]
	v_pk_fma_f32 v[68:69], v[132:133], v[54:55], v[68:69]
	v_pk_fma_f32 v[120:121], v[166:167], v[54:55], v[120:121]
	v_pk_fma_f32 v[68:69], v[124:125], v[58:59], v[68:69]
	v_pk_fma_f32 v[122:123], v[162:163], v[46:47], v[122:123]
	v_pk_fma_f32 v[68:69], v[118:119], v[50:51], v[68:69]
	v_pk_fma_f32 v[120:121], v[162:163], v[58:59], v[120:121]
	v_pk_fma_f32 v[68:69], v[112:113], v[52:53], v[68:69]
	v_pk_fma_f32 v[122:123], v[160:161], v[54:55], v[122:123]
	v_pk_fma_f32 v[130:131], v[110:111], v[56:57], v[68:69]
	v_pk_fma_f32 v[68:69], v[160:161], v[36:37], v[170:171]
	v_pk_fma_f32 v[120:121], v[160:161], v[50:51], v[120:121]
	v_pk_fma_f32 v[68:69], v[158:159], v[38:39], v[68:69]
	v_pk_fma_f32 v[122:123], v[158:159], v[58:59], v[122:123]
	v_pk_fma_f32 v[68:69], v[146:147], v[42:43], v[68:69]
	v_pk_fma_f32 v[120:121], v[158:159], v[52:53], v[120:121]
	v_pk_fma_f32 v[68:69], v[144:145], v[60:61], v[68:69]
	v_pk_fma_f32 v[122:123], v[146:147], v[50:51], v[122:123]
	v_pk_fma_f32 v[68:69], v[136:137], v[44:45], v[68:69]
	v_pk_fma_f32 v[120:121], v[146:147], v[56:57], v[120:121]
	v_pk_fma_f32 v[68:69], v[132:133], v[46:47], v[68:69]
	v_pk_fma_f32 v[122:123], v[144:145], v[52:53], v[122:123]
	v_pk_fma_f32 v[68:69], v[124:125], v[54:55], v[68:69]
	v_pk_fma_f32 v[184:185], v[136:137], v[56:57], v[122:123]
	v_pk_fma_f32 v[68:69], v[118:119], v[58:59], v[68:69]
	v_pk_fma_f32 v[66:67], v[144:145], v[70:71], v[66:67]
	v_pk_fma_f32 v[68:69], v[112:113], v[50:51], v[68:69]
	v_pk_fma_f32 v[66:67], v[136:137], v[72:73], v[66:67]
	v_pk_fma_f32 v[68:69], v[110:111], v[52:53], v[68:69]
	v_lshlrev_b32_e32 v70, 16, v225
	v_pk_fma_f32 v[128:129], v[108:109], v[56:57], v[68:69]
	v_pk_fma_f32 v[68:69], v[158:159], v[22:23], v[114:115]
	v_and_b32_e32 v71, 0xffff0000, v225
	v_pk_fma_f32 v[68:69], v[146:147], v[26:27], v[68:69]
; __device__ __forceinline__ float bflo(unsigned w) { return __uint_as_float(w << 16); }
; __device__ __forceinline__ float bfhi(unsigned w) { return __uint_as_float(w & 0xffff0000u); }
; __device__ __forceinline__ void c_unit(Frame& F, int L, int u, bool dry) {
;     ...
;         for (int i = 0; i < 46; ++i) {
;             const float h0 = bflo(hv[16 * sub + i]), h1 = bfhi(hv[16 * sub + i]);
; #pragma unroll
;             for (int t = 0; t < 16; ++t) { const int j = i - t; if (j >= 0 && j < CONVW) { acc[t].x = fmaf(h0, wv[j].x, acc[t].x); acc[t].y = fmaf(h1, wv[j].y, acc[t].y); } }
;         }
	v_lshlrev_b32_e32 v72, 16, v228
	v_pk_fma_f32 v[68:69], v[144:145], v[28:29], v[68:69]
	v_and_b32_e32 v73, 0xffff0000, v228
	v_pk_fma_f32 v[68:69], v[136:137], v[30:31], v[68:69]
	v_lshlrev_b32_e32 v78, 16, v227
	v_pk_fma_f32 v[68:69], v[132:133], v[34:35], v[68:69]
	v_and_b32_e32 v79, 0xffff0000, v227
	v_pk_fma_f32 v[68:69], v[124:125], v[32:33], v[68:69]
	v_lshlrev_b32_e32 v114, 16, v230
	v_pk_fma_f32 v[68:69], v[118:119], v[18:19], v[68:69]
	v_and_b32_e32 v115, 0xffff0000, v230
	v_pk_fma_f32 v[68:69], v[112:113], v[20:21], v[68:69]
	s_nop 0
	v_pk_fma_f32 v[68:69], v[110:111], v[24:25], v[68:69]
	s_nop 0
	v_pk_fma_f32 v[68:69], v[108:109], v[16:17], v[68:69]
	s_nop 0
	v_pk_fma_f32 v[150:151], v[102:103], v[14:15], v[68:69]
	v_pk_fma_f32 v[68:69], v[158:159], v[36:37], v[172:173]
	s_nop 0
	v_pk_fma_f32 v[68:69], v[146:147], v[38:39], v[68:69]
	s_nop 0
	v_pk_fma_f32 v[68:69], v[144:145], v[42:43], v[68:69]
	s_nop 0
	v_pk_fma_f32 v[68:69], v[136:137], v[60:61], v[68:69]
	s_nop 0
	v_pk_fma_f32 v[68:69], v[132:133], v[44:45], v[68:69]
	s_nop 0
	v_pk_fma_f32 v[68:69], v[124:125], v[46:47], v[68:69]
	s_nop 0
	v_pk_fma_f32 v[68:69], v[118:119], v[54:55], v[68:69]
	s_nop 0
	v_pk_fma_f32 v[68:69], v[112:113], v[58:59], v[68:69]
	s_nop 0
	v_pk_fma_f32 v[68:69], v[110:111], v[50:51], v[68:69]
	s_nop 0
	v_pk_fma_f32 v[68:69], v[108:109], v[52:53], v[68:69]
	s_nop 0
	v_pk_fma_f32 v[126:127], v[102:103], v[56:57], v[68:69]
	v_pk_fma_f32 v[68:69], v[146:147], v[22:23], v[116:117]
	s_nop 0
	v_pk_fma_f32 v[68:69], v[144:145], v[26:27], v[68:69]
	s_nop 0
	v_pk_fma_f32 v[68:69], v[136:137], v[28:29], v[68:69]
	s_nop 0
	v_pk_fma_f32 v[68:69], v[132:133], v[30:31], v[68:69]
	s_nop 0
	v_pk_fma_f32 v[68:69], v[124:125], v[34:35], v[68:69]
	s_nop 0
	v_pk_fma_f32 v[68:69], v[118:119], v[32:33], v[68:69]
	s_nop 0
	v_pk_fma_f32 v[68:69], v[112:113], v[18:19], v[68:69]
	s_nop 0
	v_pk_fma_f32 v[68:69], v[110:111], v[20:21], v[68:69]
	s_nop 0
	v_pk_fma_f32 v[68:69], v[108:109], v[24:25], v[68:69]
	s_nop 0
	v_pk_fma_f32 v[68:69], v[102:103], v[16:17], v[68:69]
	s_nop 0
	v_pk_fma_f32 v[152:153], v[106:107], v[14:15], v[68:69]
	v_pk_fma_f32 v[68:69], v[146:147], v[36:37], v[174:175]
	s_nop 0
	v_pk_fma_f32 v[68:69], v[144:145], v[38:39], v[68:69]
	s_nop 0
	v_pk_fma_f32 v[68:69], v[136:137], v[42:43], v[68:69]
	s_nop 0
	v_pk_fma_f32 v[68:69], v[132:133], v[60:61], v[68:69]
	s_nop 0
	v_pk_fma_f32 v[68:69], v[124:125], v[44:45], v[68:69]
	s_nop 0
	v_pk_fma_f32 v[68:69], v[118:119], v[46:47], v[68:69]
	s_nop 0
	v_pk_fma_f32 v[68:69], v[112:113], v[54:55], v[68:69]
	s_nop 0
	v_pk_fma_f32 v[68:69], v[110:111], v[58:59], v[68:69]
	s_nop 0
	v_pk_fma_f32 v[68:69], v[108:109], v[50:51], v[68:69]
	s_nop 0
	v_pk_fma_f32 v[68:69], v[102:103], v[52:53], v[68:69]
	s_nop 0
	v_pk_fma_f32 v[122:123], v[106:107], v[56:57], v[68:69]
	v_pk_fma_f32 v[68:69], v[144:145], v[22:23], v[120:121]
	s_nop 0
	v_pk_fma_f32 v[68:69], v[136:137], v[26:27], v[68:69]
	s_nop 0
	v_pk_fma_f32 v[68:69], v[132:133], v[28:29], v[68:69]
	s_nop 0
	v_pk_fma_f32 v[68:69], v[124:125], v[30:31], v[68:69]
	s_nop 0
	v_pk_fma_f32 v[68:69], v[118:119], v[34:35], v[68:69]
	s_nop 0
	v_pk_fma_f32 v[68:69], v[112:113], v[32:33], v[68:69]
	s_nop 0
	v_pk_fma_f32 v[68:69], v[110:111], v[18:19], v[68:69]
	s_nop 0
	v_pk_fma_f32 v[68:69], v[108:109], v[20:21], v[68:69]
	s_nop 0
	v_pk_fma_f32 v[68:69], v[102:103], v[24:25], v[68:69]
	s_nop 0
	v_pk_fma_f32 v[68:69], v[106:107], v[16:17], v[68:69]
	s_nop 0
	v_pk_fma_f32 v[146:147], v[104:105], v[14:15], v[68:69]
	v_pk_fma_f32 v[68:69], v[144:145], v[36:37], v[176:177]
	v_pk_fma_f32 v[144:145], v[106:107], v[2:3], v[150:151]
	v_pk_fma_f32 v[68:69], v[136:137], v[38:39], v[68:69]
	v_pk_fma_f32 v[144:145], v[104:105], v[10:11], v[144:145]
	v_pk_fma_f32 v[68:69], v[132:133], v[42:43], v[68:69]
	v_pk_fma_f32 v[144:145], v[100:101], v[4:5], v[144:145]
	v_pk_fma_f32 v[68:69], v[124:125], v[60:61], v[68:69]
	v_pk_fma_f32 v[144:145], v[180:181], v[6:7], v[144:145]
	v_pk_fma_f32 v[68:69], v[118:119], v[44:45], v[68:69]
	s_nop 0
	v_pk_fma_f32 v[68:69], v[112:113], v[46:47], v[68:69]
	s_nop 0
	v_pk_fma_f32 v[68:69], v[110:111], v[54:55], v[68:69]
	s_nop 0
	v_pk_fma_f32 v[68:69], v[108:109], v[58:59], v[68:69]
	s_nop 0
	v_pk_fma_f32 v[68:69], v[102:103], v[50:51], v[68:69]
	s_nop 0
	v_pk_fma_f32 v[68:69], v[106:107], v[52:53], v[68:69]
	s_nop 0
	v_pk_fma_f32 v[120:121], v[104:105], v[56:57], v[68:69]
	v_pk_fma_f32 v[68:69], v[136:137], v[22:23], v[178:179]
	s_nop 0
	v_pk_fma_f32 v[68:69], v[132:133], v[26:27], v[68:69]
	s_nop 0
	v_pk_fma_f32 v[68:69], v[124:125], v[28:29], v[68:69]
	s_nop 0
	v_pk_fma_f32 v[68:69], v[118:119], v[30:31], v[68:69]
	s_nop 0
	v_pk_fma_f32 v[68:69], v[112:113], v[34:35], v[68:69]
	s_nop 0
	v_pk_fma_f32 v[68:69], v[110:111], v[32:33], v[68:69]
	s_nop 0
	v_pk_fma_f32 v[68:69], v[108:109], v[18:19], v[68:69]
	s_nop 0
	v_pk_fma_f32 v[68:69], v[102:103], v[20:21], v[68:69]
	s_nop 0
	v_pk_fma_f32 v[68:69], v[106:107], v[24:25], v[68:69]
	s_nop 0
	v_pk_fma_f32 v[68:69], v[104:105], v[16:17], v[68:69]
	s_nop 0
	v_pk_fma_f32 v[140:141], v[100:101], v[14:15], v[68:69]
	v_pk_fma_f32 v[68:69], v[136:137], v[36:37], v[182:183]
	v_pk_fma_f32 v[36:37], v[132:133], v[36:37], v[66:67]
	v_pk_fma_f32 v[68:69], v[132:133], v[38:39], v[68:69]
	v_lshlrev_b32_e32 v66, 16, v224
	v_pk_fma_f32 v[68:69], v[124:125], v[42:43], v[68:69]
	v_and_b32_e32 v67, 0xffff0000, v224
	v_pk_fma_f32 v[68:69], v[118:119], v[60:61], v[68:69]
	v_pk_fma_f32 v[144:145], v[66:67], v[12:13], v[144:145]
	v_pk_fma_f32 v[68:69], v[112:113], v[44:45], v[68:69]
	v_pk_fma_f32 v[36:37], v[124:125], v[38:39], v[36:37]
	v_pk_fma_f32 v[68:69], v[110:111], v[46:47], v[68:69]
	v_add_f32_e32 v150, v144, v145
	v_pk_fma_f32 v[68:69], v[108:109], v[54:55], v[68:69]
	v_pk_fma_f32 v[36:37], v[118:119], v[42:43], v[36:37]
	v_pk_fma_f32 v[68:69], v[102:103], v[58:59], v[68:69]
	v_pk_fma_f32 v[36:37], v[112:113], v[60:61], v[36:37]
	v_pk_fma_f32 v[68:69], v[106:107], v[50:51], v[68:69]
	v_pk_fma_f32 v[36:37], v[110:111], v[44:45], v[36:37]
	v_pk_fma_f32 v[68:69], v[104:105], v[52:53], v[68:69]
	v_pk_fma_f32 v[36:37], v[108:109], v[46:47], v[36:37]
	v_pk_fma_f32 v[116:117], v[100:101], v[56:57], v[68:69]
	v_pk_fma_f32 v[68:69], v[132:133], v[22:23], v[184:185]
	s_waitcnt vmcnt(29)
; #define GAS __attribute__((address_space(1)))
; __device__ __forceinline__ unsigned cvtpk(float lo, float hi) { f32x2 v = {lo, hi}; bf16x2_t b = __builtin_convertvector(v, bf16x2_t); return __builtin_bit_cast(unsigned, b); }
; __device__ __forceinline__ float bflo(unsigned w) { return __uint_as_float(w << 16); }
; __device__ __forceinline__ float bfhi(unsigned w) { return __uint_as_float(w & 0xffff0000u); }
; __device__ __forceinline__ float fsilu(float x) { return x * fsigmoid(x); }
; __device__ __forceinline__ void c_unit(Frame& F, int L, int u, bool dry) {
;     ...
;         for (int i = 0; i < 46; ++i) {
;             const float h0 = bflo(hv[16 * sub + i]), h1 = bfhi(hv[16 * sub + i]);
; #pragma unroll
;             for (int t = 0; t < 16; ++t) { const int j = i - t; if (j >= 0 && j < CONVW) { acc[t].x = fmaf(h0, wv[j].x, acc[t].x); acc[t].y = fmaf(h1, wv[j].y, acc[t].y); } }
;         }
; #pragma unroll
;         for (int t = 0; t < 16; ++t) {
;             float s = acc[t].x + acc[t].y, qq = acc[t].x * acc[t].x + acc[t].y * acc[t].y;
;             s = half_wave_sum(s); qq = half_wave_sum(qq);
;             const float mu = __builtin_ldexpf(s, -6), rstd = rsqrtf(fmaxf(__builtin_ldexpf(qq, -6) - mu * mu, 0.f) + LN_EPS);
;             const float h0 = (acc[t].x - mu) * rstd * gv.x + bv.x, h1 = (acc[t].y - mu) * rstd * gv.y + bv.y;
;             const unsigned ov = cvtpk(fsilu(h0) * bflo(sc[16 * sub + t]), fsilu(h1) * bfhi(sc[16 * sub + t])); if (!dry) *(GAS unsigned*)(SCG + (size_t)(tb + t) * 512) = ov;
;         }
	v_lshlrev_b32_e32 v132, 16, v219
	v_pk_fma_f32 v[68:69], v[124:125], v[26:27], v[68:69]
	v_pk_fma_f32 v[124:125], v[124:125], v[22:23], v[148:149]
	v_pk_mul_f32 v[148:149], v[144:145], v[144:145]
	v_pk_fma_f32 v[68:69], v[118:119], v[28:29], v[68:69]
	v_add_f32_e32 v148, v148, v149
	v_add_f32_dpp v149, v150, v150 quad_perm:[1,0,3,2] row_mask:0xf bank_mask:0xf bound_ctrl:1
	v_pk_fma_f32 v[68:69], v[112:113], v[30:31], v[68:69]
	v_add_f32_dpp v148, v148, v148 quad_perm:[1,0,3,2] row_mask:0xf bank_mask:0xf bound_ctrl:1
	v_add_f32_dpp v149, v149, v149 quad_perm:[2,3,0,1] row_mask:0xf bank_mask:0xf bound_ctrl:1
	v_pk_fma_f32 v[68:69], v[110:111], v[34:35], v[68:69]
	v_add_f32_dpp v148, v148, v148 quad_perm:[2,3,0,1] row_mask:0xf bank_mask:0xf bound_ctrl:1
	v_add_f32_dpp v149, v149, v149 row_half_mirror row_mask:0xf bank_mask:0xf bound_ctrl:1
	v_and_b32_e32 v133, 0xffff0000, v219
	v_add_f32_dpp v148, v148, v148 row_half_mirror row_mask:0xf bank_mask:0xf bound_ctrl:1
	v_add_f32_dpp v149, v149, v149 row_mirror row_mask:0xf bank_mask:0xf bound_ctrl:1
	v_mov_b32_e32 v150, v149
	s_nop 1
	v_permlane16_swap_b32 v149, v150
	v_add_f32_dpp v148, v148, v148 row_mirror row_mask:0xf bank_mask:0xf bound_ctrl:1
	v_add_f32_e32 v149, v149, v150
	v_mov_b32_e32 v150, v148
	s_nop 1
	v_permlane16_swap_b32 v148, v150
	v_pk_fma_f32 v[68:69], v[108:109], v[32:33], v[68:69]
	v_add_f32_e32 v150, v148, v150
	v_ldexp_f32 v148, v149, -6
	v_ldexp_f32 v149, v150, -6
	v_fma_f32 v149, -v148, v148, v149
	v_max_f32_e32 v149, 0, v149
	v_add_f32_e32 v149, 0x3727c5ac, v149
	v_pk_fma_f32 v[68:69], v[102:103], v[18:19], v[68:69]
	v_pk_fma_f32 v[124:125], v[118:119], v[26:27], v[124:125]
	v_rsq_f32_e32 v149, v149
	v_pk_fma_f32 v[68:69], v[106:107], v[20:21], v[68:69]
	v_pk_fma_f32 v[118:119], v[118:119], v[22:23], v[142:143]
	v_pk_fma_f32 v[68:69], v[104:105], v[24:25], v[68:69]
	v_mov_b32_e32 v150, v149
	v_pk_add_f32 v[144:145], v[144:145], v[148:149] op_sel_hi:[1,0] neg_lo:[0,1] neg_hi:[0,1]
	v_pk_fma_f32 v[68:69], v[100:101], v[16:17], v[68:69]
	v_pk_mul_f32 v[144:145], v[144:145], v[150:151] op_sel_hi:[1,0]
	v_pk_fma_f32 v[136:137], v[180:181], v[14:15], v[68:69]
	v_pk_fma_f32 v[144:145], v[0:1], v[144:145], v[8:9]
	v_lshlrev_b32_e32 v68, 16, v226
	v_mul_f32_e32 v148, 0xbfb8aa3b, v144
	v_mul_f32_e32 v149, 0xbfb8aa3b, v145
	v_exp_f32_e32 v148, v148
	v_exp_f32_e32 v149, v149
	v_and_b32_e32 v69, 0xffff0000, v226
	v_pk_fma_f32 v[118:119], v[112:113], v[26:27], v[118:119]
	v_add_f32_e32 v148, 1.0, v148
	v_add_f32_e32 v149, 1.0, v149
	v_rcp_f32_e32 v148, v148
	v_rcp_f32_e32 v149, v149
	v_pk_fma_f32 v[118:119], v[110:111], v[28:29], v[118:119]
	v_pk_fma_f32 v[124:125], v[112:113], v[28:29], v[124:125]
	v_pk_fma_f32 v[118:119], v[108:109], v[30:31], v[118:119]
	v_pk_mul_f32 v[144:145], v[144:145], v[148:149]
	v_pk_fma_f32 v[118:119], v[102:103], v[34:35], v[118:119]
	v_pk_mul_f32 v[132:133], v[144:145], v[132:133]
	v_pk_fma_f32 v[118:119], v[106:107], v[32:33], v[118:119]
	v_cvt_pk_bf16_f32 v132, v132, v133
	global_store_dword v[98:99], v132, off
	v_pk_fma_f32 v[98:99], v[104:105], v[2:3], v[152:153]
	v_pk_fma_f32 v[118:119], v[104:105], v[18:19], v[118:119]
	v_pk_fma_f32 v[98:99], v[100:101], v[10:11], v[98:99]
	s_waitcnt vmcnt(29)
	v_lshlrev_b32_e32 v132, 16, v218
	v_pk_fma_f32 v[98:99], v[180:181], v[4:5], v[98:99]
	v_and_b32_e32 v133, 0xffff0000, v218
	v_pk_fma_f32 v[98:99], v[66:67], v[6:7], v[98:99]
	v_pk_fma_f32 v[112:113], v[112:113], v[22:23], v[138:139]
	v_pk_fma_f32 v[98:99], v[68:69], v[12:13], v[98:99]
	v_pk_fma_f32 v[112:113], v[110:111], v[26:27], v[112:113]
	v_add_f32_e32 v144, v98, v99
	v_pk_mul_f32 v[142:143], v[98:99], v[98:99]
	v_pk_fma_f32 v[112:113], v[108:109], v[28:29], v[112:113]
	v_add_f32_e32 v142, v142, v143
	v_add_f32_dpp v143, v144, v144 quad_perm:[1,0,3,2] row_mask:0xf bank_mask:0xf bound_ctrl:1
	v_pk_fma_f32 v[112:113], v[102:103], v[30:31], v[112:113]
	v_add_f32_dpp v142, v142, v142 quad_perm:[1,0,3,2] row_mask:0xf bank_mask:0xf bound_ctrl:1
	v_add_f32_dpp v143, v143, v143 quad_perm:[2,3,0,1] row_mask:0xf bank_mask:0xf bound_ctrl:1
	v_pk_fma_f32 v[112:113], v[106:107], v[34:35], v[112:113]
	v_add_f32_dpp v142, v142, v142 quad_perm:[2,3,0,1] row_mask:0xf bank_mask:0xf bound_ctrl:1
	v_add_f32_dpp v143, v143, v143 row_half_mirror row_mask:0xf bank_mask:0xf bound_ctrl:1
	v_pk_fma_f32 v[112:113], v[104:105], v[32:33], v[112:113]
	v_add_f32_dpp v142, v142, v142 row_half_mirror row_mask:0xf bank_mask:0xf bound_ctrl:1
	v_add_f32_dpp v143, v143, v143 row_mirror row_mask:0xf bank_mask:0xf bound_ctrl:1
	v_mov_b32_e32 v144, v143
	s_nop 1
	v_permlane16_swap_b32 v143, v144
	v_add_f32_dpp v142, v142, v142 row_mirror row_mask:0xf bank_mask:0xf bound_ctrl:1
	v_add_f32_e32 v143, v143, v144
	v_mov_b32_e32 v144, v142
	s_nop 1
	v_permlane16_swap_b32 v142, v144
	v_pk_fma_f32 v[112:113], v[100:101], v[18:19], v[112:113]
	v_add_f32_e32 v144, v142, v144
	v_ldexp_f32 v142, v143, -6
	v_ldexp_f32 v143, v144, -6
	v_fma_f32 v143, -v142, v142, v143
	v_max_f32_e32 v143, 0, v143
	v_add_f32_e32 v143, 0x3727c5ac, v143
	v_pk_fma_f32 v[124:125], v[110:111], v[30:31], v[124:125]
	v_pk_fma_f32 v[110:111], v[110:111], v[22:23], v[134:135]
	v_rsq_f32_e32 v143, v143
	v_pk_fma_f32 v[110:111], v[108:109], v[26:27], v[110:111]
	v_pk_fma_f32 v[124:125], v[108:109], v[34:35], v[124:125]
	v_pk_fma_f32 v[110:111], v[102:103], v[28:29], v[110:111]
	v_mov_b32_e32 v144, v143
	v_pk_add_f32 v[98:99], v[98:99], v[142:143] op_sel_hi:[1,0] neg_lo:[0,1] neg_hi:[0,1]
	v_pk_fma_f32 v[110:111], v[106:107], v[30:31], v[110:111]
	v_pk_mul_f32 v[98:99], v[98:99], v[144:145] op_sel_hi:[1,0]
	v_pk_fma_f32 v[110:111], v[104:105], v[34:35], v[110:111]
	v_pk_fma_f32 v[142:143], v[0:1], v[98:99], v[8:9]
	v_pk_fma_f32 v[110:111], v[100:101], v[32:33], v[110:111]
	v_mul_f32_e32 v98, 0xbfb8aa3b, v142
	v_exp_f32_e32 v144, v98
	v_mul_f32_e32 v98, 0xbfb8aa3b, v143
	v_exp_f32_e32 v145, v98
	v_pk_fma_f32 v[98:99], v[100:101], v[20:21], v[118:119]
	v_add_f32_e32 v118, 1.0, v144
	v_rcp_f32_e32 v118, v118
	v_add_f32_e32 v119, 1.0, v145
	v_rcp_f32_e32 v119, v119
	v_pk_fma_f32 v[110:111], v[180:181], v[18:19], v[110:111]
	v_pk_fma_f32 v[108:109], v[108:109], v[22:23], v[130:131]
	v_pk_fma_f32 v[124:125], v[102:103], v[32:33], v[124:125]
	v_pk_mul_f32 v[118:119], v[142:143], v[118:119]
	v_pk_fma_f32 v[108:109], v[102:103], v[26:27], v[108:109]
	v_pk_mul_f32 v[118:119], v[118:119], v[132:133]
	v_pk_fma_f32 v[108:109], v[106:107], v[28:29], v[108:109]
	v_cvt_pk_bf16_f32 v118, v118, v119
	global_store_dword v[96:97], v118, off
	v_pk_fma_f32 v[96:97], v[100:101], v[2:3], v[146:147]
	s_waitcnt vmcnt(28)
; #define GAS __attribute__((address_space(1)))
; __device__ __forceinline__ unsigned cvtpk(float lo, float hi) { f32x2 v = {lo, hi}; bf16x2_t b = __builtin_convertvector(v, bf16x2_t); return __builtin_bit_cast(unsigned, b); }
; __device__ __forceinline__ float bflo(unsigned w) { return __uint_as_float(w << 16); }
; __device__ __forceinline__ float bfhi(unsigned w) { return __uint_as_float(w & 0xffff0000u); }
; __device__ __forceinline__ float fsilu(float x) { return x * fsigmoid(x); }
; __device__ __forceinline__ void c_unit(Frame& F, int L, int u, bool dry) {
;     ...
;         for (int i = 0; i < 46; ++i) {
;             const float h0 = bflo(hv[16 * sub + i]), h1 = bfhi(hv[16 * sub + i]);
; #pragma unroll
;             for (int t = 0; t < 16; ++t) { const int j = i - t; if (j >= 0 && j < CONVW) { acc[t].x = fmaf(h0, wv[j].x, acc[t].x); acc[t].y = fmaf(h1, wv[j].y, acc[t].y); } }
;         }
; #pragma unroll
;         for (int t = 0; t < 16; ++t) {
;             float s = acc[t].x + acc[t].y, qq = acc[t].x * acc[t].x + acc[t].y * acc[t].y;
;             s = half_wave_sum(s); qq = half_wave_sum(qq);
;             const float mu = __builtin_ldexpf(s, -6), rstd = rsqrtf(fmaxf(__builtin_ldexpf(qq, -6) - mu * mu, 0.f) + LN_EPS);
;             const float h0 = (acc[t].x - mu) * rstd * gv.x + bv.x, h1 = (acc[t].y - mu) * rstd * gv.y + bv.y;
;             const unsigned ov = cvtpk(fsilu(h0) * bflo(sc[16 * sub + t]), fsilu(h1) * bfhi(sc[16 * sub + t])); if (!dry) *(GAS unsigned*)(SCG + (size_t)(tb + t) * 512) = ov;
;         }
	v_lshlrev_b32_e32 v118, 16, v217
	v_pk_fma_f32 v[96:97], v[180:181], v[10:11], v[96:97]
	v_and_b32_e32 v119, 0xffff0000, v217
	v_pk_fma_f32 v[96:97], v[66:67], v[4:5], v[96:97]
	v_pk_fma_f32 v[108:109], v[104:105], v[30:31], v[108:109]
	v_pk_fma_f32 v[96:97], v[68:69], v[6:7], v[96:97]
	v_pk_fma_f32 v[108:109], v[100:101], v[34:35], v[108:109]
	v_pk_fma_f32 v[96:97], v[70:71], v[12:13], v[96:97]
	v_pk_fma_f32 v[108:109], v[180:181], v[32:33], v[108:109]
	v_add_f32_e32 v138, v96, v97
	v_pk_mul_f32 v[132:133], v[96:97], v[96:97]
	v_pk_fma_f32 v[108:109], v[66:67], v[18:19], v[108:109]
	v_add_f32_e32 v132, v132, v133
	v_add_f32_dpp v133, v138, v138 quad_perm:[1,0,3,2] row_mask:0xf bank_mask:0xf bound_ctrl:1
	v_pk_fma_f32 v[124:125], v[106:107], v[18:19], v[124:125]
	v_add_f32_dpp v132, v132, v132 quad_perm:[1,0,3,2] row_mask:0xf bank_mask:0xf bound_ctrl:1
	v_add_f32_dpp v133, v133, v133 quad_perm:[2,3,0,1] row_mask:0xf bank_mask:0xf bound_ctrl:1
	v_pk_fma_f32 v[124:125], v[104:105], v[20:21], v[124:125]
	v_add_f32_dpp v132, v132, v132 quad_perm:[2,3,0,1] row_mask:0xf bank_mask:0xf bound_ctrl:1
	v_add_f32_dpp v133, v133, v133 row_half_mirror row_mask:0xf bank_mask:0xf bound_ctrl:1
	v_pk_fma_f32 v[124:125], v[100:101], v[24:25], v[124:125]
	v_add_f32_dpp v132, v132, v132 row_half_mirror row_mask:0xf bank_mask:0xf bound_ctrl:1
	v_add_f32_dpp v133, v133, v133 row_mirror row_mask:0xf bank_mask:0xf bound_ctrl:1
	v_mov_b32_e32 v138, v133
	s_nop 1
	v_permlane16_swap_b32 v133, v138
	v_add_f32_dpp v132, v132, v132 row_mirror row_mask:0xf bank_mask:0xf bound_ctrl:1
	v_add_f32_e32 v133, v133, v138
	v_mov_b32_e32 v138, v132
	s_nop 1
	v_permlane16_swap_b32 v132, v138
	v_pk_fma_f32 v[124:125], v[180:181], v[16:17], v[124:125]
	v_add_f32_e32 v138, v132, v138
	v_ldexp_f32 v132, v133, -6
	v_ldexp_f32 v133, v138, -6
	v_fma_f32 v133, -v132, v132, v133
	v_max_f32_e32 v133, 0, v133
	v_add_f32_e32 v133, 0x3727c5ac, v133
	v_pk_fma_f32 v[124:125], v[66:67], v[14:15], v[124:125]
	v_pk_fma_f32 v[36:37], v[102:103], v[54:55], v[36:37]
	v_rsq_f32_e32 v133, v133
	v_pk_fma_f32 v[102:103], v[102:103], v[22:23], v[128:129]
	v_pk_fma_f32 v[98:99], v[180:181], v[24:25], v[98:99]
	v_pk_fma_f32 v[102:103], v[106:107], v[26:27], v[102:103]
	v_mov_b32_e32 v138, v133
	v_pk_add_f32 v[96:97], v[96:97], v[132:133] op_sel_hi:[1,0] neg_lo:[0,1] neg_hi:[0,1]
	v_pk_fma_f32 v[102:103], v[104:105], v[28:29], v[102:103]
	v_pk_mul_f32 v[96:97], v[96:97], v[138:139] op_sel_hi:[1,0]
	v_pk_fma_f32 v[102:103], v[100:101], v[30:31], v[102:103]
	v_pk_fma_f32 v[132:133], v[0:1], v[96:97], v[8:9]
	v_pk_fma_f32 v[102:103], v[180:181], v[34:35], v[102:103]
	v_mul_f32_e32 v96, 0xbfb8aa3b, v132
	v_exp_f32_e32 v138, v96
	v_mul_f32_e32 v96, 0xbfb8aa3b, v133
	v_exp_f32_e32 v139, v96
	v_pk_fma_f32 v[96:97], v[180:181], v[20:21], v[112:113]
	v_add_f32_e32 v112, 1.0, v138
	v_rcp_f32_e32 v112, v112
	v_add_f32_e32 v113, 1.0, v139
	v_rcp_f32_e32 v113, v113
	v_pk_fma_f32 v[102:103], v[66:67], v[32:33], v[102:103]
	v_pk_fma_f32 v[98:99], v[66:67], v[16:17], v[98:99]
	v_pk_fma_f32 v[102:103], v[68:69], v[18:19], v[102:103]
	v_pk_mul_f32 v[112:113], v[132:133], v[112:113]
	v_pk_fma_f32 v[98:99], v[68:69], v[14:15], v[98:99]
	v_pk_mul_f32 v[112:113], v[112:113], v[118:119]
	v_pk_fma_f32 v[36:37], v[106:107], v[58:59], v[36:37]
	v_cvt_pk_bf16_f32 v112, v112, v113
	global_store_dword v[94:95], v112, off
	v_pk_fma_f32 v[94:95], v[180:181], v[2:3], v[140:141]
	s_waitcnt vmcnt(28)
	v_lshlrev_b32_e32 v112, 16, v216
	v_pk_fma_f32 v[94:95], v[66:67], v[10:11], v[94:95]
	v_and_b32_e32 v113, 0xffff0000, v216
	v_pk_fma_f32 v[94:95], v[68:69], v[4:5], v[94:95]
	v_lshlrev_b32_e32 v58, 16, v229
	v_pk_fma_f32 v[94:95], v[70:71], v[6:7], v[94:95]
	v_and_b32_e32 v59, 0xffff0000, v229
	v_pk_fma_f32 v[94:95], v[72:73], v[12:13], v[94:95]
	v_pk_fma_f32 v[96:97], v[66:67], v[24:25], v[96:97]
	v_add_f32_e32 v132, v94, v95
	v_pk_mul_f32 v[118:119], v[94:95], v[94:95]
	v_pk_fma_f32 v[96:97], v[68:69], v[16:17], v[96:97]
	v_add_f32_e32 v118, v118, v119
	v_add_f32_dpp v119, v132, v132 quad_perm:[1,0,3,2] row_mask:0xf bank_mask:0xf bound_ctrl:1
	v_pk_fma_f32 v[96:97], v[70:71], v[14:15], v[96:97]
	v_add_f32_dpp v118, v118, v118 quad_perm:[1,0,3,2] row_mask:0xf bank_mask:0xf bound_ctrl:1
	v_add_f32_dpp v119, v119, v119 quad_perm:[2,3,0,1] row_mask:0xf bank_mask:0xf bound_ctrl:1
	v_pk_fma_f32 v[36:37], v[104:105], v[50:51], v[36:37]
	v_add_f32_dpp v118, v118, v118 quad_perm:[2,3,0,1] row_mask:0xf bank_mask:0xf bound_ctrl:1
	v_add_f32_dpp v119, v119, v119 row_half_mirror row_mask:0xf bank_mask:0xf bound_ctrl:1
	v_pk_fma_f32 v[36:37], v[100:101], v[52:53], v[36:37]
	v_add_f32_dpp v118, v118, v118 row_half_mirror row_mask:0xf bank_mask:0xf bound_ctrl:1
	v_add_f32_dpp v119, v119, v119 row_mirror row_mask:0xf bank_mask:0xf bound_ctrl:1
	v_mov_b32_e32 v132, v119
	s_nop 1
	v_permlane16_swap_b32 v119, v132
	v_add_f32_dpp v118, v118, v118 row_mirror row_mask:0xf bank_mask:0xf bound_ctrl:1
	v_add_f32_e32 v119, v119, v132
	v_mov_b32_e32 v132, v118
	s_nop 1
	v_permlane16_swap_b32 v118, v132
	v_pk_fma_f32 v[60:61], v[180:181], v[56:57], v[36:37]
	v_add_f32_e32 v132, v118, v132
	v_ldexp_f32 v118, v119, -6
	v_ldexp_f32 v119, v132, -6
	v_fma_f32 v119, -v118, v118, v119
	v_max_f32_e32 v119, 0, v119
	v_add_f32_e32 v119, 0x3727c5ac, v119
	v_lshlrev_b32_e32 v56, 16, v232
	v_and_b32_e32 v57, 0xffff0000, v232
	v_rsq_f32_e32 v119, v119
	v_lshlrev_b32_e32 v54, 16, v231
	v_and_b32_e32 v55, 0xffff0000, v231
	v_lshlrev_b32_e32 v52, 16, v234
	v_mov_b32_e32 v132, v119
	v_pk_add_f32 v[94:95], v[94:95], v[118:119] op_sel_hi:[1,0] neg_lo:[0,1] neg_hi:[0,1]
	v_and_b32_e32 v53, 0xffff0000, v234
	v_pk_mul_f32 v[94:95], v[94:95], v[132:133] op_sel_hi:[1,0]
	v_lshlrev_b32_e32 v50, 16, v233
	v_pk_fma_f32 v[118:119], v[0:1], v[94:95], v[8:9]
	v_and_b32_e32 v51, 0xffff0000, v233
	v_mul_f32_e32 v94, 0xbfb8aa3b, v118
	v_exp_f32_e32 v132, v94
	v_mul_f32_e32 v94, 0xbfb8aa3b, v119
	v_exp_f32_e32 v133, v94
	v_pk_fma_f32 v[94:95], v[66:67], v[20:21], v[110:111]
	v_add_f32_e32 v110, 1.0, v132
	v_rcp_f32_e32 v110, v110
	v_add_f32_e32 v111, 1.0, v133
	v_rcp_f32_e32 v111, v111
	v_pk_fma_f32 v[94:95], v[68:69], v[24:25], v[94:95]
	v_lshlrev_b32_e32 v36, 16, v236
	v_pk_fma_f32 v[94:95], v[70:71], v[16:17], v[94:95]
	v_pk_mul_f32 v[110:111], v[118:119], v[110:111]
	v_pk_fma_f32 v[94:95], v[72:73], v[14:15], v[94:95]
	v_pk_mul_f32 v[110:111], v[110:111], v[112:113]
	v_and_b32_e32 v37, 0xffff0000, v236
	v_cvt_pk_bf16_f32 v110, v110, v111
	global_store_dword v[92:93], v110, off
	v_pk_fma_f32 v[92:93], v[66:67], v[2:3], v[136:137]
	s_waitcnt vmcnt(26)
; #define GAS __attribute__((address_space(1)))
; __device__ __forceinline__ unsigned cvtpk(float lo, float hi) { f32x2 v = {lo, hi}; bf16x2_t b = __builtin_convertvector(v, bf16x2_t); return __builtin_bit_cast(unsigned, b); }
; __device__ __forceinline__ float bflo(unsigned w) { return __uint_as_float(w << 16); }
; __device__ __forceinline__ float bfhi(unsigned w) { return __uint_as_float(w & 0xffff0000u); }
; __device__ __forceinline__ float fsilu(float x) { return x * fsigmoid(x); }
; __device__ __forceinline__ void c_unit(Frame& F, int L, int u, bool dry) {
;     ...
;         for (int i = 0; i < 46; ++i) {
;             const float h0 = bflo(hv[16 * sub + i]), h1 = bfhi(hv[16 * sub + i]);
; #pragma unroll
;             for (int t = 0; t < 16; ++t) { const int j = i - t; if (j >= 0 && j < CONVW) { acc[t].x = fmaf(h0, wv[j].x, acc[t].x); acc[t].y = fmaf(h1, wv[j].y, acc[t].y); } }
;         }
; #pragma unroll
;         for (int t = 0; t < 16; ++t) {
;             float s = acc[t].x + acc[t].y, qq = acc[t].x * acc[t].x + acc[t].y * acc[t].y;
;             s = half_wave_sum(s); qq = half_wave_sum(qq);
;             const float mu = __builtin_ldexpf(s, -6), rstd = rsqrtf(fmaxf(__builtin_ldexpf(qq, -6) - mu * mu, 0.f) + LN_EPS);
;             const float h0 = (acc[t].x - mu) * rstd * gv.x + bv.x, h1 = (acc[t].y - mu) * rstd * gv.y + bv.y;
;             const unsigned ov = cvtpk(fsilu(h0) * bflo(sc[16 * sub + t]), fsilu(h1) * bfhi(sc[16 * sub + t])); if (!dry) *(GAS unsigned*)(SCG + (size_t)(tb + t) * 512) = ov;
;         }
	v_lshlrev_b32_e32 v110, 16, v214
	v_pk_fma_f32 v[92:93], v[68:69], v[10:11], v[92:93]
	v_and_b32_e32 v111, 0xffff0000, v214
	v_pk_fma_f32 v[92:93], v[70:71], v[4:5], v[92:93]
	v_lshlrev_b32_e32 v38, 16, v235
	v_pk_fma_f32 v[92:93], v[72:73], v[6:7], v[92:93]
	v_and_b32_e32 v39, 0xffff0000, v235
	v_pk_fma_f32 v[92:93], v[78:79], v[12:13], v[92:93]
	v_lshlrev_b32_e32 v42, 16, v238
	v_add_f32_e32 v118, v92, v93
	v_pk_mul_f32 v[112:113], v[92:93], v[92:93]
	v_and_b32_e32 v43, 0xffff0000, v238
	v_add_f32_e32 v112, v112, v113
	v_add_f32_dpp v113, v118, v118 quad_perm:[1,0,3,2] row_mask:0xf bank_mask:0xf bound_ctrl:1
	v_lshlrev_b32_e32 v44, 16, v237
	v_add_f32_dpp v112, v112, v112 quad_perm:[1,0,3,2] row_mask:0xf bank_mask:0xf bound_ctrl:1
	v_add_f32_dpp v113, v113, v113 quad_perm:[2,3,0,1] row_mask:0xf bank_mask:0xf bound_ctrl:1
	v_and_b32_e32 v45, 0xffff0000, v237
	v_add_f32_dpp v112, v112, v112 quad_perm:[2,3,0,1] row_mask:0xf bank_mask:0xf bound_ctrl:1
	v_add_f32_dpp v113, v113, v113 row_half_mirror row_mask:0xf bank_mask:0xf bound_ctrl:1
	v_lshlrev_b32_e32 v46, 16, v192
	v_add_f32_dpp v112, v112, v112 row_half_mirror row_mask:0xf bank_mask:0xf bound_ctrl:1
	v_add_f32_dpp v113, v113, v113 row_mirror row_mask:0xf bank_mask:0xf bound_ctrl:1
	v_mov_b32_e32 v118, v113
	s_nop 1
	v_permlane16_swap_b32 v113, v118
	v_add_f32_dpp v112, v112, v112 row_mirror row_mask:0xf bank_mask:0xf bound_ctrl:1
	v_add_f32_e32 v113, v113, v118
	v_mov_b32_e32 v118, v112
	s_nop 1
	v_permlane16_swap_b32 v112, v118
	v_and_b32_e32 v47, 0xffff0000, v192
	v_add_f32_e32 v118, v112, v118
	v_ldexp_f32 v112, v113, -6
	v_ldexp_f32 v113, v118, -6
	v_fma_f32 v113, -v112, v112, v113
	v_max_f32_e32 v113, 0, v113
	v_add_f32_e32 v113, 0x3727c5ac, v113
	s_nop 1
	v_rsq_f32_e32 v113, v113
	s_nop 0
	v_mov_b32_e32 v118, v113
	v_pk_add_f32 v[92:93], v[92:93], v[112:113] op_sel_hi:[1,0] neg_lo:[0,1] neg_hi:[0,1]
	s_nop 0
	v_pk_mul_f32 v[92:93], v[92:93], v[118:119] op_sel_hi:[1,0]
	s_nop 0
	v_pk_fma_f32 v[112:113], v[0:1], v[92:93], v[8:9]
	s_nop 0
	v_mul_f32_e32 v92, 0xbfb8aa3b, v112
	v_exp_f32_e32 v118, v92
	v_mul_f32_e32 v92, 0xbfb8aa3b, v113
	v_exp_f32_e32 v119, v92
	v_pk_fma_f32 v[92:93], v[68:69], v[20:21], v[108:109]
	v_add_f32_e32 v108, 1.0, v118
	v_rcp_f32_e32 v108, v108
	v_add_f32_e32 v109, 1.0, v119
	v_rcp_f32_e32 v109, v109
	v_pk_fma_f32 v[92:93], v[70:71], v[24:25], v[92:93]
	v_pk_mul_f32 v[108:109], v[112:113], v[108:109]
	s_nop 0
	v_pk_mul_f32 v[108:109], v[108:109], v[110:111]
	v_pk_fma_f32 v[92:93], v[72:73], v[16:17], v[92:93]
	v_cvt_pk_bf16_f32 v108, v108, v109
	global_store_dword v[90:91], v108, off
	v_pk_fma_f32 v[90:91], v[68:69], v[2:3], v[124:125]
	s_waitcnt vmcnt(26)
	v_lshlrev_b32_e32 v108, 16, v212
	v_pk_fma_f32 v[90:91], v[70:71], v[10:11], v[90:91]
	v_and_b32_e32 v109, 0xffff0000, v212
	v_pk_fma_f32 v[90:91], v[72:73], v[4:5], v[90:91]
	v_pk_fma_f32 v[92:93], v[78:79], v[14:15], v[92:93]
	v_pk_fma_f32 v[90:91], v[78:79], v[6:7], v[90:91]
	s_nop 0
	v_pk_fma_f32 v[90:91], v[114:115], v[12:13], v[90:91]
	s_nop 0
	v_add_f32_e32 v112, v90, v91
	v_pk_mul_f32 v[110:111], v[90:91], v[90:91]
	s_nop 0
	v_add_f32_e32 v110, v110, v111
	v_add_f32_dpp v111, v112, v112 quad_perm:[1,0,3,2] row_mask:0xf bank_mask:0xf bound_ctrl:1
	s_nop 0
	v_add_f32_dpp v110, v110, v110 quad_perm:[1,0,3,2] row_mask:0xf bank_mask:0xf bound_ctrl:1
	v_add_f32_dpp v111, v111, v111 quad_perm:[2,3,0,1] row_mask:0xf bank_mask:0xf bound_ctrl:1
	s_nop 0
	v_add_f32_dpp v110, v110, v110 quad_perm:[2,3,0,1] row_mask:0xf bank_mask:0xf bound_ctrl:1
	v_add_f32_dpp v111, v111, v111 row_half_mirror row_mask:0xf bank_mask:0xf bound_ctrl:1
	s_nop 0
	v_add_f32_dpp v110, v110, v110 row_half_mirror row_mask:0xf bank_mask:0xf bound_ctrl:1
	v_add_f32_dpp v111, v111, v111 row_mirror row_mask:0xf bank_mask:0xf bound_ctrl:1
	v_mov_b32_e32 v112, v111
	s_nop 1
	v_permlane16_swap_b32 v111, v112
	v_add_f32_dpp v110, v110, v110 row_mirror row_mask:0xf bank_mask:0xf bound_ctrl:1
	v_add_f32_e32 v111, v111, v112
	v_mov_b32_e32 v112, v110
	s_nop 1
	v_permlane16_swap_b32 v110, v112
	s_nop 0
	v_add_f32_e32 v112, v110, v112
	v_ldexp_f32 v110, v111, -6
	v_ldexp_f32 v111, v112, -6
	v_fma_f32 v111, -v110, v110, v111
	v_max_f32_e32 v111, 0, v111
	v_add_f32_e32 v111, 0x3727c5ac, v111
	s_nop 1
	v_rsq_f32_e32 v111, v111
	s_nop 0
	v_mov_b32_e32 v112, v111
	v_pk_add_f32 v[90:91], v[90:91], v[110:111] op_sel_hi:[1,0] neg_lo:[0,1] neg_hi:[0,1]
	s_nop 0
	v_pk_mul_f32 v[90:91], v[90:91], v[112:113] op_sel_hi:[1,0]
	s_nop 0
	v_pk_fma_f32 v[110:111], v[0:1], v[90:91], v[8:9]
	s_nop 0
	v_mul_f32_e32 v90, 0xbfb8aa3b, v110
	v_exp_f32_e32 v112, v90
	v_mul_f32_e32 v90, 0xbfb8aa3b, v111
	v_exp_f32_e32 v113, v90
	v_pk_fma_f32 v[90:91], v[70:71], v[20:21], v[102:103]
	v_add_f32_e32 v102, 1.0, v112
	v_rcp_f32_e32 v102, v102
	v_add_f32_e32 v103, 1.0, v113
	v_rcp_f32_e32 v103, v103
	v_pk_fma_f32 v[90:91], v[72:73], v[24:25], v[90:91]
	v_pk_mul_f32 v[102:103], v[110:111], v[102:103]
	s_nop 0
	v_pk_mul_f32 v[102:103], v[102:103], v[108:109]
	v_pk_fma_f32 v[90:91], v[78:79], v[16:17], v[90:91]
	v_cvt_pk_bf16_f32 v102, v102, v103
	global_store_dword v[88:89], v102, off
	v_pk_fma_f32 v[88:89], v[70:71], v[2:3], v[98:99]
	v_pk_fma_f32 v[98:99], v[106:107], v[22:23], v[126:127]
	v_pk_fma_f32 v[88:89], v[72:73], v[10:11], v[88:89]
	v_pk_fma_f32 v[98:99], v[104:105], v[26:27], v[98:99]
	v_pk_fma_f32 v[88:89], v[78:79], v[4:5], v[88:89]
	v_pk_fma_f32 v[98:99], v[100:101], v[28:29], v[98:99]
	v_pk_fma_f32 v[88:89], v[114:115], v[6:7], v[88:89]
	v_pk_fma_f32 v[98:99], v[180:181], v[30:31], v[98:99]
	v_pk_fma_f32 v[88:89], v[58:59], v[12:13], v[88:89]
	v_pk_fma_f32 v[98:99], v[66:67], v[34:35], v[98:99]
	v_add_f32_e32 v108, v88, v89
	v_pk_mul_f32 v[106:107], v[88:89], v[88:89]
	v_pk_fma_f32 v[98:99], v[68:69], v[32:33], v[98:99]
	v_add_f32_e32 v106, v106, v107
	v_add_f32_dpp v107, v108, v108 quad_perm:[1,0,3,2] row_mask:0xf bank_mask:0xf bound_ctrl:1
	v_pk_fma_f32 v[98:99], v[70:71], v[18:19], v[98:99]
	v_add_f32_dpp v106, v106, v106 quad_perm:[1,0,3,2] row_mask:0xf bank_mask:0xf bound_ctrl:1
	v_add_f32_dpp v107, v107, v107 quad_perm:[2,3,0,1] row_mask:0xf bank_mask:0xf bound_ctrl:1
	s_waitcnt vmcnt(25)
; #define GAS __attribute__((address_space(1)))
; __device__ __forceinline__ unsigned cvtpk(float lo, float hi) { f32x2 v = {lo, hi}; bf16x2_t b = __builtin_convertvector(v, bf16x2_t); return __builtin_bit_cast(unsigned, b); }
; __device__ __forceinline__ float bflo(unsigned w) { return __uint_as_float(w << 16); }
; __device__ __forceinline__ float bfhi(unsigned w) { return __uint_as_float(w & 0xffff0000u); }
; __device__ __forceinline__ float fsilu(float x) { return x * fsigmoid(x); }
; __device__ __forceinline__ void c_unit(Frame& F, int L, int u, bool dry) {
;     ...
;         for (int i = 0; i < 46; ++i) {
;             const float h0 = bflo(hv[16 * sub + i]), h1 = bfhi(hv[16 * sub + i]);
; #pragma unroll
;             for (int t = 0; t < 16; ++t) { const int j = i - t; if (j >= 0 && j < CONVW) { acc[t].x = fmaf(h0, wv[j].x, acc[t].x); acc[t].y = fmaf(h1, wv[j].y, acc[t].y); } }
;         }
; #pragma unroll
;         for (int t = 0; t < 16; ++t) {
;             float s = acc[t].x + acc[t].y, qq = acc[t].x * acc[t].x + acc[t].y * acc[t].y;
;             s = half_wave_sum(s); qq = half_wave_sum(qq);
;             const float mu = __builtin_ldexpf(s, -6), rstd = rsqrtf(fmaxf(__builtin_ldexpf(qq, -6) - mu * mu, 0.f) + LN_EPS);
;             const float h0 = (acc[t].x - mu) * rstd * gv.x + bv.x, h1 = (acc[t].y - mu) * rstd * gv.y + bv.y;
;             const unsigned ov = cvtpk(fsilu(h0) * bflo(sc[16 * sub + t]), fsilu(h1) * bfhi(sc[16 * sub + t])); if (!dry) *(GAS unsigned*)(SCG + (size_t)(tb + t) * 512) = ov;
;         }
	v_lshlrev_b32_e32 v102, 16, v211
	v_add_f32_dpp v106, v106, v106 quad_perm:[2,3,0,1] row_mask:0xf bank_mask:0xf bound_ctrl:1
	v_add_f32_dpp v107, v107, v107 row_half_mirror row_mask:0xf bank_mask:0xf bound_ctrl:1
	v_and_b32_e32 v103, 0xffff0000, v211
	v_add_f32_dpp v106, v106, v106 row_half_mirror row_mask:0xf bank_mask:0xf bound_ctrl:1
	v_add_f32_dpp v107, v107, v107 row_mirror row_mask:0xf bank_mask:0xf bound_ctrl:1
	v_mov_b32_e32 v108, v107
	s_nop 1
	v_permlane16_swap_b32 v107, v108
	v_add_f32_dpp v106, v106, v106 row_mirror row_mask:0xf bank_mask:0xf bound_ctrl:1
	v_add_f32_e32 v107, v107, v108
	v_mov_b32_e32 v108, v106
	s_nop 1
	v_permlane16_swap_b32 v106, v108
	v_pk_fma_f32 v[90:91], v[114:115], v[14:15], v[90:91]
	v_add_f32_e32 v108, v106, v108
	v_ldexp_f32 v106, v107, -6
	v_ldexp_f32 v107, v108, -6
	v_fma_f32 v107, -v106, v106, v107
	v_max_f32_e32 v107, 0, v107
	v_add_f32_e32 v107, 0x3727c5ac, v107
	v_pk_fma_f32 v[90:91], v[58:59], v[2:3], v[90:91]
	s_nop 0
	v_rsq_f32_e32 v107, v107
	v_pk_fma_f32 v[90:91], v[56:57], v[10:11], v[90:91]
	v_mov_b32_e32 v108, v107
	v_pk_add_f32 v[88:89], v[88:89], v[106:107] op_sel_hi:[1,0] neg_lo:[0,1] neg_hi:[0,1]
	v_pk_fma_f32 v[90:91], v[54:55], v[4:5], v[90:91]
	v_pk_mul_f32 v[88:89], v[88:89], v[108:109] op_sel_hi:[1,0]
	v_pk_fma_f32 v[90:91], v[52:53], v[6:7], v[90:91]
	v_pk_fma_f32 v[106:107], v[0:1], v[88:89], v[8:9]
	v_pk_fma_f32 v[90:91], v[50:51], v[12:13], v[90:91]
	v_mul_f32_e32 v88, 0xbfb8aa3b, v106
	v_exp_f32_e32 v108, v88
	v_mul_f32_e32 v88, 0xbfb8aa3b, v107
	v_exp_f32_e32 v109, v88
	v_pk_fma_f32 v[88:89], v[72:73], v[20:21], v[98:99]
	v_add_f32_e32 v98, 1.0, v108
	v_rcp_f32_e32 v98, v98
	v_add_f32_e32 v99, 1.0, v109
	v_rcp_f32_e32 v99, v99
	v_pk_fma_f32 v[88:89], v[78:79], v[24:25], v[88:89]
	v_pk_mul_f32 v[98:99], v[106:107], v[98:99]
	s_nop 0
	v_pk_mul_f32 v[98:99], v[98:99], v[102:103]
	v_pk_fma_f32 v[88:89], v[114:115], v[16:17], v[88:89]
	v_cvt_pk_bf16_f32 v98, v98, v99
	global_store_dword v[86:87], v98, off
	v_pk_fma_f32 v[86:87], v[72:73], v[2:3], v[96:97]
	v_pk_fma_f32 v[96:97], v[104:105], v[22:23], v[122:123]
	v_pk_fma_f32 v[86:87], v[78:79], v[10:11], v[86:87]
	v_pk_fma_f32 v[96:97], v[100:101], v[26:27], v[96:97]
	v_pk_fma_f32 v[86:87], v[114:115], v[4:5], v[86:87]
	v_pk_fma_f32 v[96:97], v[180:181], v[28:29], v[96:97]
	v_pk_fma_f32 v[86:87], v[58:59], v[6:7], v[86:87]
	v_pk_fma_f32 v[96:97], v[66:67], v[30:31], v[96:97]
	v_pk_fma_f32 v[86:87], v[56:57], v[12:13], v[86:87]
	v_pk_fma_f32 v[96:97], v[68:69], v[34:35], v[96:97]
	v_add_f32_e32 v104, v86, v87
	v_pk_mul_f32 v[102:103], v[86:87], v[86:87]
	v_pk_fma_f32 v[96:97], v[70:71], v[32:33], v[96:97]
	v_add_f32_e32 v102, v102, v103
	v_add_f32_dpp v103, v104, v104 quad_perm:[1,0,3,2] row_mask:0xf bank_mask:0xf bound_ctrl:1
	v_pk_fma_f32 v[96:97], v[72:73], v[18:19], v[96:97]
	v_add_f32_dpp v102, v102, v102 quad_perm:[1,0,3,2] row_mask:0xf bank_mask:0xf bound_ctrl:1
	v_add_f32_dpp v103, v103, v103 quad_perm:[2,3,0,1] row_mask:0xf bank_mask:0xf bound_ctrl:1
	s_waitcnt vmcnt(25)
	v_lshlrev_b32_e32 v98, 16, v210
	v_add_f32_dpp v102, v102, v102 quad_perm:[2,3,0,1] row_mask:0xf bank_mask:0xf bound_ctrl:1
	v_add_f32_dpp v103, v103, v103 row_half_mirror row_mask:0xf bank_mask:0xf bound_ctrl:1
	v_and_b32_e32 v99, 0xffff0000, v210
	v_add_f32_dpp v102, v102, v102 row_half_mirror row_mask:0xf bank_mask:0xf bound_ctrl:1
	v_add_f32_dpp v103, v103, v103 row_mirror row_mask:0xf bank_mask:0xf bound_ctrl:1
	v_mov_b32_e32 v104, v103
	s_nop 1
	v_permlane16_swap_b32 v103, v104
	v_add_f32_dpp v102, v102, v102 row_mirror row_mask:0xf bank_mask:0xf bound_ctrl:1
	v_add_f32_e32 v103, v103, v104
	v_mov_b32_e32 v104, v102
	s_nop 1
	v_permlane16_swap_b32 v102, v104
	v_pk_fma_f32 v[88:89], v[58:59], v[14:15], v[88:89]
	v_add_f32_e32 v104, v102, v104
	v_ldexp_f32 v102, v103, -6
	v_ldexp_f32 v103, v104, -6
	v_fma_f32 v103, -v102, v102, v103
	v_max_f32_e32 v103, 0, v103
	v_add_f32_e32 v103, 0x3727c5ac, v103
	s_nop 1
	v_rsq_f32_e32 v103, v103
	s_nop 0
	v_mov_b32_e32 v104, v103
	v_pk_add_f32 v[86:87], v[86:87], v[102:103] op_sel_hi:[1,0] neg_lo:[0,1] neg_hi:[0,1]
	s_nop 0
	v_pk_mul_f32 v[86:87], v[86:87], v[104:105] op_sel_hi:[1,0]
	s_nop 0
	v_pk_fma_f32 v[102:103], v[0:1], v[86:87], v[8:9]
	s_nop 0
	v_mul_f32_e32 v86, 0xbfb8aa3b, v102
	v_exp_f32_e32 v104, v86
	v_mul_f32_e32 v86, 0xbfb8aa3b, v103
	v_exp_f32_e32 v105, v86
	v_pk_fma_f32 v[86:87], v[78:79], v[20:21], v[96:97]
	v_add_f32_e32 v96, 1.0, v104
	v_rcp_f32_e32 v96, v96
	v_add_f32_e32 v97, 1.0, v105
	v_rcp_f32_e32 v97, v97
	v_pk_fma_f32 v[86:87], v[114:115], v[24:25], v[86:87]
	v_pk_mul_f32 v[96:97], v[102:103], v[96:97]
	s_nop 0
	v_pk_mul_f32 v[96:97], v[96:97], v[98:99]
	v_pk_fma_f32 v[86:87], v[58:59], v[16:17], v[86:87]
	v_cvt_pk_bf16_f32 v96, v96, v97
	global_store_dword v[84:85], v96, off
	v_pk_fma_f32 v[84:85], v[78:79], v[2:3], v[94:95]
	v_pk_fma_f32 v[94:95], v[100:101], v[22:23], v[120:121]
	v_pk_fma_f32 v[84:85], v[114:115], v[10:11], v[84:85]
	v_pk_fma_f32 v[94:95], v[180:181], v[26:27], v[94:95]
	v_pk_fma_f32 v[84:85], v[58:59], v[4:5], v[84:85]
	v_pk_fma_f32 v[94:95], v[66:67], v[28:29], v[94:95]
	v_pk_fma_f32 v[84:85], v[56:57], v[6:7], v[84:85]
	v_pk_fma_f32 v[94:95], v[68:69], v[30:31], v[94:95]
	v_pk_fma_f32 v[84:85], v[54:55], v[12:13], v[84:85]
	v_pk_fma_f32 v[94:95], v[70:71], v[34:35], v[94:95]
	v_add_f32_e32 v100, v84, v85
	v_pk_mul_f32 v[98:99], v[84:85], v[84:85]
	v_pk_fma_f32 v[94:95], v[72:73], v[32:33], v[94:95]
	v_add_f32_e32 v98, v98, v99
	v_add_f32_dpp v99, v100, v100 quad_perm:[1,0,3,2] row_mask:0xf bank_mask:0xf bound_ctrl:1
	v_pk_fma_f32 v[94:95], v[78:79], v[18:19], v[94:95]
	v_add_f32_dpp v98, v98, v98 quad_perm:[1,0,3,2] row_mask:0xf bank_mask:0xf bound_ctrl:1
	v_add_f32_dpp v99, v99, v99 quad_perm:[2,3,0,1] row_mask:0xf bank_mask:0xf bound_ctrl:1
	s_waitcnt vmcnt(25)
; #define GAS __attribute__((address_space(1)))
; __device__ __forceinline__ unsigned cvtpk(float lo, float hi) { f32x2 v = {lo, hi}; bf16x2_t b = __builtin_convertvector(v, bf16x2_t); return __builtin_bit_cast(unsigned, b); }
; __device__ __forceinline__ float bflo(unsigned w) { return __uint_as_float(w << 16); }
; __device__ __forceinline__ float bfhi(unsigned w) { return __uint_as_float(w & 0xffff0000u); }
; __device__ __forceinline__ float fsilu(float x) { return x * fsigmoid(x); }
; __device__ __forceinline__ void c_unit(Frame& F, int L, int u, bool dry) {
;     ...
;         for (int i = 0; i < 46; ++i) {
;             const float h0 = bflo(hv[16 * sub + i]), h1 = bfhi(hv[16 * sub + i]);
; #pragma unroll
;             for (int t = 0; t < 16; ++t) { const int j = i - t; if (j >= 0 && j < CONVW) { acc[t].x = fmaf(h0, wv[j].x, acc[t].x); acc[t].y = fmaf(h1, wv[j].y, acc[t].y); } }
;         }
; #pragma unroll
;         for (int t = 0; t < 16; ++t) {
;             float s = acc[t].x + acc[t].y, qq = acc[t].x * acc[t].x + acc[t].y * acc[t].y;
;             s = half_wave_sum(s); qq = half_wave_sum(qq);
;             const float mu = __builtin_ldexpf(s, -6), rstd = rsqrtf(fmaxf(__builtin_ldexpf(qq, -6) - mu * mu, 0.f) + LN_EPS);
;             const float h0 = (acc[t].x - mu) * rstd * gv.x + bv.x, h1 = (acc[t].y - mu) * rstd * gv.y + bv.y;
;             const unsigned ov = cvtpk(fsilu(h0) * bflo(sc[16 * sub + t]), fsilu(h1) * bfhi(sc[16 * sub + t])); if (!dry) *(GAS unsigned*)(SCG + (size_t)(tb + t) * 512) = ov;
;         }
	v_lshlrev_b32_e32 v96, 16, v209
	v_add_f32_dpp v98, v98, v98 quad_perm:[2,3,0,1] row_mask:0xf bank_mask:0xf bound_ctrl:1
	v_add_f32_dpp v99, v99, v99 row_half_mirror row_mask:0xf bank_mask:0xf bound_ctrl:1
	v_and_b32_e32 v97, 0xffff0000, v209
	v_add_f32_dpp v98, v98, v98 row_half_mirror row_mask:0xf bank_mask:0xf bound_ctrl:1
	v_add_f32_dpp v99, v99, v99 row_mirror row_mask:0xf bank_mask:0xf bound_ctrl:1
	v_mov_b32_e32 v100, v99
	s_nop 1
	v_permlane16_swap_b32 v99, v100
	v_add_f32_dpp v98, v98, v98 row_mirror row_mask:0xf bank_mask:0xf bound_ctrl:1
	v_add_f32_e32 v99, v99, v100
	v_mov_b32_e32 v100, v98
	s_nop 1
	v_permlane16_swap_b32 v98, v100
	v_pk_fma_f32 v[86:87], v[56:57], v[14:15], v[86:87]
	v_add_f32_e32 v100, v98, v100
	v_ldexp_f32 v98, v99, -6
	v_ldexp_f32 v99, v100, -6
	v_fma_f32 v99, -v98, v98, v99
	v_max_f32_e32 v99, 0, v99
	v_add_f32_e32 v99, 0x3727c5ac, v99
	s_nop 1
	v_rsq_f32_e32 v99, v99
	s_nop 0
	v_mov_b32_e32 v100, v99
	v_pk_add_f32 v[84:85], v[84:85], v[98:99] op_sel_hi:[1,0] neg_lo:[0,1] neg_hi:[0,1]
	s_nop 0
	v_pk_mul_f32 v[84:85], v[84:85], v[100:101] op_sel_hi:[1,0]
	s_nop 0
	v_pk_fma_f32 v[98:99], v[0:1], v[84:85], v[8:9]
	s_nop 0
	v_mul_f32_e32 v84, 0xbfb8aa3b, v98
	v_exp_f32_e32 v100, v84
	v_mul_f32_e32 v84, 0xbfb8aa3b, v99
	v_exp_f32_e32 v101, v84
	v_pk_fma_f32 v[84:85], v[114:115], v[20:21], v[94:95]
	v_add_f32_e32 v94, 1.0, v100
	v_rcp_f32_e32 v94, v94
	v_add_f32_e32 v95, 1.0, v101
	v_rcp_f32_e32 v95, v95
	v_pk_fma_f32 v[84:85], v[58:59], v[24:25], v[84:85]
	v_pk_mul_f32 v[94:95], v[98:99], v[94:95]
	s_nop 0
	v_pk_mul_f32 v[94:95], v[94:95], v[96:97]
	v_pk_fma_f32 v[84:85], v[56:57], v[16:17], v[84:85]
	v_cvt_pk_bf16_f32 v94, v94, v95
	global_store_dword v[82:83], v94, off
	v_pk_fma_f32 v[82:83], v[114:115], v[2:3], v[92:93]
	v_pk_fma_f32 v[92:93], v[180:181], v[22:23], v[116:117]
	v_pk_fma_f32 v[82:83], v[58:59], v[10:11], v[82:83]
	v_pk_fma_f32 v[22:23], v[66:67], v[22:23], v[60:61]
	v_pk_fma_f32 v[82:83], v[56:57], v[4:5], v[82:83]
	v_pk_fma_f32 v[92:93], v[66:67], v[26:27], v[92:93]
	v_pk_fma_f32 v[82:83], v[54:55], v[6:7], v[82:83]
	v_pk_fma_f32 v[22:23], v[68:69], v[26:27], v[22:23]
	v_pk_fma_f32 v[82:83], v[52:53], v[12:13], v[82:83]
	v_pk_fma_f32 v[92:93], v[68:69], v[28:29], v[92:93]
	v_add_f32_e32 v98, v82, v83
	v_pk_mul_f32 v[96:97], v[82:83], v[82:83]
	v_pk_fma_f32 v[22:23], v[70:71], v[28:29], v[22:23]
	v_add_f32_e32 v96, v96, v97
	v_add_f32_dpp v97, v98, v98 quad_perm:[1,0,3,2] row_mask:0xf bank_mask:0xf bound_ctrl:1
	v_add_f32_e32 v28, v90, v91
	v_add_f32_dpp v96, v96, v96 quad_perm:[1,0,3,2] row_mask:0xf bank_mask:0xf bound_ctrl:1
	v_add_f32_dpp v97, v97, v97 quad_perm:[2,3,0,1] row_mask:0xf bank_mask:0xf bound_ctrl:1
	v_pk_mul_f32 v[26:27], v[90:91], v[90:91]
	v_add_f32_dpp v96, v96, v96 quad_perm:[2,3,0,1] row_mask:0xf bank_mask:0xf bound_ctrl:1
	v_add_f32_dpp v97, v97, v97 row_half_mirror row_mask:0xf bank_mask:0xf bound_ctrl:1
	v_add_f32_e32 v26, v26, v27
	v_add_f32_dpp v96, v96, v96 row_half_mirror row_mask:0xf bank_mask:0xf bound_ctrl:1
	v_add_f32_dpp v97, v97, v97 row_mirror row_mask:0xf bank_mask:0xf bound_ctrl:1
	v_mov_b32_e32 v98, v97
	s_nop 1
	v_permlane16_swap_b32 v97, v98
	v_add_f32_dpp v96, v96, v96 row_mirror row_mask:0xf bank_mask:0xf bound_ctrl:1
	v_add_f32_e32 v97, v97, v98
	v_mov_b32_e32 v98, v96
	s_nop 1
	v_permlane16_swap_b32 v96, v98
	v_add_f32_dpp v27, v28, v28 quad_perm:[1,0,3,2] row_mask:0xf bank_mask:0xf bound_ctrl:1
	v_add_f32_e32 v98, v96, v98
	v_ldexp_f32 v96, v97, -6
	v_add_f32_dpp v27, v27, v27 quad_perm:[2,3,0,1] row_mask:0xf bank_mask:0xf bound_ctrl:1
	v_ldexp_f32 v97, v98, -6
	v_add_f32_dpp v26, v26, v26 quad_perm:[1,0,3,2] row_mask:0xf bank_mask:0xf bound_ctrl:1
	v_add_f32_dpp v27, v27, v27 row_half_mirror row_mask:0xf bank_mask:0xf bound_ctrl:1
	v_fma_f32 v97, -v96, v96, v97
	v_add_f32_dpp v26, v26, v26 quad_perm:[2,3,0,1] row_mask:0xf bank_mask:0xf bound_ctrl:1
	v_add_f32_dpp v27, v27, v27 row_mirror row_mask:0xf bank_mask:0xf bound_ctrl:1
	v_max_f32_e32 v97, 0, v97
	v_mov_b32_e32 v28, v27
	v_add_f32_dpp v26, v26, v26 row_half_mirror row_mask:0xf bank_mask:0xf bound_ctrl:1
	v_add_f32_e32 v97, 0x3727c5ac, v97
	s_nop 1
	v_permlane16_swap_b32 v27, v28
	v_add_f32_dpp v26, v26, v26 row_mirror row_mask:0xf bank_mask:0xf bound_ctrl:1
	v_add_f32_e32 v27, v27, v28
	v_mov_b32_e32 v28, v26
	s_nop 1
	v_permlane16_swap_b32 v26, v28
	v_rsq_f32_e32 v97, v97
	v_add_f32_e32 v28, v26, v28
	v_ldexp_f32 v26, v27, -6
	v_ldexp_f32 v27, v28, -6
	v_fma_f32 v27, -v26, v26, v27
	v_max_f32_e32 v27, 0, v27
	v_add_f32_e32 v27, 0x3727c5ac, v27
	v_mov_b32_e32 v98, v97
	v_pk_add_f32 v[82:83], v[82:83], v[96:97] op_sel_hi:[1,0] neg_lo:[0,1] neg_hi:[0,1]
	v_pk_fma_f32 v[92:93], v[70:71], v[30:31], v[92:93]
	v_pk_mul_f32 v[82:83], v[82:83], v[98:99] op_sel_hi:[1,0]
	v_pk_fma_f32 v[22:23], v[72:73], v[30:31], v[22:23]
	v_rsq_f32_e32 v27, v27
	v_pk_fma_f32 v[92:93], v[72:73], v[34:35], v[92:93]
	v_pk_fma_f32 v[96:97], v[0:1], v[82:83], v[8:9]
	v_pk_fma_f32 v[22:23], v[78:79], v[34:35], v[22:23]
	v_pk_fma_f32 v[92:93], v[78:79], v[32:33], v[92:93]
	v_mul_f32_e32 v82, 0xbfb8aa3b, v96
	v_pk_fma_f32 v[22:23], v[114:115], v[32:33], v[22:23]
	v_pk_fma_f32 v[92:93], v[114:115], v[18:19], v[92:93]
	v_exp_f32_e32 v98, v82
	v_mul_f32_e32 v82, 0xbfb8aa3b, v97
	v_pk_fma_f32 v[18:19], v[58:59], v[18:19], v[22:23]
	v_exp_f32_e32 v99, v82
	v_pk_fma_f32 v[82:83], v[58:59], v[20:21], v[92:93]
	v_pk_fma_f32 v[18:19], v[56:57], v[20:21], v[18:19]
	v_mov_b32_e32 v20, v27
	v_pk_add_f32 v[22:23], v[90:91], v[26:27] op_sel_hi:[1,0] neg_lo:[0,1] neg_hi:[0,1]
	v_pk_fma_f32 v[82:83], v[56:57], v[24:25], v[82:83]
; #define GAS __attribute__((address_space(1)))
; __device__ __forceinline__ unsigned cvtpk(float lo, float hi) { f32x2 v = {lo, hi}; bf16x2_t b = __builtin_convertvector(v, bf16x2_t); return __builtin_bit_cast(unsigned, b); }
; __device__ __forceinline__ float bflo(unsigned w) { return __uint_as_float(w << 16); }
; __device__ __forceinline__ float bfhi(unsigned w) { return __uint_as_float(w & 0xffff0000u); }
; __device__ __forceinline__ float fsilu(float x) { return x * fsigmoid(x); }
; __device__ __forceinline__ void c_unit(Frame& F, int L, int u, bool dry) {
;     ...
;         for (int i = 0; i < 46; ++i) {
;             const float h0 = bflo(hv[16 * sub + i]), h1 = bfhi(hv[16 * sub + i]);
; #pragma unroll
;             for (int t = 0; t < 16; ++t) { const int j = i - t; if (j >= 0 && j < CONVW) { acc[t].x = fmaf(h0, wv[j].x, acc[t].x); acc[t].y = fmaf(h1, wv[j].y, acc[t].y); } }
;         }
; #pragma unroll
;         for (int t = 0; t < 16; ++t) {
;             float s = acc[t].x + acc[t].y, qq = acc[t].x * acc[t].x + acc[t].y * acc[t].y;
;             s = half_wave_sum(s); qq = half_wave_sum(qq);
;             const float mu = __builtin_ldexpf(s, -6), rstd = rsqrtf(fmaxf(__builtin_ldexpf(qq, -6) - mu * mu, 0.f) + LN_EPS);
;             const float h0 = (acc[t].x - mu) * rstd * gv.x + bv.x, h1 = (acc[t].y - mu) * rstd * gv.y + bv.y;
;             const unsigned ov = cvtpk(fsilu(h0) * bflo(sc[16 * sub + t]), fsilu(h1) * bfhi(sc[16 * sub + t])); if (!dry) *(GAS unsigned*)(SCG + (size_t)(tb + t) * 512) = ov;
;         }
	v_pk_mul_f32 v[20:21], v[22:23], v[20:21] op_sel_hi:[1,0]
	v_pk_fma_f32 v[18:19], v[54:55], v[24:25], v[18:19]
	v_pk_fma_f32 v[20:21], v[0:1], v[20:21], v[8:9]
	v_pk_fma_f32 v[82:83], v[54:55], v[16:17], v[82:83]
	v_mul_f32_e32 v22, 0xbfb8aa3b, v20
	v_mul_f32_e32 v23, 0xbfb8aa3b, v21
	v_exp_f32_e32 v22, v22
	v_exp_f32_e32 v23, v23
	v_pk_fma_f32 v[16:17], v[52:53], v[16:17], v[18:19]
	v_add_f32_e32 v92, 1.0, v98
	v_add_f32_e32 v18, 1.0, v22
	v_add_f32_e32 v19, 1.0, v23
	v_pk_fma_f32 v[22:23], v[56:57], v[2:3], v[88:89]
	v_rcp_f32_e32 v18, v18
	v_pk_fma_f32 v[22:23], v[54:55], v[10:11], v[22:23]
	v_rcp_f32_e32 v19, v19
	v_pk_fma_f32 v[22:23], v[52:53], v[4:5], v[22:23]
	v_add_f32_e32 v93, 1.0, v99
	v_pk_fma_f32 v[22:23], v[50:51], v[6:7], v[22:23]
	v_pk_fma_f32 v[84:85], v[54:55], v[14:15], v[84:85]
	v_pk_fma_f32 v[22:23], v[36:37], v[12:13], v[22:23]
	v_rcp_f32_e32 v92, v92
	v_add_f32_e32 v26, v22, v23
	v_pk_mul_f32 v[24:25], v[22:23], v[22:23]
	v_rcp_f32_e32 v93, v93
	v_add_f32_e32 v24, v24, v25
	v_add_f32_dpp v25, v26, v26 quad_perm:[1,0,3,2] row_mask:0xf bank_mask:0xf bound_ctrl:1
	v_pk_fma_f32 v[82:83], v[52:53], v[14:15], v[82:83]
	v_add_f32_dpp v24, v24, v24 quad_perm:[1,0,3,2] row_mask:0xf bank_mask:0xf bound_ctrl:1
	v_add_f32_dpp v25, v25, v25 quad_perm:[2,3,0,1] row_mask:0xf bank_mask:0xf bound_ctrl:1
	v_pk_fma_f32 v[14:15], v[50:51], v[14:15], v[16:17]
	v_add_f32_dpp v24, v24, v24 quad_perm:[2,3,0,1] row_mask:0xf bank_mask:0xf bound_ctrl:1
	v_add_f32_dpp v25, v25, v25 row_half_mirror row_mask:0xf bank_mask:0xf bound_ctrl:1
	v_pk_mul_f32 v[16:17], v[20:21], v[18:19]
	v_add_f32_dpp v24, v24, v24 row_half_mirror row_mask:0xf bank_mask:0xf bound_ctrl:1
	v_add_f32_dpp v25, v25, v25 row_mirror row_mask:0xf bank_mask:0xf bound_ctrl:1
	v_mov_b32_e32 v26, v25
	s_nop 1
	v_permlane16_swap_b32 v25, v26
	v_add_f32_dpp v24, v24, v24 row_mirror row_mask:0xf bank_mask:0xf bound_ctrl:1
	v_add_f32_e32 v25, v25, v26
	v_mov_b32_e32 v26, v24
	s_nop 1
	v_permlane16_swap_b32 v24, v26
	v_lshlrev_b32_e32 v94, 16, v215
	v_add_f32_e32 v26, v24, v26
	v_ldexp_f32 v24, v25, -6
	v_ldexp_f32 v25, v26, -6
	v_fma_f32 v25, -v24, v24, v25
	v_max_f32_e32 v25, 0, v25
	v_add_f32_e32 v25, 0x3727c5ac, v25
	v_and_b32_e32 v95, 0xffff0000, v215
	v_pk_mul_f32 v[92:93], v[96:97], v[92:93]
	v_rsq_f32_e32 v25, v25
	v_pk_mul_f32 v[92:93], v[92:93], v[94:95]
	v_mov_b32_e32 v18, v25
	v_pk_add_f32 v[20:21], v[22:23], v[24:25] op_sel_hi:[1,0] neg_lo:[0,1] neg_hi:[0,1]
	v_cvt_pk_bf16_f32 v92, v92, v93
	v_pk_mul_f32 v[18:19], v[20:21], v[18:19] op_sel_hi:[1,0]
	global_store_dword v[80:81], v92, off
	v_pk_fma_f32 v[18:19], v[0:1], v[18:19], v[8:9]
	s_waitcnt vmcnt(26)
	v_lshlrev_b32_e32 v80, 16, v213
	v_mul_f32_e32 v20, 0xbfb8aa3b, v18
	v_mul_f32_e32 v21, 0xbfb8aa3b, v19
	v_exp_f32_e32 v20, v20
	v_exp_f32_e32 v21, v21
	v_and_b32_e32 v81, 0xffff0000, v213
	v_pk_mul_f32 v[16:17], v[16:17], v[80:81]
	s_nop 0
	v_cvt_pk_bf16_f32 v22, v16, v17
	v_add_f32_e32 v16, 1.0, v20
	v_add_f32_e32 v17, 1.0, v21
	v_rcp_f32_e32 v16, v16
	v_rcp_f32_e32 v17, v17
	global_store_dword v[76:77], v22, off
	s_waitcnt vmcnt(26)
	v_lshlrev_b32_e32 v20, 16, v208
	v_and_b32_e32 v21, 0xffff0000, v208
	v_pk_mul_f32 v[16:17], v[18:19], v[16:17]
	v_pk_fma_f32 v[18:19], v[54:55], v[2:3], v[86:87]
	v_pk_mul_f32 v[16:17], v[16:17], v[20:21]
	v_pk_fma_f32 v[18:19], v[52:53], v[10:11], v[18:19]
	v_cvt_pk_bf16_f32 v16, v16, v17
	v_pk_fma_f32 v[18:19], v[50:51], v[4:5], v[18:19]
	global_store_dword v[74:75], v16, off
	v_pk_fma_f32 v[18:19], v[36:37], v[6:7], v[18:19]
	s_nop 0
	v_pk_fma_f32 v[18:19], v[38:39], v[12:13], v[18:19]
	s_nop 0
	v_add_f32_e32 v24, v18, v19
	v_pk_mul_f32 v[22:23], v[18:19], v[18:19]
	s_nop 0
	v_add_f32_e32 v22, v22, v23
	v_add_f32_dpp v23, v24, v24 quad_perm:[1,0,3,2] row_mask:0xf bank_mask:0xf bound_ctrl:1
	s_nop 0
	v_add_f32_dpp v22, v22, v22 quad_perm:[1,0,3,2] row_mask:0xf bank_mask:0xf bound_ctrl:1
	v_add_f32_dpp v23, v23, v23 quad_perm:[2,3,0,1] row_mask:0xf bank_mask:0xf bound_ctrl:1
	s_nop 0
	v_add_f32_dpp v22, v22, v22 quad_perm:[2,3,0,1] row_mask:0xf bank_mask:0xf bound_ctrl:1
	v_add_f32_dpp v23, v23, v23 row_half_mirror row_mask:0xf bank_mask:0xf bound_ctrl:1
	s_nop 0
	v_add_f32_dpp v22, v22, v22 row_half_mirror row_mask:0xf bank_mask:0xf bound_ctrl:1
	v_add_f32_dpp v23, v23, v23 row_mirror row_mask:0xf bank_mask:0xf bound_ctrl:1
	v_mov_b32_e32 v24, v23
	s_nop 1
	v_permlane16_swap_b32 v23, v24
	v_add_f32_dpp v22, v22, v22 row_mirror row_mask:0xf bank_mask:0xf bound_ctrl:1
	v_add_f32_e32 v23, v23, v24
	v_mov_b32_e32 v24, v22
	s_nop 1
	v_permlane16_swap_b32 v22, v24
	s_nop 0
	v_add_f32_e32 v24, v22, v24
	v_ldexp_f32 v22, v23, -6
	v_ldexp_f32 v23, v24, -6
	v_fma_f32 v23, -v22, v22, v23
	v_max_f32_e32 v23, 0, v23
	v_add_f32_e32 v23, 0x3727c5ac, v23
	s_nop 1
	v_rsq_f32_e32 v23, v23
	s_nop 0
	v_mov_b32_e32 v16, v23
	v_pk_add_f32 v[18:19], v[18:19], v[22:23] op_sel_hi:[1,0] neg_lo:[0,1] neg_hi:[0,1]
	v_pk_fma_f32 v[22:23], v[52:53], v[2:3], v[84:85]
	v_pk_mul_f32 v[16:17], v[18:19], v[16:17] op_sel_hi:[1,0]
	v_pk_fma_f32 v[22:23], v[50:51], v[10:11], v[22:23]
	v_pk_fma_f32 v[16:17], v[0:1], v[16:17], v[8:9]
	v_pk_fma_f32 v[22:23], v[36:37], v[4:5], v[22:23]
	v_mul_f32_e32 v18, 0xbfb8aa3b, v16
	v_exp_f32_e32 v19, v18
	v_mul_f32_e32 v18, 0xbfb8aa3b, v17
	v_exp_f32_e32 v21, v18
	v_pk_fma_f32 v[22:23], v[38:39], v[6:7], v[22:23]
	v_add_f32_e32 v19, 1.0, v19
	v_rcp_f32_e32 v20, v19
	v_add_f32_e32 v19, 1.0, v21
	v_pk_fma_f32 v[22:23], v[42:43], v[12:13], v[22:23]
	v_rcp_f32_e32 v21, v19
	v_add_f32_e32 v19, v22, v23
	v_pk_mul_f32 v[24:25], v[22:23], v[22:23]
	s_waitcnt vmcnt(25)
; #define GAS __attribute__((address_space(1)))
; __device__ __forceinline__ unsigned cvtpk(float lo, float hi) { f32x2 v = {lo, hi}; bf16x2_t b = __builtin_convertvector(v, bf16x2_t); return __builtin_bit_cast(unsigned, b); }
; __device__ __forceinline__ float bflo(unsigned w) { return __uint_as_float(w << 16); }
; __device__ __forceinline__ float bfhi(unsigned w) { return __uint_as_float(w & 0xffff0000u); }
; __device__ __forceinline__ float fsilu(float x) { return x * fsigmoid(x); }
; __device__ __forceinline__ void c_unit(Frame& F, int L, int u, bool dry) {
;     ...
;         for (int i = 0; i < 46; ++i) {
;             const float h0 = bflo(hv[16 * sub + i]), h1 = bfhi(hv[16 * sub + i]);
; #pragma unroll
;             for (int t = 0; t < 16; ++t) { const int j = i - t; if (j >= 0 && j < CONVW) { acc[t].x = fmaf(h0, wv[j].x, acc[t].x); acc[t].y = fmaf(h1, wv[j].y, acc[t].y); } }
;         }
; #pragma unroll
;         for (int t = 0; t < 16; ++t) {
;             float s = acc[t].x + acc[t].y, qq = acc[t].x * acc[t].x + acc[t].y * acc[t].y;
;             s = half_wave_sum(s); qq = half_wave_sum(qq);
;             const float mu = __builtin_ldexpf(s, -6), rstd = rsqrtf(fmaxf(__builtin_ldexpf(qq, -6) - mu * mu, 0.f) + LN_EPS);
;             const float h0 = (acc[t].x - mu) * rstd * gv.x + bv.x, h1 = (acc[t].y - mu) * rstd * gv.y + bv.y;
;             const unsigned ov = cvtpk(fsilu(h0) * bflo(sc[16 * sub + t]), fsilu(h1) * bfhi(sc[16 * sub + t])); if (!dry) *(GAS unsigned*)(SCG + (size_t)(tb + t) * 512) = ov;
;         }
	v_lshlrev_b32_e32 v18, 16, v207
	v_add_f32_dpp v19, v19, v19 quad_perm:[1,0,3,2] row_mask:0xf bank_mask:0xf bound_ctrl:1
	v_add_f32_e32 v24, v24, v25
	v_pk_mul_f32 v[16:17], v[16:17], v[20:21]
	v_add_f32_dpp v19, v19, v19 quad_perm:[2,3,0,1] row_mask:0xf bank_mask:0xf bound_ctrl:1
	v_add_f32_dpp v24, v24, v24 quad_perm:[1,0,3,2] row_mask:0xf bank_mask:0xf bound_ctrl:1
	s_nop 0
	v_add_f32_dpp v19, v19, v19 row_half_mirror row_mask:0xf bank_mask:0xf bound_ctrl:1
	v_add_f32_dpp v24, v24, v24 quad_perm:[2,3,0,1] row_mask:0xf bank_mask:0xf bound_ctrl:1
	s_nop 0
	v_add_f32_dpp v19, v19, v19 row_mirror row_mask:0xf bank_mask:0xf bound_ctrl:1
	v_mov_b32_e32 v25, v19
	v_add_f32_dpp v24, v24, v24 row_half_mirror row_mask:0xf bank_mask:0xf bound_ctrl:1
	s_nop 1
	v_permlane16_swap_b32 v19, v25
	s_nop 0
	v_add_f32_e32 v19, v19, v25
	v_add_f32_dpp v24, v24, v24 row_mirror row_mask:0xf bank_mask:0xf bound_ctrl:1
	v_mov_b32_e32 v25, v24
	s_nop 1
	v_permlane16_swap_b32 v24, v25
	s_nop 0
	v_add_f32_e32 v25, v24, v25
	v_ldexp_f32 v24, v19, -6
	v_ldexp_f32 v19, v25, -6
	v_fma_f32 v19, -v24, v24, v19
	v_max_f32_e32 v19, 0, v19
	v_add_f32_e32 v19, 0x3727c5ac, v19
	v_mul_f32_e32 v25, 0x4b800000, v19
	v_cmp_gt_f32_e32 vcc, s0, v19
	s_nop 1
	v_cndmask_b32_e32 v19, v19, v25, vcc
	v_rsq_f32_e32 v25, v19
	v_and_b32_e32 v19, 0xffff0000, v207
	v_pk_mul_f32 v[16:17], v[16:17], v[18:19]
	v_mul_f32_e32 v18, 0x45800000, v25
	v_cndmask_b32_e32 v18, v25, v18, vcc
	v_pk_add_f32 v[20:21], v[22:23], v[24:25] op_sel_hi:[1,0] neg_lo:[0,1] neg_hi:[0,1]
	v_cvt_pk_bf16_f32 v22, v16, v17
	v_pk_mul_f32 v[18:19], v[20:21], v[18:19] op_sel_hi:[1,0]
	global_store_dword v[64:65], v22, off
	v_pk_fma_f32 v[18:19], v[0:1], v[18:19], v[8:9]
	s_nop 0
	v_mul_f32_e32 v20, 0xbfb8aa3b, v18
	v_mul_f32_e32 v21, 0xbfb8aa3b, v19
	v_exp_f32_e32 v20, v20
	v_exp_f32_e32 v21, v21
	v_add_f32_e32 v16, 1.0, v20
	v_add_f32_e32 v17, 1.0, v21
	v_rcp_f32_e32 v16, v16
	v_rcp_f32_e32 v17, v17
	s_waitcnt vmcnt(25)
	v_lshlrev_b32_e32 v20, 16, v206
	v_and_b32_e32 v21, 0xffff0000, v206
	v_pk_mul_f32 v[16:17], v[18:19], v[16:17]
	v_pk_fma_f32 v[18:19], v[50:51], v[2:3], v[82:83]
	v_pk_fma_f32 v[2:3], v[36:37], v[2:3], v[14:15]
	v_pk_fma_f32 v[18:19], v[36:37], v[10:11], v[18:19]
	v_pk_fma_f32 v[2:3], v[38:39], v[10:11], v[2:3]
	v_pk_fma_f32 v[18:19], v[38:39], v[4:5], v[18:19]
	v_pk_fma_f32 v[2:3], v[42:43], v[4:5], v[2:3]
	v_pk_fma_f32 v[18:19], v[42:43], v[6:7], v[18:19]
	v_pk_fma_f32 v[2:3], v[44:45], v[6:7], v[2:3]
	v_pk_fma_f32 v[18:19], v[44:45], v[12:13], v[18:19]
	v_pk_fma_f32 v[2:3], v[46:47], v[12:13], v[2:3]
	v_add_f32_e32 v24, v18, v19
	v_pk_mul_f32 v[22:23], v[18:19], v[18:19]
	v_add_f32_e32 v6, v2, v3
	v_add_f32_e32 v22, v22, v23
	v_add_f32_dpp v23, v24, v24 quad_perm:[1,0,3,2] row_mask:0xf bank_mask:0xf bound_ctrl:1
	v_pk_mul_f32 v[4:5], v[2:3], v[2:3]
	v_add_f32_dpp v22, v22, v22 quad_perm:[1,0,3,2] row_mask:0xf bank_mask:0xf bound_ctrl:1
	v_add_f32_dpp v23, v23, v23 quad_perm:[2,3,0,1] row_mask:0xf bank_mask:0xf bound_ctrl:1
	v_add_f32_e32 v4, v4, v5
	v_add_f32_dpp v22, v22, v22 quad_perm:[2,3,0,1] row_mask:0xf bank_mask:0xf bound_ctrl:1
	v_add_f32_dpp v23, v23, v23 row_half_mirror row_mask:0xf bank_mask:0xf bound_ctrl:1
	v_add_f32_dpp v5, v6, v6 quad_perm:[1,0,3,2] row_mask:0xf bank_mask:0xf bound_ctrl:1
	v_add_f32_dpp v22, v22, v22 row_half_mirror row_mask:0xf bank_mask:0xf bound_ctrl:1
	v_add_f32_dpp v23, v23, v23 row_mirror row_mask:0xf bank_mask:0xf bound_ctrl:1
	v_mov_b32_e32 v24, v23
	s_nop 1
	v_permlane16_swap_b32 v23, v24
	v_add_f32_dpp v22, v22, v22 row_mirror row_mask:0xf bank_mask:0xf bound_ctrl:1
	v_add_f32_e32 v23, v23, v24
	v_mov_b32_e32 v24, v22
	s_nop 1
	v_permlane16_swap_b32 v22, v24
	v_add_f32_dpp v5, v5, v5 quad_perm:[2,3,0,1] row_mask:0xf bank_mask:0xf bound_ctrl:1
	v_add_f32_e32 v24, v22, v24
	v_ldexp_f32 v22, v23, -6
	v_ldexp_f32 v23, v24, -6
	v_add_f32_dpp v5, v5, v5 row_half_mirror row_mask:0xf bank_mask:0xf bound_ctrl:1
	v_add_f32_dpp v4, v4, v4 quad_perm:[1,0,3,2] row_mask:0xf bank_mask:0xf bound_ctrl:1
	v_fma_f32 v23, -v22, v22, v23
	v_add_f32_dpp v5, v5, v5 row_mirror row_mask:0xf bank_mask:0xf bound_ctrl:1
	v_add_f32_dpp v4, v4, v4 quad_perm:[2,3,0,1] row_mask:0xf bank_mask:0xf bound_ctrl:1
	v_max_f32_e32 v23, 0, v23
	v_mov_b32_e32 v6, v5
	v_add_f32_dpp v4, v4, v4 row_half_mirror row_mask:0xf bank_mask:0xf bound_ctrl:1
	v_add_f32_e32 v23, 0x3727c5ac, v23
	s_nop 1
	v_permlane16_swap_b32 v5, v6
	v_add_f32_dpp v4, v4, v4 row_mirror row_mask:0xf bank_mask:0xf bound_ctrl:1
	v_add_f32_e32 v5, v5, v6
	v_mov_b32_e32 v6, v4
	s_nop 1
	v_permlane16_swap_b32 v4, v6
	v_rsq_f32_e32 v23, v23
	v_add_f32_e32 v6, v4, v6
	v_ldexp_f32 v4, v5, -6
	v_ldexp_f32 v5, v6, -6
	v_pk_mul_f32 v[16:17], v[16:17], v[20:21]
	v_fma_f32 v5, -v4, v4, v5
	v_cvt_pk_bf16_f32 v16, v16, v17
	v_max_f32_e32 v5, 0, v5
	global_store_dword v[62:63], v16, off
	v_add_f32_e32 v5, 0x3727c5ac, v5
	v_mov_b32_e32 v16, v23
	v_pk_add_f32 v[18:19], v[18:19], v[22:23] op_sel_hi:[1,0] neg_lo:[0,1] neg_hi:[0,1]
	s_nop 0
	v_rsq_f32_e32 v5, v5
	v_pk_mul_f32 v[16:17], v[18:19], v[16:17] op_sel_hi:[1,0]
	v_pk_fma_f32 v[16:17], v[0:1], v[16:17], v[8:9]
	v_mov_b32_e32 v10, v5
	v_mul_f32_e32 v18, 0xbfb8aa3b, v16
	v_exp_f32_e32 v19, v18
	v_mul_f32_e32 v18, 0xbfb8aa3b, v17
	v_pk_add_f32 v[2:3], v[2:3], v[4:5] op_sel_hi:[1,0] neg_lo:[0,1] neg_hi:[0,1]
	v_exp_f32_e32 v21, v18
	v_pk_mul_f32 v[2:3], v[2:3], v[10:11] op_sel_hi:[1,0]
	v_add_f32_e32 v19, 1.0, v19
	v_pk_fma_f32 v[0:1], v[0:1], v[2:3], v[8:9]
	v_rcp_f32_e32 v20, v19
	v_mul_f32_e32 v2, 0xbfb8aa3b, v0
	v_mul_f32_e32 v3, 0xbfb8aa3b, v1
	v_exp_f32_e32 v2, v2
	v_exp_f32_e32 v3, v3
	v_add_f32_e32 v19, 1.0, v21
	v_rcp_f32_e32 v21, v19
	v_add_f32_e32 v2, 1.0, v2
	v_add_f32_e32 v3, 1.0, v3
	v_rcp_f32_e32 v2, v2
	v_rcp_f32_e32 v3, v3
	s_waitcnt vmcnt(25)
	v_lshlrev_b32_e32 v18, 16, v204
	v_and_b32_e32 v19, 0xffff0000, v204
	v_pk_mul_f32 v[6:7], v[16:17], v[20:21]
	s_waitcnt vmcnt(24)
	v_and_b32_e32 v5, 0xffff0000, v205
	v_pk_mul_f32 v[6:7], v[6:7], v[18:19]
	v_pk_mul_f32 v[0:1], v[0:1], v[2:3]
	v_cvt_pk_bf16_f32 v4, v6, v7
	global_store_dword v[48:49], v4, off
	v_lshlrev_b32_e32 v4, 16, v205
	v_pk_mul_f32 v[0:1], v[0:1], v[4:5]
	s_nop 0
	v_cvt_pk_bf16_f32 v0, v0, v1
	global_store_dword v[40:41], v0, off
; __device__ __forceinline__ unsigned xb_add(unsigned* p, unsigned v) { return __hip_atomic_fetch_add(p, v, __ATOMIC_RELAXED, __HIP_MEMORY_SCOPE_AGENT); }
; __device__ __forceinline__ bool is_t0(int wave) { return wave == 0 && olane() == 0; }
; __device__ __forceinline__ void xcd_barrier(const XcdBarrier& b) {
;     asm volatile("s_waitcnt vmcnt(0)" ::: "memory");
;     __syncthreads();
;     if (is_t0(b.wave)) {
;         unsigned* bar = b.bar; asm volatile("" : "+s"(bar));
;         __builtin_amdgcn_s_waitcnt(0);
;         unsigned nloc = b.st[0], nx = b.st[1];
;         if (nloc == 0u) { xcd_barrier_complete(bar, b.x, nloc, nx); b.st[0] = nloc; b.st[1] = nx; }
;         const unsigned old = xb_add(&bar[XB_XSUB(b.x)], 1u);
;         const unsigned gen = old / nloc;
;         if (old + 1u == (gen + 1u) * nloc) {
.LBB0_562:
	s_nop 0
	s_nop 0
	s_nop 0
	s_nop 0
	s_or_b32 s16, s34, 3
	s_cmp_lt_i32 s16, s67
	s_cselect_b64 s[2:3], -1, 0
	s_and_b64 s[0:1], s[4:5], s[2:3]
	s_andn2_b64 vcc, exec, s[0:1]
	s_cbranch_vccnz .LBB0_632
	v_readlane_b32 s4, v253, 3
	v_readlane_b32 s5, v253, 4
	s_mov_b64 s[0:1], -1
	s_and_b64 vcc, exec, s[4:5]
	s_cbranch_vccz .LBB0_611
	s_waitcnt vmcnt(0)
	s_and_b64 vcc, exec, s[46:47]
	s_waitcnt vmcnt(0)
	s_barrier
	s_cbranch_vccnz .LBB0_610
	v_mbcnt_lo_u32_b32 v0, -1, 0
	v_mbcnt_hi_u32_b32 v0, -1, v0
	s_nop 0
	v_cmp_eq_u32_e32 vcc, 0, v0
	s_and_saveexec_b64 s[4:5], vcc
	s_cbranch_execz .LBB0_609
	v_readlane_b32 s0, v254, 35
	s_mov_b64 s[28:29], s[26:27]
	s_waitcnt vmcnt(0) expcnt(0) lgkmcnt(0)
	v_mov_b32_e32 v0, s0
	ds_read_b32 v2, v0
	v_readlane_b32 s0, v254, 36
	s_waitcnt lgkmcnt(0)
	v_cmp_ne_u32_e32 vcc, 0, v2
	v_mov_b32_e32 v0, s0
	ds_read_b32 v0, v0
	s_cbranch_vccnz .LBB0_580
	v_readlane_b32 s6, v253, 0
	v_readlane_b32 s7, v253, 1
	s_load_dwordx2 s[0:1], s[6:7], 0x4
	s_add_u32 s6, s28, 0x1000
	s_addc_u32 s7, s29, 0
	s_add_u32 s30, s28, 0x1100
	s_addc_u32 s31, s29, 0
	s_add_u32 s38, s28, 0x1200
	s_addc_u32 s39, s29, 0
	s_waitcnt lgkmcnt(0)
	s_mul_i32 s17, s0, s96
	s_add_u32 s42, s28, 0x1300
	s_mul_i32 s17, s17, s1
	s_addc_u32 s43, s29, 0
	s_mov_b32 s18, 1
	s_mov_b64 s[44:45], 0
	s_branch .LBB0_570

; __device__ __forceinline__ unsigned xb_ld(unsigned* p)              { return __hip_atomic_load(p, __ATOMIC_RELAXED, __HIP_MEMORY_SCOPE_AGENT); }
; __device__ __forceinline__ unsigned xb_add(unsigned* p, unsigned v) { return __hip_atomic_fetch_add(p, v, __ATOMIC_RELAXED, __HIP_MEMORY_SCOPE_AGENT); }
; #define XB_SPIN(cond, bar) do { unsigned _sp = 0; while (cond) { __builtin_amdgcn_s_sleep(1); \
;     if ((++_sp & 255u) == 0u) { if (xb_ld(&(bar)[XB_TMO])) break; if (_sp > XB_SPIN_CAP) { atomicAdd(&(bar)[XB_TMO], 1u); break; } } } } while (0)
; __device__ __forceinline__ bool is_t0(int wave) { return wave == 0 && olane() == 0; }
; __device__ __forceinline__ void xcdl_barrier(const XcdBarrier& b) {
;     ...
;     if (is_t0(b.wave)) {
;         unsigned* bar = b.bar; asm volatile("" : "+s"(bar));
;         __builtin_amdgcn_s_waitcnt(0);
;         const unsigned old = xb_add(&bar[XB_LSUB(b.x)], 1u);
;         const unsigned gen = old >> 5;
;         if ((old & 31u) == 31u) xb_add(&bar[XB_LGEN(b.x)], 1u);
;         else XB_SPIN(xb_ld(&bar[XB_LGEN(b.x)]) == gen, bar);
;         __builtin_amdgcn_fence(__ATOMIC_ACQUIRE, "agent");
;         asm volatile("s_waitcnt vmcnt(0)" ::: "memory");
.LBB0_611:
	s_and_b64 vcc, exec, s[0:1]
	s_cbranch_vccz .LBB0_631
	s_waitcnt vmcnt(0)
	s_and_b64 vcc, exec, s[46:47]
	s_waitcnt vmcnt(0)
	s_barrier
	s_cbranch_vccnz .LBB0_630
	v_mbcnt_lo_u32_b32 v0, -1, 0
	v_mbcnt_hi_u32_b32 v0, -1, v0
	s_nop 0
	v_cmp_eq_u32_e32 vcc, 0, v0
	s_and_saveexec_b64 s[4:5], vcc
	s_cbranch_execz .LBB0_629
	s_mov_b64 s[0:1], s[26:27]
	s_lshl_b32 s6, s23, 2
	s_add_u32 s6, s0, s6
	s_addc_u32 s7, s1, 0
	v_mov_b32_e32 v0, s6
	v_add_co_u32_e32 v0, vcc, 0x3000, v0
	v_mov_b32_e32 v1, s7
	s_nop 0
	v_addc_co_u32_e32 v1, vcc, 0, v1, vcc
	v_mov_b32_e32 v2, 1
	s_waitcnt vmcnt(0) expcnt(0) lgkmcnt(0)
	flat_atomic_add v2, v[0:1], v2 offset:1536 sc0
	s_add_u32 s28, s6, 0x4600
	s_addc_u32 s29, s7, 0
	s_add_u32 s98, s6, 0x3600
	s_addc_u32 s99, s7, 0
	s_nop 0
	s_nop 0
	s_nop 0
	s_nop 0
	s_nop 0
	s_nop 0
	s_nop 0
	s_nop 0
	s_nop 0
	s_nop 0
	s_nop 0
	s_mov_b64 s[8:9], -1
	s_waitcnt vmcnt(0) lgkmcnt(0)
	v_and_b32_e32 v0, 31, v2
	v_cmp_ne_u32_e32 vcc, 31, v0
	v_mov_b64_e32 v[0:1], s[28:29]
	s_and_saveexec_b64 s[6:7], vcc
	s_cbranch_execz .LBB0_626
	v_mov_b64_e32 v[0:1], s[98:99]
	flat_load_dword v1, v[0:1] sc1
	v_lshrrev_b32_e32 v0, 5, v2
	s_mov_b64 s[8:9], 0
	s_waitcnt vmcnt(0) lgkmcnt(0)
	v_lshrrev_b32_e32 v1, 5, v1
	v_cmp_eq_u32_e32 vcc, v1, v0
	s_and_saveexec_b64 s[38:39], vcc
	s_cbranch_execz .LBB0_625
	s_add_u32 s30, s0, 0x200
	s_addc_u32 s31, s1, 0
	s_mov_b32 s17, 1
	s_mov_b64 s[0:1], 0
	s_branch .LBB0_618

; #define GAS __attribute__((address_space(1)))
; __device__ __forceinline__ unsigned cvtpk(float lo, float hi) { f32x2 v = {lo, hi}; bf16x2_t b = __builtin_convertvector(v, bf16x2_t); return __builtin_bit_cast(unsigned, b); }
; __device__ __forceinline__ float u8f(unsigned w, int i) { return (float)((w >> (8 * i)) & 0xffu) * (1.f / 255.f); }
;     __device__ __forceinline__ void epi(const Acc& acc, const GUnit& u, int wr, int wc, int fr, int fq) const {
;         const int c0 = 256 * u.pn + 32 * wc + 8 * fq;
;         const size_t rowb = (size_t)(256 * u.pm + 64 * wr + fr);
;         const int wl = ((wr * 4 + wc) * 64 + fq * 16 + fr) * 32;
;         const unsigned char* G = MG8 + ((size_t)u.pm * 12 + 4 + u.pn) * 65536 + wl;
; #pragma unroll
;         for (int ai = 0; ai < 2; ++ai)
; #pragma unroll
;             for (int bj = 0; bj < 2; ++bj) {
;                 const u32x4 g0 = *(const GAS u32x4*)(G + (ai * 2 + bj) * 16384), g1 = *(const GAS u32x4*)(G + (ai * 2 + bj) * 16384 + 16);
; #pragma unroll
;                 for (int m = 0; m < 4; ++m) { const unsigned gx = (m < 2 ? g0 : g1)[2 * (m & 1)], gy = (m < 2 ? g0 : g1)[2 * (m & 1) + 1]; const f32x4 a0 = acc[ai][bj][m][0], a1 = acc[ai][bj][m][1];
;                     u32x4 w; w.x = cvtpk(u8f(gx, 0) * a0[0], u8f(gx, 1) * a0[1]); w.y = cvtpk(u8f(gx, 2) * a0[2], u8f(gx, 3) * a0[3]);
;                     w.z = cvtpk(u8f(gy, 0) * a1[0], u8f(gy, 1) * a1[1]); w.w = cvtpk(u8f(gy, 2) * a1[2], u8f(gy, 3) * a1[3]);
;                     *(GAS u32x4*)(MERGED + (rowb + 128 * ai + 16 * m) * 1024 + c0 + 128 * bj) = w; }
;             }
;     }
.LBB0_652:
	v_cndmask_b32_e64 v128, 0, 1, s[48:49]
	s_mul_hi_i32 s9, s68, 12
	s_mul_i32 s50, s68, 12
	v_cmp_ne_u32_e64 s[38:39], 1, v128
	s_andn2_b64 vcc, exec, s[48:49]
	s_mov_b64 s[0:1], -1
	s_cbranch_vccnz .LBB0_654
	s_add_u32 s90, s16, 0xffffff00
	s_addc_u32 s91, s17, -1
	s_ashr_i32 s1, s86, 31
	s_add_u32 s0, s50, s86
	s_addc_u32 s1, s9, s1
	s_lshl_b64 s[0:1], s[0:1], 16
	v_lshl_add_u64 v[136:137], v[202:203], 0, s[0:1]
	v_lshl_add_u64 v[184:185], v[136:137], 0, s[70:71]
	s_mov_b64 s[0:1], 0x44000
	v_lshl_add_u64 v[186:187], v[136:137], 0, s[0:1]
	s_mov_b64 s[0:1], 0x48000
	v_lshl_add_u64 v[188:189], v[136:137], 0, s[0:1]
	s_mov_b64 s[0:1], 0x4c000
	v_lshl_add_u64 v[190:191], v[136:137], 0, s[0:1]
	global_load_dwordx4 v[152:155], v[184:185], off
	global_load_dwordx4 v[156:159], v[184:185], off offset:16
	global_load_dwordx4 v[160:163], v[186:187], off
	global_load_dwordx4 v[164:167], v[186:187], off offset:16
	global_load_dwordx4 v[168:171], v[188:189], off
	global_load_dwordx4 v[172:175], v[188:189], off offset:16
	global_load_dwordx4 v[176:179], v[190:191], off
	global_load_dwordx4 v[180:183], v[190:191], off offset:16
	v_add_co_u32_e32 v130, vcc, s59, v136
	v_lshl_add_u64 v[128:129], v[136:137], 0, s[70:71]
	s_nop 0
	v_addc_co_u32_e32 v131, vcc, 0, v137, vcc
	s_waitcnt vmcnt(6)
	v_mov_b32_e32 v132, v152
	v_mov_b32_e32 v133, v153
	v_mov_b32_e32 v134, v154
	v_mov_b32_e32 v135, v155
	s_nop 0
	v_mov_b32_e32 v128, v156
	v_mov_b32_e32 v129, v157
	v_mov_b32_e32 v130, v158
	v_mov_b32_e32 v131, v159
	v_lshl_add_u32 v144, s68, 8, v208
	v_ashrrev_i32_e32 v145, 31, v144
	v_lshl_or_b32 v138, s86, 8, v210
	v_ashrrev_i32_e32 v139, 31, v138
	s_mov_b64 s[0:1], 0x8000
	s_nop 0
	v_cvt_f32_ubyte1_e32 v141, v132
	v_cvt_f32_ubyte0_e32 v140, v132
	v_cvt_f32_ubyte3_e32 v143, v132
	v_cvt_f32_ubyte2_e32 v142, v132
	v_pk_mul_f32 v[140:141], v[140:141], s[20:21] op_sel_hi:[1,0]
	v_pk_mul_f32 v[142:143], v[142:143], s[20:21] op_sel_hi:[1,0]
	v_pk_mul_f32 v[140:141], v[108:109], v[140:141]
	v_pk_mul_f32 v[142:143], v[110:111], v[142:143]
	v_cvt_pk_bf16_f32 v140, v140, v141
	v_cvt_pk_bf16_f32 v141, v142, v143
	v_cvt_f32_ubyte1_e32 v143, v133
	v_cvt_f32_ubyte0_e32 v142, v133
	v_cvt_f32_ubyte3_e32 v147, v133
	v_cvt_f32_ubyte2_e32 v146, v133
	v_pk_mul_f32 v[142:143], v[142:143], s[20:21] op_sel_hi:[1,0]
	v_pk_mul_f32 v[132:133], v[146:147], s[20:21] op_sel_hi:[1,0]
	v_pk_mul_f32 v[142:143], v[104:105], v[142:143]
	v_pk_mul_f32 v[132:133], v[106:107], v[132:133]
	v_cvt_pk_bf16_f32 v142, v142, v143
	v_cvt_pk_bf16_f32 v143, v132, v133
	v_lshlrev_b64 v[132:133], 11, v[144:145]
	v_lshl_add_u64 v[132:133], s[44:45], 0, v[132:133]
	v_lshl_add_u64 v[138:139], v[138:139], 1, v[132:133]
	global_store_dwordx4 v[138:139], v[140:143], off
	v_cvt_f32_ubyte1_e32 v133, v134
	v_cvt_f32_ubyte0_e32 v132, v134
	v_cvt_f32_ubyte3_e32 v141, v134
	v_cvt_f32_ubyte2_e32 v140, v134
	v_pk_mul_f32 v[132:133], v[132:133], s[20:21] op_sel_hi:[1,0]
	v_pk_mul_f32 v[140:141], v[140:141], s[20:21] op_sel_hi:[1,0]
	v_pk_mul_f32 v[132:133], v[100:101], v[132:133]
	v_pk_mul_f32 v[140:141], v[102:103], v[140:141]
	v_cvt_pk_bf16_f32 v132, v132, v133
	v_cvt_pk_bf16_f32 v133, v140, v141
	v_cvt_f32_ubyte1_e32 v141, v135
	v_cvt_f32_ubyte0_e32 v140, v135
	v_pk_mul_f32 v[140:141], v[140:141], s[20:21] op_sel_hi:[1,0]
	v_lshl_add_u64 v[142:143], v[138:139], 0, s[0:1]
	v_pk_mul_f32 v[140:141], v[96:97], v[140:141]
	s_mov_b64 s[0:1], 0x10000
	v_cvt_pk_bf16_f32 v134, v140, v141
	v_cvt_f32_ubyte3_e32 v141, v135
	v_cvt_f32_ubyte2_e32 v140, v135
	v_pk_mul_f32 v[140:141], v[140:141], s[20:21] op_sel_hi:[1,0]
	s_nop 0
	v_pk_mul_f32 v[140:141], v[98:99], v[140:141]
	s_nop 0
	v_cvt_pk_bf16_f32 v135, v140, v141
	v_add_co_u32_e32 v140, vcc, s58, v138
	s_nop 1
	v_addc_co_u32_e32 v141, vcc, 0, v139, vcc
	global_store_dwordx4 v[140:141], v[132:135], off
	v_cvt_f32_ubyte3_e32 v141, v129
	v_cvt_f32_ubyte2_e32 v140, v129
	v_cvt_f32_ubyte1_e32 v133, v128
	v_cvt_f32_ubyte0_e32 v132, v128
	v_cvt_f32_ubyte3_e32 v135, v128
	v_cvt_f32_ubyte2_e32 v134, v128
	v_pk_mul_f32 v[132:133], v[132:133], s[20:21] op_sel_hi:[1,0]
	v_pk_mul_f32 v[134:135], v[134:135], s[20:21] op_sel_hi:[1,0]
	v_pk_mul_f32 v[132:133], v[92:93], v[132:133]
	v_pk_mul_f32 v[134:135], v[94:95], v[134:135]
	v_cvt_pk_bf16_f32 v132, v132, v133
	v_cvt_pk_bf16_f32 v133, v134, v135
	v_cvt_f32_ubyte1_e32 v135, v129
	v_cvt_f32_ubyte0_e32 v134, v129
	v_pk_mul_f32 v[134:135], v[134:135], s[20:21] op_sel_hi:[1,0]
	v_pk_mul_f32 v[128:129], v[140:141], s[20:21] op_sel_hi:[1,0]
	v_pk_mul_f32 v[134:135], v[88:89], v[134:135]
	v_pk_mul_f32 v[128:129], v[90:91], v[128:129]
	v_lshl_add_u64 v[140:141], v[138:139], 0, s[0:1]
	s_mov_b32 s0, 0x10000
	v_cvt_pk_bf16_f32 v134, v134, v135
	v_cvt_pk_bf16_f32 v135, v128, v129
	v_add_co_u32_e32 v128, vcc, s0, v138
	s_mov_b64 s[0:1], 0x18000
	s_nop 0
	v_addc_co_u32_e32 v129, vcc, 0, v139, vcc
	global_store_dwordx4 v[128:129], v[132:135], off
	v_cvt_f32_ubyte1_e32 v129, v130
	v_cvt_f32_ubyte0_e32 v128, v130
	v_cvt_f32_ubyte3_e32 v133, v130
	v_cvt_f32_ubyte2_e32 v132, v130
	v_pk_mul_f32 v[128:129], v[128:129], s[20:21] op_sel_hi:[1,0]
	v_pk_mul_f32 v[132:133], v[132:133], s[20:21] op_sel_hi:[1,0]
	v_pk_mul_f32 v[128:129], v[84:85], v[128:129]
	v_pk_mul_f32 v[132:133], v[86:87], v[132:133]
	v_cvt_pk_bf16_f32 v128, v128, v129
	v_cvt_pk_bf16_f32 v129, v132, v133
	v_cvt_f32_ubyte1_e32 v133, v131
	v_cvt_f32_ubyte0_e32 v132, v131
	v_pk_mul_f32 v[132:133], v[132:133], s[20:21] op_sel_hi:[1,0]
	s_nop 0
	v_pk_mul_f32 v[132:133], v[80:81], v[132:133]
	s_nop 0
	v_cvt_pk_bf16_f32 v130, v132, v133
	v_cvt_f32_ubyte3_e32 v133, v131
	v_cvt_f32_ubyte2_e32 v132, v131
	v_pk_mul_f32 v[132:133], v[132:133], s[20:21] op_sel_hi:[1,0]
	s_nop 0
	v_pk_mul_f32 v[132:133], v[82:83], v[132:133]
	s_nop 0
	v_cvt_pk_bf16_f32 v131, v132, v133
	v_lshl_add_u64 v[132:133], v[138:139], 0, s[0:1]
	s_mov_b32 s0, 0x18000
	v_add_co_u32_e32 v134, vcc, s0, v138
	s_mov_b64 s[0:1], 0x44000
	s_nop 0
	v_addc_co_u32_e32 v135, vcc, 0, v139, vcc
	global_store_dwordx4 v[134:135], v[128:131], off
	s_nop 1
	v_lshl_add_u64 v[128:129], v[136:137], 0, s[0:1]
	s_mov_b32 s0, 0x44000
	v_add_co_u32_e32 v130, vcc, s0, v136
	s_mov_b64 s[0:1], 0x48000
	s_nop 0
	v_addc_co_u32_e32 v131, vcc, 0, v137, vcc
	s_waitcnt vmcnt(8)
; #define GAS __attribute__((address_space(1)))
; __device__ __forceinline__ unsigned cvtpk(float lo, float hi) { f32x2 v = {lo, hi}; bf16x2_t b = __builtin_convertvector(v, bf16x2_t); return __builtin_bit_cast(unsigned, b); }
; __device__ __forceinline__ float u8f(unsigned w, int i) { return (float)((w >> (8 * i)) & 0xffu) * (1.f / 255.f); }
;     __device__ __forceinline__ void epi(const Acc& acc, const GUnit& u, int wr, int wc, int fr, int fq) const {
;         const int c0 = 256 * u.pn + 32 * wc + 8 * fq;
;         const size_t rowb = (size_t)(256 * u.pm + 64 * wr + fr);
;         const int wl = ((wr * 4 + wc) * 64 + fq * 16 + fr) * 32;
;         const unsigned char* G = MG8 + ((size_t)u.pm * 12 + 4 + u.pn) * 65536 + wl;
; #pragma unroll
;         for (int ai = 0; ai < 2; ++ai)
; #pragma unroll
;             for (int bj = 0; bj < 2; ++bj) {
;                 const u32x4 g0 = *(const GAS u32x4*)(G + (ai * 2 + bj) * 16384), g1 = *(const GAS u32x4*)(G + (ai * 2 + bj) * 16384 + 16);
; #pragma unroll
;                 for (int m = 0; m < 4; ++m) { const unsigned gx = (m < 2 ? g0 : g1)[2 * (m & 1)], gy = (m < 2 ? g0 : g1)[2 * (m & 1) + 1]; const f32x4 a0 = acc[ai][bj][m][0], a1 = acc[ai][bj][m][1];
;                     u32x4 w; w.x = cvtpk(u8f(gx, 0) * a0[0], u8f(gx, 1) * a0[1]); w.y = cvtpk(u8f(gx, 2) * a0[2], u8f(gx, 3) * a0[3]);
;                     w.z = cvtpk(u8f(gy, 0) * a1[0], u8f(gy, 1) * a1[1]); w.w = cvtpk(u8f(gy, 2) * a1[2], u8f(gy, 3) * a1[3]);
;                     *(GAS u32x4*)(MERGED + (rowb + 128 * ai + 16 * m) * 1024 + c0 + 128 * bj) = w; }
;             }
;     }
	v_mov_b32_e32 v144, v160
	v_mov_b32_e32 v145, v161
	v_mov_b32_e32 v146, v162
	v_mov_b32_e32 v147, v163
	s_nop 0
	v_mov_b32_e32 v128, v164
	v_mov_b32_e32 v129, v165
	v_mov_b32_e32 v130, v166
	v_mov_b32_e32 v131, v167
	s_nop 0
	v_cvt_f32_ubyte1_e32 v135, v144
	v_cvt_f32_ubyte0_e32 v134, v144
	v_pk_mul_f32 v[134:135], v[134:135], s[20:21] op_sel_hi:[1,0]
	s_nop 0
	v_pk_mul_f32 v[134:135], v[76:77], v[134:135]
	s_nop 0
	v_cvt_pk_bf16_f32 v148, v134, v135
	v_cvt_f32_ubyte3_e32 v135, v144
	v_cvt_f32_ubyte2_e32 v134, v144
	v_pk_mul_f32 v[134:135], v[134:135], s[20:21] op_sel_hi:[1,0]
	s_nop 0
	v_pk_mul_f32 v[134:135], v[78:79], v[134:135]
	s_nop 0
	v_cvt_pk_bf16_f32 v149, v134, v135
	v_cvt_f32_ubyte1_e32 v135, v145
	v_cvt_f32_ubyte0_e32 v134, v145
	v_pk_mul_f32 v[134:135], v[134:135], s[20:21] op_sel_hi:[1,0]
	s_nop 0
	v_pk_mul_f32 v[134:135], v[72:73], v[134:135]
	s_nop 0
	v_cvt_pk_bf16_f32 v150, v134, v135
	v_cvt_f32_ubyte3_e32 v135, v145
	v_cvt_f32_ubyte2_e32 v134, v145
	v_pk_mul_f32 v[134:135], v[134:135], s[20:21] op_sel_hi:[1,0]
	s_nop 0
	v_pk_mul_f32 v[134:135], v[74:75], v[134:135]
	s_nop 0
	v_cvt_pk_bf16_f32 v151, v134, v135
	v_cvt_f32_ubyte1_e32 v135, v146
	v_cvt_f32_ubyte0_e32 v134, v146
	v_pk_mul_f32 v[134:135], v[134:135], s[20:21] op_sel_hi:[1,0]
	global_store_dwordx4 v[138:139], v[148:151], off offset:256
	v_pk_mul_f32 v[134:135], v[68:69], v[134:135]
	s_nop 0
	v_cvt_pk_bf16_f32 v144, v134, v135
	v_cvt_f32_ubyte3_e32 v135, v146
	v_cvt_f32_ubyte2_e32 v134, v146
	v_pk_mul_f32 v[134:135], v[134:135], s[20:21] op_sel_hi:[1,0]
	s_nop 0
	v_pk_mul_f32 v[134:135], v[70:71], v[134:135]
	s_nop 0
	v_cvt_pk_bf16_f32 v145, v134, v135
	v_cvt_f32_ubyte1_e32 v135, v147
	v_cvt_f32_ubyte0_e32 v134, v147
	v_pk_mul_f32 v[134:135], v[134:135], s[20:21] op_sel_hi:[1,0]
	s_nop 0
	v_pk_mul_f32 v[134:135], v[64:65], v[134:135]
	s_nop 0
	v_cvt_pk_bf16_f32 v146, v134, v135
	v_cvt_f32_ubyte3_e32 v135, v147
	v_cvt_f32_ubyte2_e32 v134, v147
	v_pk_mul_f32 v[134:135], v[134:135], s[20:21] op_sel_hi:[1,0]
	s_nop 0
	v_pk_mul_f32 v[134:135], v[66:67], v[134:135]
	s_nop 0
	v_cvt_pk_bf16_f32 v147, v134, v135
	s_nop 0
	v_cvt_f32_ubyte1_e32 v135, v128
	v_cvt_f32_ubyte0_e32 v134, v128
	v_pk_mul_f32 v[134:135], v[134:135], s[20:21] op_sel_hi:[1,0]
	global_store_dwordx4 v[142:143], v[144:147], off offset:256
	v_pk_mul_f32 v[134:135], v[60:61], v[134:135]
	s_nop 0
	v_cvt_pk_bf16_f32 v142, v134, v135
	v_cvt_f32_ubyte3_e32 v135, v128
	v_cvt_f32_ubyte2_e32 v134, v128
	v_pk_mul_f32 v[134:135], v[134:135], s[20:21] op_sel_hi:[1,0]
	s_nop 0
	v_pk_mul_f32 v[134:135], v[62:63], v[134:135]
	s_nop 0
	v_cvt_pk_bf16_f32 v143, v134, v135
	v_cvt_f32_ubyte1_e32 v135, v129
	v_cvt_f32_ubyte0_e32 v134, v129
	v_pk_mul_f32 v[134:135], v[134:135], s[20:21] op_sel_hi:[1,0]
	s_nop 0
	v_pk_mul_f32 v[134:135], v[56:57], v[134:135]
	s_nop 0
	v_cvt_pk_bf16_f32 v144, v134, v135
	v_cvt_f32_ubyte3_e32 v135, v129
	v_cvt_f32_ubyte2_e32 v134, v129
	v_pk_mul_f32 v[128:129], v[134:135], s[20:21] op_sel_hi:[1,0]
	v_cvt_f32_ubyte3_e32 v135, v130
	v_pk_mul_f32 v[128:129], v[58:59], v[128:129]
	v_cvt_f32_ubyte2_e32 v134, v130
	v_cvt_pk_bf16_f32 v145, v128, v129
	v_cvt_f32_ubyte1_e32 v129, v130
	v_cvt_f32_ubyte0_e32 v128, v130
	v_pk_mul_f32 v[128:129], v[128:129], s[20:21] op_sel_hi:[1,0]
	v_pk_mul_f32 v[134:135], v[134:135], s[20:21] op_sel_hi:[1,0]
	v_pk_mul_f32 v[128:129], v[52:53], v[128:129]
	v_pk_mul_f32 v[134:135], v[54:55], v[134:135]
	v_cvt_pk_bf16_f32 v128, v128, v129
	v_cvt_pk_bf16_f32 v129, v134, v135
	v_cvt_f32_ubyte1_e32 v135, v131
	v_cvt_f32_ubyte0_e32 v134, v131
	v_pk_mul_f32 v[134:135], v[134:135], s[20:21] op_sel_hi:[1,0]
	global_store_dwordx4 v[140:141], v[142:145], off offset:256
	v_pk_mul_f32 v[134:135], v[48:49], v[134:135]
	s_nop 0
	v_cvt_pk_bf16_f32 v130, v134, v135
	v_cvt_f32_ubyte3_e32 v135, v131
	v_cvt_f32_ubyte2_e32 v134, v131
	v_pk_mul_f32 v[134:135], v[134:135], s[20:21] op_sel_hi:[1,0]
	s_nop 0
	v_pk_mul_f32 v[134:135], v[50:51], v[134:135]
	s_nop 0
	v_cvt_pk_bf16_f32 v131, v134, v135
	global_store_dwordx4 v[132:133], v[128:131], off offset:256
	s_nop 1
	v_add_co_u32_e32 v130, vcc, s60, v136
	v_lshl_add_u64 v[128:129], v[136:137], 0, s[0:1]
	s_nop 0
	v_addc_co_u32_e32 v131, vcc, 0, v137, vcc
	s_waitcnt vmcnt(10)
; #define GAS __attribute__((address_space(1)))
; __device__ __forceinline__ unsigned cvtpk(float lo, float hi) { f32x2 v = {lo, hi}; bf16x2_t b = __builtin_convertvector(v, bf16x2_t); return __builtin_bit_cast(unsigned, b); }
; __device__ __forceinline__ float u8f(unsigned w, int i) { return (float)((w >> (8 * i)) & 0xffu) * (1.f / 255.f); }
;     __device__ __forceinline__ void epi(const Acc& acc, const GUnit& u, int wr, int wc, int fr, int fq) const {
;         const int c0 = 256 * u.pn + 32 * wc + 8 * fq;
;         const size_t rowb = (size_t)(256 * u.pm + 64 * wr + fr);
;         const int wl = ((wr * 4 + wc) * 64 + fq * 16 + fr) * 32;
;         const unsigned char* G = MG8 + ((size_t)u.pm * 12 + 4 + u.pn) * 65536 + wl;
; #pragma unroll
;         for (int ai = 0; ai < 2; ++ai)
; #pragma unroll
;             for (int bj = 0; bj < 2; ++bj) {
;                 const u32x4 g0 = *(const GAS u32x4*)(G + (ai * 2 + bj) * 16384), g1 = *(const GAS u32x4*)(G + (ai * 2 + bj) * 16384 + 16);
; #pragma unroll
;                 for (int m = 0; m < 4; ++m) { const unsigned gx = (m < 2 ? g0 : g1)[2 * (m & 1)], gy = (m < 2 ? g0 : g1)[2 * (m & 1) + 1]; const f32x4 a0 = acc[ai][bj][m][0], a1 = acc[ai][bj][m][1];
;                     u32x4 w; w.x = cvtpk(u8f(gx, 0) * a0[0], u8f(gx, 1) * a0[1]); w.y = cvtpk(u8f(gx, 2) * a0[2], u8f(gx, 3) * a0[3]);
;                     w.z = cvtpk(u8f(gy, 0) * a1[0], u8f(gy, 1) * a1[1]); w.w = cvtpk(u8f(gy, 2) * a1[2], u8f(gy, 3) * a1[3]);
;                     *(GAS u32x4*)(MERGED + (rowb + 128 * ai + 16 * m) * 1024 + c0 + 128 * bj) = w; }
;             }
;     }
	v_mov_b32_e32 v132, v168
	v_mov_b32_e32 v133, v169
	v_mov_b32_e32 v134, v170
	v_mov_b32_e32 v135, v171
	s_nop 0
	v_mov_b32_e32 v128, v172
	v_mov_b32_e32 v129, v173
	v_mov_b32_e32 v130, v174
	v_mov_b32_e32 v131, v175
	s_nop 0
	v_cvt_f32_ubyte1_e32 v141, v132
	v_cvt_f32_ubyte0_e32 v140, v132
	v_cvt_f32_ubyte3_e32 v143, v132
	v_cvt_f32_ubyte2_e32 v142, v132
	v_pk_mul_f32 v[140:141], v[140:141], s[20:21] op_sel_hi:[1,0]
	v_pk_mul_f32 v[142:143], v[142:143], s[20:21] op_sel_hi:[1,0]
	v_pk_mul_f32 v[140:141], v[44:45], v[140:141]
	v_pk_mul_f32 v[142:143], v[46:47], v[142:143]
	v_cvt_pk_bf16_f32 v140, v140, v141
	v_cvt_pk_bf16_f32 v141, v142, v143
	v_cvt_f32_ubyte1_e32 v143, v133
	v_cvt_f32_ubyte0_e32 v142, v133
	v_cvt_f32_ubyte3_e32 v145, v133
	v_cvt_f32_ubyte2_e32 v144, v133
	v_pk_mul_f32 v[142:143], v[142:143], s[20:21] op_sel_hi:[1,0]
	v_pk_mul_f32 v[132:133], v[144:145], s[20:21] op_sel_hi:[1,0]
	v_pk_mul_f32 v[142:143], v[40:41], v[142:143]
	v_pk_mul_f32 v[132:133], v[42:43], v[132:133]
	v_add_co_u32_e32 v144, vcc, s59, v138
	v_cvt_pk_bf16_f32 v142, v142, v143
	v_cvt_pk_bf16_f32 v143, v132, v133
	v_addc_co_u32_e32 v145, vcc, 0, v139, vcc
	global_store_dwordx4 v[144:145], v[140:143], off
	v_cvt_f32_ubyte3_e32 v145, v135
	v_cvt_f32_ubyte2_e32 v144, v135
	v_cvt_f32_ubyte1_e32 v141, v134
	v_cvt_f32_ubyte0_e32 v140, v134
	v_cvt_f32_ubyte3_e32 v143, v134
	v_cvt_f32_ubyte2_e32 v142, v134
	v_pk_mul_f32 v[140:141], v[140:141], s[20:21] op_sel_hi:[1,0]
	v_pk_mul_f32 v[142:143], v[142:143], s[20:21] op_sel_hi:[1,0]
	v_pk_mul_f32 v[140:141], v[36:37], v[140:141]
	v_pk_mul_f32 v[142:143], v[38:39], v[142:143]
	v_cvt_pk_bf16_f32 v140, v140, v141
	v_cvt_pk_bf16_f32 v141, v142, v143
	v_cvt_f32_ubyte1_e32 v143, v135
	v_cvt_f32_ubyte0_e32 v142, v135
	v_pk_mul_f32 v[142:143], v[142:143], s[20:21] op_sel_hi:[1,0]
	v_pk_mul_f32 v[134:135], v[144:145], s[20:21] op_sel_hi:[1,0]
	v_pk_mul_f32 v[142:143], v[32:33], v[142:143]
	v_pk_mul_f32 v[134:135], v[34:35], v[134:135]
	v_add_co_u32_e32 v144, vcc, s60, v138
	v_cvt_pk_bf16_f32 v142, v142, v143
	v_cvt_pk_bf16_f32 v143, v134, v135
	v_addc_co_u32_e32 v145, vcc, 0, v139, vcc
	global_store_dwordx4 v[144:145], v[140:143], off
	s_nop 0
	v_cvt_f32_ubyte3_e32 v145, v129
	v_cvt_f32_ubyte2_e32 v144, v129
	v_cvt_f32_ubyte1_e32 v141, v128
	v_cvt_f32_ubyte0_e32 v140, v128
	v_cvt_f32_ubyte3_e32 v143, v128
	v_cvt_f32_ubyte2_e32 v142, v128
	v_pk_mul_f32 v[140:141], v[140:141], s[20:21] op_sel_hi:[1,0]
	v_pk_mul_f32 v[142:143], v[142:143], s[20:21] op_sel_hi:[1,0]
	v_pk_mul_f32 v[140:141], v[28:29], v[140:141]
	v_pk_mul_f32 v[142:143], v[30:31], v[142:143]
	v_cvt_pk_bf16_f32 v140, v140, v141
	v_cvt_pk_bf16_f32 v141, v142, v143
	v_cvt_f32_ubyte1_e32 v143, v129
	v_cvt_f32_ubyte0_e32 v142, v129
	v_pk_mul_f32 v[142:143], v[142:143], s[20:21] op_sel_hi:[1,0]
	v_pk_mul_f32 v[128:129], v[144:145], s[20:21] op_sel_hi:[1,0]
	v_lshl_add_u64 v[134:135], v[138:139], 0, s[0:1]
	v_pk_mul_f32 v[142:143], v[24:25], v[142:143]
	v_pk_mul_f32 v[128:129], v[26:27], v[128:129]
	s_mov_b64 s[0:1], 0x50000
	v_cvt_pk_bf16_f32 v142, v142, v143
	v_cvt_pk_bf16_f32 v143, v128, v129
	v_lshl_add_u64 v[128:129], v[138:139], 0, s[0:1]
	s_mov_b32 s0, 0x50000
	v_add_co_u32_e32 v144, vcc, s0, v138
	s_mov_b64 s[0:1], 0x58000
	s_nop 0
	v_addc_co_u32_e32 v145, vcc, 0, v139, vcc
	global_store_dwordx4 v[144:145], v[140:143], off
	v_cvt_f32_ubyte3_e32 v145, v131
	v_cvt_f32_ubyte2_e32 v144, v131
	v_cvt_f32_ubyte1_e32 v141, v130
	v_cvt_f32_ubyte0_e32 v140, v130
	v_cvt_f32_ubyte3_e32 v143, v130
	v_cvt_f32_ubyte2_e32 v142, v130
	v_pk_mul_f32 v[140:141], v[140:141], s[20:21] op_sel_hi:[1,0]
	v_pk_mul_f32 v[142:143], v[142:143], s[20:21] op_sel_hi:[1,0]
	v_pk_mul_f32 v[140:141], v[20:21], v[140:141]
	v_pk_mul_f32 v[142:143], v[22:23], v[142:143]
	v_cvt_pk_bf16_f32 v140, v140, v141
	v_cvt_pk_bf16_f32 v141, v142, v143
	v_cvt_f32_ubyte1_e32 v143, v131
	v_cvt_f32_ubyte0_e32 v142, v131
	v_pk_mul_f32 v[142:143], v[142:143], s[20:21] op_sel_hi:[1,0]
	v_pk_mul_f32 v[130:131], v[144:145], s[20:21] op_sel_hi:[1,0]
	v_pk_mul_f32 v[142:143], v[16:17], v[142:143]
	v_pk_mul_f32 v[130:131], v[18:19], v[130:131]
	v_cvt_pk_bf16_f32 v142, v142, v143
	v_cvt_pk_bf16_f32 v143, v130, v131
	v_lshl_add_u64 v[130:131], v[138:139], 0, s[0:1]
	s_mov_b32 s0, 0x58000
	v_lshl_add_u64 v[132:133], v[138:139], 0, s[70:71]
	v_add_co_u32_e32 v138, vcc, s0, v138
	s_mov_b64 s[0:1], 0x4c000
	s_nop 0
	v_addc_co_u32_e32 v139, vcc, 0, v139, vcc
	global_store_dwordx4 v[138:139], v[140:143], off
	s_nop 1
	v_lshl_add_u64 v[140:141], v[136:137], 0, s[0:1]
	s_mov_b32 s0, 0x4c000
	v_add_co_u32_e32 v136, vcc, s0, v136
	s_nop 1
	v_addc_co_u32_e32 v137, vcc, 0, v137, vcc
	s_waitcnt vmcnt(12)
; #define GAS __attribute__((address_space(1)))
; __device__ __forceinline__ unsigned cvtpk(float lo, float hi) { f32x2 v = {lo, hi}; bf16x2_t b = __builtin_convertvector(v, bf16x2_t); return __builtin_bit_cast(unsigned, b); }
; __device__ __forceinline__ float u8f(unsigned w, int i) { return (float)((w >> (8 * i)) & 0xffu) * (1.f / 255.f); }
;     __device__ __forceinline__ void epi(const Acc& acc, const GUnit& u, int wr, int wc, int fr, int fq) const {
;         const int c0 = 256 * u.pn + 32 * wc + 8 * fq;
;         const size_t rowb = (size_t)(256 * u.pm + 64 * wr + fr);
;         const int wl = ((wr * 4 + wc) * 64 + fq * 16 + fr) * 32;
;         const unsigned char* G = MG8 + ((size_t)u.pm * 12 + 4 + u.pn) * 65536 + wl;
; #pragma unroll
;         for (int ai = 0; ai < 2; ++ai)
; #pragma unroll
;             for (int bj = 0; bj < 2; ++bj) {
;                 const u32x4 g0 = *(const GAS u32x4*)(G + (ai * 2 + bj) * 16384), g1 = *(const GAS u32x4*)(G + (ai * 2 + bj) * 16384 + 16);
; #pragma unroll
;                 for (int m = 0; m < 4; ++m) { const unsigned gx = (m < 2 ? g0 : g1)[2 * (m & 1)], gy = (m < 2 ? g0 : g1)[2 * (m & 1) + 1]; const f32x4 a0 = acc[ai][bj][m][0], a1 = acc[ai][bj][m][1];
;                     u32x4 w; w.x = cvtpk(u8f(gx, 0) * a0[0], u8f(gx, 1) * a0[1]); w.y = cvtpk(u8f(gx, 2) * a0[2], u8f(gx, 3) * a0[3]);
;                     w.z = cvtpk(u8f(gy, 0) * a1[0], u8f(gy, 1) * a1[1]); w.w = cvtpk(u8f(gy, 2) * a1[2], u8f(gy, 3) * a1[3]);
;                     *(GAS u32x4*)(MERGED + (rowb + 128 * ai + 16 * m) * 1024 + c0 + 128 * bj) = w; }
;             }
;     }
	v_mov_b32_e32 v136, v176
	v_mov_b32_e32 v137, v177
	v_mov_b32_e32 v138, v178
	v_mov_b32_e32 v139, v179
	s_nop 0
	v_mov_b32_e32 v140, v180
	v_mov_b32_e32 v141, v181
	v_mov_b32_e32 v142, v182
	v_mov_b32_e32 v143, v183
	s_nop 0
	v_cvt_f32_ubyte1_e32 v145, v136
	v_cvt_f32_ubyte0_e32 v144, v136
	v_cvt_f32_ubyte3_e32 v147, v136
	v_cvt_f32_ubyte2_e32 v146, v136
	v_pk_mul_f32 v[144:145], v[144:145], s[20:21] op_sel_hi:[1,0]
	v_pk_mul_f32 v[146:147], v[146:147], s[20:21] op_sel_hi:[1,0]
	v_pk_mul_f32 v[144:145], v[12:13], v[144:145]
	v_pk_mul_f32 v[146:147], v[14:15], v[146:147]
	v_cvt_pk_bf16_f32 v144, v144, v145
	v_cvt_pk_bf16_f32 v145, v146, v147
	v_cvt_f32_ubyte1_e32 v147, v137
	v_cvt_f32_ubyte0_e32 v146, v137
	v_cvt_f32_ubyte3_e32 v149, v137
	v_cvt_f32_ubyte2_e32 v148, v137
	v_pk_mul_f32 v[146:147], v[146:147], s[20:21] op_sel_hi:[1,0]
	v_pk_mul_f32 v[136:137], v[148:149], s[20:21] op_sel_hi:[1,0]
	v_pk_mul_f32 v[146:147], v[8:9], v[146:147]
	v_pk_mul_f32 v[136:137], v[10:11], v[136:137]
	v_cvt_pk_bf16_f32 v146, v146, v147
	v_cvt_pk_bf16_f32 v147, v136, v137
	global_store_dwordx4 v[132:133], v[144:147], off offset:256
	v_cvt_f32_ubyte1_e32 v133, v138
	v_cvt_f32_ubyte0_e32 v132, v138
	v_pk_mul_f32 v[132:133], v[132:133], s[20:21] op_sel_hi:[1,0]
	s_nop 0
	v_pk_mul_f32 v[132:133], v[4:5], v[132:133]
	s_nop 0
	v_cvt_pk_bf16_f32 v136, v132, v133
	v_cvt_f32_ubyte3_e32 v133, v138
	v_cvt_f32_ubyte2_e32 v132, v138
	v_pk_mul_f32 v[132:133], v[132:133], s[20:21] op_sel_hi:[1,0]
	s_nop 0
	v_pk_mul_f32 v[132:133], v[6:7], v[132:133]
	s_nop 0
	v_cvt_pk_bf16_f32 v137, v132, v133
	v_cvt_f32_ubyte1_e32 v133, v139
	v_cvt_f32_ubyte0_e32 v132, v139
	v_pk_mul_f32 v[132:133], v[132:133], s[20:21] op_sel_hi:[1,0]
	s_nop 0
	v_pk_mul_f32 v[132:133], v[0:1], v[132:133]
	s_nop 0
	v_cvt_pk_bf16_f32 v138, v132, v133
	v_cvt_f32_ubyte3_e32 v133, v139
	v_cvt_f32_ubyte2_e32 v132, v139
	v_pk_mul_f32 v[132:133], v[132:133], s[20:21] op_sel_hi:[1,0]
	s_nop 0
	v_pk_mul_f32 v[132:133], v[2:3], v[132:133]
	s_nop 0
	v_cvt_pk_bf16_f32 v139, v132, v133
	global_store_dwordx4 v[134:135], v[136:139], off offset:256
	s_nop 0
	v_cvt_f32_ubyte1_e32 v133, v140
	v_cvt_f32_ubyte0_e32 v132, v140
	v_cvt_f32_ubyte3_e32 v135, v140
	v_cvt_f32_ubyte2_e32 v134, v140
	v_pk_mul_f32 v[132:133], v[132:133], s[20:21] op_sel_hi:[1,0]
	v_pk_mul_f32 v[134:135], v[134:135], s[20:21] op_sel_hi:[1,0]
	v_pk_mul_f32 v[132:133], v[112:113], v[132:133]
	v_pk_mul_f32 v[134:135], v[114:115], v[134:135]
	v_cvt_pk_bf16_f32 v132, v132, v133
	v_cvt_pk_bf16_f32 v133, v134, v135
	v_cvt_f32_ubyte1_e32 v135, v141
	v_cvt_f32_ubyte0_e32 v134, v141
	v_cvt_f32_ubyte3_e32 v137, v141
	v_cvt_f32_ubyte2_e32 v136, v141
	v_pk_mul_f32 v[134:135], v[134:135], s[20:21] op_sel_hi:[1,0]
	v_pk_mul_f32 v[136:137], v[136:137], s[20:21] op_sel_hi:[1,0]
	v_pk_mul_f32 v[134:135], v[116:117], v[134:135]
	v_pk_mul_f32 v[136:137], v[118:119], v[136:137]
	v_cvt_pk_bf16_f32 v134, v134, v135
	v_cvt_pk_bf16_f32 v135, v136, v137
	global_store_dwordx4 v[128:129], v[132:135], off offset:256
	v_cvt_f32_ubyte1_e32 v129, v142
	v_cvt_f32_ubyte0_e32 v128, v142
	v_pk_mul_f32 v[128:129], v[128:129], s[20:21] op_sel_hi:[1,0]
	s_nop 0
	v_pk_mul_f32 v[128:129], v[120:121], v[128:129]
	s_nop 0
	v_cvt_pk_bf16_f32 v132, v128, v129
	v_cvt_f32_ubyte3_e32 v129, v142
	v_cvt_f32_ubyte2_e32 v128, v142
	v_pk_mul_f32 v[128:129], v[128:129], s[20:21] op_sel_hi:[1,0]
	s_nop 0
	v_pk_mul_f32 v[128:129], v[122:123], v[128:129]
	s_nop 0
	v_cvt_pk_bf16_f32 v133, v128, v129
	v_cvt_f32_ubyte1_e32 v129, v143
	v_cvt_f32_ubyte0_e32 v128, v143
	v_pk_mul_f32 v[128:129], v[128:129], s[20:21] op_sel_hi:[1,0]
	s_nop 0
	v_pk_mul_f32 v[128:129], v[124:125], v[128:129]
	s_nop 0
	v_cvt_pk_bf16_f32 v134, v128, v129
	v_cvt_f32_ubyte3_e32 v129, v143
	v_cvt_f32_ubyte2_e32 v128, v143
	v_pk_mul_f32 v[128:129], v[128:129], s[20:21] op_sel_hi:[1,0]
	s_nop 0
	v_pk_mul_f32 v[128:129], v[126:127], v[128:129]
	s_nop 0
	v_cvt_pk_bf16_f32 v135, v128, v129
	global_store_dwordx4 v[130:131], v[132:135], off offset:256
	s_cbranch_execnz .LBB0_637
	s_branch .LBB0_655
	s_nop 0
	s_nop 0
	s_nop 0
	s_nop 0
	s_nop 0
	s_nop 0
	s_nop 0
	s_nop 0
	s_nop 0
	s_nop 0
	s_nop 0
	s_nop 0
	s_nop 0
	s_nop 0
